# full-line DMA layout with plain two-deep accumulator chains (no operand-sharing order)
# baseline (speedup 1.0000x reference)
.LBB0_74:
	s_ashr_i32 s27, s26, 31
	s_lshl_b64 s[28:29], s[26:27], 19
	s_add_u32 s28, s3, s28
	s_addc_u32 s29, s35, s29
	s_and_b64 s[30:31], s[4:5], exec
	s_cselect_b32 s27, s29, s49
	s_cselect_b32 s68, s28, s48
	s_ashr_i32 s23, s22, 31
	s_lshl_b64 s[30:31], s[22:23], 19
	s_add_u32 s30, s50, s30
	s_addc_u32 s31, s51, s31
	s_and_b64 s[70:71], s[4:5], exec
	s_cselect_b32 s69, s31, s47
	s_cselect_b32 s70, s30, s46
	s_lshl_b32 s23, s44, 8
	v_add_u32_e32 v0, s23, v148
	s_add_u32 s71, s46, 0x100
	v_ashrrev_i32_e32 v1, 31, v0
	s_addc_u32 s74, s47, 0
	v_lshl_add_u64 v[144:145], v[0:1], 4, s[12:13]
	s_add_u32 s44, s48, 0x40080
	s_addc_u32 s45, s49, 0
	s_mov_b32 s75, -2
	s_mov_b64 s[46:47], 0
	s_cmp_eq_u32 s59, 1
	s_cbranch_scc1 .Lfa_0
	v_add_u32_e32 v153, s64, v147
	ds_read_b128 v[160:163], v153
	v_xor_b32_e32 v253, 64, v153
	ds_read_b128 v[164:167], v253
	ds_read_b128 v[168:171], v153 offset:2048
	ds_read_b128 v[172:175], v253 offset:2048
	v_add_u32_e32 v153, s65, v147
	ds_read_b128 v[176:179], v153
	v_xor_b32_e32 v253, 64, v153
	ds_read_b128 v[180:183], v253
	ds_read_b128 v[186:189], v153 offset:2048
	ds_read_b128 v[190:193], v253 offset:2048
	s_add_u32 s48, s44, 0xfffc0080
	s_addc_u32 s49, s45, -1
	s_and_b64 s[46:47], s[46:47], exec
	s_cselect_b32 s49, s27, s49
	s_cselect_b32 s48, s68, s48
	s_cselect_b32 s47, s69, s74
	s_cselect_b32 s46, s70, s71
	v_lshl_add_u64 v[154:155], s[44:45], 0, v[138:139]
	s_add_i32 m0, s55, 0xc000
	ds_read_b128 v[194:197], v150
	v_xor_b32_e32 v253, 64, v150
	ds_read_b128 v[198:201], v253
	ds_read_b128 v[202:205], v150 offset:2048
	ds_read_b128 v[206:209], v253 offset:2048
	ds_read_b128 v[210:213], v150 offset:4096
	ds_read_b128 v[214:217], v253 offset:4096
	ds_read_b128 v[218:221], v150 offset:6144
	ds_read_b128 v[222:225], v253 offset:6144
	global_load_lds_dwordx4 v[154:155], off
	v_lshl_add_u64 v[154:155], s[44:45], 0, v[136:137]
	s_add_i32 m0, s55, 0xe000
	s_nop 0
	global_load_lds_dwordx4 v[154:155], off
	s_waitcnt vmcnt(16)
	s_waitcnt lgkmcnt(0)
	s_barrier
	s_setprio 1
	s_waitcnt lgkmcnt(0)
	v_mfma_f32_16x16x32_bf16 v[124:127], v[160:163], v[194:197], 0
	v_mfma_f32_16x16x32_bf16 v[116:119], v[168:171], v[194:197], 0
	v_mfma_f32_16x16x32_bf16 v[108:111], v[160:163], v[202:205], 0
	v_mfma_f32_16x16x32_bf16 v[100:103], v[168:171], v[202:205], 0
	v_mfma_f32_16x16x32_bf16 v[92:95], v[160:163], v[210:213], 0
	v_mfma_f32_16x16x32_bf16 v[84:87], v[168:171], v[210:213], 0
	v_mfma_f32_16x16x32_bf16 v[76:79], v[160:163], v[218:221], 0
	v_mfma_f32_16x16x32_bf16 v[68:71], v[168:171], v[218:221], 0
	v_mfma_f32_16x16x32_bf16 v[124:127], v[164:167], v[198:201], v[124:127]
	v_mfma_f32_16x16x32_bf16 v[116:119], v[172:175], v[198:201], v[116:119]
	v_mfma_f32_16x16x32_bf16 v[108:111], v[164:167], v[206:209], v[108:111]
	v_mfma_f32_16x16x32_bf16 v[100:103], v[172:175], v[206:209], v[100:103]
	v_mfma_f32_16x16x32_bf16 v[92:95], v[164:167], v[214:217], v[92:95]
	v_mfma_f32_16x16x32_bf16 v[84:87], v[172:175], v[214:217], v[84:87]
	v_mfma_f32_16x16x32_bf16 v[76:79], v[164:167], v[222:225], v[76:79]
	v_mfma_f32_16x16x32_bf16 v[68:71], v[172:175], v[222:225], v[68:71]
	s_setprio 0
	s_setprio 1
	v_mfma_f32_16x16x32_bf16 v[120:123], v[176:179], v[194:197], 0
	v_mfma_f32_16x16x32_bf16 v[112:115], v[186:189], v[194:197], 0
	v_mfma_f32_16x16x32_bf16 v[104:107], v[176:179], v[202:205], 0
	v_mfma_f32_16x16x32_bf16 v[96:99], v[186:189], v[202:205], 0
	v_mfma_f32_16x16x32_bf16 v[88:91], v[176:179], v[210:213], 0
	v_mfma_f32_16x16x32_bf16 v[80:83], v[186:189], v[210:213], 0
	v_mfma_f32_16x16x32_bf16 v[72:75], v[176:179], v[218:221], 0
	v_mfma_f32_16x16x32_bf16 v[64:67], v[186:189], v[218:221], 0
	v_mfma_f32_16x16x32_bf16 v[120:123], v[180:183], v[198:201], v[120:123]
	v_mfma_f32_16x16x32_bf16 v[112:115], v[190:193], v[198:201], v[112:115]
	v_mfma_f32_16x16x32_bf16 v[104:107], v[180:183], v[206:209], v[104:107]
	v_mfma_f32_16x16x32_bf16 v[96:99], v[190:193], v[206:209], v[96:99]
	v_mfma_f32_16x16x32_bf16 v[88:91], v[180:183], v[214:217], v[88:91]
	v_mfma_f32_16x16x32_bf16 v[80:83], v[190:193], v[214:217], v[80:83]
	v_mfma_f32_16x16x32_bf16 v[72:75], v[180:183], v[222:225], v[72:75]
	v_mfma_f32_16x16x32_bf16 v[64:67], v[190:193], v[222:225], v[64:67]
	s_setprio 0
	s_barrier
	s_add_i32 s76, s64, s52
	v_lshl_add_u64 v[154:155], s[46:47], 0, v[132:133]
	s_mov_b32 m0, s76
	ds_read_b128 v[194:197], v150 offset:16384
	v_xor_b32_e32 v253, 64, v150
	ds_read_b128 v[198:201], v253 offset:16384
	ds_read_b128 v[202:205], v150 offset:18432
	ds_read_b128 v[206:209], v253 offset:18432
	ds_read_b128 v[210:213], v150 offset:20480
	ds_read_b128 v[214:217], v253 offset:20480
	ds_read_b128 v[218:221], v150 offset:22528
	ds_read_b128 v[222:225], v253 offset:22528
	global_load_lds_dwordx4 v[154:155], off
	s_add_i32 m0, s76, 0x2000
	s_add_u32 s76, s46, 0x40000
	v_lshl_add_u64 v[226:227], s[46:47], 0, v[128:129]
	s_addc_u32 s77, s47, 0
	s_add_i32 s78, s65, s52
	global_load_lds_dwordx4 v[226:227], off
	v_lshl_add_u64 v[228:229], s[76:77], 0, v[132:133]
	s_mov_b32 m0, s78
	v_lshl_add_u64 v[230:231], s[48:49], 0, v[130:131]
	global_load_lds_dwordx4 v[228:229], off
	v_lshl_add_u64 v[228:229], s[76:77], 0, v[128:129]
	s_add_i32 m0, s78, 0x2000
	s_nop 0
	global_load_lds_dwordx4 v[228:229], off
	v_lshl_add_u64 v[228:229], s[48:49], 0, v[134:135]
	s_mov_b32 m0, s55
	s_nop 0
	global_load_lds_dwordx4 v[228:229], off
	s_mov_b32 m0, s56
	s_nop 0
	global_load_lds_dwordx4 v[230:231], off
	s_waitcnt vmcnt(16)
	s_waitcnt lgkmcnt(0)
	s_barrier
	s_setprio 1
	s_waitcnt lgkmcnt(0)
	v_mfma_f32_16x16x32_bf16 v[60:63], v[160:163], v[194:197], 0
	v_mfma_f32_16x16x32_bf16 v[52:55], v[168:171], v[194:197], 0
	v_mfma_f32_16x16x32_bf16 v[44:47], v[160:163], v[202:205], 0
	v_mfma_f32_16x16x32_bf16 v[36:39], v[168:171], v[202:205], 0
	v_mfma_f32_16x16x32_bf16 v[28:31], v[160:163], v[210:213], 0
	v_mfma_f32_16x16x32_bf16 v[20:23], v[168:171], v[210:213], 0
	v_mfma_f32_16x16x32_bf16 v[12:15], v[160:163], v[218:221], 0
	v_mfma_f32_16x16x32_bf16 v[4:7], v[168:171], v[218:221], 0
	v_mfma_f32_16x16x32_bf16 v[60:63], v[164:167], v[198:201], v[60:63]
	v_mfma_f32_16x16x32_bf16 v[52:55], v[172:175], v[198:201], v[52:55]
	v_mfma_f32_16x16x32_bf16 v[44:47], v[164:167], v[206:209], v[44:47]
	v_mfma_f32_16x16x32_bf16 v[36:39], v[172:175], v[206:209], v[36:39]
	v_mfma_f32_16x16x32_bf16 v[28:31], v[164:167], v[214:217], v[28:31]
	v_mfma_f32_16x16x32_bf16 v[20:23], v[172:175], v[214:217], v[20:23]
	v_mfma_f32_16x16x32_bf16 v[12:15], v[164:167], v[222:225], v[12:15]
	v_mfma_f32_16x16x32_bf16 v[4:7], v[172:175], v[222:225], v[4:7]
	s_setprio 0
	s_setprio 1
	v_mfma_f32_16x16x32_bf16 v[56:59], v[176:179], v[194:197], 0
	v_mfma_f32_16x16x32_bf16 v[48:51], v[186:189], v[194:197], 0
	v_mfma_f32_16x16x32_bf16 v[40:43], v[176:179], v[202:205], 0
	v_mfma_f32_16x16x32_bf16 v[32:35], v[186:189], v[202:205], 0
	v_mfma_f32_16x16x32_bf16 v[24:27], v[176:179], v[210:213], 0
	v_mfma_f32_16x16x32_bf16 v[16:19], v[186:189], v[210:213], 0
	v_mfma_f32_16x16x32_bf16 v[8:11], v[176:179], v[218:221], 0
	v_mfma_f32_16x16x32_bf16 v[0:3], v[186:189], v[218:221], 0
	v_mfma_f32_16x16x32_bf16 v[56:59], v[180:183], v[198:201], v[56:59]
	v_mfma_f32_16x16x32_bf16 v[48:51], v[190:193], v[198:201], v[48:51]
	v_mfma_f32_16x16x32_bf16 v[40:43], v[180:183], v[206:209], v[40:43]
	v_mfma_f32_16x16x32_bf16 v[32:35], v[190:193], v[206:209], v[32:35]
	v_mfma_f32_16x16x32_bf16 v[24:27], v[180:183], v[214:217], v[24:27]
	v_mfma_f32_16x16x32_bf16 v[16:19], v[190:193], v[214:217], v[16:19]
	v_mfma_f32_16x16x32_bf16 v[8:11], v[180:183], v[222:225], v[8:11]
	v_mfma_f32_16x16x32_bf16 v[0:3], v[190:193], v[222:225], v[0:3]
	s_setprio 0
	s_barrier
	s_add_i32 s76, 0, 0x18000
	v_add_u32_e32 v153, s76, v147
	s_add_i32 s77, 0, 0x1c000
	ds_read_b128 v[160:163], v153
	v_xor_b32_e32 v253, 64, v153
	ds_read_b128 v[164:167], v253
	ds_read_b128 v[168:171], v153 offset:2048
	ds_read_b128 v[172:175], v253 offset:2048
	v_add_u32_e32 v153, s77, v147
	ds_read_b128 v[176:179], v153
	v_xor_b32_e32 v253, 64, v153
	ds_read_b128 v[180:183], v253
	ds_read_b128 v[186:189], v153 offset:2048
	ds_read_b128 v[190:193], v253 offset:2048
	s_add_u32 s48, s48, 0x40000
	s_addc_u32 s49, s49, 0
	s_mov_b32 m0, s57
	v_lshl_add_u64 v[232:233], s[48:49], 0, v[134:135]
	ds_read_b128 v[194:197], v150 offset:32768
	v_xor_b32_e32 v253, 64, v150
	ds_read_b128 v[198:201], v253 offset:32768
	ds_read_b128 v[202:205], v150 offset:34816
	ds_read_b128 v[206:209], v253 offset:34816
	ds_read_b128 v[210:213], v150 offset:36864
	ds_read_b128 v[214:217], v253 offset:36864
	ds_read_b128 v[218:221], v150 offset:38912
	ds_read_b128 v[222:225], v253 offset:38912
	global_load_lds_dwordx4 v[232:233], off
	v_lshl_add_u64 v[232:233], s[48:49], 0, v[130:131]
	s_mov_b32 m0, s58
	s_nop 0
	global_load_lds_dwordx4 v[232:233], off
	s_waitcnt vmcnt(8)
	s_waitcnt lgkmcnt(0)
	s_barrier
	s_setprio 1
	s_waitcnt lgkmcnt(0)
	v_mfma_f32_16x16x32_bf16 v[124:127], v[160:163], v[194:197], v[124:127]
	v_mfma_f32_16x16x32_bf16 v[124:127], v[164:167], v[198:201], v[124:127]
	v_mfma_f32_16x16x32_bf16 v[116:119], v[168:171], v[194:197], v[116:119]
	v_mfma_f32_16x16x32_bf16 v[116:119], v[172:175], v[198:201], v[116:119]
	v_mfma_f32_16x16x32_bf16 v[108:111], v[160:163], v[202:205], v[108:111]
	v_mfma_f32_16x16x32_bf16 v[108:111], v[164:167], v[206:209], v[108:111]
	v_mfma_f32_16x16x32_bf16 v[100:103], v[168:171], v[202:205], v[100:103]
	v_mfma_f32_16x16x32_bf16 v[100:103], v[172:175], v[206:209], v[100:103]
	v_mfma_f32_16x16x32_bf16 v[92:95], v[160:163], v[210:213], v[92:95]
	v_mfma_f32_16x16x32_bf16 v[92:95], v[164:167], v[214:217], v[92:95]
	v_mfma_f32_16x16x32_bf16 v[84:87], v[168:171], v[210:213], v[84:87]
	v_mfma_f32_16x16x32_bf16 v[84:87], v[172:175], v[214:217], v[84:87]
	v_mfma_f32_16x16x32_bf16 v[76:79], v[160:163], v[218:221], v[76:79]
	v_mfma_f32_16x16x32_bf16 v[76:79], v[164:167], v[222:225], v[76:79]
	v_mfma_f32_16x16x32_bf16 v[68:71], v[168:171], v[218:221], v[68:71]
	v_mfma_f32_16x16x32_bf16 v[68:71], v[172:175], v[222:225], v[68:71]
	s_setprio 0
	s_setprio 1
	v_mfma_f32_16x16x32_bf16 v[120:123], v[176:179], v[194:197], v[120:123]
	v_mfma_f32_16x16x32_bf16 v[120:123], v[180:183], v[198:201], v[120:123]
	v_mfma_f32_16x16x32_bf16 v[112:115], v[186:189], v[194:197], v[112:115]
	v_mfma_f32_16x16x32_bf16 v[112:115], v[190:193], v[198:201], v[112:115]
	v_mfma_f32_16x16x32_bf16 v[104:107], v[176:179], v[202:205], v[104:107]
	v_mfma_f32_16x16x32_bf16 v[104:107], v[180:183], v[206:209], v[104:107]
	v_mfma_f32_16x16x32_bf16 v[96:99], v[186:189], v[202:205], v[96:99]
	v_mfma_f32_16x16x32_bf16 v[96:99], v[190:193], v[206:209], v[96:99]
	v_mfma_f32_16x16x32_bf16 v[88:91], v[176:179], v[210:213], v[88:91]
	v_mfma_f32_16x16x32_bf16 v[88:91], v[180:183], v[214:217], v[88:91]
	v_mfma_f32_16x16x32_bf16 v[80:83], v[186:189], v[210:213], v[80:83]
	v_mfma_f32_16x16x32_bf16 v[80:83], v[190:193], v[214:217], v[80:83]
	v_mfma_f32_16x16x32_bf16 v[72:75], v[176:179], v[218:221], v[72:75]
	v_mfma_f32_16x16x32_bf16 v[72:75], v[180:183], v[222:225], v[72:75]
	v_mfma_f32_16x16x32_bf16 v[64:67], v[186:189], v[218:221], v[64:67]
	v_mfma_f32_16x16x32_bf16 v[64:67], v[190:193], v[222:225], v[64:67]
	s_setprio 0
	s_barrier
	s_add_i32 s48, s76, s52
	v_lshl_add_u64 v[154:155], v[154:155], 0, s[14:15]
	s_mov_b32 m0, s48
	ds_read_b128 v[194:197], v150 offset:49152
	v_xor_b32_e32 v253, 64, v150
	ds_read_b128 v[198:201], v253 offset:49152
	ds_read_b128 v[202:205], v150 offset:51200
	ds_read_b128 v[206:209], v253 offset:51200
	ds_read_b128 v[210:213], v150 offset:53248
	ds_read_b128 v[214:217], v253 offset:53248
	ds_read_b128 v[218:221], v150 offset:55296
	ds_read_b128 v[222:225], v253 offset:55296
	global_load_lds_dwordx4 v[154:155], off
	s_add_i32 m0, s48, 0x2000
	s_add_u32 s46, s46, 0x40080
	v_lshl_add_u64 v[154:155], v[226:227], 0, s[14:15]
	s_addc_u32 s47, s47, 0
	s_add_i32 s48, s77, s52
	global_load_lds_dwordx4 v[154:155], off
	v_lshl_add_u64 v[154:155], s[46:47], 0, v[132:133]
	s_mov_b32 m0, s48
	s_nop 0
	global_load_lds_dwordx4 v[154:155], off
	v_lshl_add_u64 v[154:155], s[46:47], 0, v[128:129]
	s_add_i32 m0, s48, 0x2000
	s_nop 0
	global_load_lds_dwordx4 v[154:155], off
	v_lshl_add_u64 v[154:155], v[228:229], 0, s[14:15]
	s_mov_b32 m0, s60
	s_nop 0
	global_load_lds_dwordx4 v[154:155], off
	v_lshl_add_u64 v[154:155], v[230:231], 0, s[14:15]
	s_mov_b32 m0, s61
	s_nop 0
	global_load_lds_dwordx4 v[154:155], off
	s_waitcnt vmcnt(8)
	s_waitcnt lgkmcnt(0)
	s_barrier
	s_setprio 1
	s_waitcnt lgkmcnt(0)
	v_mfma_f32_16x16x32_bf16 v[60:63], v[160:163], v[194:197], v[60:63]
	v_mfma_f32_16x16x32_bf16 v[60:63], v[164:167], v[198:201], v[60:63]
	v_mfma_f32_16x16x32_bf16 v[52:55], v[168:171], v[194:197], v[52:55]
	v_mfma_f32_16x16x32_bf16 v[52:55], v[172:175], v[198:201], v[52:55]
	v_mfma_f32_16x16x32_bf16 v[44:47], v[160:163], v[202:205], v[44:47]
	v_mfma_f32_16x16x32_bf16 v[44:47], v[164:167], v[206:209], v[44:47]
	v_mfma_f32_16x16x32_bf16 v[36:39], v[168:171], v[202:205], v[36:39]
	v_mfma_f32_16x16x32_bf16 v[36:39], v[172:175], v[206:209], v[36:39]
	v_mfma_f32_16x16x32_bf16 v[28:31], v[160:163], v[210:213], v[28:31]
	v_mfma_f32_16x16x32_bf16 v[28:31], v[164:167], v[214:217], v[28:31]
	v_mfma_f32_16x16x32_bf16 v[20:23], v[168:171], v[210:213], v[20:23]
	v_mfma_f32_16x16x32_bf16 v[20:23], v[172:175], v[214:217], v[20:23]
	v_mfma_f32_16x16x32_bf16 v[12:15], v[160:163], v[218:221], v[12:15]
	v_mfma_f32_16x16x32_bf16 v[12:15], v[164:167], v[222:225], v[12:15]
	v_mfma_f32_16x16x32_bf16 v[4:7], v[168:171], v[218:221], v[4:7]
	v_mfma_f32_16x16x32_bf16 v[4:7], v[172:175], v[222:225], v[4:7]
	s_setprio 0
	s_setprio 1
	v_mfma_f32_16x16x32_bf16 v[56:59], v[176:179], v[194:197], v[56:59]
	v_mfma_f32_16x16x32_bf16 v[56:59], v[180:183], v[198:201], v[56:59]
	v_mfma_f32_16x16x32_bf16 v[48:51], v[186:189], v[194:197], v[48:51]
	v_mfma_f32_16x16x32_bf16 v[48:51], v[190:193], v[198:201], v[48:51]
	v_mfma_f32_16x16x32_bf16 v[40:43], v[176:179], v[202:205], v[40:43]
	v_mfma_f32_16x16x32_bf16 v[40:43], v[180:183], v[206:209], v[40:43]
	v_mfma_f32_16x16x32_bf16 v[32:35], v[186:189], v[202:205], v[32:35]
	v_mfma_f32_16x16x32_bf16 v[32:35], v[190:193], v[206:209], v[32:35]
	v_mfma_f32_16x16x32_bf16 v[24:27], v[176:179], v[210:213], v[24:27]
	v_mfma_f32_16x16x32_bf16 v[24:27], v[180:183], v[214:217], v[24:27]
	v_mfma_f32_16x16x32_bf16 v[16:19], v[186:189], v[210:213], v[16:19]
	v_mfma_f32_16x16x32_bf16 v[16:19], v[190:193], v[214:217], v[16:19]
	v_mfma_f32_16x16x32_bf16 v[8:11], v[176:179], v[218:221], v[8:11]
	v_mfma_f32_16x16x32_bf16 v[8:11], v[180:183], v[222:225], v[8:11]
	v_mfma_f32_16x16x32_bf16 v[0:3], v[186:189], v[218:221], v[0:3]
	v_mfma_f32_16x16x32_bf16 v[0:3], v[190:193], v[222:225], v[0:3]
	s_setprio 0
	s_barrier
	s_add_i32 s75, s75, 2
	s_add_u32 s71, s71, 0x100
	s_addc_u32 s74, s74, 0
	s_add_u32 s44, s44, 0x100
	s_addc_u32 s45, s45, 0
	s_branch .LBB0_76
.Lfa_0:
	v_add_u32_e32 v153, s64, v147
	ds_read_b128 v[160:163], v153
	v_xor_b32_e32 v253, 64, v153
	ds_read_b128 v[164:167], v253
	ds_read_b128 v[168:171], v153 offset:2048
	ds_read_b128 v[172:175], v253 offset:2048
	v_add_u32_e32 v153, s65, v147
	ds_read_b128 v[176:179], v153
	v_xor_b32_e32 v253, 64, v153
	ds_read_b128 v[180:183], v253
	ds_read_b128 v[186:189], v153 offset:2048
	ds_read_b128 v[190:193], v253 offset:2048
	s_add_u32 s48, s44, 0xfffc0080
	s_addc_u32 s49, s45, -1
	s_and_b64 s[46:47], s[46:47], exec
	s_cselect_b32 s49, s27, s49
	s_cselect_b32 s48, s68, s48
	s_cselect_b32 s47, s69, s74
	s_cselect_b32 s46, s70, s71
	v_lshl_add_u64 v[154:155], s[44:45], 0, v[138:139]
	s_add_i32 m0, s55, 0xc000
	ds_read_b128 v[194:197], v150
	v_xor_b32_e32 v253, 64, v150
	ds_read_b128 v[198:201], v253
	ds_read_b128 v[202:205], v150 offset:2048
	ds_read_b128 v[206:209], v253 offset:2048
	ds_read_b128 v[210:213], v150 offset:4096
	ds_read_b128 v[214:217], v253 offset:4096
	ds_read_b128 v[218:221], v150 offset:6144
	ds_read_b128 v[222:225], v253 offset:6144
	global_load_lds_dwordx4 v[154:155], off
	v_lshl_add_u64 v[154:155], s[44:45], 0, v[136:137]
	s_add_i32 m0, s55, 0xe000
	s_nop 0
	global_load_lds_dwordx4 v[154:155], off
	s_waitcnt vmcnt(8)
	s_waitcnt lgkmcnt(0)
	s_barrier
	s_setprio 1
	s_waitcnt lgkmcnt(0)
	v_mfma_f32_16x16x32_bf16 v[124:127], v[160:163], v[194:197], 0
	v_mfma_f32_16x16x32_bf16 v[116:119], v[168:171], v[194:197], 0
	v_mfma_f32_16x16x32_bf16 v[108:111], v[160:163], v[202:205], 0
	v_mfma_f32_16x16x32_bf16 v[100:103], v[168:171], v[202:205], 0
	v_mfma_f32_16x16x32_bf16 v[92:95], v[160:163], v[210:213], 0
	v_mfma_f32_16x16x32_bf16 v[84:87], v[168:171], v[210:213], 0
	v_mfma_f32_16x16x32_bf16 v[76:79], v[160:163], v[218:221], 0
	v_mfma_f32_16x16x32_bf16 v[68:71], v[168:171], v[218:221], 0
	v_mfma_f32_16x16x32_bf16 v[124:127], v[164:167], v[198:201], v[124:127]
	v_mfma_f32_16x16x32_bf16 v[116:119], v[172:175], v[198:201], v[116:119]
	v_mfma_f32_16x16x32_bf16 v[108:111], v[164:167], v[206:209], v[108:111]
	v_mfma_f32_16x16x32_bf16 v[100:103], v[172:175], v[206:209], v[100:103]
	v_mfma_f32_16x16x32_bf16 v[92:95], v[164:167], v[214:217], v[92:95]
	v_mfma_f32_16x16x32_bf16 v[84:87], v[172:175], v[214:217], v[84:87]
	v_mfma_f32_16x16x32_bf16 v[76:79], v[164:167], v[222:225], v[76:79]
	v_mfma_f32_16x16x32_bf16 v[68:71], v[172:175], v[222:225], v[68:71]
	s_setprio 0
	s_setprio 1
	v_mfma_f32_16x16x32_bf16 v[120:123], v[176:179], v[194:197], 0
	v_mfma_f32_16x16x32_bf16 v[112:115], v[186:189], v[194:197], 0
	v_mfma_f32_16x16x32_bf16 v[104:107], v[176:179], v[202:205], 0
	v_mfma_f32_16x16x32_bf16 v[96:99], v[186:189], v[202:205], 0
	v_mfma_f32_16x16x32_bf16 v[88:91], v[176:179], v[210:213], 0
	v_mfma_f32_16x16x32_bf16 v[80:83], v[186:189], v[210:213], 0
	v_mfma_f32_16x16x32_bf16 v[72:75], v[176:179], v[218:221], 0
	v_mfma_f32_16x16x32_bf16 v[64:67], v[186:189], v[218:221], 0
	v_mfma_f32_16x16x32_bf16 v[120:123], v[180:183], v[198:201], v[120:123]
	v_mfma_f32_16x16x32_bf16 v[112:115], v[190:193], v[198:201], v[112:115]
	v_mfma_f32_16x16x32_bf16 v[104:107], v[180:183], v[206:209], v[104:107]
	v_mfma_f32_16x16x32_bf16 v[96:99], v[190:193], v[206:209], v[96:99]
	v_mfma_f32_16x16x32_bf16 v[88:91], v[180:183], v[214:217], v[88:91]
	v_mfma_f32_16x16x32_bf16 v[80:83], v[190:193], v[214:217], v[80:83]
	v_mfma_f32_16x16x32_bf16 v[72:75], v[180:183], v[222:225], v[72:75]
	v_mfma_f32_16x16x32_bf16 v[64:67], v[190:193], v[222:225], v[64:67]
	s_setprio 0
	s_barrier
	s_add_i32 s76, s64, s52
	v_lshl_add_u64 v[154:155], s[46:47], 0, v[132:133]
	s_mov_b32 m0, s76
	ds_read_b128 v[194:197], v150 offset:16384
	v_xor_b32_e32 v253, 64, v150
	ds_read_b128 v[198:201], v253 offset:16384
	ds_read_b128 v[202:205], v150 offset:18432
	ds_read_b128 v[206:209], v253 offset:18432
	ds_read_b128 v[210:213], v150 offset:20480
	ds_read_b128 v[214:217], v253 offset:20480
	ds_read_b128 v[218:221], v150 offset:22528
	ds_read_b128 v[222:225], v253 offset:22528
	global_load_lds_dwordx4 v[154:155], off
	s_add_i32 m0, s76, 0x2000
	s_add_u32 s76, s46, 0x40000
	v_lshl_add_u64 v[226:227], s[46:47], 0, v[128:129]
	s_addc_u32 s77, s47, 0
	s_add_i32 s78, s65, s52
	global_load_lds_dwordx4 v[226:227], off
	v_lshl_add_u64 v[228:229], s[76:77], 0, v[132:133]
	s_mov_b32 m0, s78
	v_lshl_add_u64 v[230:231], s[48:49], 0, v[130:131]
	global_load_lds_dwordx4 v[228:229], off
	v_lshl_add_u64 v[228:229], s[76:77], 0, v[128:129]
	s_add_i32 m0, s78, 0x2000
	s_nop 0
	global_load_lds_dwordx4 v[228:229], off
	v_lshl_add_u64 v[228:229], s[48:49], 0, v[134:135]
	s_mov_b32 m0, s55
	s_nop 0
	global_load_lds_dwordx4 v[228:229], off
	s_mov_b32 m0, s56
	s_nop 0
	global_load_lds_dwordx4 v[230:231], off
	s_waitcnt vmcnt(8)
	s_waitcnt lgkmcnt(0)
	s_barrier
	s_setprio 1
	s_waitcnt lgkmcnt(0)
	v_mfma_f32_16x16x32_bf16 v[60:63], v[160:163], v[194:197], 0
	v_mfma_f32_16x16x32_bf16 v[52:55], v[168:171], v[194:197], 0
	v_mfma_f32_16x16x32_bf16 v[44:47], v[160:163], v[202:205], 0
	v_mfma_f32_16x16x32_bf16 v[36:39], v[168:171], v[202:205], 0
	v_mfma_f32_16x16x32_bf16 v[28:31], v[160:163], v[210:213], 0
	v_mfma_f32_16x16x32_bf16 v[20:23], v[168:171], v[210:213], 0
	v_mfma_f32_16x16x32_bf16 v[12:15], v[160:163], v[218:221], 0
	v_mfma_f32_16x16x32_bf16 v[4:7], v[168:171], v[218:221], 0
	v_mfma_f32_16x16x32_bf16 v[60:63], v[164:167], v[198:201], v[60:63]
	v_mfma_f32_16x16x32_bf16 v[52:55], v[172:175], v[198:201], v[52:55]
	v_mfma_f32_16x16x32_bf16 v[44:47], v[164:167], v[206:209], v[44:47]
	v_mfma_f32_16x16x32_bf16 v[36:39], v[172:175], v[206:209], v[36:39]
	v_mfma_f32_16x16x32_bf16 v[28:31], v[164:167], v[214:217], v[28:31]
	v_mfma_f32_16x16x32_bf16 v[20:23], v[172:175], v[214:217], v[20:23]
	v_mfma_f32_16x16x32_bf16 v[12:15], v[164:167], v[222:225], v[12:15]
	v_mfma_f32_16x16x32_bf16 v[4:7], v[172:175], v[222:225], v[4:7]
	s_setprio 0
	s_setprio 1
	v_mfma_f32_16x16x32_bf16 v[56:59], v[176:179], v[194:197], 0
	v_mfma_f32_16x16x32_bf16 v[48:51], v[186:189], v[194:197], 0
	v_mfma_f32_16x16x32_bf16 v[40:43], v[176:179], v[202:205], 0
	v_mfma_f32_16x16x32_bf16 v[32:35], v[186:189], v[202:205], 0
	v_mfma_f32_16x16x32_bf16 v[24:27], v[176:179], v[210:213], 0
	v_mfma_f32_16x16x32_bf16 v[16:19], v[186:189], v[210:213], 0
	v_mfma_f32_16x16x32_bf16 v[8:11], v[176:179], v[218:221], 0
	v_mfma_f32_16x16x32_bf16 v[0:3], v[186:189], v[218:221], 0
	v_mfma_f32_16x16x32_bf16 v[56:59], v[180:183], v[198:201], v[56:59]
	v_mfma_f32_16x16x32_bf16 v[48:51], v[190:193], v[198:201], v[48:51]
	v_mfma_f32_16x16x32_bf16 v[40:43], v[180:183], v[206:209], v[40:43]
	v_mfma_f32_16x16x32_bf16 v[32:35], v[190:193], v[206:209], v[32:35]
	v_mfma_f32_16x16x32_bf16 v[24:27], v[180:183], v[214:217], v[24:27]
	v_mfma_f32_16x16x32_bf16 v[16:19], v[190:193], v[214:217], v[16:19]
	v_mfma_f32_16x16x32_bf16 v[8:11], v[180:183], v[222:225], v[8:11]
	v_mfma_f32_16x16x32_bf16 v[0:3], v[190:193], v[222:225], v[0:3]
	s_setprio 0
	s_barrier
	s_add_i32 s76, 0, 0x18000
	v_add_u32_e32 v153, s76, v147
	s_add_i32 s77, 0, 0x1c000
	ds_read_b128 v[160:163], v153
	v_xor_b32_e32 v253, 64, v153
	ds_read_b128 v[164:167], v253
	ds_read_b128 v[168:171], v153 offset:2048
	ds_read_b128 v[172:175], v253 offset:2048
	v_add_u32_e32 v153, s77, v147
	ds_read_b128 v[176:179], v153
	v_xor_b32_e32 v253, 64, v153
	ds_read_b128 v[180:183], v253
	ds_read_b128 v[186:189], v153 offset:2048
	ds_read_b128 v[190:193], v253 offset:2048
	s_add_u32 s48, s48, 0x40000
	s_addc_u32 s49, s49, 0
	s_mov_b32 m0, s57
	v_lshl_add_u64 v[232:233], s[48:49], 0, v[134:135]
	ds_read_b128 v[194:197], v150 offset:32768
	v_xor_b32_e32 v253, 64, v150
	ds_read_b128 v[198:201], v253 offset:32768
	ds_read_b128 v[202:205], v150 offset:34816
	ds_read_b128 v[206:209], v253 offset:34816
	ds_read_b128 v[210:213], v150 offset:36864
	ds_read_b128 v[214:217], v253 offset:36864
	ds_read_b128 v[218:221], v150 offset:38912
	ds_read_b128 v[222:225], v253 offset:38912
	global_load_lds_dwordx4 v[232:233], off
	v_lshl_add_u64 v[232:233], s[48:49], 0, v[130:131]
	s_mov_b32 m0, s58
	s_nop 0
	global_load_lds_dwordx4 v[232:233], off
	s_waitcnt vmcnt(8)
	s_waitcnt lgkmcnt(0)
	s_barrier
	s_setprio 1
	s_waitcnt lgkmcnt(0)
	v_mfma_f32_16x16x32_bf16 v[124:127], v[160:163], v[194:197], v[124:127]
	v_mfma_f32_16x16x32_bf16 v[124:127], v[164:167], v[198:201], v[124:127]
	v_mfma_f32_16x16x32_bf16 v[116:119], v[168:171], v[194:197], v[116:119]
	v_mfma_f32_16x16x32_bf16 v[116:119], v[172:175], v[198:201], v[116:119]
	v_mfma_f32_16x16x32_bf16 v[108:111], v[160:163], v[202:205], v[108:111]
	v_mfma_f32_16x16x32_bf16 v[108:111], v[164:167], v[206:209], v[108:111]
	v_mfma_f32_16x16x32_bf16 v[100:103], v[168:171], v[202:205], v[100:103]
	v_mfma_f32_16x16x32_bf16 v[100:103], v[172:175], v[206:209], v[100:103]
	v_mfma_f32_16x16x32_bf16 v[92:95], v[160:163], v[210:213], v[92:95]
	v_mfma_f32_16x16x32_bf16 v[92:95], v[164:167], v[214:217], v[92:95]
	v_mfma_f32_16x16x32_bf16 v[84:87], v[168:171], v[210:213], v[84:87]
	v_mfma_f32_16x16x32_bf16 v[84:87], v[172:175], v[214:217], v[84:87]
	v_mfma_f32_16x16x32_bf16 v[76:79], v[160:163], v[218:221], v[76:79]
	v_mfma_f32_16x16x32_bf16 v[76:79], v[164:167], v[222:225], v[76:79]
	v_mfma_f32_16x16x32_bf16 v[68:71], v[168:171], v[218:221], v[68:71]
	v_mfma_f32_16x16x32_bf16 v[68:71], v[172:175], v[222:225], v[68:71]
	s_setprio 0
	s_setprio 1
	v_mfma_f32_16x16x32_bf16 v[120:123], v[176:179], v[194:197], v[120:123]
	v_mfma_f32_16x16x32_bf16 v[120:123], v[180:183], v[198:201], v[120:123]
	v_mfma_f32_16x16x32_bf16 v[112:115], v[186:189], v[194:197], v[112:115]
	v_mfma_f32_16x16x32_bf16 v[112:115], v[190:193], v[198:201], v[112:115]
	v_mfma_f32_16x16x32_bf16 v[104:107], v[176:179], v[202:205], v[104:107]
	v_mfma_f32_16x16x32_bf16 v[104:107], v[180:183], v[206:209], v[104:107]
	v_mfma_f32_16x16x32_bf16 v[96:99], v[186:189], v[202:205], v[96:99]
	v_mfma_f32_16x16x32_bf16 v[96:99], v[190:193], v[206:209], v[96:99]
	v_mfma_f32_16x16x32_bf16 v[88:91], v[176:179], v[210:213], v[88:91]
	v_mfma_f32_16x16x32_bf16 v[88:91], v[180:183], v[214:217], v[88:91]
	v_mfma_f32_16x16x32_bf16 v[80:83], v[186:189], v[210:213], v[80:83]
	v_mfma_f32_16x16x32_bf16 v[80:83], v[190:193], v[214:217], v[80:83]
	v_mfma_f32_16x16x32_bf16 v[72:75], v[176:179], v[218:221], v[72:75]
	v_mfma_f32_16x16x32_bf16 v[72:75], v[180:183], v[222:225], v[72:75]
	v_mfma_f32_16x16x32_bf16 v[64:67], v[186:189], v[218:221], v[64:67]
	v_mfma_f32_16x16x32_bf16 v[64:67], v[190:193], v[222:225], v[64:67]
	s_setprio 0
	s_barrier
	s_add_i32 s48, s76, s52
	v_lshl_add_u64 v[154:155], v[154:155], 0, s[14:15]
	s_mov_b32 m0, s48
	ds_read_b128 v[194:197], v150 offset:49152
	v_xor_b32_e32 v253, 64, v150
	ds_read_b128 v[198:201], v253 offset:49152
	ds_read_b128 v[202:205], v150 offset:51200
	ds_read_b128 v[206:209], v253 offset:51200
	ds_read_b128 v[210:213], v150 offset:53248
	ds_read_b128 v[214:217], v253 offset:53248
	ds_read_b128 v[218:221], v150 offset:55296
	ds_read_b128 v[222:225], v253 offset:55296
	global_load_lds_dwordx4 v[154:155], off
	s_add_i32 m0, s48, 0x2000
	s_add_u32 s46, s46, 0x40080
	v_lshl_add_u64 v[154:155], v[226:227], 0, s[14:15]
	s_addc_u32 s47, s47, 0
	s_add_i32 s48, s77, s52
	global_load_lds_dwordx4 v[154:155], off
	v_lshl_add_u64 v[154:155], s[46:47], 0, v[132:133]
	s_mov_b32 m0, s48
	s_nop 0
	global_load_lds_dwordx4 v[154:155], off
	v_lshl_add_u64 v[154:155], s[46:47], 0, v[128:129]
	s_add_i32 m0, s48, 0x2000
	s_nop 0
	global_load_lds_dwordx4 v[154:155], off
	v_lshl_add_u64 v[154:155], v[228:229], 0, s[14:15]
	s_mov_b32 m0, s60
	s_nop 0
	global_load_lds_dwordx4 v[154:155], off
	v_lshl_add_u64 v[154:155], v[230:231], 0, s[14:15]
	s_mov_b32 m0, s61
	s_nop 0
	global_load_lds_dwordx4 v[154:155], off
	s_waitcnt vmcnt(8)
	s_waitcnt lgkmcnt(0)
	s_barrier
	s_setprio 1
	s_waitcnt lgkmcnt(0)
	v_mfma_f32_16x16x32_bf16 v[60:63], v[160:163], v[194:197], v[60:63]
	v_mfma_f32_16x16x32_bf16 v[60:63], v[164:167], v[198:201], v[60:63]
	v_mfma_f32_16x16x32_bf16 v[52:55], v[168:171], v[194:197], v[52:55]
	v_mfma_f32_16x16x32_bf16 v[52:55], v[172:175], v[198:201], v[52:55]
	v_mfma_f32_16x16x32_bf16 v[44:47], v[160:163], v[202:205], v[44:47]
	v_mfma_f32_16x16x32_bf16 v[44:47], v[164:167], v[206:209], v[44:47]
	v_mfma_f32_16x16x32_bf16 v[36:39], v[168:171], v[202:205], v[36:39]
	v_mfma_f32_16x16x32_bf16 v[36:39], v[172:175], v[206:209], v[36:39]
	v_mfma_f32_16x16x32_bf16 v[28:31], v[160:163], v[210:213], v[28:31]
	v_mfma_f32_16x16x32_bf16 v[28:31], v[164:167], v[214:217], v[28:31]
	v_mfma_f32_16x16x32_bf16 v[20:23], v[168:171], v[210:213], v[20:23]
	v_mfma_f32_16x16x32_bf16 v[20:23], v[172:175], v[214:217], v[20:23]
	v_mfma_f32_16x16x32_bf16 v[12:15], v[160:163], v[218:221], v[12:15]
	v_mfma_f32_16x16x32_bf16 v[12:15], v[164:167], v[222:225], v[12:15]
	v_mfma_f32_16x16x32_bf16 v[4:7], v[168:171], v[218:221], v[4:7]
	v_mfma_f32_16x16x32_bf16 v[4:7], v[172:175], v[222:225], v[4:7]
	s_setprio 0
	s_setprio 1
	v_mfma_f32_16x16x32_bf16 v[56:59], v[176:179], v[194:197], v[56:59]
	v_mfma_f32_16x16x32_bf16 v[56:59], v[180:183], v[198:201], v[56:59]
	v_mfma_f32_16x16x32_bf16 v[48:51], v[186:189], v[194:197], v[48:51]
	v_mfma_f32_16x16x32_bf16 v[48:51], v[190:193], v[198:201], v[48:51]
	v_mfma_f32_16x16x32_bf16 v[40:43], v[176:179], v[202:205], v[40:43]
	v_mfma_f32_16x16x32_bf16 v[40:43], v[180:183], v[206:209], v[40:43]
	v_mfma_f32_16x16x32_bf16 v[32:35], v[186:189], v[202:205], v[32:35]
	v_mfma_f32_16x16x32_bf16 v[32:35], v[190:193], v[206:209], v[32:35]
	v_mfma_f32_16x16x32_bf16 v[24:27], v[176:179], v[210:213], v[24:27]
	v_mfma_f32_16x16x32_bf16 v[24:27], v[180:183], v[214:217], v[24:27]
	v_mfma_f32_16x16x32_bf16 v[16:19], v[186:189], v[210:213], v[16:19]
	v_mfma_f32_16x16x32_bf16 v[16:19], v[190:193], v[214:217], v[16:19]
	v_mfma_f32_16x16x32_bf16 v[8:11], v[176:179], v[218:221], v[8:11]
	v_mfma_f32_16x16x32_bf16 v[8:11], v[180:183], v[222:225], v[8:11]
	v_mfma_f32_16x16x32_bf16 v[0:3], v[186:189], v[218:221], v[0:3]
	v_mfma_f32_16x16x32_bf16 v[0:3], v[190:193], v[222:225], v[0:3]
	s_setprio 0
	s_barrier
	s_add_i32 s75, s75, 2
	s_add_u32 s71, s71, 0x100
	s_addc_u32 s74, s74, 0
	s_add_u32 s44, s44, 0x100
	s_addc_u32 s45, s45, 0
	s_branch .LBB0_76
.LBB0_75:
	v_add_u32_e32 v153, s64, v147
	ds_read_b128 v[160:163], v153
	v_xor_b32_e32 v253, 64, v153
	ds_read_b128 v[164:167], v253
	ds_read_b128 v[168:171], v153 offset:2048
	ds_read_b128 v[172:175], v253 offset:2048
	v_add_u32_e32 v153, s65, v147
	ds_read_b128 v[176:179], v153
	v_xor_b32_e32 v253, 64, v153
	ds_read_b128 v[180:183], v253
	ds_read_b128 v[186:189], v153 offset:2048
	ds_read_b128 v[190:193], v253 offset:2048
	s_add_u32 s48, s44, 0xfffc0080
	s_addc_u32 s49, s45, -1
	s_and_b64 s[46:47], s[46:47], exec
	s_cselect_b32 s49, s27, s49
	s_cselect_b32 s48, s68, s48
	s_cselect_b32 s47, s69, s74
	s_cselect_b32 s46, s70, s71
	v_lshl_add_u64 v[154:155], s[44:45], 0, v[138:139]
	s_add_i32 m0, s55, 0xc000
	ds_read_b128 v[194:197], v150
	v_xor_b32_e32 v253, 64, v150
	ds_read_b128 v[198:201], v253
	ds_read_b128 v[202:205], v150 offset:2048
	ds_read_b128 v[206:209], v253 offset:2048
	ds_read_b128 v[210:213], v150 offset:4096
	ds_read_b128 v[214:217], v253 offset:4096
	ds_read_b128 v[218:221], v150 offset:6144
	ds_read_b128 v[222:225], v253 offset:6144
	global_load_lds_dwordx4 v[154:155], off
	v_lshl_add_u64 v[154:155], s[44:45], 0, v[136:137]
	s_add_i32 m0, s55, 0xe000
	s_nop 0
	global_load_lds_dwordx4 v[154:155], off
	s_waitcnt vmcnt(8)
	s_waitcnt lgkmcnt(0)
	s_barrier
	s_setprio 1
	s_waitcnt lgkmcnt(0)
	v_mfma_f32_16x16x32_bf16 v[124:127], v[160:163], v[194:197], v[124:127]
	v_mfma_f32_16x16x32_bf16 v[124:127], v[164:167], v[198:201], v[124:127]
	v_mfma_f32_16x16x32_bf16 v[116:119], v[168:171], v[194:197], v[116:119]
	v_mfma_f32_16x16x32_bf16 v[116:119], v[172:175], v[198:201], v[116:119]
	v_mfma_f32_16x16x32_bf16 v[108:111], v[160:163], v[202:205], v[108:111]
	v_mfma_f32_16x16x32_bf16 v[108:111], v[164:167], v[206:209], v[108:111]
	v_mfma_f32_16x16x32_bf16 v[100:103], v[168:171], v[202:205], v[100:103]
	v_mfma_f32_16x16x32_bf16 v[100:103], v[172:175], v[206:209], v[100:103]
	v_mfma_f32_16x16x32_bf16 v[92:95], v[160:163], v[210:213], v[92:95]
	v_mfma_f32_16x16x32_bf16 v[92:95], v[164:167], v[214:217], v[92:95]
	v_mfma_f32_16x16x32_bf16 v[84:87], v[168:171], v[210:213], v[84:87]
	v_mfma_f32_16x16x32_bf16 v[84:87], v[172:175], v[214:217], v[84:87]
	v_mfma_f32_16x16x32_bf16 v[76:79], v[160:163], v[218:221], v[76:79]
	v_mfma_f32_16x16x32_bf16 v[76:79], v[164:167], v[222:225], v[76:79]
	v_mfma_f32_16x16x32_bf16 v[68:71], v[168:171], v[218:221], v[68:71]
	v_mfma_f32_16x16x32_bf16 v[68:71], v[172:175], v[222:225], v[68:71]
	s_setprio 0
	s_setprio 1
	v_mfma_f32_16x16x32_bf16 v[120:123], v[176:179], v[194:197], v[120:123]
	v_mfma_f32_16x16x32_bf16 v[120:123], v[180:183], v[198:201], v[120:123]
	v_mfma_f32_16x16x32_bf16 v[112:115], v[186:189], v[194:197], v[112:115]
	v_mfma_f32_16x16x32_bf16 v[112:115], v[190:193], v[198:201], v[112:115]
	v_mfma_f32_16x16x32_bf16 v[104:107], v[176:179], v[202:205], v[104:107]
	v_mfma_f32_16x16x32_bf16 v[104:107], v[180:183], v[206:209], v[104:107]
	v_mfma_f32_16x16x32_bf16 v[96:99], v[186:189], v[202:205], v[96:99]
	v_mfma_f32_16x16x32_bf16 v[96:99], v[190:193], v[206:209], v[96:99]
	v_mfma_f32_16x16x32_bf16 v[88:91], v[176:179], v[210:213], v[88:91]
	v_mfma_f32_16x16x32_bf16 v[88:91], v[180:183], v[214:217], v[88:91]
	v_mfma_f32_16x16x32_bf16 v[80:83], v[186:189], v[210:213], v[80:83]
	v_mfma_f32_16x16x32_bf16 v[80:83], v[190:193], v[214:217], v[80:83]
	v_mfma_f32_16x16x32_bf16 v[72:75], v[176:179], v[218:221], v[72:75]
	v_mfma_f32_16x16x32_bf16 v[72:75], v[180:183], v[222:225], v[72:75]
	v_mfma_f32_16x16x32_bf16 v[64:67], v[186:189], v[218:221], v[64:67]
	v_mfma_f32_16x16x32_bf16 v[64:67], v[190:193], v[222:225], v[64:67]
	s_setprio 0
	s_barrier
	s_add_i32 s76, s64, s52
	v_lshl_add_u64 v[154:155], s[46:47], 0, v[132:133]
	s_mov_b32 m0, s76
	ds_read_b128 v[194:197], v150 offset:16384
	v_xor_b32_e32 v253, 64, v150
	ds_read_b128 v[198:201], v253 offset:16384
	ds_read_b128 v[202:205], v150 offset:18432
	ds_read_b128 v[206:209], v253 offset:18432
	ds_read_b128 v[210:213], v150 offset:20480
	ds_read_b128 v[214:217], v253 offset:20480
	ds_read_b128 v[218:221], v150 offset:22528
	ds_read_b128 v[222:225], v253 offset:22528
	global_load_lds_dwordx4 v[154:155], off
	s_add_i32 m0, s76, 0x2000
	s_add_u32 s76, s46, 0x40000
	v_lshl_add_u64 v[226:227], s[46:47], 0, v[128:129]
	s_addc_u32 s77, s47, 0
	s_add_i32 s78, s65, s52
	global_load_lds_dwordx4 v[226:227], off
	v_lshl_add_u64 v[228:229], s[76:77], 0, v[132:133]
	s_mov_b32 m0, s78
	v_lshl_add_u64 v[230:231], s[48:49], 0, v[130:131]
	global_load_lds_dwordx4 v[228:229], off
	v_lshl_add_u64 v[228:229], s[76:77], 0, v[128:129]
	s_add_i32 m0, s78, 0x2000
	s_nop 0
	global_load_lds_dwordx4 v[228:229], off
	v_lshl_add_u64 v[228:229], s[48:49], 0, v[134:135]
	s_mov_b32 m0, s55
	s_nop 0
	global_load_lds_dwordx4 v[228:229], off
	s_mov_b32 m0, s56
	s_nop 0
	global_load_lds_dwordx4 v[230:231], off
	s_waitcnt vmcnt(8)
	s_waitcnt lgkmcnt(0)
	s_barrier
	s_setprio 1
	s_waitcnt lgkmcnt(0)
	v_mfma_f32_16x16x32_bf16 v[60:63], v[160:163], v[194:197], v[60:63]
	v_mfma_f32_16x16x32_bf16 v[60:63], v[164:167], v[198:201], v[60:63]
	v_mfma_f32_16x16x32_bf16 v[52:55], v[168:171], v[194:197], v[52:55]
	v_mfma_f32_16x16x32_bf16 v[52:55], v[172:175], v[198:201], v[52:55]
	v_mfma_f32_16x16x32_bf16 v[44:47], v[160:163], v[202:205], v[44:47]
	v_mfma_f32_16x16x32_bf16 v[44:47], v[164:167], v[206:209], v[44:47]
	v_mfma_f32_16x16x32_bf16 v[36:39], v[168:171], v[202:205], v[36:39]
	v_mfma_f32_16x16x32_bf16 v[36:39], v[172:175], v[206:209], v[36:39]
	v_mfma_f32_16x16x32_bf16 v[28:31], v[160:163], v[210:213], v[28:31]
	v_mfma_f32_16x16x32_bf16 v[28:31], v[164:167], v[214:217], v[28:31]
	v_mfma_f32_16x16x32_bf16 v[20:23], v[168:171], v[210:213], v[20:23]
	v_mfma_f32_16x16x32_bf16 v[20:23], v[172:175], v[214:217], v[20:23]
	v_mfma_f32_16x16x32_bf16 v[12:15], v[160:163], v[218:221], v[12:15]
	v_mfma_f32_16x16x32_bf16 v[12:15], v[164:167], v[222:225], v[12:15]
	v_mfma_f32_16x16x32_bf16 v[4:7], v[168:171], v[218:221], v[4:7]
	v_mfma_f32_16x16x32_bf16 v[4:7], v[172:175], v[222:225], v[4:7]
	s_setprio 0
	s_setprio 1
	v_mfma_f32_16x16x32_bf16 v[56:59], v[176:179], v[194:197], v[56:59]
	v_mfma_f32_16x16x32_bf16 v[56:59], v[180:183], v[198:201], v[56:59]
	v_mfma_f32_16x16x32_bf16 v[48:51], v[186:189], v[194:197], v[48:51]
	v_mfma_f32_16x16x32_bf16 v[48:51], v[190:193], v[198:201], v[48:51]
	v_mfma_f32_16x16x32_bf16 v[40:43], v[176:179], v[202:205], v[40:43]
	v_mfma_f32_16x16x32_bf16 v[40:43], v[180:183], v[206:209], v[40:43]
	v_mfma_f32_16x16x32_bf16 v[32:35], v[186:189], v[202:205], v[32:35]
	v_mfma_f32_16x16x32_bf16 v[32:35], v[190:193], v[206:209], v[32:35]
	v_mfma_f32_16x16x32_bf16 v[24:27], v[176:179], v[210:213], v[24:27]
	v_mfma_f32_16x16x32_bf16 v[24:27], v[180:183], v[214:217], v[24:27]
	v_mfma_f32_16x16x32_bf16 v[16:19], v[186:189], v[210:213], v[16:19]
	v_mfma_f32_16x16x32_bf16 v[16:19], v[190:193], v[214:217], v[16:19]
	v_mfma_f32_16x16x32_bf16 v[8:11], v[176:179], v[218:221], v[8:11]
	v_mfma_f32_16x16x32_bf16 v[8:11], v[180:183], v[222:225], v[8:11]
	v_mfma_f32_16x16x32_bf16 v[0:3], v[186:189], v[218:221], v[0:3]
	v_mfma_f32_16x16x32_bf16 v[0:3], v[190:193], v[222:225], v[0:3]
	s_setprio 0
	s_barrier
	s_add_i32 s76, 0, 0x18000
	v_add_u32_e32 v153, s76, v147
	s_add_i32 s77, 0, 0x1c000
	ds_read_b128 v[160:163], v153
	v_xor_b32_e32 v253, 64, v153
	ds_read_b128 v[164:167], v253
	ds_read_b128 v[168:171], v153 offset:2048
	ds_read_b128 v[172:175], v253 offset:2048
	v_add_u32_e32 v153, s77, v147
	ds_read_b128 v[176:179], v153
	v_xor_b32_e32 v253, 64, v153
	ds_read_b128 v[180:183], v253
	ds_read_b128 v[186:189], v153 offset:2048
	ds_read_b128 v[190:193], v253 offset:2048
	s_add_u32 s48, s48, 0x40000
	s_addc_u32 s49, s49, 0
	s_mov_b32 m0, s57
	v_lshl_add_u64 v[232:233], s[48:49], 0, v[134:135]
	ds_read_b128 v[194:197], v150 offset:32768
	v_xor_b32_e32 v253, 64, v150
	ds_read_b128 v[198:201], v253 offset:32768
	ds_read_b128 v[202:205], v150 offset:34816
	ds_read_b128 v[206:209], v253 offset:34816
	ds_read_b128 v[210:213], v150 offset:36864
	ds_read_b128 v[214:217], v253 offset:36864
	ds_read_b128 v[218:221], v150 offset:38912
	ds_read_b128 v[222:225], v253 offset:38912
	global_load_lds_dwordx4 v[232:233], off
	v_lshl_add_u64 v[232:233], s[48:49], 0, v[130:131]
	s_mov_b32 m0, s58
	s_nop 0
	global_load_lds_dwordx4 v[232:233], off
	s_waitcnt vmcnt(8)
	s_waitcnt lgkmcnt(0)
	s_barrier
	s_setprio 1
	s_waitcnt lgkmcnt(0)
	v_mfma_f32_16x16x32_bf16 v[124:127], v[160:163], v[194:197], v[124:127]
	v_mfma_f32_16x16x32_bf16 v[124:127], v[164:167], v[198:201], v[124:127]
	v_mfma_f32_16x16x32_bf16 v[116:119], v[168:171], v[194:197], v[116:119]
	v_mfma_f32_16x16x32_bf16 v[116:119], v[172:175], v[198:201], v[116:119]
	v_mfma_f32_16x16x32_bf16 v[108:111], v[160:163], v[202:205], v[108:111]
	v_mfma_f32_16x16x32_bf16 v[108:111], v[164:167], v[206:209], v[108:111]
	v_mfma_f32_16x16x32_bf16 v[100:103], v[168:171], v[202:205], v[100:103]
	v_mfma_f32_16x16x32_bf16 v[100:103], v[172:175], v[206:209], v[100:103]
	v_mfma_f32_16x16x32_bf16 v[92:95], v[160:163], v[210:213], v[92:95]
	v_mfma_f32_16x16x32_bf16 v[92:95], v[164:167], v[214:217], v[92:95]
	v_mfma_f32_16x16x32_bf16 v[84:87], v[168:171], v[210:213], v[84:87]
	v_mfma_f32_16x16x32_bf16 v[84:87], v[172:175], v[214:217], v[84:87]
	v_mfma_f32_16x16x32_bf16 v[76:79], v[160:163], v[218:221], v[76:79]
	v_mfma_f32_16x16x32_bf16 v[76:79], v[164:167], v[222:225], v[76:79]
	v_mfma_f32_16x16x32_bf16 v[68:71], v[168:171], v[218:221], v[68:71]
	v_mfma_f32_16x16x32_bf16 v[68:71], v[172:175], v[222:225], v[68:71]
	s_setprio 0
	s_setprio 1
	v_mfma_f32_16x16x32_bf16 v[120:123], v[176:179], v[194:197], v[120:123]
	v_mfma_f32_16x16x32_bf16 v[120:123], v[180:183], v[198:201], v[120:123]
	v_mfma_f32_16x16x32_bf16 v[112:115], v[186:189], v[194:197], v[112:115]
	v_mfma_f32_16x16x32_bf16 v[112:115], v[190:193], v[198:201], v[112:115]
	v_mfma_f32_16x16x32_bf16 v[104:107], v[176:179], v[202:205], v[104:107]
	v_mfma_f32_16x16x32_bf16 v[104:107], v[180:183], v[206:209], v[104:107]
	v_mfma_f32_16x16x32_bf16 v[96:99], v[186:189], v[202:205], v[96:99]
	v_mfma_f32_16x16x32_bf16 v[96:99], v[190:193], v[206:209], v[96:99]
	v_mfma_f32_16x16x32_bf16 v[88:91], v[176:179], v[210:213], v[88:91]
	v_mfma_f32_16x16x32_bf16 v[88:91], v[180:183], v[214:217], v[88:91]
	v_mfma_f32_16x16x32_bf16 v[80:83], v[186:189], v[210:213], v[80:83]
	v_mfma_f32_16x16x32_bf16 v[80:83], v[190:193], v[214:217], v[80:83]
	v_mfma_f32_16x16x32_bf16 v[72:75], v[176:179], v[218:221], v[72:75]
	v_mfma_f32_16x16x32_bf16 v[72:75], v[180:183], v[222:225], v[72:75]
	v_mfma_f32_16x16x32_bf16 v[64:67], v[186:189], v[218:221], v[64:67]
	v_mfma_f32_16x16x32_bf16 v[64:67], v[190:193], v[222:225], v[64:67]
	s_setprio 0
	s_barrier
	s_add_i32 s48, s76, s52
	v_lshl_add_u64 v[154:155], v[154:155], 0, s[14:15]
	s_mov_b32 m0, s48
	ds_read_b128 v[194:197], v150 offset:49152
	v_xor_b32_e32 v253, 64, v150
	ds_read_b128 v[198:201], v253 offset:49152
	ds_read_b128 v[202:205], v150 offset:51200
	ds_read_b128 v[206:209], v253 offset:51200
	ds_read_b128 v[210:213], v150 offset:53248
	ds_read_b128 v[214:217], v253 offset:53248
	ds_read_b128 v[218:221], v150 offset:55296
	ds_read_b128 v[222:225], v253 offset:55296
	global_load_lds_dwordx4 v[154:155], off
	s_add_i32 m0, s48, 0x2000
	s_add_u32 s46, s46, 0x40080
	v_lshl_add_u64 v[154:155], v[226:227], 0, s[14:15]
	s_addc_u32 s47, s47, 0
	s_add_i32 s48, s77, s52
	global_load_lds_dwordx4 v[154:155], off
	v_lshl_add_u64 v[154:155], s[46:47], 0, v[132:133]
	s_mov_b32 m0, s48
	s_nop 0
	global_load_lds_dwordx4 v[154:155], off
	v_lshl_add_u64 v[154:155], s[46:47], 0, v[128:129]
	s_add_i32 m0, s48, 0x2000
	s_nop 0
	global_load_lds_dwordx4 v[154:155], off
	v_lshl_add_u64 v[154:155], v[228:229], 0, s[14:15]
	s_mov_b32 m0, s60
	s_nop 0
	global_load_lds_dwordx4 v[154:155], off
	v_lshl_add_u64 v[154:155], v[230:231], 0, s[14:15]
	s_mov_b32 m0, s61
	s_nop 0
	global_load_lds_dwordx4 v[154:155], off
	s_waitcnt vmcnt(8)
	s_waitcnt lgkmcnt(0)
	s_barrier
	s_setprio 1
	s_waitcnt lgkmcnt(0)
	v_mfma_f32_16x16x32_bf16 v[60:63], v[160:163], v[194:197], v[60:63]
	v_mfma_f32_16x16x32_bf16 v[60:63], v[164:167], v[198:201], v[60:63]
	v_mfma_f32_16x16x32_bf16 v[52:55], v[168:171], v[194:197], v[52:55]
	v_mfma_f32_16x16x32_bf16 v[52:55], v[172:175], v[198:201], v[52:55]
	v_mfma_f32_16x16x32_bf16 v[44:47], v[160:163], v[202:205], v[44:47]
	v_mfma_f32_16x16x32_bf16 v[44:47], v[164:167], v[206:209], v[44:47]
	v_mfma_f32_16x16x32_bf16 v[36:39], v[168:171], v[202:205], v[36:39]
	v_mfma_f32_16x16x32_bf16 v[36:39], v[172:175], v[206:209], v[36:39]
	v_mfma_f32_16x16x32_bf16 v[28:31], v[160:163], v[210:213], v[28:31]
	v_mfma_f32_16x16x32_bf16 v[28:31], v[164:167], v[214:217], v[28:31]
	v_mfma_f32_16x16x32_bf16 v[20:23], v[168:171], v[210:213], v[20:23]
	v_mfma_f32_16x16x32_bf16 v[20:23], v[172:175], v[214:217], v[20:23]
	v_mfma_f32_16x16x32_bf16 v[12:15], v[160:163], v[218:221], v[12:15]
	v_mfma_f32_16x16x32_bf16 v[12:15], v[164:167], v[222:225], v[12:15]
	v_mfma_f32_16x16x32_bf16 v[4:7], v[168:171], v[218:221], v[4:7]
	v_mfma_f32_16x16x32_bf16 v[4:7], v[172:175], v[222:225], v[4:7]
	s_setprio 0
	s_setprio 1
	v_mfma_f32_16x16x32_bf16 v[56:59], v[176:179], v[194:197], v[56:59]
	v_mfma_f32_16x16x32_bf16 v[56:59], v[180:183], v[198:201], v[56:59]
	v_mfma_f32_16x16x32_bf16 v[48:51], v[186:189], v[194:197], v[48:51]
	v_mfma_f32_16x16x32_bf16 v[48:51], v[190:193], v[198:201], v[48:51]
	v_mfma_f32_16x16x32_bf16 v[40:43], v[176:179], v[202:205], v[40:43]
	v_mfma_f32_16x16x32_bf16 v[40:43], v[180:183], v[206:209], v[40:43]
	v_mfma_f32_16x16x32_bf16 v[32:35], v[186:189], v[202:205], v[32:35]
	v_mfma_f32_16x16x32_bf16 v[32:35], v[190:193], v[206:209], v[32:35]
	v_mfma_f32_16x16x32_bf16 v[24:27], v[176:179], v[210:213], v[24:27]
	v_mfma_f32_16x16x32_bf16 v[24:27], v[180:183], v[214:217], v[24:27]
	v_mfma_f32_16x16x32_bf16 v[16:19], v[186:189], v[210:213], v[16:19]
	v_mfma_f32_16x16x32_bf16 v[16:19], v[190:193], v[214:217], v[16:19]
	v_mfma_f32_16x16x32_bf16 v[8:11], v[176:179], v[218:221], v[8:11]
	v_mfma_f32_16x16x32_bf16 v[8:11], v[180:183], v[222:225], v[8:11]
	v_mfma_f32_16x16x32_bf16 v[0:3], v[186:189], v[218:221], v[0:3]
	v_mfma_f32_16x16x32_bf16 v[0:3], v[190:193], v[222:225], v[0:3]
	s_setprio 0
	s_barrier
	s_add_i32 s75, s75, 2
	s_add_u32 s71, s71, 0x100
	s_addc_u32 s74, s74, 0
	s_add_u32 s44, s44, 0x100
	s_addc_u32 s45, s45, 0
	s_cmp_gt_u32 s75, 13
	s_cbranch_scc1 .LBB0_78

.Llast_0:
	v_add_u32_e32 v153, s64, v147
	ds_read_b128 v[160:163], v153
	v_xor_b32_e32 v253, 64, v153
	ds_read_b128 v[164:167], v253
	ds_read_b128 v[168:171], v153 offset:2048
	ds_read_b128 v[172:175], v253 offset:2048
	v_add_u32_e32 v153, s65, v147
	ds_read_b128 v[176:179], v153
	v_xor_b32_e32 v253, 64, v153
	ds_read_b128 v[180:183], v253
	ds_read_b128 v[186:189], v153 offset:2048
	ds_read_b128 v[190:193], v253 offset:2048
	s_add_u32 s48, s44, 0xfffc0080
	s_addc_u32 s49, s45, -1
	s_and_b64 s[46:47], s[46:47], exec
	s_cselect_b32 s49, s27, s49
	s_cselect_b32 s48, s68, s48
	s_cselect_b32 s47, s69, s74
	s_cselect_b32 s46, s70, s71
	v_lshl_add_u64 v[154:155], s[44:45], 0, v[138:139]
	s_add_i32 m0, s55, 0xc000
	ds_read_b128 v[194:197], v150
	v_xor_b32_e32 v253, 64, v150
	ds_read_b128 v[198:201], v253
	ds_read_b128 v[202:205], v150 offset:2048
	ds_read_b128 v[206:209], v253 offset:2048
	ds_read_b128 v[210:213], v150 offset:4096
	ds_read_b128 v[214:217], v253 offset:4096
	ds_read_b128 v[218:221], v150 offset:6144
	ds_read_b128 v[222:225], v253 offset:6144
	global_load_lds_dwordx4 v[154:155], off
	v_lshl_add_u64 v[154:155], s[44:45], 0, v[136:137]
	s_add_i32 m0, s55, 0xe000
	s_nop 0
	global_load_lds_dwordx4 v[154:155], off
	s_waitcnt vmcnt(8)
	s_waitcnt lgkmcnt(0)
	s_barrier
	s_setprio 1
	s_waitcnt lgkmcnt(0)
	v_mfma_f32_16x16x32_bf16 v[124:127], v[160:163], v[194:197], v[124:127]
	v_mfma_f32_16x16x32_bf16 v[124:127], v[164:167], v[198:201], v[124:127]
	v_mfma_f32_16x16x32_bf16 v[116:119], v[168:171], v[194:197], v[116:119]
	v_mfma_f32_16x16x32_bf16 v[116:119], v[172:175], v[198:201], v[116:119]
	v_mfma_f32_16x16x32_bf16 v[108:111], v[160:163], v[202:205], v[108:111]
	v_mfma_f32_16x16x32_bf16 v[108:111], v[164:167], v[206:209], v[108:111]
	v_mfma_f32_16x16x32_bf16 v[100:103], v[168:171], v[202:205], v[100:103]
	v_mfma_f32_16x16x32_bf16 v[100:103], v[172:175], v[206:209], v[100:103]
	v_mfma_f32_16x16x32_bf16 v[92:95], v[160:163], v[210:213], v[92:95]
	v_mfma_f32_16x16x32_bf16 v[92:95], v[164:167], v[214:217], v[92:95]
	v_mfma_f32_16x16x32_bf16 v[84:87], v[168:171], v[210:213], v[84:87]
	v_mfma_f32_16x16x32_bf16 v[84:87], v[172:175], v[214:217], v[84:87]
	v_mfma_f32_16x16x32_bf16 v[76:79], v[160:163], v[218:221], v[76:79]
	v_mfma_f32_16x16x32_bf16 v[76:79], v[164:167], v[222:225], v[76:79]
	v_mfma_f32_16x16x32_bf16 v[68:71], v[168:171], v[218:221], v[68:71]
	v_mfma_f32_16x16x32_bf16 v[68:71], v[172:175], v[222:225], v[68:71]
	s_setprio 0
	s_setprio 1
	v_mfma_f32_16x16x32_bf16 v[120:123], v[176:179], v[194:197], v[120:123]
	v_mfma_f32_16x16x32_bf16 v[120:123], v[180:183], v[198:201], v[120:123]
	v_mfma_f32_16x16x32_bf16 v[112:115], v[186:189], v[194:197], v[112:115]
	v_mfma_f32_16x16x32_bf16 v[112:115], v[190:193], v[198:201], v[112:115]
	v_mfma_f32_16x16x32_bf16 v[104:107], v[176:179], v[202:205], v[104:107]
	v_mfma_f32_16x16x32_bf16 v[104:107], v[180:183], v[206:209], v[104:107]
	v_mfma_f32_16x16x32_bf16 v[96:99], v[186:189], v[202:205], v[96:99]
	v_mfma_f32_16x16x32_bf16 v[96:99], v[190:193], v[206:209], v[96:99]
	v_mfma_f32_16x16x32_bf16 v[88:91], v[176:179], v[210:213], v[88:91]
	v_mfma_f32_16x16x32_bf16 v[88:91], v[180:183], v[214:217], v[88:91]
	v_mfma_f32_16x16x32_bf16 v[80:83], v[186:189], v[210:213], v[80:83]
	v_mfma_f32_16x16x32_bf16 v[80:83], v[190:193], v[214:217], v[80:83]
	v_mfma_f32_16x16x32_bf16 v[72:75], v[176:179], v[218:221], v[72:75]
	v_mfma_f32_16x16x32_bf16 v[72:75], v[180:183], v[222:225], v[72:75]
	v_mfma_f32_16x16x32_bf16 v[64:67], v[186:189], v[218:221], v[64:67]
	v_mfma_f32_16x16x32_bf16 v[64:67], v[190:193], v[222:225], v[64:67]
	s_setprio 0
	s_barrier
	s_add_i32 s76, s64, s52
	v_lshl_add_u64 v[154:155], s[46:47], 0, v[132:133]
	s_mov_b32 m0, s76
	ds_read_b128 v[194:197], v150 offset:16384
	v_xor_b32_e32 v253, 64, v150
	ds_read_b128 v[198:201], v253 offset:16384
	ds_read_b128 v[202:205], v150 offset:18432
	ds_read_b128 v[206:209], v253 offset:18432
	ds_read_b128 v[210:213], v150 offset:20480
	ds_read_b128 v[214:217], v253 offset:20480
	ds_read_b128 v[218:221], v150 offset:22528
	ds_read_b128 v[222:225], v253 offset:22528
	global_load_lds_dwordx4 v[154:155], off
	s_add_i32 m0, s76, 0x2000
	s_add_u32 s76, s46, 0x40000
	v_lshl_add_u64 v[226:227], s[46:47], 0, v[128:129]
	s_addc_u32 s77, s47, 0
	s_add_i32 s78, s65, s52
	global_load_lds_dwordx4 v[226:227], off
	v_lshl_add_u64 v[228:229], s[76:77], 0, v[132:133]
	s_mov_b32 m0, s78
	v_lshl_add_u64 v[230:231], s[48:49], 0, v[130:131]
	global_load_lds_dwordx4 v[228:229], off
	v_lshl_add_u64 v[228:229], s[76:77], 0, v[128:129]
	s_add_i32 m0, s78, 0x2000
	s_nop 0
	global_load_lds_dwordx4 v[228:229], off
	v_lshl_add_u64 v[228:229], s[48:49], 0, v[134:135]
	s_mov_b32 m0, s55
	s_nop 0
	global_load_lds_dwordx4 v[228:229], off
	s_mov_b32 m0, s56
	s_nop 0
	global_load_lds_dwordx4 v[230:231], off
	s_waitcnt vmcnt(8)
	s_waitcnt lgkmcnt(0)
	s_barrier
	s_setprio 1
	s_waitcnt lgkmcnt(0)
	v_mfma_f32_16x16x32_bf16 v[60:63], v[160:163], v[194:197], v[60:63]
	v_mfma_f32_16x16x32_bf16 v[60:63], v[164:167], v[198:201], v[60:63]
	v_mfma_f32_16x16x32_bf16 v[52:55], v[168:171], v[194:197], v[52:55]
	v_mfma_f32_16x16x32_bf16 v[52:55], v[172:175], v[198:201], v[52:55]
	v_mfma_f32_16x16x32_bf16 v[44:47], v[160:163], v[202:205], v[44:47]
	v_mfma_f32_16x16x32_bf16 v[44:47], v[164:167], v[206:209], v[44:47]
	v_mfma_f32_16x16x32_bf16 v[36:39], v[168:171], v[202:205], v[36:39]
	v_mfma_f32_16x16x32_bf16 v[36:39], v[172:175], v[206:209], v[36:39]
	v_mfma_f32_16x16x32_bf16 v[28:31], v[160:163], v[210:213], v[28:31]
	v_mfma_f32_16x16x32_bf16 v[28:31], v[164:167], v[214:217], v[28:31]
	v_mfma_f32_16x16x32_bf16 v[20:23], v[168:171], v[210:213], v[20:23]
	v_mfma_f32_16x16x32_bf16 v[20:23], v[172:175], v[214:217], v[20:23]
	v_mfma_f32_16x16x32_bf16 v[12:15], v[160:163], v[218:221], v[12:15]
	v_mfma_f32_16x16x32_bf16 v[12:15], v[164:167], v[222:225], v[12:15]
	v_mfma_f32_16x16x32_bf16 v[4:7], v[168:171], v[218:221], v[4:7]
	v_mfma_f32_16x16x32_bf16 v[4:7], v[172:175], v[222:225], v[4:7]
	s_setprio 0
	s_setprio 1
	v_mfma_f32_16x16x32_bf16 v[56:59], v[176:179], v[194:197], v[56:59]
	v_mfma_f32_16x16x32_bf16 v[56:59], v[180:183], v[198:201], v[56:59]
	v_mfma_f32_16x16x32_bf16 v[48:51], v[186:189], v[194:197], v[48:51]
	v_mfma_f32_16x16x32_bf16 v[48:51], v[190:193], v[198:201], v[48:51]
	v_mfma_f32_16x16x32_bf16 v[40:43], v[176:179], v[202:205], v[40:43]
	v_mfma_f32_16x16x32_bf16 v[40:43], v[180:183], v[206:209], v[40:43]
	v_mfma_f32_16x16x32_bf16 v[32:35], v[186:189], v[202:205], v[32:35]
	v_mfma_f32_16x16x32_bf16 v[32:35], v[190:193], v[206:209], v[32:35]
	v_mfma_f32_16x16x32_bf16 v[24:27], v[176:179], v[210:213], v[24:27]
	v_mfma_f32_16x16x32_bf16 v[24:27], v[180:183], v[214:217], v[24:27]
	v_mfma_f32_16x16x32_bf16 v[16:19], v[186:189], v[210:213], v[16:19]
	v_mfma_f32_16x16x32_bf16 v[16:19], v[190:193], v[214:217], v[16:19]
	v_mfma_f32_16x16x32_bf16 v[8:11], v[176:179], v[218:221], v[8:11]
	v_mfma_f32_16x16x32_bf16 v[8:11], v[180:183], v[222:225], v[8:11]
	v_mfma_f32_16x16x32_bf16 v[0:3], v[186:189], v[218:221], v[0:3]
	v_mfma_f32_16x16x32_bf16 v[0:3], v[190:193], v[222:225], v[0:3]
	s_setprio 0
	s_barrier
	s_add_i32 s76, 0, 0x18000
	v_add_u32_e32 v153, s76, v147
	s_add_i32 s77, 0, 0x1c000
	ds_read_b128 v[160:163], v153
	v_xor_b32_e32 v253, 64, v153
	ds_read_b128 v[164:167], v253
	ds_read_b128 v[168:171], v153 offset:2048
	ds_read_b128 v[172:175], v253 offset:2048
	v_add_u32_e32 v153, s77, v147
	ds_read_b128 v[176:179], v153
	v_xor_b32_e32 v253, 64, v153
	ds_read_b128 v[180:183], v253
	ds_read_b128 v[186:189], v153 offset:2048
	ds_read_b128 v[190:193], v253 offset:2048
	s_add_u32 s48, s48, 0x40000
	s_addc_u32 s49, s49, 0
	s_mov_b32 m0, s57
	v_lshl_add_u64 v[232:233], s[48:49], 0, v[134:135]
	ds_read_b128 v[194:197], v150 offset:32768
	v_xor_b32_e32 v253, 64, v150
	ds_read_b128 v[198:201], v253 offset:32768
	ds_read_b128 v[202:205], v150 offset:34816
	ds_read_b128 v[206:209], v253 offset:34816
	ds_read_b128 v[210:213], v150 offset:36864
	ds_read_b128 v[214:217], v253 offset:36864
	ds_read_b128 v[218:221], v150 offset:38912
	ds_read_b128 v[222:225], v253 offset:38912
	global_load_lds_dwordx4 v[232:233], off
	v_lshl_add_u64 v[232:233], s[48:49], 0, v[130:131]
	s_mov_b32 m0, s58
	s_nop 0
	global_load_lds_dwordx4 v[232:233], off
	s_waitcnt vmcnt(8)
	s_waitcnt lgkmcnt(0)
	s_barrier
	s_setprio 1
	s_waitcnt lgkmcnt(0)
	v_mfma_f32_16x16x32_bf16 v[124:127], v[160:163], v[194:197], v[124:127]
	v_mfma_f32_16x16x32_bf16 v[124:127], v[164:167], v[198:201], v[124:127]
	v_mfma_f32_16x16x32_bf16 v[116:119], v[168:171], v[194:197], v[116:119]
	v_mfma_f32_16x16x32_bf16 v[116:119], v[172:175], v[198:201], v[116:119]
	v_mfma_f32_16x16x32_bf16 v[108:111], v[160:163], v[202:205], v[108:111]
	v_mfma_f32_16x16x32_bf16 v[108:111], v[164:167], v[206:209], v[108:111]
	v_mfma_f32_16x16x32_bf16 v[100:103], v[168:171], v[202:205], v[100:103]
	v_mfma_f32_16x16x32_bf16 v[100:103], v[172:175], v[206:209], v[100:103]
	v_mfma_f32_16x16x32_bf16 v[92:95], v[160:163], v[210:213], v[92:95]
	v_mfma_f32_16x16x32_bf16 v[92:95], v[164:167], v[214:217], v[92:95]
	v_mfma_f32_16x16x32_bf16 v[84:87], v[168:171], v[210:213], v[84:87]
	v_mfma_f32_16x16x32_bf16 v[84:87], v[172:175], v[214:217], v[84:87]
	v_mfma_f32_16x16x32_bf16 v[76:79], v[160:163], v[218:221], v[76:79]
	v_mfma_f32_16x16x32_bf16 v[76:79], v[164:167], v[222:225], v[76:79]
	v_mfma_f32_16x16x32_bf16 v[68:71], v[168:171], v[218:221], v[68:71]
	v_mfma_f32_16x16x32_bf16 v[68:71], v[172:175], v[222:225], v[68:71]
	s_setprio 0
	s_setprio 1
	v_mfma_f32_16x16x32_bf16 v[120:123], v[176:179], v[194:197], v[120:123]
	v_mfma_f32_16x16x32_bf16 v[120:123], v[180:183], v[198:201], v[120:123]
	v_mfma_f32_16x16x32_bf16 v[112:115], v[186:189], v[194:197], v[112:115]
	v_mfma_f32_16x16x32_bf16 v[112:115], v[190:193], v[198:201], v[112:115]
	v_mfma_f32_16x16x32_bf16 v[104:107], v[176:179], v[202:205], v[104:107]
	v_mfma_f32_16x16x32_bf16 v[104:107], v[180:183], v[206:209], v[104:107]
	v_mfma_f32_16x16x32_bf16 v[96:99], v[186:189], v[202:205], v[96:99]
	v_mfma_f32_16x16x32_bf16 v[96:99], v[190:193], v[206:209], v[96:99]
	v_mfma_f32_16x16x32_bf16 v[88:91], v[176:179], v[210:213], v[88:91]
	v_mfma_f32_16x16x32_bf16 v[88:91], v[180:183], v[214:217], v[88:91]
	v_mfma_f32_16x16x32_bf16 v[80:83], v[186:189], v[210:213], v[80:83]
	v_mfma_f32_16x16x32_bf16 v[80:83], v[190:193], v[214:217], v[80:83]
	v_mfma_f32_16x16x32_bf16 v[72:75], v[176:179], v[218:221], v[72:75]
	v_mfma_f32_16x16x32_bf16 v[72:75], v[180:183], v[222:225], v[72:75]
	v_mfma_f32_16x16x32_bf16 v[64:67], v[186:189], v[218:221], v[64:67]
	v_mfma_f32_16x16x32_bf16 v[64:67], v[190:193], v[222:225], v[64:67]
	s_setprio 0
	s_barrier
	v_add_u32_e32 v234, 0x21000, v151
	ds_read_b128 v[236:239], v234
	ds_read_b128 v[240:243], v234 offset:256
	ds_read_b128 v[244:247], v234 offset:512
	ds_read_b128 v[248:251], v234 offset:768
	v_add_u32_e32 v235, s23, v146
	v_mul_u32_u24_e32 v235, 0x1600, v235
	v_lshl_or_b32 v234, s67, 7, v149
	v_lshl_add_u32 v235, v234, 1, v235
	s_add_i32 s48, s76, s52
	v_lshl_add_u64 v[154:155], v[154:155], 0, s[14:15]
	s_mov_b32 m0, s48
	ds_read_b128 v[194:197], v150 offset:49152
	v_xor_b32_e32 v253, 64, v150
	ds_read_b128 v[198:201], v253 offset:49152
	ds_read_b128 v[202:205], v150 offset:51200
	ds_read_b128 v[206:209], v253 offset:51200
	ds_read_b128 v[210:213], v150 offset:53248
	ds_read_b128 v[214:217], v253 offset:53248
	ds_read_b128 v[218:221], v150 offset:55296
	ds_read_b128 v[222:225], v253 offset:55296
	global_load_lds_dwordx4 v[154:155], off
	s_add_i32 m0, s48, 0x2000
	s_add_u32 s46, s46, 0x40080
	v_lshl_add_u64 v[154:155], v[226:227], 0, s[14:15]
	s_addc_u32 s47, s47, 0
	s_add_i32 s48, s77, s52
	global_load_lds_dwordx4 v[154:155], off
	v_lshl_add_u64 v[154:155], s[46:47], 0, v[132:133]
	s_mov_b32 m0, s48
	s_nop 0
	global_load_lds_dwordx4 v[154:155], off
	v_lshl_add_u64 v[154:155], s[46:47], 0, v[128:129]
	s_add_i32 m0, s48, 0x2000
	s_nop 0
	global_load_lds_dwordx4 v[154:155], off
	v_lshl_add_u64 v[154:155], v[228:229], 0, s[14:15]
	s_mov_b32 m0, s60
	s_nop 0
	global_load_lds_dwordx4 v[154:155], off
	v_lshl_add_u64 v[154:155], v[230:231], 0, s[14:15]
	s_mov_b32 m0, s61
	s_nop 0
	global_load_lds_dwordx4 v[154:155], off
	s_waitcnt lgkmcnt(8)
	v_add_f32_e32 v236, v236, v237
	v_add_f32_e32 v238, v238, v239
	v_add_f32_e32 v240, v240, v241
	v_add_f32_e32 v242, v242, v243
	v_add_f32_e32 v244, v244, v245
	v_add_f32_e32 v246, v246, v247
	v_add_f32_e32 v248, v248, v249
	v_add_f32_e32 v250, v250, v251
	v_add_f32_e32 v236, v236, v238
	v_add_f32_e32 v240, v240, v242
	v_add_f32_e32 v244, v244, v246
	v_add_f32_e32 v248, v248, v250
	v_fmamk_f32 v236, v236, 0x3a800000, v152
	v_fmamk_f32 v240, v240, 0x3a800000, v152
	v_fmamk_f32 v244, v244, 0x3a800000, v152
	v_fmamk_f32 v248, v248, 0x3a800000, v152
	v_rsq_f32_e32 v236, v236
	v_rsq_f32_e32 v240, v240
	v_rsq_f32_e32 v244, v244
	v_rsq_f32_e32 v248, v248
	v_mul_f32_e32 v252, 0xbfb8aa3b, v236
	v_mul_f32_e32 v254, v236, v236
	v_pk_mul_f32 v[120:121], v[124:125], v[120:121]
	v_pk_mul_f32 v[122:123], v[126:127], v[122:123]
	v_pk_mul_f32 v[112:113], v[116:117], v[112:113]
	v_pk_mul_f32 v[114:115], v[118:119], v[114:115]
	v_pk_mul_f32 v[124:125], v[124:125], v[252:253] op_sel_hi:[1,0]
	v_pk_mul_f32 v[126:127], v[126:127], v[252:253] op_sel_hi:[1,0]
	v_pk_mul_f32 v[116:117], v[116:117], v[252:253] op_sel_hi:[1,0]
	v_pk_mul_f32 v[118:119], v[118:119], v[252:253] op_sel_hi:[1,0]
	v_exp_f32_e32 v124, v124
	v_exp_f32_e32 v125, v125
	v_exp_f32_e32 v126, v126
	v_exp_f32_e32 v127, v127
	v_exp_f32_e32 v116, v116
	v_exp_f32_e32 v117, v117
	v_exp_f32_e32 v118, v118
	v_exp_f32_e32 v119, v119
	v_pk_add_f32 v[124:125], v[124:125], 1.0 op_sel_hi:[1,0]
	v_pk_add_f32 v[126:127], v[126:127], 1.0 op_sel_hi:[1,0]
	v_pk_add_f32 v[116:117], v[116:117], 1.0 op_sel_hi:[1,0]
	v_pk_add_f32 v[118:119], v[118:119], 1.0 op_sel_hi:[1,0]
	v_rcp_f32_e32 v124, v124
	v_rcp_f32_e32 v125, v125
	v_rcp_f32_e32 v126, v126
	v_rcp_f32_e32 v127, v127
	v_rcp_f32_e32 v116, v116
	v_rcp_f32_e32 v117, v117
	v_rcp_f32_e32 v118, v118
	v_rcp_f32_e32 v119, v119
	v_pk_mul_f32 v[120:121], v[120:121], v[254:255] op_sel_hi:[1,0]
	v_pk_mul_f32 v[122:123], v[122:123], v[254:255] op_sel_hi:[1,0]
	v_pk_mul_f32 v[112:113], v[112:113], v[254:255] op_sel_hi:[1,0]
	v_pk_mul_f32 v[114:115], v[114:115], v[254:255] op_sel_hi:[1,0]
	v_pk_mul_f32 v[120:121], v[120:121], v[124:125]
	v_pk_mul_f32 v[122:123], v[122:123], v[126:127]
	v_pk_mul_f32 v[112:113], v[112:113], v[116:117]
	v_pk_mul_f32 v[114:115], v[114:115], v[118:119]
	v_cvt_pk_bf16_f32 v120, v120, v121
	v_cvt_pk_bf16_f32 v121, v122, v123
	v_cvt_pk_bf16_f32 v122, v112, v113
	v_cvt_pk_bf16_f32 v123, v114, v115
	global_store_dwordx4 v235, v[120:123], s[10:11]
	v_add_u32_e32 v234, 0x16000, v235
	v_mul_f32_e32 v252, 0xbfb8aa3b, v240
	v_mul_f32_e32 v254, v240, v240
	v_pk_mul_f32 v[104:105], v[108:109], v[104:105]
	v_pk_mul_f32 v[106:107], v[110:111], v[106:107]
	v_pk_mul_f32 v[96:97], v[100:101], v[96:97]
	v_pk_mul_f32 v[98:99], v[102:103], v[98:99]
	v_pk_mul_f32 v[108:109], v[108:109], v[252:253] op_sel_hi:[1,0]
	v_pk_mul_f32 v[110:111], v[110:111], v[252:253] op_sel_hi:[1,0]
	v_pk_mul_f32 v[100:101], v[100:101], v[252:253] op_sel_hi:[1,0]
	v_pk_mul_f32 v[102:103], v[102:103], v[252:253] op_sel_hi:[1,0]
	v_exp_f32_e32 v108, v108
	v_exp_f32_e32 v109, v109
	v_exp_f32_e32 v110, v110
	v_exp_f32_e32 v111, v111
	v_exp_f32_e32 v100, v100
	v_exp_f32_e32 v101, v101
	v_exp_f32_e32 v102, v102
	v_exp_f32_e32 v103, v103
	v_pk_add_f32 v[108:109], v[108:109], 1.0 op_sel_hi:[1,0]
	v_pk_add_f32 v[110:111], v[110:111], 1.0 op_sel_hi:[1,0]
	v_pk_add_f32 v[100:101], v[100:101], 1.0 op_sel_hi:[1,0]
	v_pk_add_f32 v[102:103], v[102:103], 1.0 op_sel_hi:[1,0]
	v_rcp_f32_e32 v108, v108
	v_rcp_f32_e32 v109, v109
	v_rcp_f32_e32 v110, v110
	v_rcp_f32_e32 v111, v111
	v_rcp_f32_e32 v100, v100
	v_rcp_f32_e32 v101, v101
	v_rcp_f32_e32 v102, v102
	v_rcp_f32_e32 v103, v103
	v_pk_mul_f32 v[104:105], v[104:105], v[254:255] op_sel_hi:[1,0]
	v_pk_mul_f32 v[106:107], v[106:107], v[254:255] op_sel_hi:[1,0]
	v_pk_mul_f32 v[96:97], v[96:97], v[254:255] op_sel_hi:[1,0]
	v_pk_mul_f32 v[98:99], v[98:99], v[254:255] op_sel_hi:[1,0]
	v_pk_mul_f32 v[104:105], v[104:105], v[108:109]
	v_pk_mul_f32 v[106:107], v[106:107], v[110:111]
	v_pk_mul_f32 v[96:97], v[96:97], v[100:101]
	v_pk_mul_f32 v[98:99], v[98:99], v[102:103]
	v_cvt_pk_bf16_f32 v104, v104, v105
	v_cvt_pk_bf16_f32 v105, v106, v107
	v_cvt_pk_bf16_f32 v106, v96, v97
	v_cvt_pk_bf16_f32 v107, v98, v99
	global_store_dwordx4 v234, v[104:107], s[10:11]
	v_add_u32_e32 v235, 0x16000, v234
	v_mul_f32_e32 v252, 0xbfb8aa3b, v244
	v_mul_f32_e32 v254, v244, v244
	v_pk_mul_f32 v[88:89], v[92:93], v[88:89]
	v_pk_mul_f32 v[90:91], v[94:95], v[90:91]
	v_pk_mul_f32 v[80:81], v[84:85], v[80:81]
	v_pk_mul_f32 v[82:83], v[86:87], v[82:83]
	v_pk_mul_f32 v[92:93], v[92:93], v[252:253] op_sel_hi:[1,0]
	v_pk_mul_f32 v[94:95], v[94:95], v[252:253] op_sel_hi:[1,0]
	v_pk_mul_f32 v[84:85], v[84:85], v[252:253] op_sel_hi:[1,0]
	v_pk_mul_f32 v[86:87], v[86:87], v[252:253] op_sel_hi:[1,0]
	v_exp_f32_e32 v92, v92
	v_exp_f32_e32 v93, v93
	v_exp_f32_e32 v94, v94
	v_exp_f32_e32 v95, v95
	v_exp_f32_e32 v84, v84
	v_exp_f32_e32 v85, v85
	v_exp_f32_e32 v86, v86
	v_exp_f32_e32 v87, v87
	v_pk_add_f32 v[92:93], v[92:93], 1.0 op_sel_hi:[1,0]
	v_pk_add_f32 v[94:95], v[94:95], 1.0 op_sel_hi:[1,0]
	v_pk_add_f32 v[84:85], v[84:85], 1.0 op_sel_hi:[1,0]
	v_pk_add_f32 v[86:87], v[86:87], 1.0 op_sel_hi:[1,0]
	v_rcp_f32_e32 v92, v92
	v_rcp_f32_e32 v93, v93
	v_rcp_f32_e32 v94, v94
	v_rcp_f32_e32 v95, v95
	v_rcp_f32_e32 v84, v84
	v_rcp_f32_e32 v85, v85
	v_rcp_f32_e32 v86, v86
	v_rcp_f32_e32 v87, v87
	v_pk_mul_f32 v[88:89], v[88:89], v[254:255] op_sel_hi:[1,0]
	v_pk_mul_f32 v[90:91], v[90:91], v[254:255] op_sel_hi:[1,0]
	v_pk_mul_f32 v[80:81], v[80:81], v[254:255] op_sel_hi:[1,0]
	v_pk_mul_f32 v[82:83], v[82:83], v[254:255] op_sel_hi:[1,0]
	v_pk_mul_f32 v[88:89], v[88:89], v[92:93]
	v_pk_mul_f32 v[90:91], v[90:91], v[94:95]
	v_pk_mul_f32 v[80:81], v[80:81], v[84:85]
	v_pk_mul_f32 v[82:83], v[82:83], v[86:87]
	v_cvt_pk_bf16_f32 v88, v88, v89
	v_cvt_pk_bf16_f32 v89, v90, v91
	v_cvt_pk_bf16_f32 v90, v80, v81
	v_cvt_pk_bf16_f32 v91, v82, v83
	global_store_dwordx4 v235, v[88:91], s[10:11]
	v_add_u32_e32 v234, 0x16000, v235
	v_mul_f32_e32 v252, 0xbfb8aa3b, v248
	v_mul_f32_e32 v254, v248, v248
	v_pk_mul_f32 v[72:73], v[76:77], v[72:73]
	v_pk_mul_f32 v[74:75], v[78:79], v[74:75]
	v_pk_mul_f32 v[64:65], v[68:69], v[64:65]
	v_pk_mul_f32 v[66:67], v[70:71], v[66:67]
	v_pk_mul_f32 v[76:77], v[76:77], v[252:253] op_sel_hi:[1,0]
	v_pk_mul_f32 v[78:79], v[78:79], v[252:253] op_sel_hi:[1,0]
	v_pk_mul_f32 v[68:69], v[68:69], v[252:253] op_sel_hi:[1,0]
	v_pk_mul_f32 v[70:71], v[70:71], v[252:253] op_sel_hi:[1,0]
	v_exp_f32_e32 v76, v76
	v_exp_f32_e32 v77, v77
	v_exp_f32_e32 v78, v78
	v_exp_f32_e32 v79, v79
	v_exp_f32_e32 v68, v68
	v_exp_f32_e32 v69, v69
	v_exp_f32_e32 v70, v70
	v_exp_f32_e32 v71, v71
	v_pk_add_f32 v[76:77], v[76:77], 1.0 op_sel_hi:[1,0]
	v_pk_add_f32 v[78:79], v[78:79], 1.0 op_sel_hi:[1,0]
	v_pk_add_f32 v[68:69], v[68:69], 1.0 op_sel_hi:[1,0]
	v_pk_add_f32 v[70:71], v[70:71], 1.0 op_sel_hi:[1,0]
	v_rcp_f32_e32 v76, v76
	v_rcp_f32_e32 v77, v77
	v_rcp_f32_e32 v78, v78
	v_rcp_f32_e32 v79, v79
	v_rcp_f32_e32 v68, v68
	v_rcp_f32_e32 v69, v69
	v_rcp_f32_e32 v70, v70
	v_rcp_f32_e32 v71, v71
	v_pk_mul_f32 v[72:73], v[72:73], v[254:255] op_sel_hi:[1,0]
	v_pk_mul_f32 v[74:75], v[74:75], v[254:255] op_sel_hi:[1,0]
	v_pk_mul_f32 v[64:65], v[64:65], v[254:255] op_sel_hi:[1,0]
	v_pk_mul_f32 v[66:67], v[66:67], v[254:255] op_sel_hi:[1,0]
	v_pk_mul_f32 v[72:73], v[72:73], v[76:77]
	v_pk_mul_f32 v[74:75], v[74:75], v[78:79]
	v_pk_mul_f32 v[64:65], v[64:65], v[68:69]
	v_pk_mul_f32 v[66:67], v[66:67], v[70:71]
	v_cvt_pk_bf16_f32 v72, v72, v73
	v_cvt_pk_bf16_f32 v73, v74, v75
	v_cvt_pk_bf16_f32 v74, v64, v65
	v_cvt_pk_bf16_f32 v75, v66, v67
	global_store_dwordx4 v234, v[72:75], s[10:11]
	s_waitcnt vmcnt(12)
	s_waitcnt lgkmcnt(0)
	s_barrier
	s_setprio 1
	s_waitcnt lgkmcnt(0)
	v_mfma_f32_16x16x32_bf16 v[60:63], v[160:163], v[194:197], v[60:63]
	v_mfma_f32_16x16x32_bf16 v[60:63], v[164:167], v[198:201], v[60:63]
	v_mfma_f32_16x16x32_bf16 v[52:55], v[168:171], v[194:197], v[52:55]
	v_mfma_f32_16x16x32_bf16 v[52:55], v[172:175], v[198:201], v[52:55]
	v_mfma_f32_16x16x32_bf16 v[44:47], v[160:163], v[202:205], v[44:47]
	v_mfma_f32_16x16x32_bf16 v[44:47], v[164:167], v[206:209], v[44:47]
	v_mfma_f32_16x16x32_bf16 v[36:39], v[168:171], v[202:205], v[36:39]
	v_mfma_f32_16x16x32_bf16 v[36:39], v[172:175], v[206:209], v[36:39]
	v_mfma_f32_16x16x32_bf16 v[28:31], v[160:163], v[210:213], v[28:31]
	v_mfma_f32_16x16x32_bf16 v[28:31], v[164:167], v[214:217], v[28:31]
	v_mfma_f32_16x16x32_bf16 v[20:23], v[168:171], v[210:213], v[20:23]
	v_mfma_f32_16x16x32_bf16 v[20:23], v[172:175], v[214:217], v[20:23]
	v_mfma_f32_16x16x32_bf16 v[12:15], v[160:163], v[218:221], v[12:15]
	v_mfma_f32_16x16x32_bf16 v[12:15], v[164:167], v[222:225], v[12:15]
	v_mfma_f32_16x16x32_bf16 v[4:7], v[168:171], v[218:221], v[4:7]
	v_mfma_f32_16x16x32_bf16 v[4:7], v[172:175], v[222:225], v[4:7]
	s_setprio 0
	s_setprio 1
	v_mfma_f32_16x16x32_bf16 v[56:59], v[176:179], v[194:197], v[56:59]
	v_mfma_f32_16x16x32_bf16 v[56:59], v[180:183], v[198:201], v[56:59]
	v_mfma_f32_16x16x32_bf16 v[48:51], v[186:189], v[194:197], v[48:51]
	v_mfma_f32_16x16x32_bf16 v[48:51], v[190:193], v[198:201], v[48:51]
	v_mfma_f32_16x16x32_bf16 v[40:43], v[176:179], v[202:205], v[40:43]
	v_mfma_f32_16x16x32_bf16 v[40:43], v[180:183], v[206:209], v[40:43]
	v_mfma_f32_16x16x32_bf16 v[32:35], v[186:189], v[202:205], v[32:35]
	v_mfma_f32_16x16x32_bf16 v[32:35], v[190:193], v[206:209], v[32:35]
	v_mfma_f32_16x16x32_bf16 v[24:27], v[176:179], v[210:213], v[24:27]
	v_mfma_f32_16x16x32_bf16 v[24:27], v[180:183], v[214:217], v[24:27]
	v_mfma_f32_16x16x32_bf16 v[16:19], v[186:189], v[210:213], v[16:19]
	v_mfma_f32_16x16x32_bf16 v[16:19], v[190:193], v[214:217], v[16:19]
	v_mfma_f32_16x16x32_bf16 v[8:11], v[176:179], v[218:221], v[8:11]
	v_mfma_f32_16x16x32_bf16 v[8:11], v[180:183], v[222:225], v[8:11]
	v_mfma_f32_16x16x32_bf16 v[0:3], v[186:189], v[218:221], v[0:3]
	v_mfma_f32_16x16x32_bf16 v[0:3], v[190:193], v[222:225], v[0:3]
	s_setprio 0
	s_barrier
	s_add_i32 s75, s75, 2
	s_add_u32 s71, s71, 0x100
	s_addc_u32 s74, s74, 0
	s_add_u32 s44, s44, 0x100
	s_addc_u32 s45, s45, 0

.LBB0_158:
	s_add_u32 s81, s56, 0x100
	s_addc_u32 s82, s57, 0
	s_mov_b32 s83, -2
	s_waitcnt lgkmcnt(0)
	s_cmp_eq_u32 s70, 1
	s_cbranch_scc1 .Lfa_1
	ds_read_b128 v[128:131], v189
	v_xor_b32_e32 v253, 64, v189
	ds_read_b128 v[132:135], v253
	ds_read_b128 v[136:139], v189 offset:2048
	ds_read_b128 v[140:143], v253 offset:2048
	ds_read_b128 v[144:147], v190
	v_xor_b32_e32 v253, 64, v190
	ds_read_b128 v[148:151], v253
	ds_read_b128 v[172:175], v190 offset:2048
	ds_read_b128 v[176:179], v253 offset:2048
	s_add_u32 s56, s54, 0x100
	s_addc_u32 s57, s55, 0
	s_cmp_eq_u32 s83, 40
	s_cselect_b32 s61, s15, s57
	s_cselect_b32 s60, s14, s56
	s_cselect_b32 s59, s53, s82
	s_cselect_b32 s58, s52, s81
	v_lshl_add_u64 v[222:223], s[54:55], 0, v[166:167]
	s_add_i32 m0, s66, 0xc000
	ds_read_b128 v[180:183], v191
	v_xor_b32_e32 v253, 64, v191
	ds_read_b128 v[194:197], v253
	ds_read_b128 v[198:201], v191 offset:2048
	ds_read_b128 v[202:205], v253 offset:2048
	ds_read_b128 v[206:209], v191 offset:4096
	ds_read_b128 v[210:213], v253 offset:4096
	ds_read_b128 v[214:217], v191 offset:6144
	ds_read_b128 v[218:221], v253 offset:6144
	global_load_lds_dwordx4 v[222:223], off
	v_lshl_add_u64 v[222:223], s[54:55], 0, v[164:165]
	s_add_i32 m0, s66, 0xe000
	s_nop 0
	global_load_lds_dwordx4 v[222:223], off
	s_waitcnt vmcnt(24)
	s_waitcnt lgkmcnt(0)
	s_barrier
	s_setprio 1
	s_waitcnt lgkmcnt(0)
	v_mfma_f32_16x16x32_bf16 v[124:127], v[128:131], v[180:183], 0
	v_mfma_f32_16x16x32_bf16 v[120:123], v[136:139], v[180:183], 0
	v_mfma_f32_16x16x32_bf16 v[108:111], v[128:131], v[198:201], 0
	v_mfma_f32_16x16x32_bf16 v[104:107], v[136:139], v[198:201], 0
	v_mfma_f32_16x16x32_bf16 v[92:95], v[128:131], v[206:209], 0
	v_mfma_f32_16x16x32_bf16 v[88:91], v[136:139], v[206:209], 0
	v_mfma_f32_16x16x32_bf16 v[76:79], v[128:131], v[214:217], 0
	v_mfma_f32_16x16x32_bf16 v[72:75], v[136:139], v[214:217], 0
	v_mfma_f32_16x16x32_bf16 v[124:127], v[132:135], v[194:197], v[124:127]
	v_mfma_f32_16x16x32_bf16 v[120:123], v[140:143], v[194:197], v[120:123]
	v_mfma_f32_16x16x32_bf16 v[108:111], v[132:135], v[202:205], v[108:111]
	v_mfma_f32_16x16x32_bf16 v[104:107], v[140:143], v[202:205], v[104:107]
	v_mfma_f32_16x16x32_bf16 v[92:95], v[132:135], v[210:213], v[92:95]
	v_mfma_f32_16x16x32_bf16 v[88:91], v[140:143], v[210:213], v[88:91]
	v_mfma_f32_16x16x32_bf16 v[76:79], v[132:135], v[218:221], v[76:79]
	v_mfma_f32_16x16x32_bf16 v[72:75], v[140:143], v[218:221], v[72:75]
	s_setprio 0
	s_setprio 1
	v_mfma_f32_16x16x32_bf16 v[116:119], v[144:147], v[180:183], 0
	v_mfma_f32_16x16x32_bf16 v[112:115], v[172:175], v[180:183], 0
	v_mfma_f32_16x16x32_bf16 v[100:103], v[144:147], v[198:201], 0
	v_mfma_f32_16x16x32_bf16 v[96:99], v[172:175], v[198:201], 0
	v_mfma_f32_16x16x32_bf16 v[84:87], v[144:147], v[206:209], 0
	v_mfma_f32_16x16x32_bf16 v[80:83], v[172:175], v[206:209], 0
	v_mfma_f32_16x16x32_bf16 v[68:71], v[144:147], v[214:217], 0
	v_mfma_f32_16x16x32_bf16 v[64:67], v[172:175], v[214:217], 0
	v_mfma_f32_16x16x32_bf16 v[116:119], v[148:151], v[194:197], v[116:119]
	v_mfma_f32_16x16x32_bf16 v[112:115], v[176:179], v[194:197], v[112:115]
	v_mfma_f32_16x16x32_bf16 v[100:103], v[148:151], v[202:205], v[100:103]
	v_mfma_f32_16x16x32_bf16 v[96:99], v[176:179], v[202:205], v[96:99]
	v_mfma_f32_16x16x32_bf16 v[84:87], v[148:151], v[210:213], v[84:87]
	v_mfma_f32_16x16x32_bf16 v[80:83], v[176:179], v[210:213], v[80:83]
	v_mfma_f32_16x16x32_bf16 v[68:71], v[148:151], v[218:221], v[68:71]
	v_mfma_f32_16x16x32_bf16 v[64:67], v[176:179], v[218:221], v[64:67]
	s_setprio 0
	s_barrier
	s_add_i32 s54, s77, s65
	v_lshl_add_u64 v[222:223], s[58:59], 0, v[154:155]
	s_mov_b32 m0, s54
	ds_read_b128 v[180:183], v191 offset:16384
	v_xor_b32_e32 v253, 64, v191
	ds_read_b128 v[194:197], v253 offset:16384
	ds_read_b128 v[198:201], v191 offset:18432
	ds_read_b128 v[202:205], v253 offset:18432
	ds_read_b128 v[206:209], v191 offset:20480
	ds_read_b128 v[210:213], v253 offset:20480
	ds_read_b128 v[214:217], v191 offset:22528
	ds_read_b128 v[218:221], v253 offset:22528
	global_load_lds_dwordx4 v[222:223], off
	s_add_i32 m0, s54, 0x2000
	s_add_u32 s54, s58, 0xb0000
	v_lshl_add_u64 v[224:225], s[58:59], 0, v[162:163]
	s_addc_u32 s55, s59, 0
	s_add_i32 s84, s78, s65
	global_load_lds_dwordx4 v[224:225], off
	v_lshl_add_u64 v[226:227], s[54:55], 0, v[154:155]
	s_mov_b32 m0, s84
	v_lshl_add_u64 v[228:229], s[60:61], 0, v[160:161]
	global_load_lds_dwordx4 v[226:227], off
	v_lshl_add_u64 v[226:227], s[54:55], 0, v[162:163]
	s_add_i32 m0, s84, 0x2000
	s_nop 0
	global_load_lds_dwordx4 v[226:227], off
	v_lshl_add_u64 v[226:227], s[60:61], 0, v[152:153]
	s_mov_b32 m0, s66
	s_nop 0
	global_load_lds_dwordx4 v[226:227], off
	s_mov_b32 m0, s67
	s_nop 0
	global_load_lds_dwordx4 v[228:229], off
	s_waitcnt vmcnt(24)
	s_waitcnt lgkmcnt(0)
	s_barrier
	s_setprio 1
	s_waitcnt lgkmcnt(0)
	v_mfma_f32_16x16x32_bf16 v[60:63], v[128:131], v[180:183], 0
	v_mfma_f32_16x16x32_bf16 v[56:59], v[136:139], v[180:183], 0
	v_mfma_f32_16x16x32_bf16 v[44:47], v[128:131], v[198:201], 0
	v_mfma_f32_16x16x32_bf16 v[40:43], v[136:139], v[198:201], 0
	v_mfma_f32_16x16x32_bf16 v[28:31], v[128:131], v[206:209], 0
	v_mfma_f32_16x16x32_bf16 v[24:27], v[136:139], v[206:209], 0
	v_mfma_f32_16x16x32_bf16 v[12:15], v[128:131], v[214:217], 0
	v_mfma_f32_16x16x32_bf16 v[8:11], v[136:139], v[214:217], 0
	v_mfma_f32_16x16x32_bf16 v[60:63], v[132:135], v[194:197], v[60:63]
	v_mfma_f32_16x16x32_bf16 v[56:59], v[140:143], v[194:197], v[56:59]
	v_mfma_f32_16x16x32_bf16 v[44:47], v[132:135], v[202:205], v[44:47]
	v_mfma_f32_16x16x32_bf16 v[40:43], v[140:143], v[202:205], v[40:43]
	v_mfma_f32_16x16x32_bf16 v[28:31], v[132:135], v[210:213], v[28:31]
	v_mfma_f32_16x16x32_bf16 v[24:27], v[140:143], v[210:213], v[24:27]
	v_mfma_f32_16x16x32_bf16 v[12:15], v[132:135], v[218:221], v[12:15]
	v_mfma_f32_16x16x32_bf16 v[8:11], v[140:143], v[218:221], v[8:11]
	s_setprio 0
	s_setprio 1
	v_mfma_f32_16x16x32_bf16 v[52:55], v[144:147], v[180:183], 0
	v_mfma_f32_16x16x32_bf16 v[48:51], v[172:175], v[180:183], 0
	v_mfma_f32_16x16x32_bf16 v[36:39], v[144:147], v[198:201], 0
	v_mfma_f32_16x16x32_bf16 v[32:35], v[172:175], v[198:201], 0
	v_mfma_f32_16x16x32_bf16 v[20:23], v[144:147], v[206:209], 0
	v_mfma_f32_16x16x32_bf16 v[16:19], v[172:175], v[206:209], 0
	v_mfma_f32_16x16x32_bf16 v[4:7], v[144:147], v[214:217], 0
	v_mfma_f32_16x16x32_bf16 v[0:3], v[172:175], v[214:217], 0
	v_mfma_f32_16x16x32_bf16 v[52:55], v[148:151], v[194:197], v[52:55]
	v_mfma_f32_16x16x32_bf16 v[48:51], v[176:179], v[194:197], v[48:51]
	v_mfma_f32_16x16x32_bf16 v[36:39], v[148:151], v[202:205], v[36:39]
	v_mfma_f32_16x16x32_bf16 v[32:35], v[176:179], v[202:205], v[32:35]
	v_mfma_f32_16x16x32_bf16 v[20:23], v[148:151], v[210:213], v[20:23]
	v_mfma_f32_16x16x32_bf16 v[16:19], v[176:179], v[210:213], v[16:19]
	v_mfma_f32_16x16x32_bf16 v[4:7], v[148:151], v[218:221], v[4:7]
	v_mfma_f32_16x16x32_bf16 v[0:3], v[176:179], v[218:221], v[0:3]
	s_setprio 0
	s_barrier
	s_add_i32 s84, 0, 0x18000
	s_add_i32 s85, 0, 0x1c000
	v_add_u32_e32 v140, s84, v186
	v_add_u32_e32 v176, s85, v186
	ds_read_b128 v[128:131], v140
	v_xor_b32_e32 v253, 64, v140
	ds_read_b128 v[132:135], v253
	ds_read_b128 v[136:139], v140 offset:2048
	ds_read_b128 v[140:143], v253 offset:2048
	ds_read_b128 v[144:147], v176
	v_xor_b32_e32 v253, 64, v176
	ds_read_b128 v[148:151], v253
	ds_read_b128 v[172:175], v176 offset:2048
	ds_read_b128 v[176:179], v253 offset:2048
	s_add_u32 s54, s60, 0xb0000
	s_addc_u32 s55, s61, 0
	s_mov_b32 m0, s68
	v_lshl_add_u64 v[230:231], s[54:55], 0, v[152:153]
	ds_read_b128 v[180:183], v191 offset:32768
	v_xor_b32_e32 v253, 64, v191
	ds_read_b128 v[194:197], v253 offset:32768
	ds_read_b128 v[198:201], v191 offset:34816
	ds_read_b128 v[202:205], v253 offset:34816
	ds_read_b128 v[206:209], v191 offset:36864
	ds_read_b128 v[210:213], v253 offset:36864
	ds_read_b128 v[214:217], v191 offset:38912
	ds_read_b128 v[218:221], v253 offset:38912
	global_load_lds_dwordx4 v[230:231], off
	v_lshl_add_u64 v[230:231], s[54:55], 0, v[160:161]
	s_mov_b32 m0, s69
	s_nop 0
	global_load_lds_dwordx4 v[230:231], off
	s_waitcnt vmcnt(8)
	s_waitcnt lgkmcnt(0)
	s_barrier
	s_setprio 1
	s_waitcnt lgkmcnt(0)
	v_mfma_f32_16x16x32_bf16 v[124:127], v[128:131], v[180:183], v[124:127]
	v_mfma_f32_16x16x32_bf16 v[124:127], v[132:135], v[194:197], v[124:127]
	v_mfma_f32_16x16x32_bf16 v[120:123], v[136:139], v[180:183], v[120:123]
	v_mfma_f32_16x16x32_bf16 v[120:123], v[140:143], v[194:197], v[120:123]
	v_mfma_f32_16x16x32_bf16 v[108:111], v[128:131], v[198:201], v[108:111]
	v_mfma_f32_16x16x32_bf16 v[108:111], v[132:135], v[202:205], v[108:111]
	v_mfma_f32_16x16x32_bf16 v[104:107], v[136:139], v[198:201], v[104:107]
	v_mfma_f32_16x16x32_bf16 v[104:107], v[140:143], v[202:205], v[104:107]
	v_mfma_f32_16x16x32_bf16 v[92:95], v[128:131], v[206:209], v[92:95]
	v_mfma_f32_16x16x32_bf16 v[92:95], v[132:135], v[210:213], v[92:95]
	v_mfma_f32_16x16x32_bf16 v[88:91], v[136:139], v[206:209], v[88:91]
	v_mfma_f32_16x16x32_bf16 v[88:91], v[140:143], v[210:213], v[88:91]
	v_mfma_f32_16x16x32_bf16 v[76:79], v[128:131], v[214:217], v[76:79]
	v_mfma_f32_16x16x32_bf16 v[76:79], v[132:135], v[218:221], v[76:79]
	v_mfma_f32_16x16x32_bf16 v[72:75], v[136:139], v[214:217], v[72:75]
	v_mfma_f32_16x16x32_bf16 v[72:75], v[140:143], v[218:221], v[72:75]
	s_setprio 0
	s_setprio 1
	v_mfma_f32_16x16x32_bf16 v[116:119], v[144:147], v[180:183], v[116:119]
	v_mfma_f32_16x16x32_bf16 v[116:119], v[148:151], v[194:197], v[116:119]
	v_mfma_f32_16x16x32_bf16 v[112:115], v[172:175], v[180:183], v[112:115]
	v_mfma_f32_16x16x32_bf16 v[112:115], v[176:179], v[194:197], v[112:115]
	v_mfma_f32_16x16x32_bf16 v[100:103], v[144:147], v[198:201], v[100:103]
	v_mfma_f32_16x16x32_bf16 v[100:103], v[148:151], v[202:205], v[100:103]
	v_mfma_f32_16x16x32_bf16 v[96:99], v[172:175], v[198:201], v[96:99]
	v_mfma_f32_16x16x32_bf16 v[96:99], v[176:179], v[202:205], v[96:99]
	v_mfma_f32_16x16x32_bf16 v[84:87], v[144:147], v[206:209], v[84:87]
	v_mfma_f32_16x16x32_bf16 v[84:87], v[148:151], v[210:213], v[84:87]
	v_mfma_f32_16x16x32_bf16 v[80:83], v[172:175], v[206:209], v[80:83]
	v_mfma_f32_16x16x32_bf16 v[80:83], v[176:179], v[210:213], v[80:83]
	v_mfma_f32_16x16x32_bf16 v[68:71], v[144:147], v[214:217], v[68:71]
	v_mfma_f32_16x16x32_bf16 v[68:71], v[148:151], v[218:221], v[68:71]
	v_mfma_f32_16x16x32_bf16 v[64:67], v[172:175], v[214:217], v[64:67]
	v_mfma_f32_16x16x32_bf16 v[64:67], v[176:179], v[218:221], v[64:67]
	s_setprio 0
	s_barrier
	s_add_i32 s54, s84, s65
	v_lshl_add_u64 v[222:223], v[222:223], 0, s[28:29]
	s_mov_b32 m0, s54
	ds_read_b128 v[180:183], v191 offset:49152
	v_xor_b32_e32 v253, 64, v191
	ds_read_b128 v[194:197], v253 offset:49152
	ds_read_b128 v[198:201], v191 offset:51200
	ds_read_b128 v[202:205], v253 offset:51200
	ds_read_b128 v[206:209], v191 offset:53248
	ds_read_b128 v[210:213], v253 offset:53248
	ds_read_b128 v[214:217], v191 offset:55296
	ds_read_b128 v[218:221], v253 offset:55296
	global_load_lds_dwordx4 v[222:223], off
	s_add_i32 m0, s54, 0x2000
	s_add_u32 s54, s58, 0xb0080
	v_lshl_add_u64 v[222:223], v[224:225], 0, s[28:29]
	s_addc_u32 s55, s59, 0
	s_add_i32 s58, s85, s65
	global_load_lds_dwordx4 v[222:223], off
	v_lshl_add_u64 v[222:223], s[54:55], 0, v[154:155]
	s_mov_b32 m0, s58
	s_nop 0
	global_load_lds_dwordx4 v[222:223], off
	v_lshl_add_u64 v[222:223], s[54:55], 0, v[162:163]
	s_add_i32 m0, s58, 0x2000
	s_nop 0
	global_load_lds_dwordx4 v[222:223], off
	v_lshl_add_u64 v[222:223], v[226:227], 0, s[28:29]
	s_mov_b32 m0, s3
	s_nop 0
	global_load_lds_dwordx4 v[222:223], off
	v_lshl_add_u64 v[222:223], v[228:229], 0, s[28:29]
	s_mov_b32 m0, s71
	s_nop 0
	global_load_lds_dwordx4 v[222:223], off
	s_waitcnt vmcnt(8)
	s_waitcnt lgkmcnt(0)
	s_barrier
	s_setprio 1
	s_waitcnt lgkmcnt(0)
	v_mfma_f32_16x16x32_bf16 v[60:63], v[128:131], v[180:183], v[60:63]
	v_mfma_f32_16x16x32_bf16 v[60:63], v[132:135], v[194:197], v[60:63]
	v_mfma_f32_16x16x32_bf16 v[56:59], v[136:139], v[180:183], v[56:59]
	v_mfma_f32_16x16x32_bf16 v[56:59], v[140:143], v[194:197], v[56:59]
	v_mfma_f32_16x16x32_bf16 v[44:47], v[128:131], v[198:201], v[44:47]
	v_mfma_f32_16x16x32_bf16 v[44:47], v[132:135], v[202:205], v[44:47]
	v_mfma_f32_16x16x32_bf16 v[40:43], v[136:139], v[198:201], v[40:43]
	v_mfma_f32_16x16x32_bf16 v[40:43], v[140:143], v[202:205], v[40:43]
	v_mfma_f32_16x16x32_bf16 v[28:31], v[128:131], v[206:209], v[28:31]
	v_mfma_f32_16x16x32_bf16 v[28:31], v[132:135], v[210:213], v[28:31]
	v_mfma_f32_16x16x32_bf16 v[24:27], v[136:139], v[206:209], v[24:27]
	v_mfma_f32_16x16x32_bf16 v[24:27], v[140:143], v[210:213], v[24:27]
	v_mfma_f32_16x16x32_bf16 v[12:15], v[128:131], v[214:217], v[12:15]
	v_mfma_f32_16x16x32_bf16 v[12:15], v[132:135], v[218:221], v[12:15]
	v_mfma_f32_16x16x32_bf16 v[8:11], v[136:139], v[214:217], v[8:11]
	v_mfma_f32_16x16x32_bf16 v[8:11], v[140:143], v[218:221], v[8:11]
	s_setprio 0
	s_setprio 1
	v_mfma_f32_16x16x32_bf16 v[52:55], v[144:147], v[180:183], v[52:55]
	v_mfma_f32_16x16x32_bf16 v[52:55], v[148:151], v[194:197], v[52:55]
	v_mfma_f32_16x16x32_bf16 v[48:51], v[172:175], v[180:183], v[48:51]
	v_mfma_f32_16x16x32_bf16 v[48:51], v[176:179], v[194:197], v[48:51]
	v_mfma_f32_16x16x32_bf16 v[36:39], v[144:147], v[198:201], v[36:39]
	v_mfma_f32_16x16x32_bf16 v[36:39], v[148:151], v[202:205], v[36:39]
	v_mfma_f32_16x16x32_bf16 v[32:35], v[172:175], v[198:201], v[32:35]
	v_mfma_f32_16x16x32_bf16 v[32:35], v[176:179], v[202:205], v[32:35]
	v_mfma_f32_16x16x32_bf16 v[20:23], v[144:147], v[206:209], v[20:23]
	v_mfma_f32_16x16x32_bf16 v[20:23], v[148:151], v[210:213], v[20:23]
	v_mfma_f32_16x16x32_bf16 v[16:19], v[172:175], v[206:209], v[16:19]
	v_mfma_f32_16x16x32_bf16 v[16:19], v[176:179], v[210:213], v[16:19]
	v_mfma_f32_16x16x32_bf16 v[4:7], v[144:147], v[214:217], v[4:7]
	v_mfma_f32_16x16x32_bf16 v[4:7], v[148:151], v[218:221], v[4:7]
	v_mfma_f32_16x16x32_bf16 v[0:3], v[172:175], v[214:217], v[0:3]
	v_mfma_f32_16x16x32_bf16 v[0:3], v[176:179], v[218:221], v[0:3]
	s_setprio 0
	s_barrier
	s_add_i32 s83, s83, 2
	s_add_u32 s81, s81, 0x100
	s_addc_u32 s82, s82, 0
	s_cmp_gt_u32 s83, 41
	s_mov_b64 s[54:55], s[56:57]
	s_branch .LBB0_159
.Lfa_1:
	ds_read_b128 v[128:131], v189
	v_xor_b32_e32 v253, 64, v189
	ds_read_b128 v[132:135], v253
	ds_read_b128 v[136:139], v189 offset:2048
	ds_read_b128 v[140:143], v253 offset:2048
	ds_read_b128 v[144:147], v190
	v_xor_b32_e32 v253, 64, v190
	ds_read_b128 v[148:151], v253
	ds_read_b128 v[172:175], v190 offset:2048
	ds_read_b128 v[176:179], v253 offset:2048
	s_add_u32 s56, s54, 0x100
	s_addc_u32 s57, s55, 0
	s_cmp_eq_u32 s83, 40
	s_cselect_b32 s61, s15, s57
	s_cselect_b32 s60, s14, s56
	s_cselect_b32 s59, s53, s82
	s_cselect_b32 s58, s52, s81
	v_lshl_add_u64 v[222:223], s[54:55], 0, v[166:167]
	s_add_i32 m0, s66, 0xc000
	ds_read_b128 v[180:183], v191
	v_xor_b32_e32 v253, 64, v191
	ds_read_b128 v[194:197], v253
	ds_read_b128 v[198:201], v191 offset:2048
	ds_read_b128 v[202:205], v253 offset:2048
	ds_read_b128 v[206:209], v191 offset:4096
	ds_read_b128 v[210:213], v253 offset:4096
	ds_read_b128 v[214:217], v191 offset:6144
	ds_read_b128 v[218:221], v253 offset:6144
	global_load_lds_dwordx4 v[222:223], off
	v_lshl_add_u64 v[222:223], s[54:55], 0, v[164:165]
	s_add_i32 m0, s66, 0xe000
	s_nop 0
	global_load_lds_dwordx4 v[222:223], off
	s_waitcnt vmcnt(8)
	s_waitcnt lgkmcnt(0)
	s_barrier
	s_setprio 1
	s_waitcnt lgkmcnt(0)
	v_mfma_f32_16x16x32_bf16 v[124:127], v[128:131], v[180:183], 0
	v_mfma_f32_16x16x32_bf16 v[120:123], v[136:139], v[180:183], 0
	v_mfma_f32_16x16x32_bf16 v[108:111], v[128:131], v[198:201], 0
	v_mfma_f32_16x16x32_bf16 v[104:107], v[136:139], v[198:201], 0
	v_mfma_f32_16x16x32_bf16 v[92:95], v[128:131], v[206:209], 0
	v_mfma_f32_16x16x32_bf16 v[88:91], v[136:139], v[206:209], 0
	v_mfma_f32_16x16x32_bf16 v[76:79], v[128:131], v[214:217], 0
	v_mfma_f32_16x16x32_bf16 v[72:75], v[136:139], v[214:217], 0
	v_mfma_f32_16x16x32_bf16 v[124:127], v[132:135], v[194:197], v[124:127]
	v_mfma_f32_16x16x32_bf16 v[120:123], v[140:143], v[194:197], v[120:123]
	v_mfma_f32_16x16x32_bf16 v[108:111], v[132:135], v[202:205], v[108:111]
	v_mfma_f32_16x16x32_bf16 v[104:107], v[140:143], v[202:205], v[104:107]
	v_mfma_f32_16x16x32_bf16 v[92:95], v[132:135], v[210:213], v[92:95]
	v_mfma_f32_16x16x32_bf16 v[88:91], v[140:143], v[210:213], v[88:91]
	v_mfma_f32_16x16x32_bf16 v[76:79], v[132:135], v[218:221], v[76:79]
	v_mfma_f32_16x16x32_bf16 v[72:75], v[140:143], v[218:221], v[72:75]
	s_setprio 0
	s_setprio 1
	v_mfma_f32_16x16x32_bf16 v[116:119], v[144:147], v[180:183], 0
	v_mfma_f32_16x16x32_bf16 v[112:115], v[172:175], v[180:183], 0
	v_mfma_f32_16x16x32_bf16 v[100:103], v[144:147], v[198:201], 0
	v_mfma_f32_16x16x32_bf16 v[96:99], v[172:175], v[198:201], 0
	v_mfma_f32_16x16x32_bf16 v[84:87], v[144:147], v[206:209], 0
	v_mfma_f32_16x16x32_bf16 v[80:83], v[172:175], v[206:209], 0
	v_mfma_f32_16x16x32_bf16 v[68:71], v[144:147], v[214:217], 0
	v_mfma_f32_16x16x32_bf16 v[64:67], v[172:175], v[214:217], 0
	v_mfma_f32_16x16x32_bf16 v[116:119], v[148:151], v[194:197], v[116:119]
	v_mfma_f32_16x16x32_bf16 v[112:115], v[176:179], v[194:197], v[112:115]
	v_mfma_f32_16x16x32_bf16 v[100:103], v[148:151], v[202:205], v[100:103]
	v_mfma_f32_16x16x32_bf16 v[96:99], v[176:179], v[202:205], v[96:99]
	v_mfma_f32_16x16x32_bf16 v[84:87], v[148:151], v[210:213], v[84:87]
	v_mfma_f32_16x16x32_bf16 v[80:83], v[176:179], v[210:213], v[80:83]
	v_mfma_f32_16x16x32_bf16 v[68:71], v[148:151], v[218:221], v[68:71]
	v_mfma_f32_16x16x32_bf16 v[64:67], v[176:179], v[218:221], v[64:67]
	s_setprio 0
	s_barrier
	s_add_i32 s54, s77, s65
	v_lshl_add_u64 v[222:223], s[58:59], 0, v[154:155]
	s_mov_b32 m0, s54
	ds_read_b128 v[180:183], v191 offset:16384
	v_xor_b32_e32 v253, 64, v191
	ds_read_b128 v[194:197], v253 offset:16384
	ds_read_b128 v[198:201], v191 offset:18432
	ds_read_b128 v[202:205], v253 offset:18432
	ds_read_b128 v[206:209], v191 offset:20480
	ds_read_b128 v[210:213], v253 offset:20480
	ds_read_b128 v[214:217], v191 offset:22528
	ds_read_b128 v[218:221], v253 offset:22528
	global_load_lds_dwordx4 v[222:223], off
	s_add_i32 m0, s54, 0x2000
	s_add_u32 s54, s58, 0xb0000
	v_lshl_add_u64 v[224:225], s[58:59], 0, v[162:163]
	s_addc_u32 s55, s59, 0
	s_add_i32 s84, s78, s65
	global_load_lds_dwordx4 v[224:225], off
	v_lshl_add_u64 v[226:227], s[54:55], 0, v[154:155]
	s_mov_b32 m0, s84
	v_lshl_add_u64 v[228:229], s[60:61], 0, v[160:161]
	global_load_lds_dwordx4 v[226:227], off
	v_lshl_add_u64 v[226:227], s[54:55], 0, v[162:163]
	s_add_i32 m0, s84, 0x2000
	s_nop 0
	global_load_lds_dwordx4 v[226:227], off
	v_lshl_add_u64 v[226:227], s[60:61], 0, v[152:153]
	s_mov_b32 m0, s66
	s_nop 0
	global_load_lds_dwordx4 v[226:227], off
	s_mov_b32 m0, s67
	s_nop 0
	global_load_lds_dwordx4 v[228:229], off
	s_waitcnt vmcnt(8)
	s_waitcnt lgkmcnt(0)
	s_barrier
	s_setprio 1
	s_waitcnt lgkmcnt(0)
	v_mfma_f32_16x16x32_bf16 v[60:63], v[128:131], v[180:183], 0
	v_mfma_f32_16x16x32_bf16 v[56:59], v[136:139], v[180:183], 0
	v_mfma_f32_16x16x32_bf16 v[44:47], v[128:131], v[198:201], 0
	v_mfma_f32_16x16x32_bf16 v[40:43], v[136:139], v[198:201], 0
	v_mfma_f32_16x16x32_bf16 v[28:31], v[128:131], v[206:209], 0
	v_mfma_f32_16x16x32_bf16 v[24:27], v[136:139], v[206:209], 0
	v_mfma_f32_16x16x32_bf16 v[12:15], v[128:131], v[214:217], 0
	v_mfma_f32_16x16x32_bf16 v[8:11], v[136:139], v[214:217], 0
	v_mfma_f32_16x16x32_bf16 v[60:63], v[132:135], v[194:197], v[60:63]
	v_mfma_f32_16x16x32_bf16 v[56:59], v[140:143], v[194:197], v[56:59]
	v_mfma_f32_16x16x32_bf16 v[44:47], v[132:135], v[202:205], v[44:47]
	v_mfma_f32_16x16x32_bf16 v[40:43], v[140:143], v[202:205], v[40:43]
	v_mfma_f32_16x16x32_bf16 v[28:31], v[132:135], v[210:213], v[28:31]
	v_mfma_f32_16x16x32_bf16 v[24:27], v[140:143], v[210:213], v[24:27]
	v_mfma_f32_16x16x32_bf16 v[12:15], v[132:135], v[218:221], v[12:15]
	v_mfma_f32_16x16x32_bf16 v[8:11], v[140:143], v[218:221], v[8:11]
	s_setprio 0
	s_setprio 1
	v_mfma_f32_16x16x32_bf16 v[52:55], v[144:147], v[180:183], 0
	v_mfma_f32_16x16x32_bf16 v[48:51], v[172:175], v[180:183], 0
	v_mfma_f32_16x16x32_bf16 v[36:39], v[144:147], v[198:201], 0
	v_mfma_f32_16x16x32_bf16 v[32:35], v[172:175], v[198:201], 0
	v_mfma_f32_16x16x32_bf16 v[20:23], v[144:147], v[206:209], 0
	v_mfma_f32_16x16x32_bf16 v[16:19], v[172:175], v[206:209], 0
	v_mfma_f32_16x16x32_bf16 v[4:7], v[144:147], v[214:217], 0
	v_mfma_f32_16x16x32_bf16 v[0:3], v[172:175], v[214:217], 0
	v_mfma_f32_16x16x32_bf16 v[52:55], v[148:151], v[194:197], v[52:55]
	v_mfma_f32_16x16x32_bf16 v[48:51], v[176:179], v[194:197], v[48:51]
	v_mfma_f32_16x16x32_bf16 v[36:39], v[148:151], v[202:205], v[36:39]
	v_mfma_f32_16x16x32_bf16 v[32:35], v[176:179], v[202:205], v[32:35]
	v_mfma_f32_16x16x32_bf16 v[20:23], v[148:151], v[210:213], v[20:23]
	v_mfma_f32_16x16x32_bf16 v[16:19], v[176:179], v[210:213], v[16:19]
	v_mfma_f32_16x16x32_bf16 v[4:7], v[148:151], v[218:221], v[4:7]
	v_mfma_f32_16x16x32_bf16 v[0:3], v[176:179], v[218:221], v[0:3]
	s_setprio 0
	s_barrier
	s_add_i32 s84, 0, 0x18000
	s_add_i32 s85, 0, 0x1c000
	v_add_u32_e32 v140, s84, v186
	v_add_u32_e32 v176, s85, v186
	ds_read_b128 v[128:131], v140
	v_xor_b32_e32 v253, 64, v140
	ds_read_b128 v[132:135], v253
	ds_read_b128 v[136:139], v140 offset:2048
	ds_read_b128 v[140:143], v253 offset:2048
	ds_read_b128 v[144:147], v176
	v_xor_b32_e32 v253, 64, v176
	ds_read_b128 v[148:151], v253
	ds_read_b128 v[172:175], v176 offset:2048
	ds_read_b128 v[176:179], v253 offset:2048
	s_add_u32 s54, s60, 0xb0000
	s_addc_u32 s55, s61, 0
	s_mov_b32 m0, s68
	v_lshl_add_u64 v[230:231], s[54:55], 0, v[152:153]
	ds_read_b128 v[180:183], v191 offset:32768
	v_xor_b32_e32 v253, 64, v191
	ds_read_b128 v[194:197], v253 offset:32768
	ds_read_b128 v[198:201], v191 offset:34816
	ds_read_b128 v[202:205], v253 offset:34816
	ds_read_b128 v[206:209], v191 offset:36864
	ds_read_b128 v[210:213], v253 offset:36864
	ds_read_b128 v[214:217], v191 offset:38912
	ds_read_b128 v[218:221], v253 offset:38912
	global_load_lds_dwordx4 v[230:231], off
	v_lshl_add_u64 v[230:231], s[54:55], 0, v[160:161]
	s_mov_b32 m0, s69
	s_nop 0
	global_load_lds_dwordx4 v[230:231], off
	s_waitcnt vmcnt(8)
	s_waitcnt lgkmcnt(0)
	s_barrier
	s_setprio 1
	s_waitcnt lgkmcnt(0)
	v_mfma_f32_16x16x32_bf16 v[124:127], v[128:131], v[180:183], v[124:127]
	v_mfma_f32_16x16x32_bf16 v[124:127], v[132:135], v[194:197], v[124:127]
	v_mfma_f32_16x16x32_bf16 v[120:123], v[136:139], v[180:183], v[120:123]
	v_mfma_f32_16x16x32_bf16 v[120:123], v[140:143], v[194:197], v[120:123]
	v_mfma_f32_16x16x32_bf16 v[108:111], v[128:131], v[198:201], v[108:111]
	v_mfma_f32_16x16x32_bf16 v[108:111], v[132:135], v[202:205], v[108:111]
	v_mfma_f32_16x16x32_bf16 v[104:107], v[136:139], v[198:201], v[104:107]
	v_mfma_f32_16x16x32_bf16 v[104:107], v[140:143], v[202:205], v[104:107]
	v_mfma_f32_16x16x32_bf16 v[92:95], v[128:131], v[206:209], v[92:95]
	v_mfma_f32_16x16x32_bf16 v[92:95], v[132:135], v[210:213], v[92:95]
	v_mfma_f32_16x16x32_bf16 v[88:91], v[136:139], v[206:209], v[88:91]
	v_mfma_f32_16x16x32_bf16 v[88:91], v[140:143], v[210:213], v[88:91]
	v_mfma_f32_16x16x32_bf16 v[76:79], v[128:131], v[214:217], v[76:79]
	v_mfma_f32_16x16x32_bf16 v[76:79], v[132:135], v[218:221], v[76:79]
	v_mfma_f32_16x16x32_bf16 v[72:75], v[136:139], v[214:217], v[72:75]
	v_mfma_f32_16x16x32_bf16 v[72:75], v[140:143], v[218:221], v[72:75]
	s_setprio 0
	s_setprio 1
	v_mfma_f32_16x16x32_bf16 v[116:119], v[144:147], v[180:183], v[116:119]
	v_mfma_f32_16x16x32_bf16 v[116:119], v[148:151], v[194:197], v[116:119]
	v_mfma_f32_16x16x32_bf16 v[112:115], v[172:175], v[180:183], v[112:115]
	v_mfma_f32_16x16x32_bf16 v[112:115], v[176:179], v[194:197], v[112:115]
	v_mfma_f32_16x16x32_bf16 v[100:103], v[144:147], v[198:201], v[100:103]
	v_mfma_f32_16x16x32_bf16 v[100:103], v[148:151], v[202:205], v[100:103]
	v_mfma_f32_16x16x32_bf16 v[96:99], v[172:175], v[198:201], v[96:99]
	v_mfma_f32_16x16x32_bf16 v[96:99], v[176:179], v[202:205], v[96:99]
	v_mfma_f32_16x16x32_bf16 v[84:87], v[144:147], v[206:209], v[84:87]
	v_mfma_f32_16x16x32_bf16 v[84:87], v[148:151], v[210:213], v[84:87]
	v_mfma_f32_16x16x32_bf16 v[80:83], v[172:175], v[206:209], v[80:83]
	v_mfma_f32_16x16x32_bf16 v[80:83], v[176:179], v[210:213], v[80:83]
	v_mfma_f32_16x16x32_bf16 v[68:71], v[144:147], v[214:217], v[68:71]
	v_mfma_f32_16x16x32_bf16 v[68:71], v[148:151], v[218:221], v[68:71]
	v_mfma_f32_16x16x32_bf16 v[64:67], v[172:175], v[214:217], v[64:67]
	v_mfma_f32_16x16x32_bf16 v[64:67], v[176:179], v[218:221], v[64:67]
	s_setprio 0
	s_barrier
	s_add_i32 s54, s84, s65
	v_lshl_add_u64 v[222:223], v[222:223], 0, s[28:29]
	s_mov_b32 m0, s54
	ds_read_b128 v[180:183], v191 offset:49152
	v_xor_b32_e32 v253, 64, v191
	ds_read_b128 v[194:197], v253 offset:49152
	ds_read_b128 v[198:201], v191 offset:51200
	ds_read_b128 v[202:205], v253 offset:51200
	ds_read_b128 v[206:209], v191 offset:53248
	ds_read_b128 v[210:213], v253 offset:53248
	ds_read_b128 v[214:217], v191 offset:55296
	ds_read_b128 v[218:221], v253 offset:55296
	global_load_lds_dwordx4 v[222:223], off
	s_add_i32 m0, s54, 0x2000
	s_add_u32 s54, s58, 0xb0080
	v_lshl_add_u64 v[222:223], v[224:225], 0, s[28:29]
	s_addc_u32 s55, s59, 0
	s_add_i32 s58, s85, s65
	global_load_lds_dwordx4 v[222:223], off
	v_lshl_add_u64 v[222:223], s[54:55], 0, v[154:155]
	s_mov_b32 m0, s58
	s_nop 0
	global_load_lds_dwordx4 v[222:223], off
	v_lshl_add_u64 v[222:223], s[54:55], 0, v[162:163]
	s_add_i32 m0, s58, 0x2000
	s_nop 0
	global_load_lds_dwordx4 v[222:223], off
	v_lshl_add_u64 v[222:223], v[226:227], 0, s[28:29]
	s_mov_b32 m0, s3
	s_nop 0
	global_load_lds_dwordx4 v[222:223], off
	v_lshl_add_u64 v[222:223], v[228:229], 0, s[28:29]
	s_mov_b32 m0, s71
	s_nop 0
	global_load_lds_dwordx4 v[222:223], off
	s_waitcnt vmcnt(8)
	s_waitcnt lgkmcnt(0)
	s_barrier
	s_setprio 1
	s_waitcnt lgkmcnt(0)
	v_mfma_f32_16x16x32_bf16 v[60:63], v[128:131], v[180:183], v[60:63]
	v_mfma_f32_16x16x32_bf16 v[60:63], v[132:135], v[194:197], v[60:63]
	v_mfma_f32_16x16x32_bf16 v[56:59], v[136:139], v[180:183], v[56:59]
	v_mfma_f32_16x16x32_bf16 v[56:59], v[140:143], v[194:197], v[56:59]
	v_mfma_f32_16x16x32_bf16 v[44:47], v[128:131], v[198:201], v[44:47]
	v_mfma_f32_16x16x32_bf16 v[44:47], v[132:135], v[202:205], v[44:47]
	v_mfma_f32_16x16x32_bf16 v[40:43], v[136:139], v[198:201], v[40:43]
	v_mfma_f32_16x16x32_bf16 v[40:43], v[140:143], v[202:205], v[40:43]
	v_mfma_f32_16x16x32_bf16 v[28:31], v[128:131], v[206:209], v[28:31]
	v_mfma_f32_16x16x32_bf16 v[28:31], v[132:135], v[210:213], v[28:31]
	v_mfma_f32_16x16x32_bf16 v[24:27], v[136:139], v[206:209], v[24:27]
	v_mfma_f32_16x16x32_bf16 v[24:27], v[140:143], v[210:213], v[24:27]
	v_mfma_f32_16x16x32_bf16 v[12:15], v[128:131], v[214:217], v[12:15]
	v_mfma_f32_16x16x32_bf16 v[12:15], v[132:135], v[218:221], v[12:15]
	v_mfma_f32_16x16x32_bf16 v[8:11], v[136:139], v[214:217], v[8:11]
	v_mfma_f32_16x16x32_bf16 v[8:11], v[140:143], v[218:221], v[8:11]
	s_setprio 0
	s_setprio 1
	v_mfma_f32_16x16x32_bf16 v[52:55], v[144:147], v[180:183], v[52:55]
	v_mfma_f32_16x16x32_bf16 v[52:55], v[148:151], v[194:197], v[52:55]
	v_mfma_f32_16x16x32_bf16 v[48:51], v[172:175], v[180:183], v[48:51]
	v_mfma_f32_16x16x32_bf16 v[48:51], v[176:179], v[194:197], v[48:51]
	v_mfma_f32_16x16x32_bf16 v[36:39], v[144:147], v[198:201], v[36:39]
	v_mfma_f32_16x16x32_bf16 v[36:39], v[148:151], v[202:205], v[36:39]
	v_mfma_f32_16x16x32_bf16 v[32:35], v[172:175], v[198:201], v[32:35]
	v_mfma_f32_16x16x32_bf16 v[32:35], v[176:179], v[202:205], v[32:35]
	v_mfma_f32_16x16x32_bf16 v[20:23], v[144:147], v[206:209], v[20:23]
	v_mfma_f32_16x16x32_bf16 v[20:23], v[148:151], v[210:213], v[20:23]
	v_mfma_f32_16x16x32_bf16 v[16:19], v[172:175], v[206:209], v[16:19]
	v_mfma_f32_16x16x32_bf16 v[16:19], v[176:179], v[210:213], v[16:19]
	v_mfma_f32_16x16x32_bf16 v[4:7], v[144:147], v[214:217], v[4:7]
	v_mfma_f32_16x16x32_bf16 v[4:7], v[148:151], v[218:221], v[4:7]
	v_mfma_f32_16x16x32_bf16 v[0:3], v[172:175], v[214:217], v[0:3]
	v_mfma_f32_16x16x32_bf16 v[0:3], v[176:179], v[218:221], v[0:3]
	s_setprio 0
	s_barrier
	s_add_i32 s83, s83, 2
	s_add_u32 s81, s81, 0x100
	s_addc_u32 s82, s82, 0
	s_cmp_gt_u32 s83, 41
	s_mov_b64 s[54:55], s[56:57]
.LBB0_159:
	ds_read_b128 v[128:131], v189
	v_xor_b32_e32 v253, 64, v189
	ds_read_b128 v[132:135], v253
	ds_read_b128 v[136:139], v189 offset:2048
	ds_read_b128 v[140:143], v253 offset:2048
	ds_read_b128 v[144:147], v190
	v_xor_b32_e32 v253, 64, v190
	ds_read_b128 v[148:151], v253
	ds_read_b128 v[172:175], v190 offset:2048
	ds_read_b128 v[176:179], v253 offset:2048
	s_add_u32 s56, s54, 0x100
	s_addc_u32 s57, s55, 0
	s_cmp_eq_u32 s83, 40
	s_cselect_b32 s61, s15, s57
	s_cselect_b32 s60, s14, s56
	s_cselect_b32 s59, s53, s82
	s_cselect_b32 s58, s52, s81
	v_lshl_add_u64 v[222:223], s[54:55], 0, v[166:167]
	s_add_i32 m0, s66, 0xc000
	ds_read_b128 v[180:183], v191
	v_xor_b32_e32 v253, 64, v191
	ds_read_b128 v[194:197], v253
	ds_read_b128 v[198:201], v191 offset:2048
	ds_read_b128 v[202:205], v253 offset:2048
	ds_read_b128 v[206:209], v191 offset:4096
	ds_read_b128 v[210:213], v253 offset:4096
	ds_read_b128 v[214:217], v191 offset:6144
	ds_read_b128 v[218:221], v253 offset:6144
	global_load_lds_dwordx4 v[222:223], off
	v_lshl_add_u64 v[222:223], s[54:55], 0, v[164:165]
	s_add_i32 m0, s66, 0xe000
	s_nop 0
	global_load_lds_dwordx4 v[222:223], off
	s_waitcnt vmcnt(8)
	s_waitcnt lgkmcnt(0)
	s_barrier
	s_setprio 1
	s_waitcnt lgkmcnt(0)
	v_mfma_f32_16x16x32_bf16 v[124:127], v[128:131], v[180:183], v[124:127]
	v_mfma_f32_16x16x32_bf16 v[124:127], v[132:135], v[194:197], v[124:127]
	v_mfma_f32_16x16x32_bf16 v[120:123], v[136:139], v[180:183], v[120:123]
	v_mfma_f32_16x16x32_bf16 v[120:123], v[140:143], v[194:197], v[120:123]
	v_mfma_f32_16x16x32_bf16 v[108:111], v[128:131], v[198:201], v[108:111]
	v_mfma_f32_16x16x32_bf16 v[108:111], v[132:135], v[202:205], v[108:111]
	v_mfma_f32_16x16x32_bf16 v[104:107], v[136:139], v[198:201], v[104:107]
	v_mfma_f32_16x16x32_bf16 v[104:107], v[140:143], v[202:205], v[104:107]
	v_mfma_f32_16x16x32_bf16 v[92:95], v[128:131], v[206:209], v[92:95]
	v_mfma_f32_16x16x32_bf16 v[92:95], v[132:135], v[210:213], v[92:95]
	v_mfma_f32_16x16x32_bf16 v[88:91], v[136:139], v[206:209], v[88:91]
	v_mfma_f32_16x16x32_bf16 v[88:91], v[140:143], v[210:213], v[88:91]
	v_mfma_f32_16x16x32_bf16 v[76:79], v[128:131], v[214:217], v[76:79]
	v_mfma_f32_16x16x32_bf16 v[76:79], v[132:135], v[218:221], v[76:79]
	v_mfma_f32_16x16x32_bf16 v[72:75], v[136:139], v[214:217], v[72:75]
	v_mfma_f32_16x16x32_bf16 v[72:75], v[140:143], v[218:221], v[72:75]
	s_setprio 0
	s_setprio 1
	v_mfma_f32_16x16x32_bf16 v[116:119], v[144:147], v[180:183], v[116:119]
	v_mfma_f32_16x16x32_bf16 v[116:119], v[148:151], v[194:197], v[116:119]
	v_mfma_f32_16x16x32_bf16 v[112:115], v[172:175], v[180:183], v[112:115]
	v_mfma_f32_16x16x32_bf16 v[112:115], v[176:179], v[194:197], v[112:115]
	v_mfma_f32_16x16x32_bf16 v[100:103], v[144:147], v[198:201], v[100:103]
	v_mfma_f32_16x16x32_bf16 v[100:103], v[148:151], v[202:205], v[100:103]
	v_mfma_f32_16x16x32_bf16 v[96:99], v[172:175], v[198:201], v[96:99]
	v_mfma_f32_16x16x32_bf16 v[96:99], v[176:179], v[202:205], v[96:99]
	v_mfma_f32_16x16x32_bf16 v[84:87], v[144:147], v[206:209], v[84:87]
	v_mfma_f32_16x16x32_bf16 v[84:87], v[148:151], v[210:213], v[84:87]
	v_mfma_f32_16x16x32_bf16 v[80:83], v[172:175], v[206:209], v[80:83]
	v_mfma_f32_16x16x32_bf16 v[80:83], v[176:179], v[210:213], v[80:83]
	v_mfma_f32_16x16x32_bf16 v[68:71], v[144:147], v[214:217], v[68:71]
	v_mfma_f32_16x16x32_bf16 v[68:71], v[148:151], v[218:221], v[68:71]
	v_mfma_f32_16x16x32_bf16 v[64:67], v[172:175], v[214:217], v[64:67]
	v_mfma_f32_16x16x32_bf16 v[64:67], v[176:179], v[218:221], v[64:67]
	s_setprio 0
	s_barrier
	s_add_i32 s54, s77, s65
	v_lshl_add_u64 v[222:223], s[58:59], 0, v[154:155]
	s_mov_b32 m0, s54
	ds_read_b128 v[180:183], v191 offset:16384
	v_xor_b32_e32 v253, 64, v191
	ds_read_b128 v[194:197], v253 offset:16384
	ds_read_b128 v[198:201], v191 offset:18432
	ds_read_b128 v[202:205], v253 offset:18432
	ds_read_b128 v[206:209], v191 offset:20480
	ds_read_b128 v[210:213], v253 offset:20480
	ds_read_b128 v[214:217], v191 offset:22528
	ds_read_b128 v[218:221], v253 offset:22528
	global_load_lds_dwordx4 v[222:223], off
	s_add_i32 m0, s54, 0x2000
	s_add_u32 s54, s58, 0xb0000
	v_lshl_add_u64 v[224:225], s[58:59], 0, v[162:163]
	s_addc_u32 s55, s59, 0
	s_add_i32 s84, s78, s65
	global_load_lds_dwordx4 v[224:225], off
	v_lshl_add_u64 v[226:227], s[54:55], 0, v[154:155]
	s_mov_b32 m0, s84
	v_lshl_add_u64 v[228:229], s[60:61], 0, v[160:161]
	global_load_lds_dwordx4 v[226:227], off
	v_lshl_add_u64 v[226:227], s[54:55], 0, v[162:163]
	s_add_i32 m0, s84, 0x2000
	s_nop 0
	global_load_lds_dwordx4 v[226:227], off
	v_lshl_add_u64 v[226:227], s[60:61], 0, v[152:153]
	s_mov_b32 m0, s66
	s_nop 0
	global_load_lds_dwordx4 v[226:227], off
	s_mov_b32 m0, s67
	s_nop 0
	global_load_lds_dwordx4 v[228:229], off
	s_waitcnt vmcnt(8)
	s_waitcnt lgkmcnt(0)
	s_barrier
	s_setprio 1
	s_waitcnt lgkmcnt(0)
	v_mfma_f32_16x16x32_bf16 v[60:63], v[128:131], v[180:183], v[60:63]
	v_mfma_f32_16x16x32_bf16 v[60:63], v[132:135], v[194:197], v[60:63]
	v_mfma_f32_16x16x32_bf16 v[56:59], v[136:139], v[180:183], v[56:59]
	v_mfma_f32_16x16x32_bf16 v[56:59], v[140:143], v[194:197], v[56:59]
	v_mfma_f32_16x16x32_bf16 v[44:47], v[128:131], v[198:201], v[44:47]
	v_mfma_f32_16x16x32_bf16 v[44:47], v[132:135], v[202:205], v[44:47]
	v_mfma_f32_16x16x32_bf16 v[40:43], v[136:139], v[198:201], v[40:43]
	v_mfma_f32_16x16x32_bf16 v[40:43], v[140:143], v[202:205], v[40:43]
	v_mfma_f32_16x16x32_bf16 v[28:31], v[128:131], v[206:209], v[28:31]
	v_mfma_f32_16x16x32_bf16 v[28:31], v[132:135], v[210:213], v[28:31]
	v_mfma_f32_16x16x32_bf16 v[24:27], v[136:139], v[206:209], v[24:27]
	v_mfma_f32_16x16x32_bf16 v[24:27], v[140:143], v[210:213], v[24:27]
	v_mfma_f32_16x16x32_bf16 v[12:15], v[128:131], v[214:217], v[12:15]
	v_mfma_f32_16x16x32_bf16 v[12:15], v[132:135], v[218:221], v[12:15]
	v_mfma_f32_16x16x32_bf16 v[8:11], v[136:139], v[214:217], v[8:11]
	v_mfma_f32_16x16x32_bf16 v[8:11], v[140:143], v[218:221], v[8:11]
	s_setprio 0
	s_setprio 1
	v_mfma_f32_16x16x32_bf16 v[52:55], v[144:147], v[180:183], v[52:55]
	v_mfma_f32_16x16x32_bf16 v[52:55], v[148:151], v[194:197], v[52:55]
	v_mfma_f32_16x16x32_bf16 v[48:51], v[172:175], v[180:183], v[48:51]
	v_mfma_f32_16x16x32_bf16 v[48:51], v[176:179], v[194:197], v[48:51]
	v_mfma_f32_16x16x32_bf16 v[36:39], v[144:147], v[198:201], v[36:39]
	v_mfma_f32_16x16x32_bf16 v[36:39], v[148:151], v[202:205], v[36:39]
	v_mfma_f32_16x16x32_bf16 v[32:35], v[172:175], v[198:201], v[32:35]
	v_mfma_f32_16x16x32_bf16 v[32:35], v[176:179], v[202:205], v[32:35]
	v_mfma_f32_16x16x32_bf16 v[20:23], v[144:147], v[206:209], v[20:23]
	v_mfma_f32_16x16x32_bf16 v[20:23], v[148:151], v[210:213], v[20:23]
	v_mfma_f32_16x16x32_bf16 v[16:19], v[172:175], v[206:209], v[16:19]
	v_mfma_f32_16x16x32_bf16 v[16:19], v[176:179], v[210:213], v[16:19]
	v_mfma_f32_16x16x32_bf16 v[4:7], v[144:147], v[214:217], v[4:7]
	v_mfma_f32_16x16x32_bf16 v[4:7], v[148:151], v[218:221], v[4:7]
	v_mfma_f32_16x16x32_bf16 v[0:3], v[172:175], v[214:217], v[0:3]
	v_mfma_f32_16x16x32_bf16 v[0:3], v[176:179], v[218:221], v[0:3]
	s_setprio 0
	s_barrier
	s_add_i32 s84, 0, 0x18000
	s_add_i32 s85, 0, 0x1c000
	v_add_u32_e32 v140, s84, v186
	v_add_u32_e32 v176, s85, v186
	ds_read_b128 v[128:131], v140
	v_xor_b32_e32 v253, 64, v140
	ds_read_b128 v[132:135], v253
	ds_read_b128 v[136:139], v140 offset:2048
	ds_read_b128 v[140:143], v253 offset:2048
	ds_read_b128 v[144:147], v176
	v_xor_b32_e32 v253, 64, v176
	ds_read_b128 v[148:151], v253
	ds_read_b128 v[172:175], v176 offset:2048
	ds_read_b128 v[176:179], v253 offset:2048
	s_add_u32 s54, s60, 0xb0000
	s_addc_u32 s55, s61, 0
	s_mov_b32 m0, s68
	v_lshl_add_u64 v[230:231], s[54:55], 0, v[152:153]
	ds_read_b128 v[180:183], v191 offset:32768
	v_xor_b32_e32 v253, 64, v191
	ds_read_b128 v[194:197], v253 offset:32768
	ds_read_b128 v[198:201], v191 offset:34816
	ds_read_b128 v[202:205], v253 offset:34816
	ds_read_b128 v[206:209], v191 offset:36864
	ds_read_b128 v[210:213], v253 offset:36864
	ds_read_b128 v[214:217], v191 offset:38912
	ds_read_b128 v[218:221], v253 offset:38912
	global_load_lds_dwordx4 v[230:231], off
	v_lshl_add_u64 v[230:231], s[54:55], 0, v[160:161]
	s_mov_b32 m0, s69
	s_nop 0
	global_load_lds_dwordx4 v[230:231], off
	s_waitcnt vmcnt(8)
	s_waitcnt lgkmcnt(0)
	s_barrier
	s_setprio 1
	s_waitcnt lgkmcnt(0)
	v_mfma_f32_16x16x32_bf16 v[124:127], v[128:131], v[180:183], v[124:127]
	v_mfma_f32_16x16x32_bf16 v[124:127], v[132:135], v[194:197], v[124:127]
	v_mfma_f32_16x16x32_bf16 v[120:123], v[136:139], v[180:183], v[120:123]
	v_mfma_f32_16x16x32_bf16 v[120:123], v[140:143], v[194:197], v[120:123]
	v_mfma_f32_16x16x32_bf16 v[108:111], v[128:131], v[198:201], v[108:111]
	v_mfma_f32_16x16x32_bf16 v[108:111], v[132:135], v[202:205], v[108:111]
	v_mfma_f32_16x16x32_bf16 v[104:107], v[136:139], v[198:201], v[104:107]
	v_mfma_f32_16x16x32_bf16 v[104:107], v[140:143], v[202:205], v[104:107]
	v_mfma_f32_16x16x32_bf16 v[92:95], v[128:131], v[206:209], v[92:95]
	v_mfma_f32_16x16x32_bf16 v[92:95], v[132:135], v[210:213], v[92:95]
	v_mfma_f32_16x16x32_bf16 v[88:91], v[136:139], v[206:209], v[88:91]
	v_mfma_f32_16x16x32_bf16 v[88:91], v[140:143], v[210:213], v[88:91]
	v_mfma_f32_16x16x32_bf16 v[76:79], v[128:131], v[214:217], v[76:79]
	v_mfma_f32_16x16x32_bf16 v[76:79], v[132:135], v[218:221], v[76:79]
	v_mfma_f32_16x16x32_bf16 v[72:75], v[136:139], v[214:217], v[72:75]
	v_mfma_f32_16x16x32_bf16 v[72:75], v[140:143], v[218:221], v[72:75]
	s_setprio 0
	s_setprio 1
	v_mfma_f32_16x16x32_bf16 v[116:119], v[144:147], v[180:183], v[116:119]
	v_mfma_f32_16x16x32_bf16 v[116:119], v[148:151], v[194:197], v[116:119]
	v_mfma_f32_16x16x32_bf16 v[112:115], v[172:175], v[180:183], v[112:115]
	v_mfma_f32_16x16x32_bf16 v[112:115], v[176:179], v[194:197], v[112:115]
	v_mfma_f32_16x16x32_bf16 v[100:103], v[144:147], v[198:201], v[100:103]
	v_mfma_f32_16x16x32_bf16 v[100:103], v[148:151], v[202:205], v[100:103]
	v_mfma_f32_16x16x32_bf16 v[96:99], v[172:175], v[198:201], v[96:99]
	v_mfma_f32_16x16x32_bf16 v[96:99], v[176:179], v[202:205], v[96:99]
	v_mfma_f32_16x16x32_bf16 v[84:87], v[144:147], v[206:209], v[84:87]
	v_mfma_f32_16x16x32_bf16 v[84:87], v[148:151], v[210:213], v[84:87]
	v_mfma_f32_16x16x32_bf16 v[80:83], v[172:175], v[206:209], v[80:83]
	v_mfma_f32_16x16x32_bf16 v[80:83], v[176:179], v[210:213], v[80:83]
	v_mfma_f32_16x16x32_bf16 v[68:71], v[144:147], v[214:217], v[68:71]
	v_mfma_f32_16x16x32_bf16 v[68:71], v[148:151], v[218:221], v[68:71]
	v_mfma_f32_16x16x32_bf16 v[64:67], v[172:175], v[214:217], v[64:67]
	v_mfma_f32_16x16x32_bf16 v[64:67], v[176:179], v[218:221], v[64:67]
	s_setprio 0
	s_barrier
	s_add_i32 s54, s84, s65
	v_lshl_add_u64 v[222:223], v[222:223], 0, s[28:29]
	s_mov_b32 m0, s54
	ds_read_b128 v[180:183], v191 offset:49152
	v_xor_b32_e32 v253, 64, v191
	ds_read_b128 v[194:197], v253 offset:49152
	ds_read_b128 v[198:201], v191 offset:51200
	ds_read_b128 v[202:205], v253 offset:51200
	ds_read_b128 v[206:209], v191 offset:53248
	ds_read_b128 v[210:213], v253 offset:53248
	ds_read_b128 v[214:217], v191 offset:55296
	ds_read_b128 v[218:221], v253 offset:55296
	global_load_lds_dwordx4 v[222:223], off
	s_add_i32 m0, s54, 0x2000
	s_add_u32 s54, s58, 0xb0080
	v_lshl_add_u64 v[222:223], v[224:225], 0, s[28:29]
	s_addc_u32 s55, s59, 0
	s_add_i32 s58, s85, s65
	global_load_lds_dwordx4 v[222:223], off
	v_lshl_add_u64 v[222:223], s[54:55], 0, v[154:155]
	s_mov_b32 m0, s58
	s_nop 0
	global_load_lds_dwordx4 v[222:223], off
	v_lshl_add_u64 v[222:223], s[54:55], 0, v[162:163]
	s_add_i32 m0, s58, 0x2000
	s_nop 0
	global_load_lds_dwordx4 v[222:223], off
	v_lshl_add_u64 v[222:223], v[226:227], 0, s[28:29]
	s_mov_b32 m0, s3
	s_nop 0
	global_load_lds_dwordx4 v[222:223], off
	v_lshl_add_u64 v[222:223], v[228:229], 0, s[28:29]
	s_mov_b32 m0, s71
	s_nop 0
	global_load_lds_dwordx4 v[222:223], off
	s_waitcnt vmcnt(8)
	s_waitcnt lgkmcnt(0)
	s_barrier
	s_setprio 1
	s_waitcnt lgkmcnt(0)
	v_mfma_f32_16x16x32_bf16 v[60:63], v[128:131], v[180:183], v[60:63]
	v_mfma_f32_16x16x32_bf16 v[60:63], v[132:135], v[194:197], v[60:63]
	v_mfma_f32_16x16x32_bf16 v[56:59], v[136:139], v[180:183], v[56:59]
	v_mfma_f32_16x16x32_bf16 v[56:59], v[140:143], v[194:197], v[56:59]
	v_mfma_f32_16x16x32_bf16 v[44:47], v[128:131], v[198:201], v[44:47]
	v_mfma_f32_16x16x32_bf16 v[44:47], v[132:135], v[202:205], v[44:47]
	v_mfma_f32_16x16x32_bf16 v[40:43], v[136:139], v[198:201], v[40:43]
	v_mfma_f32_16x16x32_bf16 v[40:43], v[140:143], v[202:205], v[40:43]
	v_mfma_f32_16x16x32_bf16 v[28:31], v[128:131], v[206:209], v[28:31]
	v_mfma_f32_16x16x32_bf16 v[28:31], v[132:135], v[210:213], v[28:31]
	v_mfma_f32_16x16x32_bf16 v[24:27], v[136:139], v[206:209], v[24:27]
	v_mfma_f32_16x16x32_bf16 v[24:27], v[140:143], v[210:213], v[24:27]
	v_mfma_f32_16x16x32_bf16 v[12:15], v[128:131], v[214:217], v[12:15]
	v_mfma_f32_16x16x32_bf16 v[12:15], v[132:135], v[218:221], v[12:15]
	v_mfma_f32_16x16x32_bf16 v[8:11], v[136:139], v[214:217], v[8:11]
	v_mfma_f32_16x16x32_bf16 v[8:11], v[140:143], v[218:221], v[8:11]
	s_setprio 0
	s_setprio 1
	v_mfma_f32_16x16x32_bf16 v[52:55], v[144:147], v[180:183], v[52:55]
	v_mfma_f32_16x16x32_bf16 v[52:55], v[148:151], v[194:197], v[52:55]
	v_mfma_f32_16x16x32_bf16 v[48:51], v[172:175], v[180:183], v[48:51]
	v_mfma_f32_16x16x32_bf16 v[48:51], v[176:179], v[194:197], v[48:51]
	v_mfma_f32_16x16x32_bf16 v[36:39], v[144:147], v[198:201], v[36:39]
	v_mfma_f32_16x16x32_bf16 v[36:39], v[148:151], v[202:205], v[36:39]
	v_mfma_f32_16x16x32_bf16 v[32:35], v[172:175], v[198:201], v[32:35]
	v_mfma_f32_16x16x32_bf16 v[32:35], v[176:179], v[202:205], v[32:35]
	v_mfma_f32_16x16x32_bf16 v[20:23], v[144:147], v[206:209], v[20:23]
	v_mfma_f32_16x16x32_bf16 v[20:23], v[148:151], v[210:213], v[20:23]
	v_mfma_f32_16x16x32_bf16 v[16:19], v[172:175], v[206:209], v[16:19]
	v_mfma_f32_16x16x32_bf16 v[16:19], v[176:179], v[210:213], v[16:19]
	v_mfma_f32_16x16x32_bf16 v[4:7], v[144:147], v[214:217], v[4:7]
	v_mfma_f32_16x16x32_bf16 v[4:7], v[148:151], v[218:221], v[4:7]
	v_mfma_f32_16x16x32_bf16 v[0:3], v[172:175], v[214:217], v[0:3]
	v_mfma_f32_16x16x32_bf16 v[0:3], v[176:179], v[218:221], v[0:3]
	s_setprio 0
	s_barrier
	s_add_i32 s83, s83, 2
	s_add_u32 s81, s81, 0x100
	s_addc_u32 s82, s82, 0
	s_cmp_gt_u32 s83, 41
	s_mov_b64 s[54:55], s[56:57]
	s_cbranch_scc0 .LBB0_159
	s_and_b64 vcc, exec, s[30:31]
	s_cbranch_vccz .LBB0_162
	s_barrier

.LBB0_254:
	s_ashr_i32 s61, s60, 31
	s_lshl_b64 s[62:63], s[60:61], 19
	s_add_u32 s62, s35, s62
	s_addc_u32 s63, s47, s63
	s_and_b64 s[64:65], s[12:13], exec
	s_cselect_b32 s3, s63, s69
	s_cselect_b32 s61, s62, s68
	s_ashr_i32 s59, s58, 31
	s_lshl_b64 s[64:65], s[58:59], 19
	s_add_u32 s64, s49, s64
	s_addc_u32 s65, s70, s65
	s_and_b64 s[92:93], s[12:13], exec
	s_cselect_b32 s91, s65, s67
	s_cselect_b32 s92, s64, s66
	s_lshl_b32 s59, s14, 8
	v_add_u32_e32 v0, s59, v182
	s_add_u32 s93, s66, 0x100
	s_waitcnt lgkmcnt(0)
	v_ashrrev_i32_e32 v1, 31, v0
	s_addc_u32 s94, s67, 0
	v_lshl_add_u64 v[72:73], v[0:1], 4, s[26:27]
	s_add_u32 s14, s68, 0x40080
	s_addc_u32 s15, s69, 0
	s_mov_b32 s95, -2
	s_mov_b64 s[66:67], 0
	s_cmp_eq_u32 s90, 1
	s_cbranch_scc1 .Lfa_2
	v_add_u32_e32 v74, s83, v181
	ds_read_b128 v[88:91], v74
	v_xor_b32_e32 v253, 64, v74
	ds_read_b128 v[108:111], v253
	ds_read_b128 v[128:131], v74 offset:2048
	ds_read_b128 v[144:147], v253 offset:2048
	v_add_u32_e32 v74, s84, v181
	ds_read_b128 v[148:151], v74
	v_xor_b32_e32 v253, 64, v74
	ds_read_b128 v[152:155], v253
	ds_read_b128 v[176:179], v74 offset:2048
	ds_read_b128 v[190:193], v253 offset:2048
	s_add_u32 s68, s14, 0xfffc0080
	s_addc_u32 s69, s15, -1
	s_and_b64 s[66:67], s[66:67], exec
	s_cselect_b32 s69, s3, s69
	s_cselect_b32 s68, s61, s68
	s_cselect_b32 s67, s91, s94
	s_cselect_b32 s66, s92, s93
	v_lshl_add_u64 v[74:75], s[14:15], 0, v[170:171]
	s_add_i32 m0, s74, 0xc000
	ds_read_b128 v[194:197], v187
	v_xor_b32_e32 v253, 64, v187
	ds_read_b128 v[198:201], v253
	ds_read_b128 v[202:205], v187 offset:2048
	ds_read_b128 v[206:209], v253 offset:2048
	ds_read_b128 v[210:213], v187 offset:4096
	ds_read_b128 v[214:217], v253 offset:4096
	ds_read_b128 v[218:221], v187 offset:6144
	ds_read_b128 v[222:225], v253 offset:6144
	global_load_lds_dwordx4 v[74:75], off
	v_lshl_add_u64 v[74:75], s[14:15], 0, v[168:169]
	s_add_i32 m0, s74, 0xe000
	s_nop 0
	global_load_lds_dwordx4 v[74:75], off
	s_waitcnt vmcnt(24)
	s_waitcnt lgkmcnt(0)
	s_barrier
	s_setprio 1
	s_waitcnt lgkmcnt(0)
	v_mfma_f32_16x16x32_bf16 v[140:143], v[88:91], v[194:197], 0
	v_mfma_f32_16x16x32_bf16 v[136:139], v[128:131], v[194:197], 0
	v_mfma_f32_16x16x32_bf16 v[120:123], v[88:91], v[202:205], 0
	v_mfma_f32_16x16x32_bf16 v[116:119], v[128:131], v[202:205], 0
	v_mfma_f32_16x16x32_bf16 v[100:103], v[88:91], v[210:213], 0
	v_mfma_f32_16x16x32_bf16 v[96:99], v[128:131], v[210:213], 0
	v_mfma_f32_16x16x32_bf16 v[80:83], v[88:91], v[218:221], 0
	v_mfma_f32_16x16x32_bf16 v[74:77], v[128:131], v[218:221], 0
	v_mfma_f32_16x16x32_bf16 v[140:143], v[108:111], v[198:201], v[140:143]
	v_mfma_f32_16x16x32_bf16 v[136:139], v[144:147], v[198:201], v[136:139]
	v_mfma_f32_16x16x32_bf16 v[120:123], v[108:111], v[206:209], v[120:123]
	v_mfma_f32_16x16x32_bf16 v[116:119], v[144:147], v[206:209], v[116:119]
	v_mfma_f32_16x16x32_bf16 v[100:103], v[108:111], v[214:217], v[100:103]
	v_mfma_f32_16x16x32_bf16 v[96:99], v[144:147], v[214:217], v[96:99]
	v_mfma_f32_16x16x32_bf16 v[80:83], v[108:111], v[222:225], v[80:83]
	v_mfma_f32_16x16x32_bf16 v[74:77], v[144:147], v[222:225], v[74:77]
	s_setprio 0
	s_setprio 1
	v_mfma_f32_16x16x32_bf16 v[132:135], v[148:151], v[194:197], 0
	v_mfma_f32_16x16x32_bf16 v[124:127], v[176:179], v[194:197], 0
	v_mfma_f32_16x16x32_bf16 v[112:115], v[148:151], v[202:205], 0
	v_mfma_f32_16x16x32_bf16 v[104:107], v[176:179], v[202:205], 0
	v_mfma_f32_16x16x32_bf16 v[92:95], v[148:151], v[210:213], 0
	v_mfma_f32_16x16x32_bf16 v[84:87], v[176:179], v[210:213], 0
	v_mfma_f32_16x16x32_bf16 v[68:71], v[148:151], v[218:221], 0
	v_mfma_f32_16x16x32_bf16 v[64:67], v[176:179], v[218:221], 0
	v_mfma_f32_16x16x32_bf16 v[132:135], v[152:155], v[198:201], v[132:135]
	v_mfma_f32_16x16x32_bf16 v[124:127], v[190:193], v[198:201], v[124:127]
	v_mfma_f32_16x16x32_bf16 v[112:115], v[152:155], v[206:209], v[112:115]
	v_mfma_f32_16x16x32_bf16 v[104:107], v[190:193], v[206:209], v[104:107]
	v_mfma_f32_16x16x32_bf16 v[92:95], v[152:155], v[214:217], v[92:95]
	v_mfma_f32_16x16x32_bf16 v[84:87], v[190:193], v[214:217], v[84:87]
	v_mfma_f32_16x16x32_bf16 v[68:71], v[152:155], v[222:225], v[68:71]
	v_mfma_f32_16x16x32_bf16 v[64:67], v[190:193], v[222:225], v[64:67]
	s_setprio 0
	s_barrier
	s_add_i32 s96, s83, s71
	v_lshl_add_u64 v[226:227], s[66:67], 0, v[162:163]
	s_mov_b32 m0, s96
	ds_read_b128 v[194:197], v187 offset:16384
	v_xor_b32_e32 v253, 64, v187
	ds_read_b128 v[198:201], v253 offset:16384
	ds_read_b128 v[202:205], v187 offset:18432
	ds_read_b128 v[206:209], v253 offset:18432
	ds_read_b128 v[210:213], v187 offset:20480
	ds_read_b128 v[214:217], v253 offset:20480
	ds_read_b128 v[218:221], v187 offset:22528
	ds_read_b128 v[222:225], v253 offset:22528
	global_load_lds_dwordx4 v[226:227], off
	s_add_i32 m0, s96, 0x2000
	s_add_u32 s96, s66, 0x40000
	v_lshl_add_u64 v[228:229], s[66:67], 0, v[166:167]
	s_addc_u32 s97, s67, 0
	s_add_i32 vcc_lo, s84, s71
	global_load_lds_dwordx4 v[228:229], off
	v_lshl_add_u64 v[78:79], s[96:97], 0, v[162:163]
	s_mov_b32 m0, vcc_lo
	v_lshl_add_u64 v[230:231], s[68:69], 0, v[160:161]
	global_load_lds_dwordx4 v[78:79], off
	v_lshl_add_u64 v[78:79], s[96:97], 0, v[166:167]
	s_add_i32 m0, vcc_lo, 0x2000
	v_lshl_add_u64 v[232:233], s[68:69], 0, v[164:165]
	global_load_lds_dwordx4 v[78:79], off
	s_mov_b32 m0, s74
	s_nop 0
	global_load_lds_dwordx4 v[230:231], off
	s_mov_b32 m0, s75
	s_nop 0
	global_load_lds_dwordx4 v[232:233], off
	s_waitcnt vmcnt(24)
	s_waitcnt lgkmcnt(0)
	s_barrier
	s_setprio 1
	s_waitcnt lgkmcnt(0)
	v_mfma_f32_16x16x32_bf16 v[60:63], v[88:91], v[194:197], 0
	v_mfma_f32_16x16x32_bf16 v[56:59], v[128:131], v[194:197], 0
	v_mfma_f32_16x16x32_bf16 v[44:47], v[88:91], v[202:205], 0
	v_mfma_f32_16x16x32_bf16 v[40:43], v[128:131], v[202:205], 0
	v_mfma_f32_16x16x32_bf16 v[28:31], v[88:91], v[210:213], 0
	v_mfma_f32_16x16x32_bf16 v[24:27], v[128:131], v[210:213], 0
	v_mfma_f32_16x16x32_bf16 v[12:15], v[88:91], v[218:221], 0
	v_mfma_f32_16x16x32_bf16 v[8:11], v[128:131], v[218:221], 0
	v_mfma_f32_16x16x32_bf16 v[60:63], v[108:111], v[198:201], v[60:63]
	v_mfma_f32_16x16x32_bf16 v[56:59], v[144:147], v[198:201], v[56:59]
	v_mfma_f32_16x16x32_bf16 v[44:47], v[108:111], v[206:209], v[44:47]
	v_mfma_f32_16x16x32_bf16 v[40:43], v[144:147], v[206:209], v[40:43]
	v_mfma_f32_16x16x32_bf16 v[28:31], v[108:111], v[214:217], v[28:31]
	v_mfma_f32_16x16x32_bf16 v[24:27], v[144:147], v[214:217], v[24:27]
	v_mfma_f32_16x16x32_bf16 v[12:15], v[108:111], v[222:225], v[12:15]
	v_mfma_f32_16x16x32_bf16 v[8:11], v[144:147], v[222:225], v[8:11]
	s_setprio 0
	s_setprio 1
	v_mfma_f32_16x16x32_bf16 v[52:55], v[148:151], v[194:197], 0
	v_mfma_f32_16x16x32_bf16 v[48:51], v[176:179], v[194:197], 0
	v_mfma_f32_16x16x32_bf16 v[36:39], v[148:151], v[202:205], 0
	v_mfma_f32_16x16x32_bf16 v[32:35], v[176:179], v[202:205], 0
	v_mfma_f32_16x16x32_bf16 v[20:23], v[148:151], v[210:213], 0
	v_mfma_f32_16x16x32_bf16 v[16:19], v[176:179], v[210:213], 0
	v_mfma_f32_16x16x32_bf16 v[4:7], v[148:151], v[218:221], 0
	v_mfma_f32_16x16x32_bf16 v[0:3], v[176:179], v[218:221], 0
	v_mfma_f32_16x16x32_bf16 v[52:55], v[152:155], v[198:201], v[52:55]
	v_mfma_f32_16x16x32_bf16 v[48:51], v[190:193], v[198:201], v[48:51]
	v_mfma_f32_16x16x32_bf16 v[36:39], v[152:155], v[206:209], v[36:39]
	v_mfma_f32_16x16x32_bf16 v[32:35], v[190:193], v[206:209], v[32:35]
	v_mfma_f32_16x16x32_bf16 v[20:23], v[152:155], v[214:217], v[20:23]
	v_mfma_f32_16x16x32_bf16 v[16:19], v[190:193], v[214:217], v[16:19]
	v_mfma_f32_16x16x32_bf16 v[4:7], v[152:155], v[222:225], v[4:7]
	v_mfma_f32_16x16x32_bf16 v[0:3], v[190:193], v[222:225], v[0:3]
	s_setprio 0
	s_barrier
	s_add_i32 s96, 0, 0x18000
	v_add_u32_e32 v78, s96, v181
	s_add_i32 s97, 0, 0x1c000
	ds_read_b128 v[88:91], v78
	v_xor_b32_e32 v253, 64, v78
	ds_read_b128 v[108:111], v253
	ds_read_b128 v[128:131], v78 offset:2048
	ds_read_b128 v[144:147], v253 offset:2048
	v_add_u32_e32 v78, s97, v181
	ds_read_b128 v[148:151], v78
	v_xor_b32_e32 v253, 64, v78
	ds_read_b128 v[152:155], v253
	ds_read_b128 v[176:179], v78 offset:2048
	ds_read_b128 v[190:193], v253 offset:2048
	s_add_u32 s68, s68, 0x40000
	s_addc_u32 s69, s69, 0
	s_mov_b32 m0, s76
	v_lshl_add_u64 v[78:79], s[68:69], 0, v[160:161]
	ds_read_b128 v[194:197], v187 offset:32768
	v_xor_b32_e32 v253, 64, v187
	ds_read_b128 v[198:201], v253 offset:32768
	ds_read_b128 v[202:205], v187 offset:34816
	ds_read_b128 v[206:209], v253 offset:34816
	ds_read_b128 v[210:213], v187 offset:36864
	ds_read_b128 v[214:217], v253 offset:36864
	ds_read_b128 v[218:221], v187 offset:38912
	ds_read_b128 v[222:225], v253 offset:38912
	global_load_lds_dwordx4 v[78:79], off
	v_lshl_add_u64 v[78:79], s[68:69], 0, v[164:165]
	s_mov_b32 m0, s77
	s_nop 0
	global_load_lds_dwordx4 v[78:79], off
	s_waitcnt vmcnt(8)
	s_waitcnt lgkmcnt(0)
	s_barrier
	s_setprio 1
	s_waitcnt lgkmcnt(0)
	v_mfma_f32_16x16x32_bf16 v[140:143], v[88:91], v[194:197], v[140:143]
	v_mfma_f32_16x16x32_bf16 v[136:139], v[128:131], v[194:197], v[136:139]
	v_mfma_f32_16x16x32_bf16 v[120:123], v[88:91], v[202:205], v[120:123]
	v_mfma_f32_16x16x32_bf16 v[116:119], v[128:131], v[202:205], v[116:119]
	v_mfma_f32_16x16x32_bf16 v[100:103], v[88:91], v[210:213], v[100:103]
	v_mfma_f32_16x16x32_bf16 v[96:99], v[128:131], v[210:213], v[96:99]
	v_mfma_f32_16x16x32_bf16 v[78:81], v[88:91], v[218:221], v[80:83]
	v_mfma_f32_16x16x32_bf16 v[74:77], v[128:131], v[218:221], v[74:77]
	v_mfma_f32_16x16x32_bf16 v[140:143], v[108:111], v[198:201], v[140:143]
	v_mfma_f32_16x16x32_bf16 v[136:139], v[144:147], v[198:201], v[136:139]
	v_mfma_f32_16x16x32_bf16 v[120:123], v[108:111], v[206:209], v[120:123]
	v_mfma_f32_16x16x32_bf16 v[116:119], v[144:147], v[206:209], v[116:119]
	v_mfma_f32_16x16x32_bf16 v[100:103], v[108:111], v[214:217], v[100:103]
	v_mfma_f32_16x16x32_bf16 v[96:99], v[144:147], v[214:217], v[96:99]
	v_mfma_f32_16x16x32_bf16 v[80:83], v[108:111], v[222:225], v[78:81]
	v_mfma_f32_16x16x32_bf16 v[76:79], v[144:147], v[222:225], v[74:77]
	s_setprio 0
	s_setprio 1
	v_mfma_f32_16x16x32_bf16 v[132:135], v[148:151], v[194:197], v[132:135]
	v_mfma_f32_16x16x32_bf16 v[132:135], v[152:155], v[198:201], v[132:135]
	v_mfma_f32_16x16x32_bf16 v[124:127], v[176:179], v[194:197], v[124:127]
	v_mfma_f32_16x16x32_bf16 v[124:127], v[190:193], v[198:201], v[124:127]
	v_mfma_f32_16x16x32_bf16 v[112:115], v[148:151], v[202:205], v[112:115]
	v_mfma_f32_16x16x32_bf16 v[112:115], v[152:155], v[206:209], v[112:115]
	v_mfma_f32_16x16x32_bf16 v[104:107], v[176:179], v[202:205], v[104:107]
	v_mfma_f32_16x16x32_bf16 v[104:107], v[190:193], v[206:209], v[104:107]
	v_mfma_f32_16x16x32_bf16 v[92:95], v[148:151], v[210:213], v[92:95]
	v_mfma_f32_16x16x32_bf16 v[92:95], v[152:155], v[214:217], v[92:95]
	v_mfma_f32_16x16x32_bf16 v[84:87], v[176:179], v[210:213], v[84:87]
	v_mfma_f32_16x16x32_bf16 v[84:87], v[190:193], v[214:217], v[84:87]
	v_mfma_f32_16x16x32_bf16 v[68:71], v[148:151], v[218:221], v[68:71]
	v_mfma_f32_16x16x32_bf16 v[68:71], v[152:155], v[222:225], v[68:71]
	v_mfma_f32_16x16x32_bf16 v[64:67], v[176:179], v[218:221], v[64:67]
	v_mfma_f32_16x16x32_bf16 v[64:67], v[190:193], v[222:225], v[64:67]
	s_setprio 0
	s_barrier
	s_add_i32 s68, s96, s71
	v_lshl_add_u64 v[74:75], v[226:227], 0, s[28:29]
	s_mov_b32 m0, s68
	ds_read_b128 v[194:197], v187 offset:49152
	v_xor_b32_e32 v253, 64, v187
	ds_read_b128 v[198:201], v253 offset:49152
	ds_read_b128 v[202:205], v187 offset:51200
	ds_read_b128 v[206:209], v253 offset:51200
	ds_read_b128 v[210:213], v187 offset:53248
	ds_read_b128 v[214:217], v253 offset:53248
	ds_read_b128 v[218:221], v187 offset:55296
	ds_read_b128 v[222:225], v253 offset:55296
	global_load_lds_dwordx4 v[74:75], off
	s_add_i32 m0, s68, 0x2000
	s_add_u32 s66, s66, 0x40080
	v_lshl_add_u64 v[74:75], v[228:229], 0, s[28:29]
	s_addc_u32 s67, s67, 0
	s_add_i32 s68, s97, s71
	global_load_lds_dwordx4 v[74:75], off
	v_lshl_add_u64 v[74:75], s[66:67], 0, v[162:163]
	s_mov_b32 m0, s68
	s_nop 0
	global_load_lds_dwordx4 v[74:75], off
	v_lshl_add_u64 v[74:75], s[66:67], 0, v[166:167]
	s_add_i32 m0, s68, 0x2000
	s_nop 0
	global_load_lds_dwordx4 v[74:75], off
	v_lshl_add_u64 v[74:75], v[230:231], 0, s[28:29]
	s_mov_b32 m0, s78
	s_nop 0
	global_load_lds_dwordx4 v[74:75], off
	v_lshl_add_u64 v[74:75], v[232:233], 0, s[28:29]
	s_mov_b32 m0, s79
	s_nop 0
	global_load_lds_dwordx4 v[74:75], off
	s_waitcnt vmcnt(8)
	s_waitcnt lgkmcnt(0)
	s_barrier
	s_setprio 1
	s_waitcnt lgkmcnt(0)
	v_mfma_f32_16x16x32_bf16 v[60:63], v[88:91], v[194:197], v[60:63]
	v_mfma_f32_16x16x32_bf16 v[60:63], v[108:111], v[198:201], v[60:63]
	v_mfma_f32_16x16x32_bf16 v[56:59], v[128:131], v[194:197], v[56:59]
	v_mfma_f32_16x16x32_bf16 v[56:59], v[144:147], v[198:201], v[56:59]
	v_mfma_f32_16x16x32_bf16 v[44:47], v[88:91], v[202:205], v[44:47]
	v_mfma_f32_16x16x32_bf16 v[44:47], v[108:111], v[206:209], v[44:47]
	v_mfma_f32_16x16x32_bf16 v[40:43], v[128:131], v[202:205], v[40:43]
	v_mfma_f32_16x16x32_bf16 v[40:43], v[144:147], v[206:209], v[40:43]
	v_mfma_f32_16x16x32_bf16 v[28:31], v[88:91], v[210:213], v[28:31]
	v_mfma_f32_16x16x32_bf16 v[28:31], v[108:111], v[214:217], v[28:31]
	v_mfma_f32_16x16x32_bf16 v[24:27], v[128:131], v[210:213], v[24:27]
	v_mfma_f32_16x16x32_bf16 v[24:27], v[144:147], v[214:217], v[24:27]
	v_mfma_f32_16x16x32_bf16 v[12:15], v[88:91], v[218:221], v[12:15]
	v_mfma_f32_16x16x32_bf16 v[12:15], v[108:111], v[222:225], v[12:15]
	v_mfma_f32_16x16x32_bf16 v[8:11], v[128:131], v[218:221], v[8:11]
	v_mfma_f32_16x16x32_bf16 v[8:11], v[144:147], v[222:225], v[8:11]
	s_setprio 0
	s_setprio 1
	v_mfma_f32_16x16x32_bf16 v[52:55], v[148:151], v[194:197], v[52:55]
	v_mfma_f32_16x16x32_bf16 v[52:55], v[152:155], v[198:201], v[52:55]
	v_mfma_f32_16x16x32_bf16 v[48:51], v[176:179], v[194:197], v[48:51]
	v_mfma_f32_16x16x32_bf16 v[48:51], v[190:193], v[198:201], v[48:51]
	v_mfma_f32_16x16x32_bf16 v[36:39], v[148:151], v[202:205], v[36:39]
	v_mfma_f32_16x16x32_bf16 v[36:39], v[152:155], v[206:209], v[36:39]
	v_mfma_f32_16x16x32_bf16 v[32:35], v[176:179], v[202:205], v[32:35]
	v_mfma_f32_16x16x32_bf16 v[32:35], v[190:193], v[206:209], v[32:35]
	v_mfma_f32_16x16x32_bf16 v[20:23], v[148:151], v[210:213], v[20:23]
	v_mfma_f32_16x16x32_bf16 v[20:23], v[152:155], v[214:217], v[20:23]
	v_mfma_f32_16x16x32_bf16 v[16:19], v[176:179], v[210:213], v[16:19]
	v_mfma_f32_16x16x32_bf16 v[16:19], v[190:193], v[214:217], v[16:19]
	v_mfma_f32_16x16x32_bf16 v[4:7], v[148:151], v[218:221], v[4:7]
	v_mfma_f32_16x16x32_bf16 v[4:7], v[152:155], v[222:225], v[4:7]
	v_mfma_f32_16x16x32_bf16 v[0:3], v[176:179], v[218:221], v[0:3]
	v_mfma_f32_16x16x32_bf16 v[0:3], v[190:193], v[222:225], v[0:3]
	s_setprio 0
	s_barrier
	s_add_i32 s95, s95, 2
	s_add_u32 s93, s93, 0x100
	s_addc_u32 s94, s94, 0
	s_add_u32 s14, s14, 0x100
	s_addc_u32 s15, s15, 0
	s_branch .LBB0_256
.Lfa_2:
	v_add_u32_e32 v74, s83, v181
	ds_read_b128 v[88:91], v74
	v_xor_b32_e32 v253, 64, v74
	ds_read_b128 v[108:111], v253
	ds_read_b128 v[128:131], v74 offset:2048
	ds_read_b128 v[144:147], v253 offset:2048
	v_add_u32_e32 v74, s84, v181
	ds_read_b128 v[148:151], v74
	v_xor_b32_e32 v253, 64, v74
	ds_read_b128 v[152:155], v253
	ds_read_b128 v[176:179], v74 offset:2048
	ds_read_b128 v[190:193], v253 offset:2048
	s_add_u32 s68, s14, 0xfffc0080
	s_addc_u32 s69, s15, -1
	s_and_b64 s[66:67], s[66:67], exec
	s_cselect_b32 s69, s3, s69
	s_cselect_b32 s68, s61, s68
	s_cselect_b32 s67, s91, s94
	s_cselect_b32 s66, s92, s93
	v_lshl_add_u64 v[74:75], s[14:15], 0, v[170:171]
	s_add_i32 m0, s74, 0xc000
	ds_read_b128 v[194:197], v187
	v_xor_b32_e32 v253, 64, v187
	ds_read_b128 v[198:201], v253
	ds_read_b128 v[202:205], v187 offset:2048
	ds_read_b128 v[206:209], v253 offset:2048
	ds_read_b128 v[210:213], v187 offset:4096
	ds_read_b128 v[214:217], v253 offset:4096
	ds_read_b128 v[218:221], v187 offset:6144
	ds_read_b128 v[222:225], v253 offset:6144
	global_load_lds_dwordx4 v[74:75], off
	v_lshl_add_u64 v[74:75], s[14:15], 0, v[168:169]
	s_add_i32 m0, s74, 0xe000
	s_nop 0
	global_load_lds_dwordx4 v[74:75], off
	s_waitcnt vmcnt(8)
	s_waitcnt lgkmcnt(0)
	s_barrier
	s_setprio 1
	s_waitcnt lgkmcnt(0)
	v_mfma_f32_16x16x32_bf16 v[140:143], v[88:91], v[194:197], 0
	v_mfma_f32_16x16x32_bf16 v[136:139], v[128:131], v[194:197], 0
	v_mfma_f32_16x16x32_bf16 v[120:123], v[88:91], v[202:205], 0
	v_mfma_f32_16x16x32_bf16 v[116:119], v[128:131], v[202:205], 0
	v_mfma_f32_16x16x32_bf16 v[100:103], v[88:91], v[210:213], 0
	v_mfma_f32_16x16x32_bf16 v[96:99], v[128:131], v[210:213], 0
	v_mfma_f32_16x16x32_bf16 v[80:83], v[88:91], v[218:221], 0
	v_mfma_f32_16x16x32_bf16 v[74:77], v[128:131], v[218:221], 0
	v_mfma_f32_16x16x32_bf16 v[140:143], v[108:111], v[198:201], v[140:143]
	v_mfma_f32_16x16x32_bf16 v[136:139], v[144:147], v[198:201], v[136:139]
	v_mfma_f32_16x16x32_bf16 v[120:123], v[108:111], v[206:209], v[120:123]
	v_mfma_f32_16x16x32_bf16 v[116:119], v[144:147], v[206:209], v[116:119]
	v_mfma_f32_16x16x32_bf16 v[100:103], v[108:111], v[214:217], v[100:103]
	v_mfma_f32_16x16x32_bf16 v[96:99], v[144:147], v[214:217], v[96:99]
	v_mfma_f32_16x16x32_bf16 v[80:83], v[108:111], v[222:225], v[80:83]
	v_mfma_f32_16x16x32_bf16 v[74:77], v[144:147], v[222:225], v[74:77]
	s_setprio 0
	s_setprio 1
	v_mfma_f32_16x16x32_bf16 v[132:135], v[148:151], v[194:197], 0
	v_mfma_f32_16x16x32_bf16 v[124:127], v[176:179], v[194:197], 0
	v_mfma_f32_16x16x32_bf16 v[112:115], v[148:151], v[202:205], 0
	v_mfma_f32_16x16x32_bf16 v[104:107], v[176:179], v[202:205], 0
	v_mfma_f32_16x16x32_bf16 v[92:95], v[148:151], v[210:213], 0
	v_mfma_f32_16x16x32_bf16 v[84:87], v[176:179], v[210:213], 0
	v_mfma_f32_16x16x32_bf16 v[68:71], v[148:151], v[218:221], 0
	v_mfma_f32_16x16x32_bf16 v[64:67], v[176:179], v[218:221], 0
	v_mfma_f32_16x16x32_bf16 v[132:135], v[152:155], v[198:201], v[132:135]
	v_mfma_f32_16x16x32_bf16 v[124:127], v[190:193], v[198:201], v[124:127]
	v_mfma_f32_16x16x32_bf16 v[112:115], v[152:155], v[206:209], v[112:115]
	v_mfma_f32_16x16x32_bf16 v[104:107], v[190:193], v[206:209], v[104:107]
	v_mfma_f32_16x16x32_bf16 v[92:95], v[152:155], v[214:217], v[92:95]
	v_mfma_f32_16x16x32_bf16 v[84:87], v[190:193], v[214:217], v[84:87]
	v_mfma_f32_16x16x32_bf16 v[68:71], v[152:155], v[222:225], v[68:71]
	v_mfma_f32_16x16x32_bf16 v[64:67], v[190:193], v[222:225], v[64:67]
	s_setprio 0
	s_barrier
	s_add_i32 s96, s83, s71
	v_lshl_add_u64 v[226:227], s[66:67], 0, v[162:163]
	s_mov_b32 m0, s96
	ds_read_b128 v[194:197], v187 offset:16384
	v_xor_b32_e32 v253, 64, v187
	ds_read_b128 v[198:201], v253 offset:16384
	ds_read_b128 v[202:205], v187 offset:18432
	ds_read_b128 v[206:209], v253 offset:18432
	ds_read_b128 v[210:213], v187 offset:20480
	ds_read_b128 v[214:217], v253 offset:20480
	ds_read_b128 v[218:221], v187 offset:22528
	ds_read_b128 v[222:225], v253 offset:22528
	global_load_lds_dwordx4 v[226:227], off
	s_add_i32 m0, s96, 0x2000
	s_add_u32 s96, s66, 0x40000
	v_lshl_add_u64 v[228:229], s[66:67], 0, v[166:167]
	s_addc_u32 s97, s67, 0
	s_add_i32 vcc_lo, s84, s71
	global_load_lds_dwordx4 v[228:229], off
	v_lshl_add_u64 v[78:79], s[96:97], 0, v[162:163]
	s_mov_b32 m0, vcc_lo
	v_lshl_add_u64 v[230:231], s[68:69], 0, v[160:161]
	global_load_lds_dwordx4 v[78:79], off
	v_lshl_add_u64 v[78:79], s[96:97], 0, v[166:167]
	s_add_i32 m0, vcc_lo, 0x2000
	v_lshl_add_u64 v[232:233], s[68:69], 0, v[164:165]
	global_load_lds_dwordx4 v[78:79], off
	s_mov_b32 m0, s74
	s_nop 0
	global_load_lds_dwordx4 v[230:231], off
	s_mov_b32 m0, s75
	s_nop 0
	global_load_lds_dwordx4 v[232:233], off
	s_waitcnt vmcnt(8)
	s_waitcnt lgkmcnt(0)
	s_barrier
	s_setprio 1
	s_waitcnt lgkmcnt(0)
	v_mfma_f32_16x16x32_bf16 v[60:63], v[88:91], v[194:197], 0
	v_mfma_f32_16x16x32_bf16 v[56:59], v[128:131], v[194:197], 0
	v_mfma_f32_16x16x32_bf16 v[44:47], v[88:91], v[202:205], 0
	v_mfma_f32_16x16x32_bf16 v[40:43], v[128:131], v[202:205], 0
	v_mfma_f32_16x16x32_bf16 v[28:31], v[88:91], v[210:213], 0
	v_mfma_f32_16x16x32_bf16 v[24:27], v[128:131], v[210:213], 0
	v_mfma_f32_16x16x32_bf16 v[12:15], v[88:91], v[218:221], 0
	v_mfma_f32_16x16x32_bf16 v[8:11], v[128:131], v[218:221], 0
	v_mfma_f32_16x16x32_bf16 v[60:63], v[108:111], v[198:201], v[60:63]
	v_mfma_f32_16x16x32_bf16 v[56:59], v[144:147], v[198:201], v[56:59]
	v_mfma_f32_16x16x32_bf16 v[44:47], v[108:111], v[206:209], v[44:47]
	v_mfma_f32_16x16x32_bf16 v[40:43], v[144:147], v[206:209], v[40:43]
	v_mfma_f32_16x16x32_bf16 v[28:31], v[108:111], v[214:217], v[28:31]
	v_mfma_f32_16x16x32_bf16 v[24:27], v[144:147], v[214:217], v[24:27]
	v_mfma_f32_16x16x32_bf16 v[12:15], v[108:111], v[222:225], v[12:15]
	v_mfma_f32_16x16x32_bf16 v[8:11], v[144:147], v[222:225], v[8:11]
	s_setprio 0
	s_setprio 1
	v_mfma_f32_16x16x32_bf16 v[52:55], v[148:151], v[194:197], 0
	v_mfma_f32_16x16x32_bf16 v[48:51], v[176:179], v[194:197], 0
	v_mfma_f32_16x16x32_bf16 v[36:39], v[148:151], v[202:205], 0
	v_mfma_f32_16x16x32_bf16 v[32:35], v[176:179], v[202:205], 0
	v_mfma_f32_16x16x32_bf16 v[20:23], v[148:151], v[210:213], 0
	v_mfma_f32_16x16x32_bf16 v[16:19], v[176:179], v[210:213], 0
	v_mfma_f32_16x16x32_bf16 v[4:7], v[148:151], v[218:221], 0
	v_mfma_f32_16x16x32_bf16 v[0:3], v[176:179], v[218:221], 0
	v_mfma_f32_16x16x32_bf16 v[52:55], v[152:155], v[198:201], v[52:55]
	v_mfma_f32_16x16x32_bf16 v[48:51], v[190:193], v[198:201], v[48:51]
	v_mfma_f32_16x16x32_bf16 v[36:39], v[152:155], v[206:209], v[36:39]
	v_mfma_f32_16x16x32_bf16 v[32:35], v[190:193], v[206:209], v[32:35]
	v_mfma_f32_16x16x32_bf16 v[20:23], v[152:155], v[214:217], v[20:23]
	v_mfma_f32_16x16x32_bf16 v[16:19], v[190:193], v[214:217], v[16:19]
	v_mfma_f32_16x16x32_bf16 v[4:7], v[152:155], v[222:225], v[4:7]
	v_mfma_f32_16x16x32_bf16 v[0:3], v[190:193], v[222:225], v[0:3]
	s_setprio 0
	s_barrier
	s_add_i32 s96, 0, 0x18000
	v_add_u32_e32 v78, s96, v181
	s_add_i32 s97, 0, 0x1c000
	ds_read_b128 v[88:91], v78
	v_xor_b32_e32 v253, 64, v78
	ds_read_b128 v[108:111], v253
	ds_read_b128 v[128:131], v78 offset:2048
	ds_read_b128 v[144:147], v253 offset:2048
	v_add_u32_e32 v78, s97, v181
	ds_read_b128 v[148:151], v78
	v_xor_b32_e32 v253, 64, v78
	ds_read_b128 v[152:155], v253
	ds_read_b128 v[176:179], v78 offset:2048
	ds_read_b128 v[190:193], v253 offset:2048
	s_add_u32 s68, s68, 0x40000
	s_addc_u32 s69, s69, 0
	s_mov_b32 m0, s76
	v_lshl_add_u64 v[78:79], s[68:69], 0, v[160:161]
	ds_read_b128 v[194:197], v187 offset:32768
	v_xor_b32_e32 v253, 64, v187
	ds_read_b128 v[198:201], v253 offset:32768
	ds_read_b128 v[202:205], v187 offset:34816
	ds_read_b128 v[206:209], v253 offset:34816
	ds_read_b128 v[210:213], v187 offset:36864
	ds_read_b128 v[214:217], v253 offset:36864
	ds_read_b128 v[218:221], v187 offset:38912
	ds_read_b128 v[222:225], v253 offset:38912
	global_load_lds_dwordx4 v[78:79], off
	v_lshl_add_u64 v[78:79], s[68:69], 0, v[164:165]
	s_mov_b32 m0, s77
	s_nop 0
	global_load_lds_dwordx4 v[78:79], off
	s_waitcnt vmcnt(8)
	s_waitcnt lgkmcnt(0)
	s_barrier
	s_setprio 1
	s_waitcnt lgkmcnt(0)
	v_mfma_f32_16x16x32_bf16 v[140:143], v[88:91], v[194:197], v[140:143]
	v_mfma_f32_16x16x32_bf16 v[136:139], v[128:131], v[194:197], v[136:139]
	v_mfma_f32_16x16x32_bf16 v[120:123], v[88:91], v[202:205], v[120:123]
	v_mfma_f32_16x16x32_bf16 v[116:119], v[128:131], v[202:205], v[116:119]
	v_mfma_f32_16x16x32_bf16 v[100:103], v[88:91], v[210:213], v[100:103]
	v_mfma_f32_16x16x32_bf16 v[96:99], v[128:131], v[210:213], v[96:99]
	v_mfma_f32_16x16x32_bf16 v[78:81], v[88:91], v[218:221], v[80:83]
	v_mfma_f32_16x16x32_bf16 v[74:77], v[128:131], v[218:221], v[74:77]
	v_mfma_f32_16x16x32_bf16 v[140:143], v[108:111], v[198:201], v[140:143]
	v_mfma_f32_16x16x32_bf16 v[136:139], v[144:147], v[198:201], v[136:139]
	v_mfma_f32_16x16x32_bf16 v[120:123], v[108:111], v[206:209], v[120:123]
	v_mfma_f32_16x16x32_bf16 v[116:119], v[144:147], v[206:209], v[116:119]
	v_mfma_f32_16x16x32_bf16 v[100:103], v[108:111], v[214:217], v[100:103]
	v_mfma_f32_16x16x32_bf16 v[96:99], v[144:147], v[214:217], v[96:99]
	v_mfma_f32_16x16x32_bf16 v[80:83], v[108:111], v[222:225], v[78:81]
	v_mfma_f32_16x16x32_bf16 v[76:79], v[144:147], v[222:225], v[74:77]
	s_setprio 0
	s_setprio 1
	v_mfma_f32_16x16x32_bf16 v[132:135], v[148:151], v[194:197], v[132:135]
	v_mfma_f32_16x16x32_bf16 v[132:135], v[152:155], v[198:201], v[132:135]
	v_mfma_f32_16x16x32_bf16 v[124:127], v[176:179], v[194:197], v[124:127]
	v_mfma_f32_16x16x32_bf16 v[124:127], v[190:193], v[198:201], v[124:127]
	v_mfma_f32_16x16x32_bf16 v[112:115], v[148:151], v[202:205], v[112:115]
	v_mfma_f32_16x16x32_bf16 v[112:115], v[152:155], v[206:209], v[112:115]
	v_mfma_f32_16x16x32_bf16 v[104:107], v[176:179], v[202:205], v[104:107]
	v_mfma_f32_16x16x32_bf16 v[104:107], v[190:193], v[206:209], v[104:107]
	v_mfma_f32_16x16x32_bf16 v[92:95], v[148:151], v[210:213], v[92:95]
	v_mfma_f32_16x16x32_bf16 v[92:95], v[152:155], v[214:217], v[92:95]
	v_mfma_f32_16x16x32_bf16 v[84:87], v[176:179], v[210:213], v[84:87]
	v_mfma_f32_16x16x32_bf16 v[84:87], v[190:193], v[214:217], v[84:87]
	v_mfma_f32_16x16x32_bf16 v[68:71], v[148:151], v[218:221], v[68:71]
	v_mfma_f32_16x16x32_bf16 v[68:71], v[152:155], v[222:225], v[68:71]
	v_mfma_f32_16x16x32_bf16 v[64:67], v[176:179], v[218:221], v[64:67]
	v_mfma_f32_16x16x32_bf16 v[64:67], v[190:193], v[222:225], v[64:67]
	s_setprio 0
	s_barrier
	s_add_i32 s68, s96, s71
	v_lshl_add_u64 v[74:75], v[226:227], 0, s[28:29]
	s_mov_b32 m0, s68
	ds_read_b128 v[194:197], v187 offset:49152
	v_xor_b32_e32 v253, 64, v187
	ds_read_b128 v[198:201], v253 offset:49152
	ds_read_b128 v[202:205], v187 offset:51200
	ds_read_b128 v[206:209], v253 offset:51200
	ds_read_b128 v[210:213], v187 offset:53248
	ds_read_b128 v[214:217], v253 offset:53248
	ds_read_b128 v[218:221], v187 offset:55296
	ds_read_b128 v[222:225], v253 offset:55296
	global_load_lds_dwordx4 v[74:75], off
	s_add_i32 m0, s68, 0x2000
	s_add_u32 s66, s66, 0x40080
	v_lshl_add_u64 v[74:75], v[228:229], 0, s[28:29]
	s_addc_u32 s67, s67, 0
	s_add_i32 s68, s97, s71
	global_load_lds_dwordx4 v[74:75], off
	v_lshl_add_u64 v[74:75], s[66:67], 0, v[162:163]
	s_mov_b32 m0, s68
	s_nop 0
	global_load_lds_dwordx4 v[74:75], off
	v_lshl_add_u64 v[74:75], s[66:67], 0, v[166:167]
	s_add_i32 m0, s68, 0x2000
	s_nop 0
	global_load_lds_dwordx4 v[74:75], off
	v_lshl_add_u64 v[74:75], v[230:231], 0, s[28:29]
	s_mov_b32 m0, s78
	s_nop 0
	global_load_lds_dwordx4 v[74:75], off
	v_lshl_add_u64 v[74:75], v[232:233], 0, s[28:29]
	s_mov_b32 m0, s79
	s_nop 0
	global_load_lds_dwordx4 v[74:75], off
	s_waitcnt vmcnt(8)
	s_waitcnt lgkmcnt(0)
	s_barrier
	s_setprio 1
	s_waitcnt lgkmcnt(0)
	v_mfma_f32_16x16x32_bf16 v[60:63], v[88:91], v[194:197], v[60:63]
	v_mfma_f32_16x16x32_bf16 v[60:63], v[108:111], v[198:201], v[60:63]
	v_mfma_f32_16x16x32_bf16 v[56:59], v[128:131], v[194:197], v[56:59]
	v_mfma_f32_16x16x32_bf16 v[56:59], v[144:147], v[198:201], v[56:59]
	v_mfma_f32_16x16x32_bf16 v[44:47], v[88:91], v[202:205], v[44:47]
	v_mfma_f32_16x16x32_bf16 v[44:47], v[108:111], v[206:209], v[44:47]
	v_mfma_f32_16x16x32_bf16 v[40:43], v[128:131], v[202:205], v[40:43]
	v_mfma_f32_16x16x32_bf16 v[40:43], v[144:147], v[206:209], v[40:43]
	v_mfma_f32_16x16x32_bf16 v[28:31], v[88:91], v[210:213], v[28:31]
	v_mfma_f32_16x16x32_bf16 v[28:31], v[108:111], v[214:217], v[28:31]
	v_mfma_f32_16x16x32_bf16 v[24:27], v[128:131], v[210:213], v[24:27]
	v_mfma_f32_16x16x32_bf16 v[24:27], v[144:147], v[214:217], v[24:27]
	v_mfma_f32_16x16x32_bf16 v[12:15], v[88:91], v[218:221], v[12:15]
	v_mfma_f32_16x16x32_bf16 v[12:15], v[108:111], v[222:225], v[12:15]
	v_mfma_f32_16x16x32_bf16 v[8:11], v[128:131], v[218:221], v[8:11]
	v_mfma_f32_16x16x32_bf16 v[8:11], v[144:147], v[222:225], v[8:11]
	s_setprio 0
	s_setprio 1
	v_mfma_f32_16x16x32_bf16 v[52:55], v[148:151], v[194:197], v[52:55]
	v_mfma_f32_16x16x32_bf16 v[52:55], v[152:155], v[198:201], v[52:55]
	v_mfma_f32_16x16x32_bf16 v[48:51], v[176:179], v[194:197], v[48:51]
	v_mfma_f32_16x16x32_bf16 v[48:51], v[190:193], v[198:201], v[48:51]
	v_mfma_f32_16x16x32_bf16 v[36:39], v[148:151], v[202:205], v[36:39]
	v_mfma_f32_16x16x32_bf16 v[36:39], v[152:155], v[206:209], v[36:39]
	v_mfma_f32_16x16x32_bf16 v[32:35], v[176:179], v[202:205], v[32:35]
	v_mfma_f32_16x16x32_bf16 v[32:35], v[190:193], v[206:209], v[32:35]
	v_mfma_f32_16x16x32_bf16 v[20:23], v[148:151], v[210:213], v[20:23]
	v_mfma_f32_16x16x32_bf16 v[20:23], v[152:155], v[214:217], v[20:23]
	v_mfma_f32_16x16x32_bf16 v[16:19], v[176:179], v[210:213], v[16:19]
	v_mfma_f32_16x16x32_bf16 v[16:19], v[190:193], v[214:217], v[16:19]
	v_mfma_f32_16x16x32_bf16 v[4:7], v[148:151], v[218:221], v[4:7]
	v_mfma_f32_16x16x32_bf16 v[4:7], v[152:155], v[222:225], v[4:7]
	v_mfma_f32_16x16x32_bf16 v[0:3], v[176:179], v[218:221], v[0:3]
	v_mfma_f32_16x16x32_bf16 v[0:3], v[190:193], v[222:225], v[0:3]
	s_setprio 0
	s_barrier
	s_add_i32 s95, s95, 2
	s_add_u32 s93, s93, 0x100
	s_addc_u32 s94, s94, 0
	s_add_u32 s14, s14, 0x100
	s_addc_u32 s15, s15, 0
	s_branch .LBB0_256
.LBB0_255:
	v_add_u32_e32 v74, s83, v181
	ds_read_b128 v[88:91], v74
	v_xor_b32_e32 v253, 64, v74
	ds_read_b128 v[108:111], v253
	ds_read_b128 v[128:131], v74 offset:2048
	ds_read_b128 v[144:147], v253 offset:2048
	v_add_u32_e32 v74, s84, v181
	ds_read_b128 v[148:151], v74
	v_xor_b32_e32 v253, 64, v74
	ds_read_b128 v[152:155], v253
	ds_read_b128 v[176:179], v74 offset:2048
	ds_read_b128 v[190:193], v253 offset:2048
	s_add_u32 s68, s14, 0xfffc0080
	s_addc_u32 s69, s15, -1
	s_and_b64 s[66:67], s[66:67], exec
	s_cselect_b32 s69, s3, s69
	s_cselect_b32 s68, s61, s68
	s_cselect_b32 s67, s91, s94
	s_cselect_b32 s66, s92, s93
	v_lshl_add_u64 v[74:75], s[14:15], 0, v[170:171]
	s_add_i32 m0, s74, 0xc000
	ds_read_b128 v[194:197], v187
	v_xor_b32_e32 v253, 64, v187
	ds_read_b128 v[198:201], v253
	ds_read_b128 v[202:205], v187 offset:2048
	ds_read_b128 v[206:209], v253 offset:2048
	ds_read_b128 v[210:213], v187 offset:4096
	ds_read_b128 v[214:217], v253 offset:4096
	ds_read_b128 v[218:221], v187 offset:6144
	ds_read_b128 v[222:225], v253 offset:6144
	global_load_lds_dwordx4 v[74:75], off
	v_lshl_add_u64 v[74:75], s[14:15], 0, v[168:169]
	s_add_i32 m0, s74, 0xe000
	s_nop 0
	global_load_lds_dwordx4 v[74:75], off
	s_waitcnt vmcnt(8)
	s_waitcnt lgkmcnt(0)
	s_barrier
	s_setprio 1
	s_waitcnt lgkmcnt(0)
	v_mfma_f32_16x16x32_bf16 v[140:143], v[88:91], v[194:197], v[140:143]
	v_mfma_f32_16x16x32_bf16 v[136:139], v[128:131], v[194:197], v[136:139]
	v_mfma_f32_16x16x32_bf16 v[120:123], v[88:91], v[202:205], v[120:123]
	v_mfma_f32_16x16x32_bf16 v[116:119], v[128:131], v[202:205], v[116:119]
	v_mfma_f32_16x16x32_bf16 v[100:103], v[88:91], v[210:213], v[100:103]
	v_mfma_f32_16x16x32_bf16 v[96:99], v[128:131], v[210:213], v[96:99]
	v_mfma_f32_16x16x32_bf16 v[80:83], v[88:91], v[218:221], v[80:83]
	v_mfma_f32_16x16x32_bf16 v[74:77], v[128:131], v[218:221], v[76:79]
	v_mfma_f32_16x16x32_bf16 v[140:143], v[108:111], v[198:201], v[140:143]
	v_mfma_f32_16x16x32_bf16 v[136:139], v[144:147], v[198:201], v[136:139]
	v_mfma_f32_16x16x32_bf16 v[120:123], v[108:111], v[206:209], v[120:123]
	v_mfma_f32_16x16x32_bf16 v[116:119], v[144:147], v[206:209], v[116:119]
	v_mfma_f32_16x16x32_bf16 v[100:103], v[108:111], v[214:217], v[100:103]
	v_mfma_f32_16x16x32_bf16 v[96:99], v[144:147], v[214:217], v[96:99]
	v_mfma_f32_16x16x32_bf16 v[80:83], v[108:111], v[222:225], v[80:83]
	v_mfma_f32_16x16x32_bf16 v[74:77], v[144:147], v[222:225], v[74:77]
	s_setprio 0
	s_setprio 1
	v_mfma_f32_16x16x32_bf16 v[132:135], v[148:151], v[194:197], v[132:135]
	v_mfma_f32_16x16x32_bf16 v[132:135], v[152:155], v[198:201], v[132:135]
	v_mfma_f32_16x16x32_bf16 v[124:127], v[176:179], v[194:197], v[124:127]
	v_mfma_f32_16x16x32_bf16 v[124:127], v[190:193], v[198:201], v[124:127]
	v_mfma_f32_16x16x32_bf16 v[112:115], v[148:151], v[202:205], v[112:115]
	v_mfma_f32_16x16x32_bf16 v[112:115], v[152:155], v[206:209], v[112:115]
	v_mfma_f32_16x16x32_bf16 v[104:107], v[176:179], v[202:205], v[104:107]
	v_mfma_f32_16x16x32_bf16 v[104:107], v[190:193], v[206:209], v[104:107]
	v_mfma_f32_16x16x32_bf16 v[92:95], v[148:151], v[210:213], v[92:95]
	v_mfma_f32_16x16x32_bf16 v[92:95], v[152:155], v[214:217], v[92:95]
	v_mfma_f32_16x16x32_bf16 v[84:87], v[176:179], v[210:213], v[84:87]
	v_mfma_f32_16x16x32_bf16 v[84:87], v[190:193], v[214:217], v[84:87]
	v_mfma_f32_16x16x32_bf16 v[68:71], v[148:151], v[218:221], v[68:71]
	v_mfma_f32_16x16x32_bf16 v[68:71], v[152:155], v[222:225], v[68:71]
	v_mfma_f32_16x16x32_bf16 v[64:67], v[176:179], v[218:221], v[64:67]
	v_mfma_f32_16x16x32_bf16 v[64:67], v[190:193], v[222:225], v[64:67]
	s_setprio 0
	s_barrier
	s_add_i32 s96, s83, s71
	v_lshl_add_u64 v[226:227], s[66:67], 0, v[162:163]
	s_mov_b32 m0, s96
	ds_read_b128 v[194:197], v187 offset:16384
	v_xor_b32_e32 v253, 64, v187
	ds_read_b128 v[198:201], v253 offset:16384
	ds_read_b128 v[202:205], v187 offset:18432
	ds_read_b128 v[206:209], v253 offset:18432
	ds_read_b128 v[210:213], v187 offset:20480
	ds_read_b128 v[214:217], v253 offset:20480
	ds_read_b128 v[218:221], v187 offset:22528
	ds_read_b128 v[222:225], v253 offset:22528
	global_load_lds_dwordx4 v[226:227], off
	s_add_i32 m0, s96, 0x2000
	s_add_u32 s96, s66, 0x40000
	v_lshl_add_u64 v[228:229], s[66:67], 0, v[166:167]
	s_addc_u32 s97, s67, 0
	s_add_i32 vcc_lo, s84, s71
	global_load_lds_dwordx4 v[228:229], off
	v_lshl_add_u64 v[78:79], s[96:97], 0, v[162:163]
	s_mov_b32 m0, vcc_lo
	v_lshl_add_u64 v[230:231], s[68:69], 0, v[160:161]
	global_load_lds_dwordx4 v[78:79], off
	v_lshl_add_u64 v[78:79], s[96:97], 0, v[166:167]
	s_add_i32 m0, vcc_lo, 0x2000
	v_lshl_add_u64 v[232:233], s[68:69], 0, v[164:165]
	global_load_lds_dwordx4 v[78:79], off
	s_mov_b32 m0, s74
	s_nop 0
	global_load_lds_dwordx4 v[230:231], off
	s_mov_b32 m0, s75
	s_nop 0
	global_load_lds_dwordx4 v[232:233], off
	s_waitcnt vmcnt(8)
	s_waitcnt lgkmcnt(0)
	s_barrier
	s_setprio 1
	s_waitcnt lgkmcnt(0)
	v_mfma_f32_16x16x32_bf16 v[60:63], v[88:91], v[194:197], v[60:63]
	v_mfma_f32_16x16x32_bf16 v[60:63], v[108:111], v[198:201], v[60:63]
	v_mfma_f32_16x16x32_bf16 v[56:59], v[128:131], v[194:197], v[56:59]
	v_mfma_f32_16x16x32_bf16 v[56:59], v[144:147], v[198:201], v[56:59]
	v_mfma_f32_16x16x32_bf16 v[44:47], v[88:91], v[202:205], v[44:47]
	v_mfma_f32_16x16x32_bf16 v[44:47], v[108:111], v[206:209], v[44:47]
	v_mfma_f32_16x16x32_bf16 v[40:43], v[128:131], v[202:205], v[40:43]
	v_mfma_f32_16x16x32_bf16 v[40:43], v[144:147], v[206:209], v[40:43]
	v_mfma_f32_16x16x32_bf16 v[28:31], v[88:91], v[210:213], v[28:31]
	v_mfma_f32_16x16x32_bf16 v[28:31], v[108:111], v[214:217], v[28:31]
	v_mfma_f32_16x16x32_bf16 v[24:27], v[128:131], v[210:213], v[24:27]
	v_mfma_f32_16x16x32_bf16 v[24:27], v[144:147], v[214:217], v[24:27]
	v_mfma_f32_16x16x32_bf16 v[12:15], v[88:91], v[218:221], v[12:15]
	v_mfma_f32_16x16x32_bf16 v[12:15], v[108:111], v[222:225], v[12:15]
	v_mfma_f32_16x16x32_bf16 v[8:11], v[128:131], v[218:221], v[8:11]
	v_mfma_f32_16x16x32_bf16 v[8:11], v[144:147], v[222:225], v[8:11]
	s_setprio 0
	s_setprio 1
	v_mfma_f32_16x16x32_bf16 v[52:55], v[148:151], v[194:197], v[52:55]
	v_mfma_f32_16x16x32_bf16 v[52:55], v[152:155], v[198:201], v[52:55]
	v_mfma_f32_16x16x32_bf16 v[48:51], v[176:179], v[194:197], v[48:51]
	v_mfma_f32_16x16x32_bf16 v[48:51], v[190:193], v[198:201], v[48:51]
	v_mfma_f32_16x16x32_bf16 v[36:39], v[148:151], v[202:205], v[36:39]
	v_mfma_f32_16x16x32_bf16 v[36:39], v[152:155], v[206:209], v[36:39]
	v_mfma_f32_16x16x32_bf16 v[32:35], v[176:179], v[202:205], v[32:35]
	v_mfma_f32_16x16x32_bf16 v[32:35], v[190:193], v[206:209], v[32:35]
	v_mfma_f32_16x16x32_bf16 v[20:23], v[148:151], v[210:213], v[20:23]
	v_mfma_f32_16x16x32_bf16 v[20:23], v[152:155], v[214:217], v[20:23]
	v_mfma_f32_16x16x32_bf16 v[16:19], v[176:179], v[210:213], v[16:19]
	v_mfma_f32_16x16x32_bf16 v[16:19], v[190:193], v[214:217], v[16:19]
	v_mfma_f32_16x16x32_bf16 v[4:7], v[148:151], v[218:221], v[4:7]
	v_mfma_f32_16x16x32_bf16 v[4:7], v[152:155], v[222:225], v[4:7]
	v_mfma_f32_16x16x32_bf16 v[0:3], v[176:179], v[218:221], v[0:3]
	v_mfma_f32_16x16x32_bf16 v[0:3], v[190:193], v[222:225], v[0:3]
	s_setprio 0
	s_barrier
	s_add_i32 s96, 0, 0x18000
	v_add_u32_e32 v78, s96, v181
	s_add_i32 s97, 0, 0x1c000
	ds_read_b128 v[88:91], v78
	v_xor_b32_e32 v253, 64, v78
	ds_read_b128 v[108:111], v253
	ds_read_b128 v[128:131], v78 offset:2048
	ds_read_b128 v[144:147], v253 offset:2048
	v_add_u32_e32 v78, s97, v181
	ds_read_b128 v[148:151], v78
	v_xor_b32_e32 v253, 64, v78
	ds_read_b128 v[152:155], v253
	ds_read_b128 v[176:179], v78 offset:2048
	ds_read_b128 v[190:193], v253 offset:2048
	s_add_u32 s68, s68, 0x40000
	s_addc_u32 s69, s69, 0
	s_mov_b32 m0, s76
	v_lshl_add_u64 v[78:79], s[68:69], 0, v[160:161]
	ds_read_b128 v[194:197], v187 offset:32768
	v_xor_b32_e32 v253, 64, v187
	ds_read_b128 v[198:201], v253 offset:32768
	ds_read_b128 v[202:205], v187 offset:34816
	ds_read_b128 v[206:209], v253 offset:34816
	ds_read_b128 v[210:213], v187 offset:36864
	ds_read_b128 v[214:217], v253 offset:36864
	ds_read_b128 v[218:221], v187 offset:38912
	ds_read_b128 v[222:225], v253 offset:38912
	global_load_lds_dwordx4 v[78:79], off
	v_lshl_add_u64 v[78:79], s[68:69], 0, v[164:165]
	s_mov_b32 m0, s77
	s_nop 0
	global_load_lds_dwordx4 v[78:79], off
	s_waitcnt vmcnt(8)
	s_waitcnt lgkmcnt(0)
	s_barrier
	s_setprio 1
	s_waitcnt lgkmcnt(0)
	v_mfma_f32_16x16x32_bf16 v[140:143], v[88:91], v[194:197], v[140:143]
	v_mfma_f32_16x16x32_bf16 v[136:139], v[128:131], v[194:197], v[136:139]
	v_mfma_f32_16x16x32_bf16 v[120:123], v[88:91], v[202:205], v[120:123]
	v_mfma_f32_16x16x32_bf16 v[116:119], v[128:131], v[202:205], v[116:119]
	v_mfma_f32_16x16x32_bf16 v[100:103], v[88:91], v[210:213], v[100:103]
	v_mfma_f32_16x16x32_bf16 v[96:99], v[128:131], v[210:213], v[96:99]
	v_mfma_f32_16x16x32_bf16 v[78:81], v[88:91], v[218:221], v[80:83]
	v_mfma_f32_16x16x32_bf16 v[74:77], v[128:131], v[218:221], v[74:77]
	v_mfma_f32_16x16x32_bf16 v[140:143], v[108:111], v[198:201], v[140:143]
	v_mfma_f32_16x16x32_bf16 v[136:139], v[144:147], v[198:201], v[136:139]
	v_mfma_f32_16x16x32_bf16 v[120:123], v[108:111], v[206:209], v[120:123]
	v_mfma_f32_16x16x32_bf16 v[116:119], v[144:147], v[206:209], v[116:119]
	v_mfma_f32_16x16x32_bf16 v[100:103], v[108:111], v[214:217], v[100:103]
	v_mfma_f32_16x16x32_bf16 v[96:99], v[144:147], v[214:217], v[96:99]
	v_mfma_f32_16x16x32_bf16 v[80:83], v[108:111], v[222:225], v[78:81]
	v_mfma_f32_16x16x32_bf16 v[76:79], v[144:147], v[222:225], v[74:77]
	s_setprio 0
	s_setprio 1
	v_mfma_f32_16x16x32_bf16 v[132:135], v[148:151], v[194:197], v[132:135]
	v_mfma_f32_16x16x32_bf16 v[132:135], v[152:155], v[198:201], v[132:135]
	v_mfma_f32_16x16x32_bf16 v[124:127], v[176:179], v[194:197], v[124:127]
	v_mfma_f32_16x16x32_bf16 v[124:127], v[190:193], v[198:201], v[124:127]
	v_mfma_f32_16x16x32_bf16 v[112:115], v[148:151], v[202:205], v[112:115]
	v_mfma_f32_16x16x32_bf16 v[112:115], v[152:155], v[206:209], v[112:115]
	v_mfma_f32_16x16x32_bf16 v[104:107], v[176:179], v[202:205], v[104:107]
	v_mfma_f32_16x16x32_bf16 v[104:107], v[190:193], v[206:209], v[104:107]
	v_mfma_f32_16x16x32_bf16 v[92:95], v[148:151], v[210:213], v[92:95]
	v_mfma_f32_16x16x32_bf16 v[92:95], v[152:155], v[214:217], v[92:95]
	v_mfma_f32_16x16x32_bf16 v[84:87], v[176:179], v[210:213], v[84:87]
	v_mfma_f32_16x16x32_bf16 v[84:87], v[190:193], v[214:217], v[84:87]
	v_mfma_f32_16x16x32_bf16 v[68:71], v[148:151], v[218:221], v[68:71]
	v_mfma_f32_16x16x32_bf16 v[68:71], v[152:155], v[222:225], v[68:71]
	v_mfma_f32_16x16x32_bf16 v[64:67], v[176:179], v[218:221], v[64:67]
	v_mfma_f32_16x16x32_bf16 v[64:67], v[190:193], v[222:225], v[64:67]
	s_setprio 0
	s_barrier
	s_add_i32 s68, s96, s71
	v_lshl_add_u64 v[74:75], v[226:227], 0, s[28:29]
	s_mov_b32 m0, s68
	ds_read_b128 v[194:197], v187 offset:49152
	v_xor_b32_e32 v253, 64, v187
	ds_read_b128 v[198:201], v253 offset:49152
	ds_read_b128 v[202:205], v187 offset:51200
	ds_read_b128 v[206:209], v253 offset:51200
	ds_read_b128 v[210:213], v187 offset:53248
	ds_read_b128 v[214:217], v253 offset:53248
	ds_read_b128 v[218:221], v187 offset:55296
	ds_read_b128 v[222:225], v253 offset:55296
	global_load_lds_dwordx4 v[74:75], off
	s_add_i32 m0, s68, 0x2000
	s_add_u32 s66, s66, 0x40080
	v_lshl_add_u64 v[74:75], v[228:229], 0, s[28:29]
	s_addc_u32 s67, s67, 0
	s_add_i32 s68, s97, s71
	global_load_lds_dwordx4 v[74:75], off
	v_lshl_add_u64 v[74:75], s[66:67], 0, v[162:163]
	s_mov_b32 m0, s68
	s_nop 0
	global_load_lds_dwordx4 v[74:75], off
	v_lshl_add_u64 v[74:75], s[66:67], 0, v[166:167]
	s_add_i32 m0, s68, 0x2000
	s_nop 0
	global_load_lds_dwordx4 v[74:75], off
	v_lshl_add_u64 v[74:75], v[230:231], 0, s[28:29]
	s_mov_b32 m0, s78
	s_nop 0
	global_load_lds_dwordx4 v[74:75], off
	v_lshl_add_u64 v[74:75], v[232:233], 0, s[28:29]
	s_mov_b32 m0, s79
	s_nop 0
	global_load_lds_dwordx4 v[74:75], off
	s_waitcnt vmcnt(8)
	s_waitcnt lgkmcnt(0)
	s_barrier
	s_setprio 1
	s_waitcnt lgkmcnt(0)
	v_mfma_f32_16x16x32_bf16 v[60:63], v[88:91], v[194:197], v[60:63]
	v_mfma_f32_16x16x32_bf16 v[60:63], v[108:111], v[198:201], v[60:63]
	v_mfma_f32_16x16x32_bf16 v[56:59], v[128:131], v[194:197], v[56:59]
	v_mfma_f32_16x16x32_bf16 v[56:59], v[144:147], v[198:201], v[56:59]
	v_mfma_f32_16x16x32_bf16 v[44:47], v[88:91], v[202:205], v[44:47]
	v_mfma_f32_16x16x32_bf16 v[44:47], v[108:111], v[206:209], v[44:47]
	v_mfma_f32_16x16x32_bf16 v[40:43], v[128:131], v[202:205], v[40:43]
	v_mfma_f32_16x16x32_bf16 v[40:43], v[144:147], v[206:209], v[40:43]
	v_mfma_f32_16x16x32_bf16 v[28:31], v[88:91], v[210:213], v[28:31]
	v_mfma_f32_16x16x32_bf16 v[28:31], v[108:111], v[214:217], v[28:31]
	v_mfma_f32_16x16x32_bf16 v[24:27], v[128:131], v[210:213], v[24:27]
	v_mfma_f32_16x16x32_bf16 v[24:27], v[144:147], v[214:217], v[24:27]
	v_mfma_f32_16x16x32_bf16 v[12:15], v[88:91], v[218:221], v[12:15]
	v_mfma_f32_16x16x32_bf16 v[12:15], v[108:111], v[222:225], v[12:15]
	v_mfma_f32_16x16x32_bf16 v[8:11], v[128:131], v[218:221], v[8:11]
	v_mfma_f32_16x16x32_bf16 v[8:11], v[144:147], v[222:225], v[8:11]
	s_setprio 0
	s_setprio 1
	v_mfma_f32_16x16x32_bf16 v[52:55], v[148:151], v[194:197], v[52:55]
	v_mfma_f32_16x16x32_bf16 v[52:55], v[152:155], v[198:201], v[52:55]
	v_mfma_f32_16x16x32_bf16 v[48:51], v[176:179], v[194:197], v[48:51]
	v_mfma_f32_16x16x32_bf16 v[48:51], v[190:193], v[198:201], v[48:51]
	v_mfma_f32_16x16x32_bf16 v[36:39], v[148:151], v[202:205], v[36:39]
	v_mfma_f32_16x16x32_bf16 v[36:39], v[152:155], v[206:209], v[36:39]
	v_mfma_f32_16x16x32_bf16 v[32:35], v[176:179], v[202:205], v[32:35]
	v_mfma_f32_16x16x32_bf16 v[32:35], v[190:193], v[206:209], v[32:35]
	v_mfma_f32_16x16x32_bf16 v[20:23], v[148:151], v[210:213], v[20:23]
	v_mfma_f32_16x16x32_bf16 v[20:23], v[152:155], v[214:217], v[20:23]
	v_mfma_f32_16x16x32_bf16 v[16:19], v[176:179], v[210:213], v[16:19]
	v_mfma_f32_16x16x32_bf16 v[16:19], v[190:193], v[214:217], v[16:19]
	v_mfma_f32_16x16x32_bf16 v[4:7], v[148:151], v[218:221], v[4:7]
	v_mfma_f32_16x16x32_bf16 v[4:7], v[152:155], v[222:225], v[4:7]
	v_mfma_f32_16x16x32_bf16 v[0:3], v[176:179], v[218:221], v[0:3]
	v_mfma_f32_16x16x32_bf16 v[0:3], v[190:193], v[222:225], v[0:3]
	s_setprio 0
	s_barrier
	s_add_i32 s95, s95, 2
	s_add_u32 s93, s93, 0x100
	s_addc_u32 s94, s94, 0
	s_add_u32 s14, s14, 0x100
	s_addc_u32 s15, s15, 0
	s_cmp_gt_u32 s95, 13
	s_cbranch_scc1 .LBB0_258

.LBB0_439:
	s_ashr_i32 s53, s52, 31
	s_lshl_b64 s[54:55], s[52:53], 20
	s_add_u32 s54, s35, s54
	s_addc_u32 s55, s66, s55
	s_and_b64 s[56:57], s[12:13], exec
	s_cselect_b32 s15, s55, s63
	s_cselect_b32 s53, s54, s62
	s_ashr_i32 s51, s50, 31
	s_lshl_b64 s[56:57], s[50:51], 20
	s_add_u32 s56, s67, s56
	s_addc_u32 s57, s68, s57
	s_and_b64 s[64:65], s[12:13], exec
	s_cselect_b32 s51, s57, s61
	s_cselect_b32 s59, s56, s60
	s_add_u32 s81, s60, 0x100
	s_addc_u32 s82, s61, 0
	s_add_u32 s60, s62, 0x80080
	s_addc_u32 s61, s63, 0
	s_mov_b32 s83, -2
	s_waitcnt lgkmcnt(0)
	s_cmp_eq_u32 s74, 1
	s_cbranch_scc1 .Lfa_3
	ds_read_b128 v[128:131], v189
	v_xor_b32_e32 v253, 64, v189
	ds_read_b128 v[132:135], v253
	ds_read_b128 v[136:139], v189 offset:2048
	ds_read_b128 v[140:143], v253 offset:2048
	ds_read_b128 v[144:147], v190
	v_xor_b32_e32 v253, 64, v190
	ds_read_b128 v[148:151], v253
	ds_read_b128 v[172:175], v190 offset:2048
	ds_read_b128 v[176:179], v253 offset:2048
	s_add_u32 s62, s60, 0xfff80080
	s_addc_u32 s63, s61, -1
	s_cmp_eq_u32 s83, 28
	s_cselect_b32 s65, s15, s63
	s_cselect_b32 s64, s53, s62
	s_cselect_b32 s63, s51, s82
	s_cselect_b32 s62, s59, s81
	v_lshl_add_u64 v[222:223], s[60:61], 0, v[166:167]
	s_add_i32 m0, s70, 0xc000
	ds_read_b128 v[180:183], v191
	v_xor_b32_e32 v253, 64, v191
	ds_read_b128 v[194:197], v253
	ds_read_b128 v[198:201], v191 offset:2048
	ds_read_b128 v[202:205], v253 offset:2048
	ds_read_b128 v[206:209], v191 offset:4096
	ds_read_b128 v[210:213], v253 offset:4096
	ds_read_b128 v[214:217], v191 offset:6144
	ds_read_b128 v[218:221], v253 offset:6144
	global_load_lds_dwordx4 v[222:223], off
	v_lshl_add_u64 v[222:223], s[60:61], 0, v[164:165]
	s_add_i32 m0, s70, 0xe000
	s_nop 0
	global_load_lds_dwordx4 v[222:223], off
	s_waitcnt vmcnt(24)
	s_waitcnt lgkmcnt(0)
	s_barrier
	s_setprio 1
	s_waitcnt lgkmcnt(0)
	v_mfma_f32_16x16x32_bf16 v[124:127], v[128:131], v[180:183], 0
	v_mfma_f32_16x16x32_bf16 v[120:123], v[136:139], v[180:183], 0
	v_mfma_f32_16x16x32_bf16 v[108:111], v[128:131], v[198:201], 0
	v_mfma_f32_16x16x32_bf16 v[104:107], v[136:139], v[198:201], 0
	v_mfma_f32_16x16x32_bf16 v[92:95], v[128:131], v[206:209], 0
	v_mfma_f32_16x16x32_bf16 v[88:91], v[136:139], v[206:209], 0
	v_mfma_f32_16x16x32_bf16 v[76:79], v[128:131], v[214:217], 0
	v_mfma_f32_16x16x32_bf16 v[72:75], v[136:139], v[214:217], 0
	v_mfma_f32_16x16x32_bf16 v[124:127], v[132:135], v[194:197], v[124:127]
	v_mfma_f32_16x16x32_bf16 v[120:123], v[140:143], v[194:197], v[120:123]
	v_mfma_f32_16x16x32_bf16 v[108:111], v[132:135], v[202:205], v[108:111]
	v_mfma_f32_16x16x32_bf16 v[104:107], v[140:143], v[202:205], v[104:107]
	v_mfma_f32_16x16x32_bf16 v[92:95], v[132:135], v[210:213], v[92:95]
	v_mfma_f32_16x16x32_bf16 v[88:91], v[140:143], v[210:213], v[88:91]
	v_mfma_f32_16x16x32_bf16 v[76:79], v[132:135], v[218:221], v[76:79]
	v_mfma_f32_16x16x32_bf16 v[72:75], v[140:143], v[218:221], v[72:75]
	s_setprio 0
	s_setprio 1
	v_mfma_f32_16x16x32_bf16 v[116:119], v[144:147], v[180:183], 0
	v_mfma_f32_16x16x32_bf16 v[112:115], v[172:175], v[180:183], 0
	v_mfma_f32_16x16x32_bf16 v[100:103], v[144:147], v[198:201], 0
	v_mfma_f32_16x16x32_bf16 v[96:99], v[172:175], v[198:201], 0
	v_mfma_f32_16x16x32_bf16 v[84:87], v[144:147], v[206:209], 0
	v_mfma_f32_16x16x32_bf16 v[80:83], v[172:175], v[206:209], 0
	v_mfma_f32_16x16x32_bf16 v[68:71], v[144:147], v[214:217], 0
	v_mfma_f32_16x16x32_bf16 v[64:67], v[172:175], v[214:217], 0
	v_mfma_f32_16x16x32_bf16 v[116:119], v[148:151], v[194:197], v[116:119]
	v_mfma_f32_16x16x32_bf16 v[112:115], v[176:179], v[194:197], v[112:115]
	v_mfma_f32_16x16x32_bf16 v[100:103], v[148:151], v[202:205], v[100:103]
	v_mfma_f32_16x16x32_bf16 v[96:99], v[176:179], v[202:205], v[96:99]
	v_mfma_f32_16x16x32_bf16 v[84:87], v[148:151], v[210:213], v[84:87]
	v_mfma_f32_16x16x32_bf16 v[80:83], v[176:179], v[210:213], v[80:83]
	v_mfma_f32_16x16x32_bf16 v[68:71], v[148:151], v[218:221], v[68:71]
	v_mfma_f32_16x16x32_bf16 v[64:67], v[176:179], v[218:221], v[64:67]
	s_setprio 0
	s_barrier
	s_add_i32 s84, s79, s69
	v_lshl_add_u64 v[222:223], s[62:63], 0, v[154:155]
	s_mov_b32 m0, s84
	ds_read_b128 v[180:183], v191 offset:16384
	v_xor_b32_e32 v253, 64, v191
	ds_read_b128 v[194:197], v253 offset:16384
	ds_read_b128 v[198:201], v191 offset:18432
	ds_read_b128 v[202:205], v253 offset:18432
	ds_read_b128 v[206:209], v191 offset:20480
	ds_read_b128 v[210:213], v253 offset:20480
	ds_read_b128 v[214:217], v191 offset:22528
	ds_read_b128 v[218:221], v253 offset:22528
	global_load_lds_dwordx4 v[222:223], off
	s_add_i32 m0, s84, 0x2000
	s_add_u32 s84, s62, 0x80000
	v_lshl_add_u64 v[224:225], s[62:63], 0, v[162:163]
	s_addc_u32 s85, s63, 0
	s_add_i32 s86, s80, s69
	global_load_lds_dwordx4 v[224:225], off
	v_lshl_add_u64 v[226:227], s[84:85], 0, v[154:155]
	s_mov_b32 m0, s86
	v_lshl_add_u64 v[228:229], s[64:65], 0, v[160:161]
	global_load_lds_dwordx4 v[226:227], off
	v_lshl_add_u64 v[226:227], s[84:85], 0, v[162:163]
	s_add_i32 m0, s86, 0x2000
	s_nop 0
	global_load_lds_dwordx4 v[226:227], off
	v_lshl_add_u64 v[226:227], s[64:65], 0, v[152:153]
	s_mov_b32 m0, s70
	s_nop 0
	global_load_lds_dwordx4 v[226:227], off
	s_mov_b32 m0, s71
	s_nop 0
	global_load_lds_dwordx4 v[228:229], off
	s_waitcnt vmcnt(24)
	s_waitcnt lgkmcnt(0)
	s_barrier
	s_setprio 1
	s_waitcnt lgkmcnt(0)
	v_mfma_f32_16x16x32_bf16 v[60:63], v[128:131], v[180:183], 0
	v_mfma_f32_16x16x32_bf16 v[56:59], v[136:139], v[180:183], 0
	v_mfma_f32_16x16x32_bf16 v[44:47], v[128:131], v[198:201], 0
	v_mfma_f32_16x16x32_bf16 v[40:43], v[136:139], v[198:201], 0
	v_mfma_f32_16x16x32_bf16 v[28:31], v[128:131], v[206:209], 0
	v_mfma_f32_16x16x32_bf16 v[24:27], v[136:139], v[206:209], 0
	v_mfma_f32_16x16x32_bf16 v[12:15], v[128:131], v[214:217], 0
	v_mfma_f32_16x16x32_bf16 v[8:11], v[136:139], v[214:217], 0
	v_mfma_f32_16x16x32_bf16 v[60:63], v[132:135], v[194:197], v[60:63]
	v_mfma_f32_16x16x32_bf16 v[56:59], v[140:143], v[194:197], v[56:59]
	v_mfma_f32_16x16x32_bf16 v[44:47], v[132:135], v[202:205], v[44:47]
	v_mfma_f32_16x16x32_bf16 v[40:43], v[140:143], v[202:205], v[40:43]
	v_mfma_f32_16x16x32_bf16 v[28:31], v[132:135], v[210:213], v[28:31]
	v_mfma_f32_16x16x32_bf16 v[24:27], v[140:143], v[210:213], v[24:27]
	v_mfma_f32_16x16x32_bf16 v[12:15], v[132:135], v[218:221], v[12:15]
	v_mfma_f32_16x16x32_bf16 v[8:11], v[140:143], v[218:221], v[8:11]
	s_setprio 0
	s_setprio 1
	v_mfma_f32_16x16x32_bf16 v[52:55], v[144:147], v[180:183], 0
	v_mfma_f32_16x16x32_bf16 v[48:51], v[172:175], v[180:183], 0
	v_mfma_f32_16x16x32_bf16 v[36:39], v[144:147], v[198:201], 0
	v_mfma_f32_16x16x32_bf16 v[32:35], v[172:175], v[198:201], 0
	v_mfma_f32_16x16x32_bf16 v[20:23], v[144:147], v[206:209], 0
	v_mfma_f32_16x16x32_bf16 v[16:19], v[172:175], v[206:209], 0
	v_mfma_f32_16x16x32_bf16 v[4:7], v[144:147], v[214:217], 0
	v_mfma_f32_16x16x32_bf16 v[0:3], v[172:175], v[214:217], 0
	v_mfma_f32_16x16x32_bf16 v[52:55], v[148:151], v[194:197], v[52:55]
	v_mfma_f32_16x16x32_bf16 v[48:51], v[176:179], v[194:197], v[48:51]
	v_mfma_f32_16x16x32_bf16 v[36:39], v[148:151], v[202:205], v[36:39]
	v_mfma_f32_16x16x32_bf16 v[32:35], v[176:179], v[202:205], v[32:35]
	v_mfma_f32_16x16x32_bf16 v[20:23], v[148:151], v[210:213], v[20:23]
	v_mfma_f32_16x16x32_bf16 v[16:19], v[176:179], v[210:213], v[16:19]
	v_mfma_f32_16x16x32_bf16 v[4:7], v[148:151], v[218:221], v[4:7]
	v_mfma_f32_16x16x32_bf16 v[0:3], v[176:179], v[218:221], v[0:3]
	s_setprio 0
	s_barrier
	s_add_i32 s84, 0, 0x18000
	s_add_i32 s85, 0, 0x1c000
	v_add_u32_e32 v140, s84, v186
	v_add_u32_e32 v176, s85, v186
	ds_read_b128 v[128:131], v140
	v_xor_b32_e32 v253, 64, v140
	ds_read_b128 v[132:135], v253
	ds_read_b128 v[136:139], v140 offset:2048
	ds_read_b128 v[140:143], v253 offset:2048
	ds_read_b128 v[144:147], v176
	v_xor_b32_e32 v253, 64, v176
	ds_read_b128 v[148:151], v253
	ds_read_b128 v[172:175], v176 offset:2048
	ds_read_b128 v[176:179], v253 offset:2048
	s_add_u32 s64, s64, 0x80000
	s_addc_u32 s65, s65, 0
	s_mov_b32 m0, s72
	v_lshl_add_u64 v[230:231], s[64:65], 0, v[152:153]
	ds_read_b128 v[180:183], v191 offset:32768
	v_xor_b32_e32 v253, 64, v191
	ds_read_b128 v[194:197], v253 offset:32768
	ds_read_b128 v[198:201], v191 offset:34816
	ds_read_b128 v[202:205], v253 offset:34816
	ds_read_b128 v[206:209], v191 offset:36864
	ds_read_b128 v[210:213], v253 offset:36864
	ds_read_b128 v[214:217], v191 offset:38912
	ds_read_b128 v[218:221], v253 offset:38912
	global_load_lds_dwordx4 v[230:231], off
	v_lshl_add_u64 v[230:231], s[64:65], 0, v[160:161]
	s_mov_b32 m0, s73
	s_nop 0
	global_load_lds_dwordx4 v[230:231], off
	s_waitcnt vmcnt(8)
	s_waitcnt lgkmcnt(0)
	s_barrier
	s_setprio 1
	s_waitcnt lgkmcnt(0)
	v_mfma_f32_16x16x32_bf16 v[124:127], v[128:131], v[180:183], v[124:127]
	v_mfma_f32_16x16x32_bf16 v[124:127], v[132:135], v[194:197], v[124:127]
	v_mfma_f32_16x16x32_bf16 v[120:123], v[136:139], v[180:183], v[120:123]
	v_mfma_f32_16x16x32_bf16 v[120:123], v[140:143], v[194:197], v[120:123]
	v_mfma_f32_16x16x32_bf16 v[108:111], v[128:131], v[198:201], v[108:111]
	v_mfma_f32_16x16x32_bf16 v[108:111], v[132:135], v[202:205], v[108:111]
	v_mfma_f32_16x16x32_bf16 v[104:107], v[136:139], v[198:201], v[104:107]
	v_mfma_f32_16x16x32_bf16 v[104:107], v[140:143], v[202:205], v[104:107]
	v_mfma_f32_16x16x32_bf16 v[92:95], v[128:131], v[206:209], v[92:95]
	v_mfma_f32_16x16x32_bf16 v[92:95], v[132:135], v[210:213], v[92:95]
	v_mfma_f32_16x16x32_bf16 v[88:91], v[136:139], v[206:209], v[88:91]
	v_mfma_f32_16x16x32_bf16 v[88:91], v[140:143], v[210:213], v[88:91]
	v_mfma_f32_16x16x32_bf16 v[76:79], v[128:131], v[214:217], v[76:79]
	v_mfma_f32_16x16x32_bf16 v[76:79], v[132:135], v[218:221], v[76:79]
	v_mfma_f32_16x16x32_bf16 v[72:75], v[136:139], v[214:217], v[72:75]
	v_mfma_f32_16x16x32_bf16 v[72:75], v[140:143], v[218:221], v[72:75]
	s_setprio 0
	s_setprio 1
	v_mfma_f32_16x16x32_bf16 v[116:119], v[144:147], v[180:183], v[116:119]
	v_mfma_f32_16x16x32_bf16 v[116:119], v[148:151], v[194:197], v[116:119]
	v_mfma_f32_16x16x32_bf16 v[112:115], v[172:175], v[180:183], v[112:115]
	v_mfma_f32_16x16x32_bf16 v[112:115], v[176:179], v[194:197], v[112:115]
	v_mfma_f32_16x16x32_bf16 v[100:103], v[144:147], v[198:201], v[100:103]
	v_mfma_f32_16x16x32_bf16 v[100:103], v[148:151], v[202:205], v[100:103]
	v_mfma_f32_16x16x32_bf16 v[96:99], v[172:175], v[198:201], v[96:99]
	v_mfma_f32_16x16x32_bf16 v[96:99], v[176:179], v[202:205], v[96:99]
	v_mfma_f32_16x16x32_bf16 v[84:87], v[144:147], v[206:209], v[84:87]
	v_mfma_f32_16x16x32_bf16 v[84:87], v[148:151], v[210:213], v[84:87]
	v_mfma_f32_16x16x32_bf16 v[80:83], v[172:175], v[206:209], v[80:83]
	v_mfma_f32_16x16x32_bf16 v[80:83], v[176:179], v[210:213], v[80:83]
	v_mfma_f32_16x16x32_bf16 v[68:71], v[144:147], v[214:217], v[68:71]
	v_mfma_f32_16x16x32_bf16 v[68:71], v[148:151], v[218:221], v[68:71]
	v_mfma_f32_16x16x32_bf16 v[64:67], v[172:175], v[214:217], v[64:67]
	v_mfma_f32_16x16x32_bf16 v[64:67], v[176:179], v[218:221], v[64:67]
	s_setprio 0
	s_barrier
	s_add_i32 s64, s84, s69
	v_lshl_add_u64 v[222:223], v[222:223], 0, s[26:27]
	s_mov_b32 m0, s64
	ds_read_b128 v[180:183], v191 offset:49152
	v_xor_b32_e32 v253, 64, v191
	ds_read_b128 v[194:197], v253 offset:49152
	ds_read_b128 v[198:201], v191 offset:51200
	ds_read_b128 v[202:205], v253 offset:51200
	ds_read_b128 v[206:209], v191 offset:53248
	ds_read_b128 v[210:213], v253 offset:53248
	ds_read_b128 v[214:217], v191 offset:55296
	ds_read_b128 v[218:221], v253 offset:55296
	global_load_lds_dwordx4 v[222:223], off
	s_add_i32 m0, s64, 0x2000
	s_add_u32 s62, s62, 0x80080
	v_lshl_add_u64 v[222:223], v[224:225], 0, s[26:27]
	s_addc_u32 s63, s63, 0
	s_add_i32 s64, s85, s69
	global_load_lds_dwordx4 v[222:223], off
	v_lshl_add_u64 v[222:223], s[62:63], 0, v[154:155]
	s_mov_b32 m0, s64
	s_nop 0
	global_load_lds_dwordx4 v[222:223], off
	v_lshl_add_u64 v[222:223], s[62:63], 0, v[162:163]
	s_add_i32 m0, s64, 0x2000
	s_nop 0
	global_load_lds_dwordx4 v[222:223], off
	v_lshl_add_u64 v[222:223], v[226:227], 0, s[26:27]
	s_mov_b32 m0, s3
	s_nop 0
	global_load_lds_dwordx4 v[222:223], off
	v_lshl_add_u64 v[222:223], v[228:229], 0, s[26:27]
	s_mov_b32 m0, s75
	s_nop 0
	global_load_lds_dwordx4 v[222:223], off
	s_waitcnt vmcnt(8)
	s_waitcnt lgkmcnt(0)
	s_barrier
	s_setprio 1
	s_waitcnt lgkmcnt(0)
	v_mfma_f32_16x16x32_bf16 v[60:63], v[128:131], v[180:183], v[60:63]
	v_mfma_f32_16x16x32_bf16 v[60:63], v[132:135], v[194:197], v[60:63]
	v_mfma_f32_16x16x32_bf16 v[56:59], v[136:139], v[180:183], v[56:59]
	v_mfma_f32_16x16x32_bf16 v[56:59], v[140:143], v[194:197], v[56:59]
	v_mfma_f32_16x16x32_bf16 v[44:47], v[128:131], v[198:201], v[44:47]
	v_mfma_f32_16x16x32_bf16 v[44:47], v[132:135], v[202:205], v[44:47]
	v_mfma_f32_16x16x32_bf16 v[40:43], v[136:139], v[198:201], v[40:43]
	v_mfma_f32_16x16x32_bf16 v[40:43], v[140:143], v[202:205], v[40:43]
	v_mfma_f32_16x16x32_bf16 v[28:31], v[128:131], v[206:209], v[28:31]
	v_mfma_f32_16x16x32_bf16 v[28:31], v[132:135], v[210:213], v[28:31]
	v_mfma_f32_16x16x32_bf16 v[24:27], v[136:139], v[206:209], v[24:27]
	v_mfma_f32_16x16x32_bf16 v[24:27], v[140:143], v[210:213], v[24:27]
	v_mfma_f32_16x16x32_bf16 v[12:15], v[128:131], v[214:217], v[12:15]
	v_mfma_f32_16x16x32_bf16 v[12:15], v[132:135], v[218:221], v[12:15]
	v_mfma_f32_16x16x32_bf16 v[8:11], v[136:139], v[214:217], v[8:11]
	v_mfma_f32_16x16x32_bf16 v[8:11], v[140:143], v[218:221], v[8:11]
	s_setprio 0
	s_setprio 1
	v_mfma_f32_16x16x32_bf16 v[52:55], v[144:147], v[180:183], v[52:55]
	v_mfma_f32_16x16x32_bf16 v[52:55], v[148:151], v[194:197], v[52:55]
	v_mfma_f32_16x16x32_bf16 v[48:51], v[172:175], v[180:183], v[48:51]
	v_mfma_f32_16x16x32_bf16 v[48:51], v[176:179], v[194:197], v[48:51]
	v_mfma_f32_16x16x32_bf16 v[36:39], v[144:147], v[198:201], v[36:39]
	v_mfma_f32_16x16x32_bf16 v[36:39], v[148:151], v[202:205], v[36:39]
	v_mfma_f32_16x16x32_bf16 v[32:35], v[172:175], v[198:201], v[32:35]
	v_mfma_f32_16x16x32_bf16 v[32:35], v[176:179], v[202:205], v[32:35]
	v_mfma_f32_16x16x32_bf16 v[20:23], v[144:147], v[206:209], v[20:23]
	v_mfma_f32_16x16x32_bf16 v[20:23], v[148:151], v[210:213], v[20:23]
	v_mfma_f32_16x16x32_bf16 v[16:19], v[172:175], v[206:209], v[16:19]
	v_mfma_f32_16x16x32_bf16 v[16:19], v[176:179], v[210:213], v[16:19]
	v_mfma_f32_16x16x32_bf16 v[4:7], v[144:147], v[214:217], v[4:7]
	v_mfma_f32_16x16x32_bf16 v[4:7], v[148:151], v[218:221], v[4:7]
	v_mfma_f32_16x16x32_bf16 v[0:3], v[172:175], v[214:217], v[0:3]
	v_mfma_f32_16x16x32_bf16 v[0:3], v[176:179], v[218:221], v[0:3]
	s_setprio 0
	s_barrier
	s_add_i32 s83, s83, 2
	s_add_u32 s81, s81, 0x100
	s_addc_u32 s82, s82, 0
	s_add_u32 s60, s60, 0x100
	s_addc_u32 s61, s61, 0
	s_cmp_gt_u32 s83, 29
	s_branch .LBB0_440
.Lfa_3:
	ds_read_b128 v[128:131], v189
	v_xor_b32_e32 v253, 64, v189
	ds_read_b128 v[132:135], v253
	ds_read_b128 v[136:139], v189 offset:2048
	ds_read_b128 v[140:143], v253 offset:2048
	ds_read_b128 v[144:147], v190
	v_xor_b32_e32 v253, 64, v190
	ds_read_b128 v[148:151], v253
	ds_read_b128 v[172:175], v190 offset:2048
	ds_read_b128 v[176:179], v253 offset:2048
	s_add_u32 s62, s60, 0xfff80080
	s_addc_u32 s63, s61, -1
	s_cmp_eq_u32 s83, 28
	s_cselect_b32 s65, s15, s63
	s_cselect_b32 s64, s53, s62
	s_cselect_b32 s63, s51, s82
	s_cselect_b32 s62, s59, s81
	v_lshl_add_u64 v[222:223], s[60:61], 0, v[166:167]
	s_add_i32 m0, s70, 0xc000
	ds_read_b128 v[180:183], v191
	v_xor_b32_e32 v253, 64, v191
	ds_read_b128 v[194:197], v253
	ds_read_b128 v[198:201], v191 offset:2048
	ds_read_b128 v[202:205], v253 offset:2048
	ds_read_b128 v[206:209], v191 offset:4096
	ds_read_b128 v[210:213], v253 offset:4096
	ds_read_b128 v[214:217], v191 offset:6144
	ds_read_b128 v[218:221], v253 offset:6144
	global_load_lds_dwordx4 v[222:223], off
	v_lshl_add_u64 v[222:223], s[60:61], 0, v[164:165]
	s_add_i32 m0, s70, 0xe000
	s_nop 0
	global_load_lds_dwordx4 v[222:223], off
	s_waitcnt vmcnt(8)
	s_waitcnt lgkmcnt(0)
	s_barrier
	s_setprio 1
	s_waitcnt lgkmcnt(0)
	v_mfma_f32_16x16x32_bf16 v[124:127], v[128:131], v[180:183], 0
	v_mfma_f32_16x16x32_bf16 v[120:123], v[136:139], v[180:183], 0
	v_mfma_f32_16x16x32_bf16 v[108:111], v[128:131], v[198:201], 0
	v_mfma_f32_16x16x32_bf16 v[104:107], v[136:139], v[198:201], 0
	v_mfma_f32_16x16x32_bf16 v[92:95], v[128:131], v[206:209], 0
	v_mfma_f32_16x16x32_bf16 v[88:91], v[136:139], v[206:209], 0
	v_mfma_f32_16x16x32_bf16 v[76:79], v[128:131], v[214:217], 0
	v_mfma_f32_16x16x32_bf16 v[72:75], v[136:139], v[214:217], 0
	v_mfma_f32_16x16x32_bf16 v[124:127], v[132:135], v[194:197], v[124:127]
	v_mfma_f32_16x16x32_bf16 v[120:123], v[140:143], v[194:197], v[120:123]
	v_mfma_f32_16x16x32_bf16 v[108:111], v[132:135], v[202:205], v[108:111]
	v_mfma_f32_16x16x32_bf16 v[104:107], v[140:143], v[202:205], v[104:107]
	v_mfma_f32_16x16x32_bf16 v[92:95], v[132:135], v[210:213], v[92:95]
	v_mfma_f32_16x16x32_bf16 v[88:91], v[140:143], v[210:213], v[88:91]
	v_mfma_f32_16x16x32_bf16 v[76:79], v[132:135], v[218:221], v[76:79]
	v_mfma_f32_16x16x32_bf16 v[72:75], v[140:143], v[218:221], v[72:75]
	s_setprio 0
	s_setprio 1
	v_mfma_f32_16x16x32_bf16 v[116:119], v[144:147], v[180:183], 0
	v_mfma_f32_16x16x32_bf16 v[112:115], v[172:175], v[180:183], 0
	v_mfma_f32_16x16x32_bf16 v[100:103], v[144:147], v[198:201], 0
	v_mfma_f32_16x16x32_bf16 v[96:99], v[172:175], v[198:201], 0
	v_mfma_f32_16x16x32_bf16 v[84:87], v[144:147], v[206:209], 0
	v_mfma_f32_16x16x32_bf16 v[80:83], v[172:175], v[206:209], 0
	v_mfma_f32_16x16x32_bf16 v[68:71], v[144:147], v[214:217], 0
	v_mfma_f32_16x16x32_bf16 v[64:67], v[172:175], v[214:217], 0
	v_mfma_f32_16x16x32_bf16 v[116:119], v[148:151], v[194:197], v[116:119]
	v_mfma_f32_16x16x32_bf16 v[112:115], v[176:179], v[194:197], v[112:115]
	v_mfma_f32_16x16x32_bf16 v[100:103], v[148:151], v[202:205], v[100:103]
	v_mfma_f32_16x16x32_bf16 v[96:99], v[176:179], v[202:205], v[96:99]
	v_mfma_f32_16x16x32_bf16 v[84:87], v[148:151], v[210:213], v[84:87]
	v_mfma_f32_16x16x32_bf16 v[80:83], v[176:179], v[210:213], v[80:83]
	v_mfma_f32_16x16x32_bf16 v[68:71], v[148:151], v[218:221], v[68:71]
	v_mfma_f32_16x16x32_bf16 v[64:67], v[176:179], v[218:221], v[64:67]
	s_setprio 0
	s_barrier
	s_add_i32 s84, s79, s69
	v_lshl_add_u64 v[222:223], s[62:63], 0, v[154:155]
	s_mov_b32 m0, s84
	ds_read_b128 v[180:183], v191 offset:16384
	v_xor_b32_e32 v253, 64, v191
	ds_read_b128 v[194:197], v253 offset:16384
	ds_read_b128 v[198:201], v191 offset:18432
	ds_read_b128 v[202:205], v253 offset:18432
	ds_read_b128 v[206:209], v191 offset:20480
	ds_read_b128 v[210:213], v253 offset:20480
	ds_read_b128 v[214:217], v191 offset:22528
	ds_read_b128 v[218:221], v253 offset:22528
	global_load_lds_dwordx4 v[222:223], off
	s_add_i32 m0, s84, 0x2000
	s_add_u32 s84, s62, 0x80000
	v_lshl_add_u64 v[224:225], s[62:63], 0, v[162:163]
	s_addc_u32 s85, s63, 0
	s_add_i32 s86, s80, s69
	global_load_lds_dwordx4 v[224:225], off
	v_lshl_add_u64 v[226:227], s[84:85], 0, v[154:155]
	s_mov_b32 m0, s86
	v_lshl_add_u64 v[228:229], s[64:65], 0, v[160:161]
	global_load_lds_dwordx4 v[226:227], off
	v_lshl_add_u64 v[226:227], s[84:85], 0, v[162:163]
	s_add_i32 m0, s86, 0x2000
	s_nop 0
	global_load_lds_dwordx4 v[226:227], off
	v_lshl_add_u64 v[226:227], s[64:65], 0, v[152:153]
	s_mov_b32 m0, s70
	s_nop 0
	global_load_lds_dwordx4 v[226:227], off
	s_mov_b32 m0, s71
	s_nop 0
	global_load_lds_dwordx4 v[228:229], off
	s_waitcnt vmcnt(8)
	s_waitcnt lgkmcnt(0)
	s_barrier
	s_setprio 1
	s_waitcnt lgkmcnt(0)
	v_mfma_f32_16x16x32_bf16 v[60:63], v[128:131], v[180:183], 0
	v_mfma_f32_16x16x32_bf16 v[56:59], v[136:139], v[180:183], 0
	v_mfma_f32_16x16x32_bf16 v[44:47], v[128:131], v[198:201], 0
	v_mfma_f32_16x16x32_bf16 v[40:43], v[136:139], v[198:201], 0
	v_mfma_f32_16x16x32_bf16 v[28:31], v[128:131], v[206:209], 0
	v_mfma_f32_16x16x32_bf16 v[24:27], v[136:139], v[206:209], 0
	v_mfma_f32_16x16x32_bf16 v[12:15], v[128:131], v[214:217], 0
	v_mfma_f32_16x16x32_bf16 v[8:11], v[136:139], v[214:217], 0
	v_mfma_f32_16x16x32_bf16 v[60:63], v[132:135], v[194:197], v[60:63]
	v_mfma_f32_16x16x32_bf16 v[56:59], v[140:143], v[194:197], v[56:59]
	v_mfma_f32_16x16x32_bf16 v[44:47], v[132:135], v[202:205], v[44:47]
	v_mfma_f32_16x16x32_bf16 v[40:43], v[140:143], v[202:205], v[40:43]
	v_mfma_f32_16x16x32_bf16 v[28:31], v[132:135], v[210:213], v[28:31]
	v_mfma_f32_16x16x32_bf16 v[24:27], v[140:143], v[210:213], v[24:27]
	v_mfma_f32_16x16x32_bf16 v[12:15], v[132:135], v[218:221], v[12:15]
	v_mfma_f32_16x16x32_bf16 v[8:11], v[140:143], v[218:221], v[8:11]
	s_setprio 0
	s_setprio 1
	v_mfma_f32_16x16x32_bf16 v[52:55], v[144:147], v[180:183], 0
	v_mfma_f32_16x16x32_bf16 v[48:51], v[172:175], v[180:183], 0
	v_mfma_f32_16x16x32_bf16 v[36:39], v[144:147], v[198:201], 0
	v_mfma_f32_16x16x32_bf16 v[32:35], v[172:175], v[198:201], 0
	v_mfma_f32_16x16x32_bf16 v[20:23], v[144:147], v[206:209], 0
	v_mfma_f32_16x16x32_bf16 v[16:19], v[172:175], v[206:209], 0
	v_mfma_f32_16x16x32_bf16 v[4:7], v[144:147], v[214:217], 0
	v_mfma_f32_16x16x32_bf16 v[0:3], v[172:175], v[214:217], 0
	v_mfma_f32_16x16x32_bf16 v[52:55], v[148:151], v[194:197], v[52:55]
	v_mfma_f32_16x16x32_bf16 v[48:51], v[176:179], v[194:197], v[48:51]
	v_mfma_f32_16x16x32_bf16 v[36:39], v[148:151], v[202:205], v[36:39]
	v_mfma_f32_16x16x32_bf16 v[32:35], v[176:179], v[202:205], v[32:35]
	v_mfma_f32_16x16x32_bf16 v[20:23], v[148:151], v[210:213], v[20:23]
	v_mfma_f32_16x16x32_bf16 v[16:19], v[176:179], v[210:213], v[16:19]
	v_mfma_f32_16x16x32_bf16 v[4:7], v[148:151], v[218:221], v[4:7]
	v_mfma_f32_16x16x32_bf16 v[0:3], v[176:179], v[218:221], v[0:3]
	s_setprio 0
	s_barrier
	s_add_i32 s84, 0, 0x18000
	s_add_i32 s85, 0, 0x1c000
	v_add_u32_e32 v140, s84, v186
	v_add_u32_e32 v176, s85, v186
	ds_read_b128 v[128:131], v140
	v_xor_b32_e32 v253, 64, v140
	ds_read_b128 v[132:135], v253
	ds_read_b128 v[136:139], v140 offset:2048
	ds_read_b128 v[140:143], v253 offset:2048
	ds_read_b128 v[144:147], v176
	v_xor_b32_e32 v253, 64, v176
	ds_read_b128 v[148:151], v253
	ds_read_b128 v[172:175], v176 offset:2048
	ds_read_b128 v[176:179], v253 offset:2048
	s_add_u32 s64, s64, 0x80000
	s_addc_u32 s65, s65, 0
	s_mov_b32 m0, s72
	v_lshl_add_u64 v[230:231], s[64:65], 0, v[152:153]
	ds_read_b128 v[180:183], v191 offset:32768
	v_xor_b32_e32 v253, 64, v191
	ds_read_b128 v[194:197], v253 offset:32768
	ds_read_b128 v[198:201], v191 offset:34816
	ds_read_b128 v[202:205], v253 offset:34816
	ds_read_b128 v[206:209], v191 offset:36864
	ds_read_b128 v[210:213], v253 offset:36864
	ds_read_b128 v[214:217], v191 offset:38912
	ds_read_b128 v[218:221], v253 offset:38912
	global_load_lds_dwordx4 v[230:231], off
	v_lshl_add_u64 v[230:231], s[64:65], 0, v[160:161]
	s_mov_b32 m0, s73
	s_nop 0
	global_load_lds_dwordx4 v[230:231], off
	s_waitcnt vmcnt(8)
	s_waitcnt lgkmcnt(0)
	s_barrier
	s_setprio 1
	s_waitcnt lgkmcnt(0)
	v_mfma_f32_16x16x32_bf16 v[124:127], v[128:131], v[180:183], v[124:127]
	v_mfma_f32_16x16x32_bf16 v[124:127], v[132:135], v[194:197], v[124:127]
	v_mfma_f32_16x16x32_bf16 v[120:123], v[136:139], v[180:183], v[120:123]
	v_mfma_f32_16x16x32_bf16 v[120:123], v[140:143], v[194:197], v[120:123]
	v_mfma_f32_16x16x32_bf16 v[108:111], v[128:131], v[198:201], v[108:111]
	v_mfma_f32_16x16x32_bf16 v[108:111], v[132:135], v[202:205], v[108:111]
	v_mfma_f32_16x16x32_bf16 v[104:107], v[136:139], v[198:201], v[104:107]
	v_mfma_f32_16x16x32_bf16 v[104:107], v[140:143], v[202:205], v[104:107]
	v_mfma_f32_16x16x32_bf16 v[92:95], v[128:131], v[206:209], v[92:95]
	v_mfma_f32_16x16x32_bf16 v[92:95], v[132:135], v[210:213], v[92:95]
	v_mfma_f32_16x16x32_bf16 v[88:91], v[136:139], v[206:209], v[88:91]
	v_mfma_f32_16x16x32_bf16 v[88:91], v[140:143], v[210:213], v[88:91]
	v_mfma_f32_16x16x32_bf16 v[76:79], v[128:131], v[214:217], v[76:79]
	v_mfma_f32_16x16x32_bf16 v[76:79], v[132:135], v[218:221], v[76:79]
	v_mfma_f32_16x16x32_bf16 v[72:75], v[136:139], v[214:217], v[72:75]
	v_mfma_f32_16x16x32_bf16 v[72:75], v[140:143], v[218:221], v[72:75]
	s_setprio 0
	s_setprio 1
	v_mfma_f32_16x16x32_bf16 v[116:119], v[144:147], v[180:183], v[116:119]
	v_mfma_f32_16x16x32_bf16 v[116:119], v[148:151], v[194:197], v[116:119]
	v_mfma_f32_16x16x32_bf16 v[112:115], v[172:175], v[180:183], v[112:115]
	v_mfma_f32_16x16x32_bf16 v[112:115], v[176:179], v[194:197], v[112:115]
	v_mfma_f32_16x16x32_bf16 v[100:103], v[144:147], v[198:201], v[100:103]
	v_mfma_f32_16x16x32_bf16 v[100:103], v[148:151], v[202:205], v[100:103]
	v_mfma_f32_16x16x32_bf16 v[96:99], v[172:175], v[198:201], v[96:99]
	v_mfma_f32_16x16x32_bf16 v[96:99], v[176:179], v[202:205], v[96:99]
	v_mfma_f32_16x16x32_bf16 v[84:87], v[144:147], v[206:209], v[84:87]
	v_mfma_f32_16x16x32_bf16 v[84:87], v[148:151], v[210:213], v[84:87]
	v_mfma_f32_16x16x32_bf16 v[80:83], v[172:175], v[206:209], v[80:83]
	v_mfma_f32_16x16x32_bf16 v[80:83], v[176:179], v[210:213], v[80:83]
	v_mfma_f32_16x16x32_bf16 v[68:71], v[144:147], v[214:217], v[68:71]
	v_mfma_f32_16x16x32_bf16 v[68:71], v[148:151], v[218:221], v[68:71]
	v_mfma_f32_16x16x32_bf16 v[64:67], v[172:175], v[214:217], v[64:67]
	v_mfma_f32_16x16x32_bf16 v[64:67], v[176:179], v[218:221], v[64:67]
	s_setprio 0
	s_barrier
	s_add_i32 s64, s84, s69
	v_lshl_add_u64 v[222:223], v[222:223], 0, s[26:27]
	s_mov_b32 m0, s64
	ds_read_b128 v[180:183], v191 offset:49152
	v_xor_b32_e32 v253, 64, v191
	ds_read_b128 v[194:197], v253 offset:49152
	ds_read_b128 v[198:201], v191 offset:51200
	ds_read_b128 v[202:205], v253 offset:51200
	ds_read_b128 v[206:209], v191 offset:53248
	ds_read_b128 v[210:213], v253 offset:53248
	ds_read_b128 v[214:217], v191 offset:55296
	ds_read_b128 v[218:221], v253 offset:55296
	global_load_lds_dwordx4 v[222:223], off
	s_add_i32 m0, s64, 0x2000
	s_add_u32 s62, s62, 0x80080
	v_lshl_add_u64 v[222:223], v[224:225], 0, s[26:27]
	s_addc_u32 s63, s63, 0
	s_add_i32 s64, s85, s69
	global_load_lds_dwordx4 v[222:223], off
	v_lshl_add_u64 v[222:223], s[62:63], 0, v[154:155]
	s_mov_b32 m0, s64
	s_nop 0
	global_load_lds_dwordx4 v[222:223], off
	v_lshl_add_u64 v[222:223], s[62:63], 0, v[162:163]
	s_add_i32 m0, s64, 0x2000
	s_nop 0
	global_load_lds_dwordx4 v[222:223], off
	v_lshl_add_u64 v[222:223], v[226:227], 0, s[26:27]
	s_mov_b32 m0, s3
	s_nop 0
	global_load_lds_dwordx4 v[222:223], off
	v_lshl_add_u64 v[222:223], v[228:229], 0, s[26:27]
	s_mov_b32 m0, s75
	s_nop 0
	global_load_lds_dwordx4 v[222:223], off
	s_waitcnt vmcnt(8)
	s_waitcnt lgkmcnt(0)
	s_barrier
	s_setprio 1
	s_waitcnt lgkmcnt(0)
	v_mfma_f32_16x16x32_bf16 v[60:63], v[128:131], v[180:183], v[60:63]
	v_mfma_f32_16x16x32_bf16 v[60:63], v[132:135], v[194:197], v[60:63]
	v_mfma_f32_16x16x32_bf16 v[56:59], v[136:139], v[180:183], v[56:59]
	v_mfma_f32_16x16x32_bf16 v[56:59], v[140:143], v[194:197], v[56:59]
	v_mfma_f32_16x16x32_bf16 v[44:47], v[128:131], v[198:201], v[44:47]
	v_mfma_f32_16x16x32_bf16 v[44:47], v[132:135], v[202:205], v[44:47]
	v_mfma_f32_16x16x32_bf16 v[40:43], v[136:139], v[198:201], v[40:43]
	v_mfma_f32_16x16x32_bf16 v[40:43], v[140:143], v[202:205], v[40:43]
	v_mfma_f32_16x16x32_bf16 v[28:31], v[128:131], v[206:209], v[28:31]
	v_mfma_f32_16x16x32_bf16 v[28:31], v[132:135], v[210:213], v[28:31]
	v_mfma_f32_16x16x32_bf16 v[24:27], v[136:139], v[206:209], v[24:27]
	v_mfma_f32_16x16x32_bf16 v[24:27], v[140:143], v[210:213], v[24:27]
	v_mfma_f32_16x16x32_bf16 v[12:15], v[128:131], v[214:217], v[12:15]
	v_mfma_f32_16x16x32_bf16 v[12:15], v[132:135], v[218:221], v[12:15]
	v_mfma_f32_16x16x32_bf16 v[8:11], v[136:139], v[214:217], v[8:11]
	v_mfma_f32_16x16x32_bf16 v[8:11], v[140:143], v[218:221], v[8:11]
	s_setprio 0
	s_setprio 1
	v_mfma_f32_16x16x32_bf16 v[52:55], v[144:147], v[180:183], v[52:55]
	v_mfma_f32_16x16x32_bf16 v[52:55], v[148:151], v[194:197], v[52:55]
	v_mfma_f32_16x16x32_bf16 v[48:51], v[172:175], v[180:183], v[48:51]
	v_mfma_f32_16x16x32_bf16 v[48:51], v[176:179], v[194:197], v[48:51]
	v_mfma_f32_16x16x32_bf16 v[36:39], v[144:147], v[198:201], v[36:39]
	v_mfma_f32_16x16x32_bf16 v[36:39], v[148:151], v[202:205], v[36:39]
	v_mfma_f32_16x16x32_bf16 v[32:35], v[172:175], v[198:201], v[32:35]
	v_mfma_f32_16x16x32_bf16 v[32:35], v[176:179], v[202:205], v[32:35]
	v_mfma_f32_16x16x32_bf16 v[20:23], v[144:147], v[206:209], v[20:23]
	v_mfma_f32_16x16x32_bf16 v[20:23], v[148:151], v[210:213], v[20:23]
	v_mfma_f32_16x16x32_bf16 v[16:19], v[172:175], v[206:209], v[16:19]
	v_mfma_f32_16x16x32_bf16 v[16:19], v[176:179], v[210:213], v[16:19]
	v_mfma_f32_16x16x32_bf16 v[4:7], v[144:147], v[214:217], v[4:7]
	v_mfma_f32_16x16x32_bf16 v[4:7], v[148:151], v[218:221], v[4:7]
	v_mfma_f32_16x16x32_bf16 v[0:3], v[172:175], v[214:217], v[0:3]
	v_mfma_f32_16x16x32_bf16 v[0:3], v[176:179], v[218:221], v[0:3]
	s_setprio 0
	s_barrier
	s_add_i32 s83, s83, 2
	s_add_u32 s81, s81, 0x100
	s_addc_u32 s82, s82, 0
	s_add_u32 s60, s60, 0x100
	s_addc_u32 s61, s61, 0
	s_cmp_gt_u32 s83, 29
.LBB0_440:
	ds_read_b128 v[128:131], v189
	v_xor_b32_e32 v253, 64, v189
	ds_read_b128 v[132:135], v253
	ds_read_b128 v[136:139], v189 offset:2048
	ds_read_b128 v[140:143], v253 offset:2048
	ds_read_b128 v[144:147], v190
	v_xor_b32_e32 v253, 64, v190
	ds_read_b128 v[148:151], v253
	ds_read_b128 v[172:175], v190 offset:2048
	ds_read_b128 v[176:179], v253 offset:2048
	s_add_u32 s62, s60, 0xfff80080
	s_addc_u32 s63, s61, -1
	s_cmp_eq_u32 s83, 28
	s_cselect_b32 s65, s15, s63
	s_cselect_b32 s64, s53, s62
	s_cselect_b32 s63, s51, s82
	s_cselect_b32 s62, s59, s81
	v_lshl_add_u64 v[222:223], s[60:61], 0, v[166:167]
	s_add_i32 m0, s70, 0xc000
	ds_read_b128 v[180:183], v191
	v_xor_b32_e32 v253, 64, v191
	ds_read_b128 v[194:197], v253
	ds_read_b128 v[198:201], v191 offset:2048
	ds_read_b128 v[202:205], v253 offset:2048
	ds_read_b128 v[206:209], v191 offset:4096
	ds_read_b128 v[210:213], v253 offset:4096
	ds_read_b128 v[214:217], v191 offset:6144
	ds_read_b128 v[218:221], v253 offset:6144
	global_load_lds_dwordx4 v[222:223], off
	v_lshl_add_u64 v[222:223], s[60:61], 0, v[164:165]
	s_add_i32 m0, s70, 0xe000
	s_nop 0
	global_load_lds_dwordx4 v[222:223], off
	s_waitcnt vmcnt(8)
	s_waitcnt lgkmcnt(0)
	s_barrier
	s_setprio 1
	s_waitcnt lgkmcnt(0)
	v_mfma_f32_16x16x32_bf16 v[124:127], v[128:131], v[180:183], v[124:127]
	v_mfma_f32_16x16x32_bf16 v[124:127], v[132:135], v[194:197], v[124:127]
	v_mfma_f32_16x16x32_bf16 v[120:123], v[136:139], v[180:183], v[120:123]
	v_mfma_f32_16x16x32_bf16 v[120:123], v[140:143], v[194:197], v[120:123]
	v_mfma_f32_16x16x32_bf16 v[108:111], v[128:131], v[198:201], v[108:111]
	v_mfma_f32_16x16x32_bf16 v[108:111], v[132:135], v[202:205], v[108:111]
	v_mfma_f32_16x16x32_bf16 v[104:107], v[136:139], v[198:201], v[104:107]
	v_mfma_f32_16x16x32_bf16 v[104:107], v[140:143], v[202:205], v[104:107]
	v_mfma_f32_16x16x32_bf16 v[92:95], v[128:131], v[206:209], v[92:95]
	v_mfma_f32_16x16x32_bf16 v[92:95], v[132:135], v[210:213], v[92:95]
	v_mfma_f32_16x16x32_bf16 v[88:91], v[136:139], v[206:209], v[88:91]
	v_mfma_f32_16x16x32_bf16 v[88:91], v[140:143], v[210:213], v[88:91]
	v_mfma_f32_16x16x32_bf16 v[76:79], v[128:131], v[214:217], v[76:79]
	v_mfma_f32_16x16x32_bf16 v[76:79], v[132:135], v[218:221], v[76:79]
	v_mfma_f32_16x16x32_bf16 v[72:75], v[136:139], v[214:217], v[72:75]
	v_mfma_f32_16x16x32_bf16 v[72:75], v[140:143], v[218:221], v[72:75]
	s_setprio 0
	s_setprio 1
	v_mfma_f32_16x16x32_bf16 v[116:119], v[144:147], v[180:183], v[116:119]
	v_mfma_f32_16x16x32_bf16 v[116:119], v[148:151], v[194:197], v[116:119]
	v_mfma_f32_16x16x32_bf16 v[112:115], v[172:175], v[180:183], v[112:115]
	v_mfma_f32_16x16x32_bf16 v[112:115], v[176:179], v[194:197], v[112:115]
	v_mfma_f32_16x16x32_bf16 v[100:103], v[144:147], v[198:201], v[100:103]
	v_mfma_f32_16x16x32_bf16 v[100:103], v[148:151], v[202:205], v[100:103]
	v_mfma_f32_16x16x32_bf16 v[96:99], v[172:175], v[198:201], v[96:99]
	v_mfma_f32_16x16x32_bf16 v[96:99], v[176:179], v[202:205], v[96:99]
	v_mfma_f32_16x16x32_bf16 v[84:87], v[144:147], v[206:209], v[84:87]
	v_mfma_f32_16x16x32_bf16 v[84:87], v[148:151], v[210:213], v[84:87]
	v_mfma_f32_16x16x32_bf16 v[80:83], v[172:175], v[206:209], v[80:83]
	v_mfma_f32_16x16x32_bf16 v[80:83], v[176:179], v[210:213], v[80:83]
	v_mfma_f32_16x16x32_bf16 v[68:71], v[144:147], v[214:217], v[68:71]
	v_mfma_f32_16x16x32_bf16 v[68:71], v[148:151], v[218:221], v[68:71]
	v_mfma_f32_16x16x32_bf16 v[64:67], v[172:175], v[214:217], v[64:67]
	v_mfma_f32_16x16x32_bf16 v[64:67], v[176:179], v[218:221], v[64:67]
	s_setprio 0
	s_barrier
	s_add_i32 s84, s79, s69
	v_lshl_add_u64 v[222:223], s[62:63], 0, v[154:155]
	s_mov_b32 m0, s84
	ds_read_b128 v[180:183], v191 offset:16384
	v_xor_b32_e32 v253, 64, v191
	ds_read_b128 v[194:197], v253 offset:16384
	ds_read_b128 v[198:201], v191 offset:18432
	ds_read_b128 v[202:205], v253 offset:18432
	ds_read_b128 v[206:209], v191 offset:20480
	ds_read_b128 v[210:213], v253 offset:20480
	ds_read_b128 v[214:217], v191 offset:22528
	ds_read_b128 v[218:221], v253 offset:22528
	global_load_lds_dwordx4 v[222:223], off
	s_add_i32 m0, s84, 0x2000
	s_add_u32 s84, s62, 0x80000
	v_lshl_add_u64 v[224:225], s[62:63], 0, v[162:163]
	s_addc_u32 s85, s63, 0
	s_add_i32 s86, s80, s69
	global_load_lds_dwordx4 v[224:225], off
	v_lshl_add_u64 v[226:227], s[84:85], 0, v[154:155]
	s_mov_b32 m0, s86
	v_lshl_add_u64 v[228:229], s[64:65], 0, v[160:161]
	global_load_lds_dwordx4 v[226:227], off
	v_lshl_add_u64 v[226:227], s[84:85], 0, v[162:163]
	s_add_i32 m0, s86, 0x2000
	s_nop 0
	global_load_lds_dwordx4 v[226:227], off
	v_lshl_add_u64 v[226:227], s[64:65], 0, v[152:153]
	s_mov_b32 m0, s70
	s_nop 0
	global_load_lds_dwordx4 v[226:227], off
	s_mov_b32 m0, s71
	s_nop 0
	global_load_lds_dwordx4 v[228:229], off
	s_waitcnt vmcnt(8)
	s_waitcnt lgkmcnt(0)
	s_barrier
	s_setprio 1
	s_waitcnt lgkmcnt(0)
	v_mfma_f32_16x16x32_bf16 v[60:63], v[128:131], v[180:183], v[60:63]
	v_mfma_f32_16x16x32_bf16 v[60:63], v[132:135], v[194:197], v[60:63]
	v_mfma_f32_16x16x32_bf16 v[56:59], v[136:139], v[180:183], v[56:59]
	v_mfma_f32_16x16x32_bf16 v[56:59], v[140:143], v[194:197], v[56:59]
	v_mfma_f32_16x16x32_bf16 v[44:47], v[128:131], v[198:201], v[44:47]
	v_mfma_f32_16x16x32_bf16 v[44:47], v[132:135], v[202:205], v[44:47]
	v_mfma_f32_16x16x32_bf16 v[40:43], v[136:139], v[198:201], v[40:43]
	v_mfma_f32_16x16x32_bf16 v[40:43], v[140:143], v[202:205], v[40:43]
	v_mfma_f32_16x16x32_bf16 v[28:31], v[128:131], v[206:209], v[28:31]
	v_mfma_f32_16x16x32_bf16 v[28:31], v[132:135], v[210:213], v[28:31]
	v_mfma_f32_16x16x32_bf16 v[24:27], v[136:139], v[206:209], v[24:27]
	v_mfma_f32_16x16x32_bf16 v[24:27], v[140:143], v[210:213], v[24:27]
	v_mfma_f32_16x16x32_bf16 v[12:15], v[128:131], v[214:217], v[12:15]
	v_mfma_f32_16x16x32_bf16 v[12:15], v[132:135], v[218:221], v[12:15]
	v_mfma_f32_16x16x32_bf16 v[8:11], v[136:139], v[214:217], v[8:11]
	v_mfma_f32_16x16x32_bf16 v[8:11], v[140:143], v[218:221], v[8:11]
	s_setprio 0
	s_setprio 1
	v_mfma_f32_16x16x32_bf16 v[52:55], v[144:147], v[180:183], v[52:55]
	v_mfma_f32_16x16x32_bf16 v[52:55], v[148:151], v[194:197], v[52:55]
	v_mfma_f32_16x16x32_bf16 v[48:51], v[172:175], v[180:183], v[48:51]
	v_mfma_f32_16x16x32_bf16 v[48:51], v[176:179], v[194:197], v[48:51]
	v_mfma_f32_16x16x32_bf16 v[36:39], v[144:147], v[198:201], v[36:39]
	v_mfma_f32_16x16x32_bf16 v[36:39], v[148:151], v[202:205], v[36:39]
	v_mfma_f32_16x16x32_bf16 v[32:35], v[172:175], v[198:201], v[32:35]
	v_mfma_f32_16x16x32_bf16 v[32:35], v[176:179], v[202:205], v[32:35]
	v_mfma_f32_16x16x32_bf16 v[20:23], v[144:147], v[206:209], v[20:23]
	v_mfma_f32_16x16x32_bf16 v[20:23], v[148:151], v[210:213], v[20:23]
	v_mfma_f32_16x16x32_bf16 v[16:19], v[172:175], v[206:209], v[16:19]
	v_mfma_f32_16x16x32_bf16 v[16:19], v[176:179], v[210:213], v[16:19]
	v_mfma_f32_16x16x32_bf16 v[4:7], v[144:147], v[214:217], v[4:7]
	v_mfma_f32_16x16x32_bf16 v[4:7], v[148:151], v[218:221], v[4:7]
	v_mfma_f32_16x16x32_bf16 v[0:3], v[172:175], v[214:217], v[0:3]
	v_mfma_f32_16x16x32_bf16 v[0:3], v[176:179], v[218:221], v[0:3]
	s_setprio 0
	s_barrier
	s_add_i32 s84, 0, 0x18000
	s_add_i32 s85, 0, 0x1c000
	v_add_u32_e32 v140, s84, v186
	v_add_u32_e32 v176, s85, v186
	ds_read_b128 v[128:131], v140
	v_xor_b32_e32 v253, 64, v140
	ds_read_b128 v[132:135], v253
	ds_read_b128 v[136:139], v140 offset:2048
	ds_read_b128 v[140:143], v253 offset:2048
	ds_read_b128 v[144:147], v176
	v_xor_b32_e32 v253, 64, v176
	ds_read_b128 v[148:151], v253
	ds_read_b128 v[172:175], v176 offset:2048
	ds_read_b128 v[176:179], v253 offset:2048
	s_add_u32 s64, s64, 0x80000
	s_addc_u32 s65, s65, 0
	s_mov_b32 m0, s72
	v_lshl_add_u64 v[230:231], s[64:65], 0, v[152:153]
	ds_read_b128 v[180:183], v191 offset:32768
	v_xor_b32_e32 v253, 64, v191
	ds_read_b128 v[194:197], v253 offset:32768
	ds_read_b128 v[198:201], v191 offset:34816
	ds_read_b128 v[202:205], v253 offset:34816
	ds_read_b128 v[206:209], v191 offset:36864
	ds_read_b128 v[210:213], v253 offset:36864
	ds_read_b128 v[214:217], v191 offset:38912
	ds_read_b128 v[218:221], v253 offset:38912
	global_load_lds_dwordx4 v[230:231], off
	v_lshl_add_u64 v[230:231], s[64:65], 0, v[160:161]
	s_mov_b32 m0, s73
	s_nop 0
	global_load_lds_dwordx4 v[230:231], off
	s_waitcnt vmcnt(8)
	s_waitcnt lgkmcnt(0)
	s_barrier
	s_setprio 1
	s_waitcnt lgkmcnt(0)
	v_mfma_f32_16x16x32_bf16 v[124:127], v[128:131], v[180:183], v[124:127]
	v_mfma_f32_16x16x32_bf16 v[124:127], v[132:135], v[194:197], v[124:127]
	v_mfma_f32_16x16x32_bf16 v[120:123], v[136:139], v[180:183], v[120:123]
	v_mfma_f32_16x16x32_bf16 v[120:123], v[140:143], v[194:197], v[120:123]
	v_mfma_f32_16x16x32_bf16 v[108:111], v[128:131], v[198:201], v[108:111]
	v_mfma_f32_16x16x32_bf16 v[108:111], v[132:135], v[202:205], v[108:111]
	v_mfma_f32_16x16x32_bf16 v[104:107], v[136:139], v[198:201], v[104:107]
	v_mfma_f32_16x16x32_bf16 v[104:107], v[140:143], v[202:205], v[104:107]
	v_mfma_f32_16x16x32_bf16 v[92:95], v[128:131], v[206:209], v[92:95]
	v_mfma_f32_16x16x32_bf16 v[92:95], v[132:135], v[210:213], v[92:95]
	v_mfma_f32_16x16x32_bf16 v[88:91], v[136:139], v[206:209], v[88:91]
	v_mfma_f32_16x16x32_bf16 v[88:91], v[140:143], v[210:213], v[88:91]
	v_mfma_f32_16x16x32_bf16 v[76:79], v[128:131], v[214:217], v[76:79]
	v_mfma_f32_16x16x32_bf16 v[76:79], v[132:135], v[218:221], v[76:79]
	v_mfma_f32_16x16x32_bf16 v[72:75], v[136:139], v[214:217], v[72:75]
	v_mfma_f32_16x16x32_bf16 v[72:75], v[140:143], v[218:221], v[72:75]
	s_setprio 0
	s_setprio 1
	v_mfma_f32_16x16x32_bf16 v[116:119], v[144:147], v[180:183], v[116:119]
	v_mfma_f32_16x16x32_bf16 v[116:119], v[148:151], v[194:197], v[116:119]
	v_mfma_f32_16x16x32_bf16 v[112:115], v[172:175], v[180:183], v[112:115]
	v_mfma_f32_16x16x32_bf16 v[112:115], v[176:179], v[194:197], v[112:115]
	v_mfma_f32_16x16x32_bf16 v[100:103], v[144:147], v[198:201], v[100:103]
	v_mfma_f32_16x16x32_bf16 v[100:103], v[148:151], v[202:205], v[100:103]
	v_mfma_f32_16x16x32_bf16 v[96:99], v[172:175], v[198:201], v[96:99]
	v_mfma_f32_16x16x32_bf16 v[96:99], v[176:179], v[202:205], v[96:99]
	v_mfma_f32_16x16x32_bf16 v[84:87], v[144:147], v[206:209], v[84:87]
	v_mfma_f32_16x16x32_bf16 v[84:87], v[148:151], v[210:213], v[84:87]
	v_mfma_f32_16x16x32_bf16 v[80:83], v[172:175], v[206:209], v[80:83]
	v_mfma_f32_16x16x32_bf16 v[80:83], v[176:179], v[210:213], v[80:83]
	v_mfma_f32_16x16x32_bf16 v[68:71], v[144:147], v[214:217], v[68:71]
	v_mfma_f32_16x16x32_bf16 v[68:71], v[148:151], v[218:221], v[68:71]
	v_mfma_f32_16x16x32_bf16 v[64:67], v[172:175], v[214:217], v[64:67]
	v_mfma_f32_16x16x32_bf16 v[64:67], v[176:179], v[218:221], v[64:67]
	s_setprio 0
	s_barrier
	s_add_i32 s64, s84, s69
	v_lshl_add_u64 v[222:223], v[222:223], 0, s[26:27]
	s_mov_b32 m0, s64
	ds_read_b128 v[180:183], v191 offset:49152
	v_xor_b32_e32 v253, 64, v191
	ds_read_b128 v[194:197], v253 offset:49152
	ds_read_b128 v[198:201], v191 offset:51200
	ds_read_b128 v[202:205], v253 offset:51200
	ds_read_b128 v[206:209], v191 offset:53248
	ds_read_b128 v[210:213], v253 offset:53248
	ds_read_b128 v[214:217], v191 offset:55296
	ds_read_b128 v[218:221], v253 offset:55296
	global_load_lds_dwordx4 v[222:223], off
	s_add_i32 m0, s64, 0x2000
	s_add_u32 s62, s62, 0x80080
	v_lshl_add_u64 v[222:223], v[224:225], 0, s[26:27]
	s_addc_u32 s63, s63, 0
	s_add_i32 s64, s85, s69
	global_load_lds_dwordx4 v[222:223], off
	v_lshl_add_u64 v[222:223], s[62:63], 0, v[154:155]
	s_mov_b32 m0, s64
	s_nop 0
	global_load_lds_dwordx4 v[222:223], off
	v_lshl_add_u64 v[222:223], s[62:63], 0, v[162:163]
	s_add_i32 m0, s64, 0x2000
	s_nop 0
	global_load_lds_dwordx4 v[222:223], off
	v_lshl_add_u64 v[222:223], v[226:227], 0, s[26:27]
	s_mov_b32 m0, s3
	s_nop 0
	global_load_lds_dwordx4 v[222:223], off
	v_lshl_add_u64 v[222:223], v[228:229], 0, s[26:27]
	s_mov_b32 m0, s75
	s_nop 0
	global_load_lds_dwordx4 v[222:223], off
	s_waitcnt vmcnt(8)
	s_waitcnt lgkmcnt(0)
	s_barrier
	s_setprio 1
	s_waitcnt lgkmcnt(0)
	v_mfma_f32_16x16x32_bf16 v[60:63], v[128:131], v[180:183], v[60:63]
	v_mfma_f32_16x16x32_bf16 v[60:63], v[132:135], v[194:197], v[60:63]
	v_mfma_f32_16x16x32_bf16 v[56:59], v[136:139], v[180:183], v[56:59]
	v_mfma_f32_16x16x32_bf16 v[56:59], v[140:143], v[194:197], v[56:59]
	v_mfma_f32_16x16x32_bf16 v[44:47], v[128:131], v[198:201], v[44:47]
	v_mfma_f32_16x16x32_bf16 v[44:47], v[132:135], v[202:205], v[44:47]
	v_mfma_f32_16x16x32_bf16 v[40:43], v[136:139], v[198:201], v[40:43]
	v_mfma_f32_16x16x32_bf16 v[40:43], v[140:143], v[202:205], v[40:43]
	v_mfma_f32_16x16x32_bf16 v[28:31], v[128:131], v[206:209], v[28:31]
	v_mfma_f32_16x16x32_bf16 v[28:31], v[132:135], v[210:213], v[28:31]
	v_mfma_f32_16x16x32_bf16 v[24:27], v[136:139], v[206:209], v[24:27]
	v_mfma_f32_16x16x32_bf16 v[24:27], v[140:143], v[210:213], v[24:27]
	v_mfma_f32_16x16x32_bf16 v[12:15], v[128:131], v[214:217], v[12:15]
	v_mfma_f32_16x16x32_bf16 v[12:15], v[132:135], v[218:221], v[12:15]
	v_mfma_f32_16x16x32_bf16 v[8:11], v[136:139], v[214:217], v[8:11]
	v_mfma_f32_16x16x32_bf16 v[8:11], v[140:143], v[218:221], v[8:11]
	s_setprio 0
	s_setprio 1
	v_mfma_f32_16x16x32_bf16 v[52:55], v[144:147], v[180:183], v[52:55]
	v_mfma_f32_16x16x32_bf16 v[52:55], v[148:151], v[194:197], v[52:55]
	v_mfma_f32_16x16x32_bf16 v[48:51], v[172:175], v[180:183], v[48:51]
	v_mfma_f32_16x16x32_bf16 v[48:51], v[176:179], v[194:197], v[48:51]
	v_mfma_f32_16x16x32_bf16 v[36:39], v[144:147], v[198:201], v[36:39]
	v_mfma_f32_16x16x32_bf16 v[36:39], v[148:151], v[202:205], v[36:39]
	v_mfma_f32_16x16x32_bf16 v[32:35], v[172:175], v[198:201], v[32:35]
	v_mfma_f32_16x16x32_bf16 v[32:35], v[176:179], v[202:205], v[32:35]
	v_mfma_f32_16x16x32_bf16 v[20:23], v[144:147], v[206:209], v[20:23]
	v_mfma_f32_16x16x32_bf16 v[20:23], v[148:151], v[210:213], v[20:23]
	v_mfma_f32_16x16x32_bf16 v[16:19], v[172:175], v[206:209], v[16:19]
	v_mfma_f32_16x16x32_bf16 v[16:19], v[176:179], v[210:213], v[16:19]
	v_mfma_f32_16x16x32_bf16 v[4:7], v[144:147], v[214:217], v[4:7]
	v_mfma_f32_16x16x32_bf16 v[4:7], v[148:151], v[218:221], v[4:7]
	v_mfma_f32_16x16x32_bf16 v[0:3], v[172:175], v[214:217], v[0:3]
	v_mfma_f32_16x16x32_bf16 v[0:3], v[176:179], v[218:221], v[0:3]
	s_setprio 0
	s_barrier
	s_add_i32 s83, s83, 2
	s_add_u32 s81, s81, 0x100
	s_addc_u32 s82, s82, 0
	s_add_u32 s60, s60, 0x100
	s_addc_u32 s61, s61, 0
	s_cmp_gt_u32 s83, 29
	s_cbranch_scc0 .LBB0_440
	s_and_b64 vcc, exec, s[28:29]
	s_cbranch_vccz .LBB0_443
	s_barrier

.LBB0_525:
	s_ashr_i32 s29, s28, 31
	s_lshl_b64 s[30:31], s[28:29], 19
	s_add_u32 s30, s3, s30
	s_addc_u32 s31, s35, s31
	s_and_b64 s[44:45], s[10:11], exec
	s_cselect_b32 s29, s31, s51
	s_cselect_b32 s70, s30, s50
	s_ashr_i32 s27, s26, 31
	s_lshl_b64 s[44:45], s[26:27], 19
	s_add_u32 s44, s52, s44
	s_addc_u32 s45, s53, s45
	s_and_b64 s[72:73], s[10:11], exec
	s_cselect_b32 s71, s45, s49
	s_cselect_b32 s72, s44, s48
	s_lshl_b32 s27, s46, 8
	v_add_u32_e32 v0, s27, v148
	s_add_u32 s73, s48, 0x100
	v_ashrrev_i32_e32 v1, 31, v0
	s_addc_u32 s74, s49, 0
	v_lshl_add_u64 v[144:145], v[0:1], 4, s[16:17]
	s_add_u32 s46, s50, 0x40080
	s_addc_u32 s47, s51, 0
	s_mov_b32 s75, -2
	s_mov_b64 s[48:49], 0
	s_cmp_eq_u32 s61, 1
	s_cbranch_scc1 .Lfa_4
	v_add_u32_e32 v153, s66, v147
	ds_read_b128 v[160:163], v153
	v_xor_b32_e32 v253, 64, v153
	ds_read_b128 v[164:167], v253
	ds_read_b128 v[168:171], v153 offset:2048
	ds_read_b128 v[172:175], v253 offset:2048
	v_add_u32_e32 v153, s67, v147
	ds_read_b128 v[176:179], v153
	v_xor_b32_e32 v253, 64, v153
	ds_read_b128 v[180:183], v253
	ds_read_b128 v[186:189], v153 offset:2048
	ds_read_b128 v[190:193], v253 offset:2048
	s_add_u32 s50, s46, 0xfffc0080
	s_addc_u32 s51, s47, -1
	s_and_b64 s[48:49], s[48:49], exec
	s_cselect_b32 s51, s29, s51
	s_cselect_b32 s50, s70, s50
	s_cselect_b32 s49, s71, s74
	s_cselect_b32 s48, s72, s73
	v_lshl_add_u64 v[154:155], s[46:47], 0, v[138:139]
	s_add_i32 m0, s57, 0xc000
	ds_read_b128 v[194:197], v150
	v_xor_b32_e32 v253, 64, v150
	ds_read_b128 v[198:201], v253
	ds_read_b128 v[202:205], v150 offset:2048
	ds_read_b128 v[206:209], v253 offset:2048
	ds_read_b128 v[210:213], v150 offset:4096
	ds_read_b128 v[214:217], v253 offset:4096
	ds_read_b128 v[218:221], v150 offset:6144
	ds_read_b128 v[222:225], v253 offset:6144
	global_load_lds_dwordx4 v[154:155], off
	v_lshl_add_u64 v[154:155], s[46:47], 0, v[136:137]
	s_add_i32 m0, s57, 0xe000
	s_nop 0
	global_load_lds_dwordx4 v[154:155], off
	s_waitcnt vmcnt(16)
	s_waitcnt lgkmcnt(0)
	s_barrier
	s_setprio 1
	s_waitcnt lgkmcnt(0)
	v_mfma_f32_16x16x32_bf16 v[124:127], v[160:163], v[194:197], 0
	v_mfma_f32_16x16x32_bf16 v[116:119], v[168:171], v[194:197], 0
	v_mfma_f32_16x16x32_bf16 v[108:111], v[160:163], v[202:205], 0
	v_mfma_f32_16x16x32_bf16 v[100:103], v[168:171], v[202:205], 0
	v_mfma_f32_16x16x32_bf16 v[92:95], v[160:163], v[210:213], 0
	v_mfma_f32_16x16x32_bf16 v[84:87], v[168:171], v[210:213], 0
	v_mfma_f32_16x16x32_bf16 v[76:79], v[160:163], v[218:221], 0
	v_mfma_f32_16x16x32_bf16 v[68:71], v[168:171], v[218:221], 0
	v_mfma_f32_16x16x32_bf16 v[124:127], v[164:167], v[198:201], v[124:127]
	v_mfma_f32_16x16x32_bf16 v[116:119], v[172:175], v[198:201], v[116:119]
	v_mfma_f32_16x16x32_bf16 v[108:111], v[164:167], v[206:209], v[108:111]
	v_mfma_f32_16x16x32_bf16 v[100:103], v[172:175], v[206:209], v[100:103]
	v_mfma_f32_16x16x32_bf16 v[92:95], v[164:167], v[214:217], v[92:95]
	v_mfma_f32_16x16x32_bf16 v[84:87], v[172:175], v[214:217], v[84:87]
	v_mfma_f32_16x16x32_bf16 v[76:79], v[164:167], v[222:225], v[76:79]
	v_mfma_f32_16x16x32_bf16 v[68:71], v[172:175], v[222:225], v[68:71]
	s_setprio 0
	s_setprio 1
	v_mfma_f32_16x16x32_bf16 v[120:123], v[176:179], v[194:197], 0
	v_mfma_f32_16x16x32_bf16 v[112:115], v[186:189], v[194:197], 0
	v_mfma_f32_16x16x32_bf16 v[104:107], v[176:179], v[202:205], 0
	v_mfma_f32_16x16x32_bf16 v[96:99], v[186:189], v[202:205], 0
	v_mfma_f32_16x16x32_bf16 v[88:91], v[176:179], v[210:213], 0
	v_mfma_f32_16x16x32_bf16 v[80:83], v[186:189], v[210:213], 0
	v_mfma_f32_16x16x32_bf16 v[72:75], v[176:179], v[218:221], 0
	v_mfma_f32_16x16x32_bf16 v[64:67], v[186:189], v[218:221], 0
	v_mfma_f32_16x16x32_bf16 v[120:123], v[180:183], v[198:201], v[120:123]
	v_mfma_f32_16x16x32_bf16 v[112:115], v[190:193], v[198:201], v[112:115]
	v_mfma_f32_16x16x32_bf16 v[104:107], v[180:183], v[206:209], v[104:107]
	v_mfma_f32_16x16x32_bf16 v[96:99], v[190:193], v[206:209], v[96:99]
	v_mfma_f32_16x16x32_bf16 v[88:91], v[180:183], v[214:217], v[88:91]
	v_mfma_f32_16x16x32_bf16 v[80:83], v[190:193], v[214:217], v[80:83]
	v_mfma_f32_16x16x32_bf16 v[72:75], v[180:183], v[222:225], v[72:75]
	v_mfma_f32_16x16x32_bf16 v[64:67], v[190:193], v[222:225], v[64:67]
	s_setprio 0
	s_barrier
	s_add_i32 s76, s66, s54
	v_lshl_add_u64 v[154:155], s[48:49], 0, v[132:133]
	s_mov_b32 m0, s76
	ds_read_b128 v[194:197], v150 offset:16384
	v_xor_b32_e32 v253, 64, v150
	ds_read_b128 v[198:201], v253 offset:16384
	ds_read_b128 v[202:205], v150 offset:18432
	ds_read_b128 v[206:209], v253 offset:18432
	ds_read_b128 v[210:213], v150 offset:20480
	ds_read_b128 v[214:217], v253 offset:20480
	ds_read_b128 v[218:221], v150 offset:22528
	ds_read_b128 v[222:225], v253 offset:22528
	global_load_lds_dwordx4 v[154:155], off
	s_add_i32 m0, s76, 0x2000
	s_add_u32 s76, s48, 0x40000
	v_lshl_add_u64 v[226:227], s[48:49], 0, v[128:129]
	s_addc_u32 s77, s49, 0
	s_add_i32 s78, s67, s54
	global_load_lds_dwordx4 v[226:227], off
	v_lshl_add_u64 v[228:229], s[76:77], 0, v[132:133]
	s_mov_b32 m0, s78
	v_lshl_add_u64 v[230:231], s[50:51], 0, v[130:131]
	global_load_lds_dwordx4 v[228:229], off
	v_lshl_add_u64 v[228:229], s[76:77], 0, v[128:129]
	s_add_i32 m0, s78, 0x2000
	s_nop 0
	global_load_lds_dwordx4 v[228:229], off
	v_lshl_add_u64 v[228:229], s[50:51], 0, v[134:135]
	s_mov_b32 m0, s57
	s_nop 0
	global_load_lds_dwordx4 v[228:229], off
	s_mov_b32 m0, s58
	s_nop 0
	global_load_lds_dwordx4 v[230:231], off
	s_waitcnt vmcnt(16)
	s_waitcnt lgkmcnt(0)
	s_barrier
	s_setprio 1
	s_waitcnt lgkmcnt(0)
	v_mfma_f32_16x16x32_bf16 v[60:63], v[160:163], v[194:197], 0
	v_mfma_f32_16x16x32_bf16 v[52:55], v[168:171], v[194:197], 0
	v_mfma_f32_16x16x32_bf16 v[44:47], v[160:163], v[202:205], 0
	v_mfma_f32_16x16x32_bf16 v[36:39], v[168:171], v[202:205], 0
	v_mfma_f32_16x16x32_bf16 v[28:31], v[160:163], v[210:213], 0
	v_mfma_f32_16x16x32_bf16 v[20:23], v[168:171], v[210:213], 0
	v_mfma_f32_16x16x32_bf16 v[12:15], v[160:163], v[218:221], 0
	v_mfma_f32_16x16x32_bf16 v[4:7], v[168:171], v[218:221], 0
	v_mfma_f32_16x16x32_bf16 v[60:63], v[164:167], v[198:201], v[60:63]
	v_mfma_f32_16x16x32_bf16 v[52:55], v[172:175], v[198:201], v[52:55]
	v_mfma_f32_16x16x32_bf16 v[44:47], v[164:167], v[206:209], v[44:47]
	v_mfma_f32_16x16x32_bf16 v[36:39], v[172:175], v[206:209], v[36:39]
	v_mfma_f32_16x16x32_bf16 v[28:31], v[164:167], v[214:217], v[28:31]
	v_mfma_f32_16x16x32_bf16 v[20:23], v[172:175], v[214:217], v[20:23]
	v_mfma_f32_16x16x32_bf16 v[12:15], v[164:167], v[222:225], v[12:15]
	v_mfma_f32_16x16x32_bf16 v[4:7], v[172:175], v[222:225], v[4:7]
	s_setprio 0
	s_setprio 1
	v_mfma_f32_16x16x32_bf16 v[56:59], v[176:179], v[194:197], 0
	v_mfma_f32_16x16x32_bf16 v[48:51], v[186:189], v[194:197], 0
	v_mfma_f32_16x16x32_bf16 v[40:43], v[176:179], v[202:205], 0
	v_mfma_f32_16x16x32_bf16 v[32:35], v[186:189], v[202:205], 0
	v_mfma_f32_16x16x32_bf16 v[24:27], v[176:179], v[210:213], 0
	v_mfma_f32_16x16x32_bf16 v[16:19], v[186:189], v[210:213], 0
	v_mfma_f32_16x16x32_bf16 v[8:11], v[176:179], v[218:221], 0
	v_mfma_f32_16x16x32_bf16 v[0:3], v[186:189], v[218:221], 0
	v_mfma_f32_16x16x32_bf16 v[56:59], v[180:183], v[198:201], v[56:59]
	v_mfma_f32_16x16x32_bf16 v[48:51], v[190:193], v[198:201], v[48:51]
	v_mfma_f32_16x16x32_bf16 v[40:43], v[180:183], v[206:209], v[40:43]
	v_mfma_f32_16x16x32_bf16 v[32:35], v[190:193], v[206:209], v[32:35]
	v_mfma_f32_16x16x32_bf16 v[24:27], v[180:183], v[214:217], v[24:27]
	v_mfma_f32_16x16x32_bf16 v[16:19], v[190:193], v[214:217], v[16:19]
	v_mfma_f32_16x16x32_bf16 v[8:11], v[180:183], v[222:225], v[8:11]
	v_mfma_f32_16x16x32_bf16 v[0:3], v[190:193], v[222:225], v[0:3]
	s_setprio 0
	s_barrier
	s_add_i32 s76, 0, 0x18000
	v_add_u32_e32 v153, s76, v147
	s_add_i32 s77, 0, 0x1c000
	ds_read_b128 v[160:163], v153
	v_xor_b32_e32 v253, 64, v153
	ds_read_b128 v[164:167], v253
	ds_read_b128 v[168:171], v153 offset:2048
	ds_read_b128 v[172:175], v253 offset:2048
	v_add_u32_e32 v153, s77, v147
	ds_read_b128 v[176:179], v153
	v_xor_b32_e32 v253, 64, v153
	ds_read_b128 v[180:183], v253
	ds_read_b128 v[186:189], v153 offset:2048
	ds_read_b128 v[190:193], v253 offset:2048
	s_add_u32 s50, s50, 0x40000
	s_addc_u32 s51, s51, 0
	s_mov_b32 m0, s59
	v_lshl_add_u64 v[232:233], s[50:51], 0, v[134:135]
	ds_read_b128 v[194:197], v150 offset:32768
	v_xor_b32_e32 v253, 64, v150
	ds_read_b128 v[198:201], v253 offset:32768
	ds_read_b128 v[202:205], v150 offset:34816
	ds_read_b128 v[206:209], v253 offset:34816
	ds_read_b128 v[210:213], v150 offset:36864
	ds_read_b128 v[214:217], v253 offset:36864
	ds_read_b128 v[218:221], v150 offset:38912
	ds_read_b128 v[222:225], v253 offset:38912
	global_load_lds_dwordx4 v[232:233], off
	v_lshl_add_u64 v[232:233], s[50:51], 0, v[130:131]
	s_mov_b32 m0, s60
	s_nop 0
	global_load_lds_dwordx4 v[232:233], off
	s_waitcnt vmcnt(8)
	s_waitcnt lgkmcnt(0)
	s_barrier
	s_setprio 1
	s_waitcnt lgkmcnt(0)
	v_mfma_f32_16x16x32_bf16 v[124:127], v[160:163], v[194:197], v[124:127]
	v_mfma_f32_16x16x32_bf16 v[124:127], v[164:167], v[198:201], v[124:127]
	v_mfma_f32_16x16x32_bf16 v[116:119], v[168:171], v[194:197], v[116:119]
	v_mfma_f32_16x16x32_bf16 v[116:119], v[172:175], v[198:201], v[116:119]
	v_mfma_f32_16x16x32_bf16 v[108:111], v[160:163], v[202:205], v[108:111]
	v_mfma_f32_16x16x32_bf16 v[108:111], v[164:167], v[206:209], v[108:111]
	v_mfma_f32_16x16x32_bf16 v[100:103], v[168:171], v[202:205], v[100:103]
	v_mfma_f32_16x16x32_bf16 v[100:103], v[172:175], v[206:209], v[100:103]
	v_mfma_f32_16x16x32_bf16 v[92:95], v[160:163], v[210:213], v[92:95]
	v_mfma_f32_16x16x32_bf16 v[92:95], v[164:167], v[214:217], v[92:95]
	v_mfma_f32_16x16x32_bf16 v[84:87], v[168:171], v[210:213], v[84:87]
	v_mfma_f32_16x16x32_bf16 v[84:87], v[172:175], v[214:217], v[84:87]
	v_mfma_f32_16x16x32_bf16 v[76:79], v[160:163], v[218:221], v[76:79]
	v_mfma_f32_16x16x32_bf16 v[76:79], v[164:167], v[222:225], v[76:79]
	v_mfma_f32_16x16x32_bf16 v[68:71], v[168:171], v[218:221], v[68:71]
	v_mfma_f32_16x16x32_bf16 v[68:71], v[172:175], v[222:225], v[68:71]
	s_setprio 0
	s_setprio 1
	v_mfma_f32_16x16x32_bf16 v[120:123], v[176:179], v[194:197], v[120:123]
	v_mfma_f32_16x16x32_bf16 v[120:123], v[180:183], v[198:201], v[120:123]
	v_mfma_f32_16x16x32_bf16 v[112:115], v[186:189], v[194:197], v[112:115]
	v_mfma_f32_16x16x32_bf16 v[112:115], v[190:193], v[198:201], v[112:115]
	v_mfma_f32_16x16x32_bf16 v[104:107], v[176:179], v[202:205], v[104:107]
	v_mfma_f32_16x16x32_bf16 v[104:107], v[180:183], v[206:209], v[104:107]
	v_mfma_f32_16x16x32_bf16 v[96:99], v[186:189], v[202:205], v[96:99]
	v_mfma_f32_16x16x32_bf16 v[96:99], v[190:193], v[206:209], v[96:99]
	v_mfma_f32_16x16x32_bf16 v[88:91], v[176:179], v[210:213], v[88:91]
	v_mfma_f32_16x16x32_bf16 v[88:91], v[180:183], v[214:217], v[88:91]
	v_mfma_f32_16x16x32_bf16 v[80:83], v[186:189], v[210:213], v[80:83]
	v_mfma_f32_16x16x32_bf16 v[80:83], v[190:193], v[214:217], v[80:83]
	v_mfma_f32_16x16x32_bf16 v[72:75], v[176:179], v[218:221], v[72:75]
	v_mfma_f32_16x16x32_bf16 v[72:75], v[180:183], v[222:225], v[72:75]
	v_mfma_f32_16x16x32_bf16 v[64:67], v[186:189], v[218:221], v[64:67]
	v_mfma_f32_16x16x32_bf16 v[64:67], v[190:193], v[222:225], v[64:67]
	s_setprio 0
	s_barrier
	s_add_i32 s50, s76, s54
	v_lshl_add_u64 v[154:155], v[154:155], 0, s[20:21]
	s_mov_b32 m0, s50
	ds_read_b128 v[194:197], v150 offset:49152
	v_xor_b32_e32 v253, 64, v150
	ds_read_b128 v[198:201], v253 offset:49152
	ds_read_b128 v[202:205], v150 offset:51200
	ds_read_b128 v[206:209], v253 offset:51200
	ds_read_b128 v[210:213], v150 offset:53248
	ds_read_b128 v[214:217], v253 offset:53248
	ds_read_b128 v[218:221], v150 offset:55296
	ds_read_b128 v[222:225], v253 offset:55296
	global_load_lds_dwordx4 v[154:155], off
	s_add_i32 m0, s50, 0x2000
	s_add_u32 s48, s48, 0x40080
	v_lshl_add_u64 v[154:155], v[226:227], 0, s[20:21]
	s_addc_u32 s49, s49, 0
	s_add_i32 s50, s77, s54
	global_load_lds_dwordx4 v[154:155], off
	v_lshl_add_u64 v[154:155], s[48:49], 0, v[132:133]
	s_mov_b32 m0, s50
	s_nop 0
	global_load_lds_dwordx4 v[154:155], off
	v_lshl_add_u64 v[154:155], s[48:49], 0, v[128:129]
	s_add_i32 m0, s50, 0x2000
	s_nop 0
	global_load_lds_dwordx4 v[154:155], off
	v_lshl_add_u64 v[154:155], v[228:229], 0, s[20:21]
	s_mov_b32 m0, s62
	s_nop 0
	global_load_lds_dwordx4 v[154:155], off
	v_lshl_add_u64 v[154:155], v[230:231], 0, s[20:21]
	s_mov_b32 m0, s63
	s_nop 0
	global_load_lds_dwordx4 v[154:155], off
	s_waitcnt vmcnt(8)
	s_waitcnt lgkmcnt(0)
	s_barrier
	s_setprio 1
	s_waitcnt lgkmcnt(0)
	v_mfma_f32_16x16x32_bf16 v[60:63], v[160:163], v[194:197], v[60:63]
	v_mfma_f32_16x16x32_bf16 v[60:63], v[164:167], v[198:201], v[60:63]
	v_mfma_f32_16x16x32_bf16 v[52:55], v[168:171], v[194:197], v[52:55]
	v_mfma_f32_16x16x32_bf16 v[52:55], v[172:175], v[198:201], v[52:55]
	v_mfma_f32_16x16x32_bf16 v[44:47], v[160:163], v[202:205], v[44:47]
	v_mfma_f32_16x16x32_bf16 v[44:47], v[164:167], v[206:209], v[44:47]
	v_mfma_f32_16x16x32_bf16 v[36:39], v[168:171], v[202:205], v[36:39]
	v_mfma_f32_16x16x32_bf16 v[36:39], v[172:175], v[206:209], v[36:39]
	v_mfma_f32_16x16x32_bf16 v[28:31], v[160:163], v[210:213], v[28:31]
	v_mfma_f32_16x16x32_bf16 v[28:31], v[164:167], v[214:217], v[28:31]
	v_mfma_f32_16x16x32_bf16 v[20:23], v[168:171], v[210:213], v[20:23]
	v_mfma_f32_16x16x32_bf16 v[20:23], v[172:175], v[214:217], v[20:23]
	v_mfma_f32_16x16x32_bf16 v[12:15], v[160:163], v[218:221], v[12:15]
	v_mfma_f32_16x16x32_bf16 v[12:15], v[164:167], v[222:225], v[12:15]
	v_mfma_f32_16x16x32_bf16 v[4:7], v[168:171], v[218:221], v[4:7]
	v_mfma_f32_16x16x32_bf16 v[4:7], v[172:175], v[222:225], v[4:7]
	s_setprio 0
	s_setprio 1
	v_mfma_f32_16x16x32_bf16 v[56:59], v[176:179], v[194:197], v[56:59]
	v_mfma_f32_16x16x32_bf16 v[56:59], v[180:183], v[198:201], v[56:59]
	v_mfma_f32_16x16x32_bf16 v[48:51], v[186:189], v[194:197], v[48:51]
	v_mfma_f32_16x16x32_bf16 v[48:51], v[190:193], v[198:201], v[48:51]
	v_mfma_f32_16x16x32_bf16 v[40:43], v[176:179], v[202:205], v[40:43]
	v_mfma_f32_16x16x32_bf16 v[40:43], v[180:183], v[206:209], v[40:43]
	v_mfma_f32_16x16x32_bf16 v[32:35], v[186:189], v[202:205], v[32:35]
	v_mfma_f32_16x16x32_bf16 v[32:35], v[190:193], v[206:209], v[32:35]
	v_mfma_f32_16x16x32_bf16 v[24:27], v[176:179], v[210:213], v[24:27]
	v_mfma_f32_16x16x32_bf16 v[24:27], v[180:183], v[214:217], v[24:27]
	v_mfma_f32_16x16x32_bf16 v[16:19], v[186:189], v[210:213], v[16:19]
	v_mfma_f32_16x16x32_bf16 v[16:19], v[190:193], v[214:217], v[16:19]
	v_mfma_f32_16x16x32_bf16 v[8:11], v[176:179], v[218:221], v[8:11]
	v_mfma_f32_16x16x32_bf16 v[8:11], v[180:183], v[222:225], v[8:11]
	v_mfma_f32_16x16x32_bf16 v[0:3], v[186:189], v[218:221], v[0:3]
	v_mfma_f32_16x16x32_bf16 v[0:3], v[190:193], v[222:225], v[0:3]
	s_setprio 0
	s_barrier
	s_add_i32 s75, s75, 2
	s_add_u32 s73, s73, 0x100
	s_addc_u32 s74, s74, 0
	s_add_u32 s46, s46, 0x100
	s_addc_u32 s47, s47, 0
	s_branch .LBB0_527
.Lfa_4:
	v_add_u32_e32 v153, s66, v147
	ds_read_b128 v[160:163], v153
	v_xor_b32_e32 v253, 64, v153
	ds_read_b128 v[164:167], v253
	ds_read_b128 v[168:171], v153 offset:2048
	ds_read_b128 v[172:175], v253 offset:2048
	v_add_u32_e32 v153, s67, v147
	ds_read_b128 v[176:179], v153
	v_xor_b32_e32 v253, 64, v153
	ds_read_b128 v[180:183], v253
	ds_read_b128 v[186:189], v153 offset:2048
	ds_read_b128 v[190:193], v253 offset:2048
	s_add_u32 s50, s46, 0xfffc0080
	s_addc_u32 s51, s47, -1
	s_and_b64 s[48:49], s[48:49], exec
	s_cselect_b32 s51, s29, s51
	s_cselect_b32 s50, s70, s50
	s_cselect_b32 s49, s71, s74
	s_cselect_b32 s48, s72, s73
	v_lshl_add_u64 v[154:155], s[46:47], 0, v[138:139]
	s_add_i32 m0, s57, 0xc000
	ds_read_b128 v[194:197], v150
	v_xor_b32_e32 v253, 64, v150
	ds_read_b128 v[198:201], v253
	ds_read_b128 v[202:205], v150 offset:2048
	ds_read_b128 v[206:209], v253 offset:2048
	ds_read_b128 v[210:213], v150 offset:4096
	ds_read_b128 v[214:217], v253 offset:4096
	ds_read_b128 v[218:221], v150 offset:6144
	ds_read_b128 v[222:225], v253 offset:6144
	global_load_lds_dwordx4 v[154:155], off
	v_lshl_add_u64 v[154:155], s[46:47], 0, v[136:137]
	s_add_i32 m0, s57, 0xe000
	s_nop 0
	global_load_lds_dwordx4 v[154:155], off
	s_waitcnt vmcnt(8)
	s_waitcnt lgkmcnt(0)
	s_barrier
	s_setprio 1
	s_waitcnt lgkmcnt(0)
	v_mfma_f32_16x16x32_bf16 v[124:127], v[160:163], v[194:197], 0
	v_mfma_f32_16x16x32_bf16 v[116:119], v[168:171], v[194:197], 0
	v_mfma_f32_16x16x32_bf16 v[108:111], v[160:163], v[202:205], 0
	v_mfma_f32_16x16x32_bf16 v[100:103], v[168:171], v[202:205], 0
	v_mfma_f32_16x16x32_bf16 v[92:95], v[160:163], v[210:213], 0
	v_mfma_f32_16x16x32_bf16 v[84:87], v[168:171], v[210:213], 0
	v_mfma_f32_16x16x32_bf16 v[76:79], v[160:163], v[218:221], 0
	v_mfma_f32_16x16x32_bf16 v[68:71], v[168:171], v[218:221], 0
	v_mfma_f32_16x16x32_bf16 v[124:127], v[164:167], v[198:201], v[124:127]
	v_mfma_f32_16x16x32_bf16 v[116:119], v[172:175], v[198:201], v[116:119]
	v_mfma_f32_16x16x32_bf16 v[108:111], v[164:167], v[206:209], v[108:111]
	v_mfma_f32_16x16x32_bf16 v[100:103], v[172:175], v[206:209], v[100:103]
	v_mfma_f32_16x16x32_bf16 v[92:95], v[164:167], v[214:217], v[92:95]
	v_mfma_f32_16x16x32_bf16 v[84:87], v[172:175], v[214:217], v[84:87]
	v_mfma_f32_16x16x32_bf16 v[76:79], v[164:167], v[222:225], v[76:79]
	v_mfma_f32_16x16x32_bf16 v[68:71], v[172:175], v[222:225], v[68:71]
	s_setprio 0
	s_setprio 1
	v_mfma_f32_16x16x32_bf16 v[120:123], v[176:179], v[194:197], 0
	v_mfma_f32_16x16x32_bf16 v[112:115], v[186:189], v[194:197], 0
	v_mfma_f32_16x16x32_bf16 v[104:107], v[176:179], v[202:205], 0
	v_mfma_f32_16x16x32_bf16 v[96:99], v[186:189], v[202:205], 0
	v_mfma_f32_16x16x32_bf16 v[88:91], v[176:179], v[210:213], 0
	v_mfma_f32_16x16x32_bf16 v[80:83], v[186:189], v[210:213], 0
	v_mfma_f32_16x16x32_bf16 v[72:75], v[176:179], v[218:221], 0
	v_mfma_f32_16x16x32_bf16 v[64:67], v[186:189], v[218:221], 0
	v_mfma_f32_16x16x32_bf16 v[120:123], v[180:183], v[198:201], v[120:123]
	v_mfma_f32_16x16x32_bf16 v[112:115], v[190:193], v[198:201], v[112:115]
	v_mfma_f32_16x16x32_bf16 v[104:107], v[180:183], v[206:209], v[104:107]
	v_mfma_f32_16x16x32_bf16 v[96:99], v[190:193], v[206:209], v[96:99]
	v_mfma_f32_16x16x32_bf16 v[88:91], v[180:183], v[214:217], v[88:91]
	v_mfma_f32_16x16x32_bf16 v[80:83], v[190:193], v[214:217], v[80:83]
	v_mfma_f32_16x16x32_bf16 v[72:75], v[180:183], v[222:225], v[72:75]
	v_mfma_f32_16x16x32_bf16 v[64:67], v[190:193], v[222:225], v[64:67]
	s_setprio 0
	s_barrier
	s_add_i32 s76, s66, s54
	v_lshl_add_u64 v[154:155], s[48:49], 0, v[132:133]
	s_mov_b32 m0, s76
	ds_read_b128 v[194:197], v150 offset:16384
	v_xor_b32_e32 v253, 64, v150
	ds_read_b128 v[198:201], v253 offset:16384
	ds_read_b128 v[202:205], v150 offset:18432
	ds_read_b128 v[206:209], v253 offset:18432
	ds_read_b128 v[210:213], v150 offset:20480
	ds_read_b128 v[214:217], v253 offset:20480
	ds_read_b128 v[218:221], v150 offset:22528
	ds_read_b128 v[222:225], v253 offset:22528
	global_load_lds_dwordx4 v[154:155], off
	s_add_i32 m0, s76, 0x2000
	s_add_u32 s76, s48, 0x40000
	v_lshl_add_u64 v[226:227], s[48:49], 0, v[128:129]
	s_addc_u32 s77, s49, 0
	s_add_i32 s78, s67, s54
	global_load_lds_dwordx4 v[226:227], off
	v_lshl_add_u64 v[228:229], s[76:77], 0, v[132:133]
	s_mov_b32 m0, s78
	v_lshl_add_u64 v[230:231], s[50:51], 0, v[130:131]
	global_load_lds_dwordx4 v[228:229], off
	v_lshl_add_u64 v[228:229], s[76:77], 0, v[128:129]
	s_add_i32 m0, s78, 0x2000
	s_nop 0
	global_load_lds_dwordx4 v[228:229], off
	v_lshl_add_u64 v[228:229], s[50:51], 0, v[134:135]
	s_mov_b32 m0, s57
	s_nop 0
	global_load_lds_dwordx4 v[228:229], off
	s_mov_b32 m0, s58
	s_nop 0
	global_load_lds_dwordx4 v[230:231], off
	s_waitcnt vmcnt(8)
	s_waitcnt lgkmcnt(0)
	s_barrier
	s_setprio 1
	s_waitcnt lgkmcnt(0)
	v_mfma_f32_16x16x32_bf16 v[60:63], v[160:163], v[194:197], 0
	v_mfma_f32_16x16x32_bf16 v[52:55], v[168:171], v[194:197], 0
	v_mfma_f32_16x16x32_bf16 v[44:47], v[160:163], v[202:205], 0
	v_mfma_f32_16x16x32_bf16 v[36:39], v[168:171], v[202:205], 0
	v_mfma_f32_16x16x32_bf16 v[28:31], v[160:163], v[210:213], 0
	v_mfma_f32_16x16x32_bf16 v[20:23], v[168:171], v[210:213], 0
	v_mfma_f32_16x16x32_bf16 v[12:15], v[160:163], v[218:221], 0
	v_mfma_f32_16x16x32_bf16 v[4:7], v[168:171], v[218:221], 0
	v_mfma_f32_16x16x32_bf16 v[60:63], v[164:167], v[198:201], v[60:63]
	v_mfma_f32_16x16x32_bf16 v[52:55], v[172:175], v[198:201], v[52:55]
	v_mfma_f32_16x16x32_bf16 v[44:47], v[164:167], v[206:209], v[44:47]
	v_mfma_f32_16x16x32_bf16 v[36:39], v[172:175], v[206:209], v[36:39]
	v_mfma_f32_16x16x32_bf16 v[28:31], v[164:167], v[214:217], v[28:31]
	v_mfma_f32_16x16x32_bf16 v[20:23], v[172:175], v[214:217], v[20:23]
	v_mfma_f32_16x16x32_bf16 v[12:15], v[164:167], v[222:225], v[12:15]
	v_mfma_f32_16x16x32_bf16 v[4:7], v[172:175], v[222:225], v[4:7]
	s_setprio 0
	s_setprio 1
	v_mfma_f32_16x16x32_bf16 v[56:59], v[176:179], v[194:197], 0
	v_mfma_f32_16x16x32_bf16 v[48:51], v[186:189], v[194:197], 0
	v_mfma_f32_16x16x32_bf16 v[40:43], v[176:179], v[202:205], 0
	v_mfma_f32_16x16x32_bf16 v[32:35], v[186:189], v[202:205], 0
	v_mfma_f32_16x16x32_bf16 v[24:27], v[176:179], v[210:213], 0
	v_mfma_f32_16x16x32_bf16 v[16:19], v[186:189], v[210:213], 0
	v_mfma_f32_16x16x32_bf16 v[8:11], v[176:179], v[218:221], 0
	v_mfma_f32_16x16x32_bf16 v[0:3], v[186:189], v[218:221], 0
	v_mfma_f32_16x16x32_bf16 v[56:59], v[180:183], v[198:201], v[56:59]
	v_mfma_f32_16x16x32_bf16 v[48:51], v[190:193], v[198:201], v[48:51]
	v_mfma_f32_16x16x32_bf16 v[40:43], v[180:183], v[206:209], v[40:43]
	v_mfma_f32_16x16x32_bf16 v[32:35], v[190:193], v[206:209], v[32:35]
	v_mfma_f32_16x16x32_bf16 v[24:27], v[180:183], v[214:217], v[24:27]
	v_mfma_f32_16x16x32_bf16 v[16:19], v[190:193], v[214:217], v[16:19]
	v_mfma_f32_16x16x32_bf16 v[8:11], v[180:183], v[222:225], v[8:11]
	v_mfma_f32_16x16x32_bf16 v[0:3], v[190:193], v[222:225], v[0:3]
	s_setprio 0
	s_barrier
	s_add_i32 s76, 0, 0x18000
	v_add_u32_e32 v153, s76, v147
	s_add_i32 s77, 0, 0x1c000
	ds_read_b128 v[160:163], v153
	v_xor_b32_e32 v253, 64, v153
	ds_read_b128 v[164:167], v253
	ds_read_b128 v[168:171], v153 offset:2048
	ds_read_b128 v[172:175], v253 offset:2048
	v_add_u32_e32 v153, s77, v147
	ds_read_b128 v[176:179], v153
	v_xor_b32_e32 v253, 64, v153
	ds_read_b128 v[180:183], v253
	ds_read_b128 v[186:189], v153 offset:2048
	ds_read_b128 v[190:193], v253 offset:2048
	s_add_u32 s50, s50, 0x40000
	s_addc_u32 s51, s51, 0
	s_mov_b32 m0, s59
	v_lshl_add_u64 v[232:233], s[50:51], 0, v[134:135]
	ds_read_b128 v[194:197], v150 offset:32768
	v_xor_b32_e32 v253, 64, v150
	ds_read_b128 v[198:201], v253 offset:32768
	ds_read_b128 v[202:205], v150 offset:34816
	ds_read_b128 v[206:209], v253 offset:34816
	ds_read_b128 v[210:213], v150 offset:36864
	ds_read_b128 v[214:217], v253 offset:36864
	ds_read_b128 v[218:221], v150 offset:38912
	ds_read_b128 v[222:225], v253 offset:38912
	global_load_lds_dwordx4 v[232:233], off
	v_lshl_add_u64 v[232:233], s[50:51], 0, v[130:131]
	s_mov_b32 m0, s60
	s_nop 0
	global_load_lds_dwordx4 v[232:233], off
	s_waitcnt vmcnt(8)
	s_waitcnt lgkmcnt(0)
	s_barrier
	s_setprio 1
	s_waitcnt lgkmcnt(0)
	v_mfma_f32_16x16x32_bf16 v[124:127], v[160:163], v[194:197], v[124:127]
	v_mfma_f32_16x16x32_bf16 v[124:127], v[164:167], v[198:201], v[124:127]
	v_mfma_f32_16x16x32_bf16 v[116:119], v[168:171], v[194:197], v[116:119]
	v_mfma_f32_16x16x32_bf16 v[116:119], v[172:175], v[198:201], v[116:119]
	v_mfma_f32_16x16x32_bf16 v[108:111], v[160:163], v[202:205], v[108:111]
	v_mfma_f32_16x16x32_bf16 v[108:111], v[164:167], v[206:209], v[108:111]
	v_mfma_f32_16x16x32_bf16 v[100:103], v[168:171], v[202:205], v[100:103]
	v_mfma_f32_16x16x32_bf16 v[100:103], v[172:175], v[206:209], v[100:103]
	v_mfma_f32_16x16x32_bf16 v[92:95], v[160:163], v[210:213], v[92:95]
	v_mfma_f32_16x16x32_bf16 v[92:95], v[164:167], v[214:217], v[92:95]
	v_mfma_f32_16x16x32_bf16 v[84:87], v[168:171], v[210:213], v[84:87]
	v_mfma_f32_16x16x32_bf16 v[84:87], v[172:175], v[214:217], v[84:87]
	v_mfma_f32_16x16x32_bf16 v[76:79], v[160:163], v[218:221], v[76:79]
	v_mfma_f32_16x16x32_bf16 v[76:79], v[164:167], v[222:225], v[76:79]
	v_mfma_f32_16x16x32_bf16 v[68:71], v[168:171], v[218:221], v[68:71]
	v_mfma_f32_16x16x32_bf16 v[68:71], v[172:175], v[222:225], v[68:71]
	s_setprio 0
	s_setprio 1
	v_mfma_f32_16x16x32_bf16 v[120:123], v[176:179], v[194:197], v[120:123]
	v_mfma_f32_16x16x32_bf16 v[120:123], v[180:183], v[198:201], v[120:123]
	v_mfma_f32_16x16x32_bf16 v[112:115], v[186:189], v[194:197], v[112:115]
	v_mfma_f32_16x16x32_bf16 v[112:115], v[190:193], v[198:201], v[112:115]
	v_mfma_f32_16x16x32_bf16 v[104:107], v[176:179], v[202:205], v[104:107]
	v_mfma_f32_16x16x32_bf16 v[104:107], v[180:183], v[206:209], v[104:107]
	v_mfma_f32_16x16x32_bf16 v[96:99], v[186:189], v[202:205], v[96:99]
	v_mfma_f32_16x16x32_bf16 v[96:99], v[190:193], v[206:209], v[96:99]
	v_mfma_f32_16x16x32_bf16 v[88:91], v[176:179], v[210:213], v[88:91]
	v_mfma_f32_16x16x32_bf16 v[88:91], v[180:183], v[214:217], v[88:91]
	v_mfma_f32_16x16x32_bf16 v[80:83], v[186:189], v[210:213], v[80:83]
	v_mfma_f32_16x16x32_bf16 v[80:83], v[190:193], v[214:217], v[80:83]
	v_mfma_f32_16x16x32_bf16 v[72:75], v[176:179], v[218:221], v[72:75]
	v_mfma_f32_16x16x32_bf16 v[72:75], v[180:183], v[222:225], v[72:75]
	v_mfma_f32_16x16x32_bf16 v[64:67], v[186:189], v[218:221], v[64:67]
	v_mfma_f32_16x16x32_bf16 v[64:67], v[190:193], v[222:225], v[64:67]
	s_setprio 0
	s_barrier
	s_add_i32 s50, s76, s54
	v_lshl_add_u64 v[154:155], v[154:155], 0, s[20:21]
	s_mov_b32 m0, s50
	ds_read_b128 v[194:197], v150 offset:49152
	v_xor_b32_e32 v253, 64, v150
	ds_read_b128 v[198:201], v253 offset:49152
	ds_read_b128 v[202:205], v150 offset:51200
	ds_read_b128 v[206:209], v253 offset:51200
	ds_read_b128 v[210:213], v150 offset:53248
	ds_read_b128 v[214:217], v253 offset:53248
	ds_read_b128 v[218:221], v150 offset:55296
	ds_read_b128 v[222:225], v253 offset:55296
	global_load_lds_dwordx4 v[154:155], off
	s_add_i32 m0, s50, 0x2000
	s_add_u32 s48, s48, 0x40080
	v_lshl_add_u64 v[154:155], v[226:227], 0, s[20:21]
	s_addc_u32 s49, s49, 0
	s_add_i32 s50, s77, s54
	global_load_lds_dwordx4 v[154:155], off
	v_lshl_add_u64 v[154:155], s[48:49], 0, v[132:133]
	s_mov_b32 m0, s50
	s_nop 0
	global_load_lds_dwordx4 v[154:155], off
	v_lshl_add_u64 v[154:155], s[48:49], 0, v[128:129]
	s_add_i32 m0, s50, 0x2000
	s_nop 0
	global_load_lds_dwordx4 v[154:155], off
	v_lshl_add_u64 v[154:155], v[228:229], 0, s[20:21]
	s_mov_b32 m0, s62
	s_nop 0
	global_load_lds_dwordx4 v[154:155], off
	v_lshl_add_u64 v[154:155], v[230:231], 0, s[20:21]
	s_mov_b32 m0, s63
	s_nop 0
	global_load_lds_dwordx4 v[154:155], off
	s_waitcnt vmcnt(8)
	s_waitcnt lgkmcnt(0)
	s_barrier
	s_setprio 1
	s_waitcnt lgkmcnt(0)
	v_mfma_f32_16x16x32_bf16 v[60:63], v[160:163], v[194:197], v[60:63]
	v_mfma_f32_16x16x32_bf16 v[60:63], v[164:167], v[198:201], v[60:63]
	v_mfma_f32_16x16x32_bf16 v[52:55], v[168:171], v[194:197], v[52:55]
	v_mfma_f32_16x16x32_bf16 v[52:55], v[172:175], v[198:201], v[52:55]
	v_mfma_f32_16x16x32_bf16 v[44:47], v[160:163], v[202:205], v[44:47]
	v_mfma_f32_16x16x32_bf16 v[44:47], v[164:167], v[206:209], v[44:47]
	v_mfma_f32_16x16x32_bf16 v[36:39], v[168:171], v[202:205], v[36:39]
	v_mfma_f32_16x16x32_bf16 v[36:39], v[172:175], v[206:209], v[36:39]
	v_mfma_f32_16x16x32_bf16 v[28:31], v[160:163], v[210:213], v[28:31]
	v_mfma_f32_16x16x32_bf16 v[28:31], v[164:167], v[214:217], v[28:31]
	v_mfma_f32_16x16x32_bf16 v[20:23], v[168:171], v[210:213], v[20:23]
	v_mfma_f32_16x16x32_bf16 v[20:23], v[172:175], v[214:217], v[20:23]
	v_mfma_f32_16x16x32_bf16 v[12:15], v[160:163], v[218:221], v[12:15]
	v_mfma_f32_16x16x32_bf16 v[12:15], v[164:167], v[222:225], v[12:15]
	v_mfma_f32_16x16x32_bf16 v[4:7], v[168:171], v[218:221], v[4:7]
	v_mfma_f32_16x16x32_bf16 v[4:7], v[172:175], v[222:225], v[4:7]
	s_setprio 0
	s_setprio 1
	v_mfma_f32_16x16x32_bf16 v[56:59], v[176:179], v[194:197], v[56:59]
	v_mfma_f32_16x16x32_bf16 v[56:59], v[180:183], v[198:201], v[56:59]
	v_mfma_f32_16x16x32_bf16 v[48:51], v[186:189], v[194:197], v[48:51]
	v_mfma_f32_16x16x32_bf16 v[48:51], v[190:193], v[198:201], v[48:51]
	v_mfma_f32_16x16x32_bf16 v[40:43], v[176:179], v[202:205], v[40:43]
	v_mfma_f32_16x16x32_bf16 v[40:43], v[180:183], v[206:209], v[40:43]
	v_mfma_f32_16x16x32_bf16 v[32:35], v[186:189], v[202:205], v[32:35]
	v_mfma_f32_16x16x32_bf16 v[32:35], v[190:193], v[206:209], v[32:35]
	v_mfma_f32_16x16x32_bf16 v[24:27], v[176:179], v[210:213], v[24:27]
	v_mfma_f32_16x16x32_bf16 v[24:27], v[180:183], v[214:217], v[24:27]
	v_mfma_f32_16x16x32_bf16 v[16:19], v[186:189], v[210:213], v[16:19]
	v_mfma_f32_16x16x32_bf16 v[16:19], v[190:193], v[214:217], v[16:19]
	v_mfma_f32_16x16x32_bf16 v[8:11], v[176:179], v[218:221], v[8:11]
	v_mfma_f32_16x16x32_bf16 v[8:11], v[180:183], v[222:225], v[8:11]
	v_mfma_f32_16x16x32_bf16 v[0:3], v[186:189], v[218:221], v[0:3]
	v_mfma_f32_16x16x32_bf16 v[0:3], v[190:193], v[222:225], v[0:3]
	s_setprio 0
	s_barrier
	s_add_i32 s75, s75, 2
	s_add_u32 s73, s73, 0x100
	s_addc_u32 s74, s74, 0
	s_add_u32 s46, s46, 0x100
	s_addc_u32 s47, s47, 0
	s_branch .LBB0_527
.LBB0_526:
	v_add_u32_e32 v153, s66, v147
	ds_read_b128 v[160:163], v153
	v_xor_b32_e32 v253, 64, v153
	ds_read_b128 v[164:167], v253
	ds_read_b128 v[168:171], v153 offset:2048
	ds_read_b128 v[172:175], v253 offset:2048
	v_add_u32_e32 v153, s67, v147
	ds_read_b128 v[176:179], v153
	v_xor_b32_e32 v253, 64, v153
	ds_read_b128 v[180:183], v253
	ds_read_b128 v[186:189], v153 offset:2048
	ds_read_b128 v[190:193], v253 offset:2048
	s_add_u32 s50, s46, 0xfffc0080
	s_addc_u32 s51, s47, -1
	s_and_b64 s[48:49], s[48:49], exec
	s_cselect_b32 s51, s29, s51
	s_cselect_b32 s50, s70, s50
	s_cselect_b32 s49, s71, s74
	s_cselect_b32 s48, s72, s73
	v_lshl_add_u64 v[154:155], s[46:47], 0, v[138:139]
	s_add_i32 m0, s57, 0xc000
	ds_read_b128 v[194:197], v150
	v_xor_b32_e32 v253, 64, v150
	ds_read_b128 v[198:201], v253
	ds_read_b128 v[202:205], v150 offset:2048
	ds_read_b128 v[206:209], v253 offset:2048
	ds_read_b128 v[210:213], v150 offset:4096
	ds_read_b128 v[214:217], v253 offset:4096
	ds_read_b128 v[218:221], v150 offset:6144
	ds_read_b128 v[222:225], v253 offset:6144
	global_load_lds_dwordx4 v[154:155], off
	v_lshl_add_u64 v[154:155], s[46:47], 0, v[136:137]
	s_add_i32 m0, s57, 0xe000
	s_nop 0
	global_load_lds_dwordx4 v[154:155], off
	s_waitcnt vmcnt(8)
	s_waitcnt lgkmcnt(0)
	s_barrier
	s_setprio 1
	s_waitcnt lgkmcnt(0)
	v_mfma_f32_16x16x32_bf16 v[124:127], v[160:163], v[194:197], v[124:127]
	v_mfma_f32_16x16x32_bf16 v[124:127], v[164:167], v[198:201], v[124:127]
	v_mfma_f32_16x16x32_bf16 v[116:119], v[168:171], v[194:197], v[116:119]
	v_mfma_f32_16x16x32_bf16 v[116:119], v[172:175], v[198:201], v[116:119]
	v_mfma_f32_16x16x32_bf16 v[108:111], v[160:163], v[202:205], v[108:111]
	v_mfma_f32_16x16x32_bf16 v[108:111], v[164:167], v[206:209], v[108:111]
	v_mfma_f32_16x16x32_bf16 v[100:103], v[168:171], v[202:205], v[100:103]
	v_mfma_f32_16x16x32_bf16 v[100:103], v[172:175], v[206:209], v[100:103]
	v_mfma_f32_16x16x32_bf16 v[92:95], v[160:163], v[210:213], v[92:95]
	v_mfma_f32_16x16x32_bf16 v[92:95], v[164:167], v[214:217], v[92:95]
	v_mfma_f32_16x16x32_bf16 v[84:87], v[168:171], v[210:213], v[84:87]
	v_mfma_f32_16x16x32_bf16 v[84:87], v[172:175], v[214:217], v[84:87]
	v_mfma_f32_16x16x32_bf16 v[76:79], v[160:163], v[218:221], v[76:79]
	v_mfma_f32_16x16x32_bf16 v[76:79], v[164:167], v[222:225], v[76:79]
	v_mfma_f32_16x16x32_bf16 v[68:71], v[168:171], v[218:221], v[68:71]
	v_mfma_f32_16x16x32_bf16 v[68:71], v[172:175], v[222:225], v[68:71]
	s_setprio 0
	s_setprio 1
	v_mfma_f32_16x16x32_bf16 v[120:123], v[176:179], v[194:197], v[120:123]
	v_mfma_f32_16x16x32_bf16 v[120:123], v[180:183], v[198:201], v[120:123]
	v_mfma_f32_16x16x32_bf16 v[112:115], v[186:189], v[194:197], v[112:115]
	v_mfma_f32_16x16x32_bf16 v[112:115], v[190:193], v[198:201], v[112:115]
	v_mfma_f32_16x16x32_bf16 v[104:107], v[176:179], v[202:205], v[104:107]
	v_mfma_f32_16x16x32_bf16 v[104:107], v[180:183], v[206:209], v[104:107]
	v_mfma_f32_16x16x32_bf16 v[96:99], v[186:189], v[202:205], v[96:99]
	v_mfma_f32_16x16x32_bf16 v[96:99], v[190:193], v[206:209], v[96:99]
	v_mfma_f32_16x16x32_bf16 v[88:91], v[176:179], v[210:213], v[88:91]
	v_mfma_f32_16x16x32_bf16 v[88:91], v[180:183], v[214:217], v[88:91]
	v_mfma_f32_16x16x32_bf16 v[80:83], v[186:189], v[210:213], v[80:83]
	v_mfma_f32_16x16x32_bf16 v[80:83], v[190:193], v[214:217], v[80:83]
	v_mfma_f32_16x16x32_bf16 v[72:75], v[176:179], v[218:221], v[72:75]
	v_mfma_f32_16x16x32_bf16 v[72:75], v[180:183], v[222:225], v[72:75]
	v_mfma_f32_16x16x32_bf16 v[64:67], v[186:189], v[218:221], v[64:67]
	v_mfma_f32_16x16x32_bf16 v[64:67], v[190:193], v[222:225], v[64:67]
	s_setprio 0
	s_barrier
	s_add_i32 s76, s66, s54
	v_lshl_add_u64 v[154:155], s[48:49], 0, v[132:133]
	s_mov_b32 m0, s76
	ds_read_b128 v[194:197], v150 offset:16384
	v_xor_b32_e32 v253, 64, v150
	ds_read_b128 v[198:201], v253 offset:16384
	ds_read_b128 v[202:205], v150 offset:18432
	ds_read_b128 v[206:209], v253 offset:18432
	ds_read_b128 v[210:213], v150 offset:20480
	ds_read_b128 v[214:217], v253 offset:20480
	ds_read_b128 v[218:221], v150 offset:22528
	ds_read_b128 v[222:225], v253 offset:22528
	global_load_lds_dwordx4 v[154:155], off
	s_add_i32 m0, s76, 0x2000
	s_add_u32 s76, s48, 0x40000
	v_lshl_add_u64 v[226:227], s[48:49], 0, v[128:129]
	s_addc_u32 s77, s49, 0
	s_add_i32 s78, s67, s54
	global_load_lds_dwordx4 v[226:227], off
	v_lshl_add_u64 v[228:229], s[76:77], 0, v[132:133]
	s_mov_b32 m0, s78
	v_lshl_add_u64 v[230:231], s[50:51], 0, v[130:131]
	global_load_lds_dwordx4 v[228:229], off
	v_lshl_add_u64 v[228:229], s[76:77], 0, v[128:129]
	s_add_i32 m0, s78, 0x2000
	s_nop 0
	global_load_lds_dwordx4 v[228:229], off
	v_lshl_add_u64 v[228:229], s[50:51], 0, v[134:135]
	s_mov_b32 m0, s57
	s_nop 0
	global_load_lds_dwordx4 v[228:229], off
	s_mov_b32 m0, s58
	s_nop 0
	global_load_lds_dwordx4 v[230:231], off
	s_waitcnt vmcnt(8)
	s_waitcnt lgkmcnt(0)
	s_barrier
	s_setprio 1
	s_waitcnt lgkmcnt(0)
	v_mfma_f32_16x16x32_bf16 v[60:63], v[160:163], v[194:197], v[60:63]
	v_mfma_f32_16x16x32_bf16 v[60:63], v[164:167], v[198:201], v[60:63]
	v_mfma_f32_16x16x32_bf16 v[52:55], v[168:171], v[194:197], v[52:55]
	v_mfma_f32_16x16x32_bf16 v[52:55], v[172:175], v[198:201], v[52:55]
	v_mfma_f32_16x16x32_bf16 v[44:47], v[160:163], v[202:205], v[44:47]
	v_mfma_f32_16x16x32_bf16 v[44:47], v[164:167], v[206:209], v[44:47]
	v_mfma_f32_16x16x32_bf16 v[36:39], v[168:171], v[202:205], v[36:39]
	v_mfma_f32_16x16x32_bf16 v[36:39], v[172:175], v[206:209], v[36:39]
	v_mfma_f32_16x16x32_bf16 v[28:31], v[160:163], v[210:213], v[28:31]
	v_mfma_f32_16x16x32_bf16 v[28:31], v[164:167], v[214:217], v[28:31]
	v_mfma_f32_16x16x32_bf16 v[20:23], v[168:171], v[210:213], v[20:23]
	v_mfma_f32_16x16x32_bf16 v[20:23], v[172:175], v[214:217], v[20:23]
	v_mfma_f32_16x16x32_bf16 v[12:15], v[160:163], v[218:221], v[12:15]
	v_mfma_f32_16x16x32_bf16 v[12:15], v[164:167], v[222:225], v[12:15]
	v_mfma_f32_16x16x32_bf16 v[4:7], v[168:171], v[218:221], v[4:7]
	v_mfma_f32_16x16x32_bf16 v[4:7], v[172:175], v[222:225], v[4:7]
	s_setprio 0
	s_setprio 1
	v_mfma_f32_16x16x32_bf16 v[56:59], v[176:179], v[194:197], v[56:59]
	v_mfma_f32_16x16x32_bf16 v[56:59], v[180:183], v[198:201], v[56:59]
	v_mfma_f32_16x16x32_bf16 v[48:51], v[186:189], v[194:197], v[48:51]
	v_mfma_f32_16x16x32_bf16 v[48:51], v[190:193], v[198:201], v[48:51]
	v_mfma_f32_16x16x32_bf16 v[40:43], v[176:179], v[202:205], v[40:43]
	v_mfma_f32_16x16x32_bf16 v[40:43], v[180:183], v[206:209], v[40:43]
	v_mfma_f32_16x16x32_bf16 v[32:35], v[186:189], v[202:205], v[32:35]
	v_mfma_f32_16x16x32_bf16 v[32:35], v[190:193], v[206:209], v[32:35]
	v_mfma_f32_16x16x32_bf16 v[24:27], v[176:179], v[210:213], v[24:27]
	v_mfma_f32_16x16x32_bf16 v[24:27], v[180:183], v[214:217], v[24:27]
	v_mfma_f32_16x16x32_bf16 v[16:19], v[186:189], v[210:213], v[16:19]
	v_mfma_f32_16x16x32_bf16 v[16:19], v[190:193], v[214:217], v[16:19]
	v_mfma_f32_16x16x32_bf16 v[8:11], v[176:179], v[218:221], v[8:11]
	v_mfma_f32_16x16x32_bf16 v[8:11], v[180:183], v[222:225], v[8:11]
	v_mfma_f32_16x16x32_bf16 v[0:3], v[186:189], v[218:221], v[0:3]
	v_mfma_f32_16x16x32_bf16 v[0:3], v[190:193], v[222:225], v[0:3]
	s_setprio 0
	s_barrier
	s_add_i32 s76, 0, 0x18000
	v_add_u32_e32 v153, s76, v147
	s_add_i32 s77, 0, 0x1c000
	ds_read_b128 v[160:163], v153
	v_xor_b32_e32 v253, 64, v153
	ds_read_b128 v[164:167], v253
	ds_read_b128 v[168:171], v153 offset:2048
	ds_read_b128 v[172:175], v253 offset:2048
	v_add_u32_e32 v153, s77, v147
	ds_read_b128 v[176:179], v153
	v_xor_b32_e32 v253, 64, v153
	ds_read_b128 v[180:183], v253
	ds_read_b128 v[186:189], v153 offset:2048
	ds_read_b128 v[190:193], v253 offset:2048
	s_add_u32 s50, s50, 0x40000
	s_addc_u32 s51, s51, 0
	s_mov_b32 m0, s59
	v_lshl_add_u64 v[232:233], s[50:51], 0, v[134:135]
	ds_read_b128 v[194:197], v150 offset:32768
	v_xor_b32_e32 v253, 64, v150
	ds_read_b128 v[198:201], v253 offset:32768
	ds_read_b128 v[202:205], v150 offset:34816
	ds_read_b128 v[206:209], v253 offset:34816
	ds_read_b128 v[210:213], v150 offset:36864
	ds_read_b128 v[214:217], v253 offset:36864
	ds_read_b128 v[218:221], v150 offset:38912
	ds_read_b128 v[222:225], v253 offset:38912
	global_load_lds_dwordx4 v[232:233], off
	v_lshl_add_u64 v[232:233], s[50:51], 0, v[130:131]
	s_mov_b32 m0, s60
	s_nop 0
	global_load_lds_dwordx4 v[232:233], off
	s_waitcnt vmcnt(8)
	s_waitcnt lgkmcnt(0)
	s_barrier
	s_setprio 1
	s_waitcnt lgkmcnt(0)
	v_mfma_f32_16x16x32_bf16 v[124:127], v[160:163], v[194:197], v[124:127]
	v_mfma_f32_16x16x32_bf16 v[124:127], v[164:167], v[198:201], v[124:127]
	v_mfma_f32_16x16x32_bf16 v[116:119], v[168:171], v[194:197], v[116:119]
	v_mfma_f32_16x16x32_bf16 v[116:119], v[172:175], v[198:201], v[116:119]
	v_mfma_f32_16x16x32_bf16 v[108:111], v[160:163], v[202:205], v[108:111]
	v_mfma_f32_16x16x32_bf16 v[108:111], v[164:167], v[206:209], v[108:111]
	v_mfma_f32_16x16x32_bf16 v[100:103], v[168:171], v[202:205], v[100:103]
	v_mfma_f32_16x16x32_bf16 v[100:103], v[172:175], v[206:209], v[100:103]
	v_mfma_f32_16x16x32_bf16 v[92:95], v[160:163], v[210:213], v[92:95]
	v_mfma_f32_16x16x32_bf16 v[92:95], v[164:167], v[214:217], v[92:95]
	v_mfma_f32_16x16x32_bf16 v[84:87], v[168:171], v[210:213], v[84:87]
	v_mfma_f32_16x16x32_bf16 v[84:87], v[172:175], v[214:217], v[84:87]
	v_mfma_f32_16x16x32_bf16 v[76:79], v[160:163], v[218:221], v[76:79]
	v_mfma_f32_16x16x32_bf16 v[76:79], v[164:167], v[222:225], v[76:79]
	v_mfma_f32_16x16x32_bf16 v[68:71], v[168:171], v[218:221], v[68:71]
	v_mfma_f32_16x16x32_bf16 v[68:71], v[172:175], v[222:225], v[68:71]
	s_setprio 0
	s_setprio 1
	v_mfma_f32_16x16x32_bf16 v[120:123], v[176:179], v[194:197], v[120:123]
	v_mfma_f32_16x16x32_bf16 v[120:123], v[180:183], v[198:201], v[120:123]
	v_mfma_f32_16x16x32_bf16 v[112:115], v[186:189], v[194:197], v[112:115]
	v_mfma_f32_16x16x32_bf16 v[112:115], v[190:193], v[198:201], v[112:115]
	v_mfma_f32_16x16x32_bf16 v[104:107], v[176:179], v[202:205], v[104:107]
	v_mfma_f32_16x16x32_bf16 v[104:107], v[180:183], v[206:209], v[104:107]
	v_mfma_f32_16x16x32_bf16 v[96:99], v[186:189], v[202:205], v[96:99]
	v_mfma_f32_16x16x32_bf16 v[96:99], v[190:193], v[206:209], v[96:99]
	v_mfma_f32_16x16x32_bf16 v[88:91], v[176:179], v[210:213], v[88:91]
	v_mfma_f32_16x16x32_bf16 v[88:91], v[180:183], v[214:217], v[88:91]
	v_mfma_f32_16x16x32_bf16 v[80:83], v[186:189], v[210:213], v[80:83]
	v_mfma_f32_16x16x32_bf16 v[80:83], v[190:193], v[214:217], v[80:83]
	v_mfma_f32_16x16x32_bf16 v[72:75], v[176:179], v[218:221], v[72:75]
	v_mfma_f32_16x16x32_bf16 v[72:75], v[180:183], v[222:225], v[72:75]
	v_mfma_f32_16x16x32_bf16 v[64:67], v[186:189], v[218:221], v[64:67]
	v_mfma_f32_16x16x32_bf16 v[64:67], v[190:193], v[222:225], v[64:67]
	s_setprio 0
	s_barrier
	s_add_i32 s50, s76, s54
	v_lshl_add_u64 v[154:155], v[154:155], 0, s[20:21]
	s_mov_b32 m0, s50
	ds_read_b128 v[194:197], v150 offset:49152
	v_xor_b32_e32 v253, 64, v150
	ds_read_b128 v[198:201], v253 offset:49152
	ds_read_b128 v[202:205], v150 offset:51200
	ds_read_b128 v[206:209], v253 offset:51200
	ds_read_b128 v[210:213], v150 offset:53248
	ds_read_b128 v[214:217], v253 offset:53248
	ds_read_b128 v[218:221], v150 offset:55296
	ds_read_b128 v[222:225], v253 offset:55296
	global_load_lds_dwordx4 v[154:155], off
	s_add_i32 m0, s50, 0x2000
	s_add_u32 s48, s48, 0x40080
	v_lshl_add_u64 v[154:155], v[226:227], 0, s[20:21]
	s_addc_u32 s49, s49, 0
	s_add_i32 s50, s77, s54
	global_load_lds_dwordx4 v[154:155], off
	v_lshl_add_u64 v[154:155], s[48:49], 0, v[132:133]
	s_mov_b32 m0, s50
	s_nop 0
	global_load_lds_dwordx4 v[154:155], off
	v_lshl_add_u64 v[154:155], s[48:49], 0, v[128:129]
	s_add_i32 m0, s50, 0x2000
	s_nop 0
	global_load_lds_dwordx4 v[154:155], off
	v_lshl_add_u64 v[154:155], v[228:229], 0, s[20:21]
	s_mov_b32 m0, s62
	s_nop 0
	global_load_lds_dwordx4 v[154:155], off
	v_lshl_add_u64 v[154:155], v[230:231], 0, s[20:21]
	s_mov_b32 m0, s63
	s_nop 0
	global_load_lds_dwordx4 v[154:155], off
	s_waitcnt vmcnt(8)
	s_waitcnt lgkmcnt(0)
	s_barrier
	s_setprio 1
	s_waitcnt lgkmcnt(0)
	v_mfma_f32_16x16x32_bf16 v[60:63], v[160:163], v[194:197], v[60:63]
	v_mfma_f32_16x16x32_bf16 v[60:63], v[164:167], v[198:201], v[60:63]
	v_mfma_f32_16x16x32_bf16 v[52:55], v[168:171], v[194:197], v[52:55]
	v_mfma_f32_16x16x32_bf16 v[52:55], v[172:175], v[198:201], v[52:55]
	v_mfma_f32_16x16x32_bf16 v[44:47], v[160:163], v[202:205], v[44:47]
	v_mfma_f32_16x16x32_bf16 v[44:47], v[164:167], v[206:209], v[44:47]
	v_mfma_f32_16x16x32_bf16 v[36:39], v[168:171], v[202:205], v[36:39]
	v_mfma_f32_16x16x32_bf16 v[36:39], v[172:175], v[206:209], v[36:39]
	v_mfma_f32_16x16x32_bf16 v[28:31], v[160:163], v[210:213], v[28:31]
	v_mfma_f32_16x16x32_bf16 v[28:31], v[164:167], v[214:217], v[28:31]
	v_mfma_f32_16x16x32_bf16 v[20:23], v[168:171], v[210:213], v[20:23]
	v_mfma_f32_16x16x32_bf16 v[20:23], v[172:175], v[214:217], v[20:23]
	v_mfma_f32_16x16x32_bf16 v[12:15], v[160:163], v[218:221], v[12:15]
	v_mfma_f32_16x16x32_bf16 v[12:15], v[164:167], v[222:225], v[12:15]
	v_mfma_f32_16x16x32_bf16 v[4:7], v[168:171], v[218:221], v[4:7]
	v_mfma_f32_16x16x32_bf16 v[4:7], v[172:175], v[222:225], v[4:7]
	s_setprio 0
	s_setprio 1
	v_mfma_f32_16x16x32_bf16 v[56:59], v[176:179], v[194:197], v[56:59]
	v_mfma_f32_16x16x32_bf16 v[56:59], v[180:183], v[198:201], v[56:59]
	v_mfma_f32_16x16x32_bf16 v[48:51], v[186:189], v[194:197], v[48:51]
	v_mfma_f32_16x16x32_bf16 v[48:51], v[190:193], v[198:201], v[48:51]
	v_mfma_f32_16x16x32_bf16 v[40:43], v[176:179], v[202:205], v[40:43]
	v_mfma_f32_16x16x32_bf16 v[40:43], v[180:183], v[206:209], v[40:43]
	v_mfma_f32_16x16x32_bf16 v[32:35], v[186:189], v[202:205], v[32:35]
	v_mfma_f32_16x16x32_bf16 v[32:35], v[190:193], v[206:209], v[32:35]
	v_mfma_f32_16x16x32_bf16 v[24:27], v[176:179], v[210:213], v[24:27]
	v_mfma_f32_16x16x32_bf16 v[24:27], v[180:183], v[214:217], v[24:27]
	v_mfma_f32_16x16x32_bf16 v[16:19], v[186:189], v[210:213], v[16:19]
	v_mfma_f32_16x16x32_bf16 v[16:19], v[190:193], v[214:217], v[16:19]
	v_mfma_f32_16x16x32_bf16 v[8:11], v[176:179], v[218:221], v[8:11]
	v_mfma_f32_16x16x32_bf16 v[8:11], v[180:183], v[222:225], v[8:11]
	v_mfma_f32_16x16x32_bf16 v[0:3], v[186:189], v[218:221], v[0:3]
	v_mfma_f32_16x16x32_bf16 v[0:3], v[190:193], v[222:225], v[0:3]
	s_setprio 0
	s_barrier
	s_add_i32 s75, s75, 2
	s_add_u32 s73, s73, 0x100
	s_addc_u32 s74, s74, 0
	s_add_u32 s46, s46, 0x100
	s_addc_u32 s47, s47, 0
	s_cmp_gt_u32 s75, 13
	s_cbranch_scc1 .LBB0_529

.Llast_4:
	v_add_u32_e32 v153, s66, v147
	ds_read_b128 v[160:163], v153
	v_xor_b32_e32 v253, 64, v153
	ds_read_b128 v[164:167], v253
	ds_read_b128 v[168:171], v153 offset:2048
	ds_read_b128 v[172:175], v253 offset:2048
	v_add_u32_e32 v153, s67, v147
	ds_read_b128 v[176:179], v153
	v_xor_b32_e32 v253, 64, v153
	ds_read_b128 v[180:183], v253
	ds_read_b128 v[186:189], v153 offset:2048
	ds_read_b128 v[190:193], v253 offset:2048
	s_add_u32 s50, s46, 0xfffc0080
	s_addc_u32 s51, s47, -1
	s_and_b64 s[48:49], s[48:49], exec
	s_cselect_b32 s51, s29, s51
	s_cselect_b32 s50, s70, s50
	s_cselect_b32 s49, s71, s74
	s_cselect_b32 s48, s72, s73
	v_lshl_add_u64 v[154:155], s[46:47], 0, v[138:139]
	s_add_i32 m0, s57, 0xc000
	ds_read_b128 v[194:197], v150
	v_xor_b32_e32 v253, 64, v150
	ds_read_b128 v[198:201], v253
	ds_read_b128 v[202:205], v150 offset:2048
	ds_read_b128 v[206:209], v253 offset:2048
	ds_read_b128 v[210:213], v150 offset:4096
	ds_read_b128 v[214:217], v253 offset:4096
	ds_read_b128 v[218:221], v150 offset:6144
	ds_read_b128 v[222:225], v253 offset:6144
	global_load_lds_dwordx4 v[154:155], off
	v_lshl_add_u64 v[154:155], s[46:47], 0, v[136:137]
	s_add_i32 m0, s57, 0xe000
	s_nop 0
	global_load_lds_dwordx4 v[154:155], off
	s_waitcnt vmcnt(8)
	s_waitcnt lgkmcnt(0)
	s_barrier
	s_setprio 1
	s_waitcnt lgkmcnt(0)
	v_mfma_f32_16x16x32_bf16 v[124:127], v[160:163], v[194:197], v[124:127]
	v_mfma_f32_16x16x32_bf16 v[124:127], v[164:167], v[198:201], v[124:127]
	v_mfma_f32_16x16x32_bf16 v[116:119], v[168:171], v[194:197], v[116:119]
	v_mfma_f32_16x16x32_bf16 v[116:119], v[172:175], v[198:201], v[116:119]
	v_mfma_f32_16x16x32_bf16 v[108:111], v[160:163], v[202:205], v[108:111]
	v_mfma_f32_16x16x32_bf16 v[108:111], v[164:167], v[206:209], v[108:111]
	v_mfma_f32_16x16x32_bf16 v[100:103], v[168:171], v[202:205], v[100:103]
	v_mfma_f32_16x16x32_bf16 v[100:103], v[172:175], v[206:209], v[100:103]
	v_mfma_f32_16x16x32_bf16 v[92:95], v[160:163], v[210:213], v[92:95]
	v_mfma_f32_16x16x32_bf16 v[92:95], v[164:167], v[214:217], v[92:95]
	v_mfma_f32_16x16x32_bf16 v[84:87], v[168:171], v[210:213], v[84:87]
	v_mfma_f32_16x16x32_bf16 v[84:87], v[172:175], v[214:217], v[84:87]
	v_mfma_f32_16x16x32_bf16 v[76:79], v[160:163], v[218:221], v[76:79]
	v_mfma_f32_16x16x32_bf16 v[76:79], v[164:167], v[222:225], v[76:79]
	v_mfma_f32_16x16x32_bf16 v[68:71], v[168:171], v[218:221], v[68:71]
	v_mfma_f32_16x16x32_bf16 v[68:71], v[172:175], v[222:225], v[68:71]
	s_setprio 0
	s_setprio 1
	v_mfma_f32_16x16x32_bf16 v[120:123], v[176:179], v[194:197], v[120:123]
	v_mfma_f32_16x16x32_bf16 v[120:123], v[180:183], v[198:201], v[120:123]
	v_mfma_f32_16x16x32_bf16 v[112:115], v[186:189], v[194:197], v[112:115]
	v_mfma_f32_16x16x32_bf16 v[112:115], v[190:193], v[198:201], v[112:115]
	v_mfma_f32_16x16x32_bf16 v[104:107], v[176:179], v[202:205], v[104:107]
	v_mfma_f32_16x16x32_bf16 v[104:107], v[180:183], v[206:209], v[104:107]
	v_mfma_f32_16x16x32_bf16 v[96:99], v[186:189], v[202:205], v[96:99]
	v_mfma_f32_16x16x32_bf16 v[96:99], v[190:193], v[206:209], v[96:99]
	v_mfma_f32_16x16x32_bf16 v[88:91], v[176:179], v[210:213], v[88:91]
	v_mfma_f32_16x16x32_bf16 v[88:91], v[180:183], v[214:217], v[88:91]
	v_mfma_f32_16x16x32_bf16 v[80:83], v[186:189], v[210:213], v[80:83]
	v_mfma_f32_16x16x32_bf16 v[80:83], v[190:193], v[214:217], v[80:83]
	v_mfma_f32_16x16x32_bf16 v[72:75], v[176:179], v[218:221], v[72:75]
	v_mfma_f32_16x16x32_bf16 v[72:75], v[180:183], v[222:225], v[72:75]
	v_mfma_f32_16x16x32_bf16 v[64:67], v[186:189], v[218:221], v[64:67]
	v_mfma_f32_16x16x32_bf16 v[64:67], v[190:193], v[222:225], v[64:67]
	s_setprio 0
	s_barrier
	s_add_i32 s76, s66, s54
	v_lshl_add_u64 v[154:155], s[48:49], 0, v[132:133]
	s_mov_b32 m0, s76
	ds_read_b128 v[194:197], v150 offset:16384
	v_xor_b32_e32 v253, 64, v150
	ds_read_b128 v[198:201], v253 offset:16384
	ds_read_b128 v[202:205], v150 offset:18432
	ds_read_b128 v[206:209], v253 offset:18432
	ds_read_b128 v[210:213], v150 offset:20480
	ds_read_b128 v[214:217], v253 offset:20480
	ds_read_b128 v[218:221], v150 offset:22528
	ds_read_b128 v[222:225], v253 offset:22528
	global_load_lds_dwordx4 v[154:155], off
	s_add_i32 m0, s76, 0x2000
	s_add_u32 s76, s48, 0x40000
	v_lshl_add_u64 v[226:227], s[48:49], 0, v[128:129]
	s_addc_u32 s77, s49, 0
	s_add_i32 s78, s67, s54
	global_load_lds_dwordx4 v[226:227], off
	v_lshl_add_u64 v[228:229], s[76:77], 0, v[132:133]
	s_mov_b32 m0, s78
	v_lshl_add_u64 v[230:231], s[50:51], 0, v[130:131]
	global_load_lds_dwordx4 v[228:229], off
	v_lshl_add_u64 v[228:229], s[76:77], 0, v[128:129]
	s_add_i32 m0, s78, 0x2000
	s_nop 0
	global_load_lds_dwordx4 v[228:229], off
	v_lshl_add_u64 v[228:229], s[50:51], 0, v[134:135]
	s_mov_b32 m0, s57
	s_nop 0
	global_load_lds_dwordx4 v[228:229], off
	s_mov_b32 m0, s58
	s_nop 0
	global_load_lds_dwordx4 v[230:231], off
	s_waitcnt vmcnt(8)
	s_waitcnt lgkmcnt(0)
	s_barrier
	s_setprio 1
	s_waitcnt lgkmcnt(0)
	v_mfma_f32_16x16x32_bf16 v[60:63], v[160:163], v[194:197], v[60:63]
	v_mfma_f32_16x16x32_bf16 v[60:63], v[164:167], v[198:201], v[60:63]
	v_mfma_f32_16x16x32_bf16 v[52:55], v[168:171], v[194:197], v[52:55]
	v_mfma_f32_16x16x32_bf16 v[52:55], v[172:175], v[198:201], v[52:55]
	v_mfma_f32_16x16x32_bf16 v[44:47], v[160:163], v[202:205], v[44:47]
	v_mfma_f32_16x16x32_bf16 v[44:47], v[164:167], v[206:209], v[44:47]
	v_mfma_f32_16x16x32_bf16 v[36:39], v[168:171], v[202:205], v[36:39]
	v_mfma_f32_16x16x32_bf16 v[36:39], v[172:175], v[206:209], v[36:39]
	v_mfma_f32_16x16x32_bf16 v[28:31], v[160:163], v[210:213], v[28:31]
	v_mfma_f32_16x16x32_bf16 v[28:31], v[164:167], v[214:217], v[28:31]
	v_mfma_f32_16x16x32_bf16 v[20:23], v[168:171], v[210:213], v[20:23]
	v_mfma_f32_16x16x32_bf16 v[20:23], v[172:175], v[214:217], v[20:23]
	v_mfma_f32_16x16x32_bf16 v[12:15], v[160:163], v[218:221], v[12:15]
	v_mfma_f32_16x16x32_bf16 v[12:15], v[164:167], v[222:225], v[12:15]
	v_mfma_f32_16x16x32_bf16 v[4:7], v[168:171], v[218:221], v[4:7]
	v_mfma_f32_16x16x32_bf16 v[4:7], v[172:175], v[222:225], v[4:7]
	s_setprio 0
	s_setprio 1
	v_mfma_f32_16x16x32_bf16 v[56:59], v[176:179], v[194:197], v[56:59]
	v_mfma_f32_16x16x32_bf16 v[56:59], v[180:183], v[198:201], v[56:59]
	v_mfma_f32_16x16x32_bf16 v[48:51], v[186:189], v[194:197], v[48:51]
	v_mfma_f32_16x16x32_bf16 v[48:51], v[190:193], v[198:201], v[48:51]
	v_mfma_f32_16x16x32_bf16 v[40:43], v[176:179], v[202:205], v[40:43]
	v_mfma_f32_16x16x32_bf16 v[40:43], v[180:183], v[206:209], v[40:43]
	v_mfma_f32_16x16x32_bf16 v[32:35], v[186:189], v[202:205], v[32:35]
	v_mfma_f32_16x16x32_bf16 v[32:35], v[190:193], v[206:209], v[32:35]
	v_mfma_f32_16x16x32_bf16 v[24:27], v[176:179], v[210:213], v[24:27]
	v_mfma_f32_16x16x32_bf16 v[24:27], v[180:183], v[214:217], v[24:27]
	v_mfma_f32_16x16x32_bf16 v[16:19], v[186:189], v[210:213], v[16:19]
	v_mfma_f32_16x16x32_bf16 v[16:19], v[190:193], v[214:217], v[16:19]
	v_mfma_f32_16x16x32_bf16 v[8:11], v[176:179], v[218:221], v[8:11]
	v_mfma_f32_16x16x32_bf16 v[8:11], v[180:183], v[222:225], v[8:11]
	v_mfma_f32_16x16x32_bf16 v[0:3], v[186:189], v[218:221], v[0:3]
	v_mfma_f32_16x16x32_bf16 v[0:3], v[190:193], v[222:225], v[0:3]
	s_setprio 0
	s_barrier
	s_add_i32 s76, 0, 0x18000
	v_add_u32_e32 v153, s76, v147
	s_add_i32 s77, 0, 0x1c000
	ds_read_b128 v[160:163], v153
	v_xor_b32_e32 v253, 64, v153
	ds_read_b128 v[164:167], v253
	ds_read_b128 v[168:171], v153 offset:2048
	ds_read_b128 v[172:175], v253 offset:2048
	v_add_u32_e32 v153, s77, v147
	ds_read_b128 v[176:179], v153
	v_xor_b32_e32 v253, 64, v153
	ds_read_b128 v[180:183], v253
	ds_read_b128 v[186:189], v153 offset:2048
	ds_read_b128 v[190:193], v253 offset:2048
	s_add_u32 s50, s50, 0x40000
	s_addc_u32 s51, s51, 0
	s_mov_b32 m0, s59
	v_lshl_add_u64 v[232:233], s[50:51], 0, v[134:135]
	ds_read_b128 v[194:197], v150 offset:32768
	v_xor_b32_e32 v253, 64, v150
	ds_read_b128 v[198:201], v253 offset:32768
	ds_read_b128 v[202:205], v150 offset:34816
	ds_read_b128 v[206:209], v253 offset:34816
	ds_read_b128 v[210:213], v150 offset:36864
	ds_read_b128 v[214:217], v253 offset:36864
	ds_read_b128 v[218:221], v150 offset:38912
	ds_read_b128 v[222:225], v253 offset:38912
	global_load_lds_dwordx4 v[232:233], off
	v_lshl_add_u64 v[232:233], s[50:51], 0, v[130:131]
	s_mov_b32 m0, s60
	s_nop 0
	global_load_lds_dwordx4 v[232:233], off
	s_waitcnt vmcnt(8)
	s_waitcnt lgkmcnt(0)
	s_barrier
	s_setprio 1
	s_waitcnt lgkmcnt(0)
	v_mfma_f32_16x16x32_bf16 v[124:127], v[160:163], v[194:197], v[124:127]
	v_mfma_f32_16x16x32_bf16 v[124:127], v[164:167], v[198:201], v[124:127]
	v_mfma_f32_16x16x32_bf16 v[116:119], v[168:171], v[194:197], v[116:119]
	v_mfma_f32_16x16x32_bf16 v[116:119], v[172:175], v[198:201], v[116:119]
	v_mfma_f32_16x16x32_bf16 v[108:111], v[160:163], v[202:205], v[108:111]
	v_mfma_f32_16x16x32_bf16 v[108:111], v[164:167], v[206:209], v[108:111]
	v_mfma_f32_16x16x32_bf16 v[100:103], v[168:171], v[202:205], v[100:103]
	v_mfma_f32_16x16x32_bf16 v[100:103], v[172:175], v[206:209], v[100:103]
	v_mfma_f32_16x16x32_bf16 v[92:95], v[160:163], v[210:213], v[92:95]
	v_mfma_f32_16x16x32_bf16 v[92:95], v[164:167], v[214:217], v[92:95]
	v_mfma_f32_16x16x32_bf16 v[84:87], v[168:171], v[210:213], v[84:87]
	v_mfma_f32_16x16x32_bf16 v[84:87], v[172:175], v[214:217], v[84:87]
	v_mfma_f32_16x16x32_bf16 v[76:79], v[160:163], v[218:221], v[76:79]
	v_mfma_f32_16x16x32_bf16 v[76:79], v[164:167], v[222:225], v[76:79]
	v_mfma_f32_16x16x32_bf16 v[68:71], v[168:171], v[218:221], v[68:71]
	v_mfma_f32_16x16x32_bf16 v[68:71], v[172:175], v[222:225], v[68:71]
	s_setprio 0
	s_setprio 1
	v_mfma_f32_16x16x32_bf16 v[120:123], v[176:179], v[194:197], v[120:123]
	v_mfma_f32_16x16x32_bf16 v[120:123], v[180:183], v[198:201], v[120:123]
	v_mfma_f32_16x16x32_bf16 v[112:115], v[186:189], v[194:197], v[112:115]
	v_mfma_f32_16x16x32_bf16 v[112:115], v[190:193], v[198:201], v[112:115]
	v_mfma_f32_16x16x32_bf16 v[104:107], v[176:179], v[202:205], v[104:107]
	v_mfma_f32_16x16x32_bf16 v[104:107], v[180:183], v[206:209], v[104:107]
	v_mfma_f32_16x16x32_bf16 v[96:99], v[186:189], v[202:205], v[96:99]
	v_mfma_f32_16x16x32_bf16 v[96:99], v[190:193], v[206:209], v[96:99]
	v_mfma_f32_16x16x32_bf16 v[88:91], v[176:179], v[210:213], v[88:91]
	v_mfma_f32_16x16x32_bf16 v[88:91], v[180:183], v[214:217], v[88:91]
	v_mfma_f32_16x16x32_bf16 v[80:83], v[186:189], v[210:213], v[80:83]
	v_mfma_f32_16x16x32_bf16 v[80:83], v[190:193], v[214:217], v[80:83]
	v_mfma_f32_16x16x32_bf16 v[72:75], v[176:179], v[218:221], v[72:75]
	v_mfma_f32_16x16x32_bf16 v[72:75], v[180:183], v[222:225], v[72:75]
	v_mfma_f32_16x16x32_bf16 v[64:67], v[186:189], v[218:221], v[64:67]
	v_mfma_f32_16x16x32_bf16 v[64:67], v[190:193], v[222:225], v[64:67]
	s_setprio 0
	s_barrier
	v_add_u32_e32 v234, 0x21000, v151
	ds_read_b128 v[236:239], v234
	ds_read_b128 v[240:243], v234 offset:256
	ds_read_b128 v[244:247], v234 offset:512
	ds_read_b128 v[248:251], v234 offset:768
	v_add_u32_e32 v235, s27, v146
	v_mul_u32_u24_e32 v235, 0x1600, v235
	v_lshl_or_b32 v234, s69, 7, v149
	v_lshl_add_u32 v235, v234, 1, v235
	s_add_i32 s50, s76, s54
	v_lshl_add_u64 v[154:155], v[154:155], 0, s[20:21]
	s_mov_b32 m0, s50
	ds_read_b128 v[194:197], v150 offset:49152
	v_xor_b32_e32 v253, 64, v150
	ds_read_b128 v[198:201], v253 offset:49152
	ds_read_b128 v[202:205], v150 offset:51200
	ds_read_b128 v[206:209], v253 offset:51200
	ds_read_b128 v[210:213], v150 offset:53248
	ds_read_b128 v[214:217], v253 offset:53248
	ds_read_b128 v[218:221], v150 offset:55296
	ds_read_b128 v[222:225], v253 offset:55296
	global_load_lds_dwordx4 v[154:155], off
	s_add_i32 m0, s50, 0x2000
	s_add_u32 s48, s48, 0x40080
	v_lshl_add_u64 v[154:155], v[226:227], 0, s[20:21]
	s_addc_u32 s49, s49, 0
	s_add_i32 s50, s77, s54
	global_load_lds_dwordx4 v[154:155], off
	v_lshl_add_u64 v[154:155], s[48:49], 0, v[132:133]
	s_mov_b32 m0, s50
	s_nop 0
	global_load_lds_dwordx4 v[154:155], off
	v_lshl_add_u64 v[154:155], s[48:49], 0, v[128:129]
	s_add_i32 m0, s50, 0x2000
	s_nop 0
	global_load_lds_dwordx4 v[154:155], off
	v_lshl_add_u64 v[154:155], v[228:229], 0, s[20:21]
	s_mov_b32 m0, s62
	s_nop 0
	global_load_lds_dwordx4 v[154:155], off
	v_lshl_add_u64 v[154:155], v[230:231], 0, s[20:21]
	s_mov_b32 m0, s63
	s_nop 0
	global_load_lds_dwordx4 v[154:155], off
	s_waitcnt lgkmcnt(8)
	v_add_f32_e32 v236, v236, v237
	v_add_f32_e32 v238, v238, v239
	v_add_f32_e32 v240, v240, v241
	v_add_f32_e32 v242, v242, v243
	v_add_f32_e32 v244, v244, v245
	v_add_f32_e32 v246, v246, v247
	v_add_f32_e32 v248, v248, v249
	v_add_f32_e32 v250, v250, v251
	v_add_f32_e32 v236, v236, v238
	v_add_f32_e32 v240, v240, v242
	v_add_f32_e32 v244, v244, v246
	v_add_f32_e32 v248, v248, v250
	v_fmamk_f32 v236, v236, 0x3a800000, v152
	v_fmamk_f32 v240, v240, 0x3a800000, v152
	v_fmamk_f32 v244, v244, 0x3a800000, v152
	v_fmamk_f32 v248, v248, 0x3a800000, v152
	v_rsq_f32_e32 v236, v236
	v_rsq_f32_e32 v240, v240
	v_rsq_f32_e32 v244, v244
	v_rsq_f32_e32 v248, v248
	v_mul_f32_e32 v252, 0xbfb8aa3b, v236
	v_mul_f32_e32 v254, v236, v236
	v_pk_mul_f32 v[120:121], v[124:125], v[120:121]
	v_pk_mul_f32 v[122:123], v[126:127], v[122:123]
	v_pk_mul_f32 v[112:113], v[116:117], v[112:113]
	v_pk_mul_f32 v[114:115], v[118:119], v[114:115]
	v_pk_mul_f32 v[124:125], v[124:125], v[252:253] op_sel_hi:[1,0]
	v_pk_mul_f32 v[126:127], v[126:127], v[252:253] op_sel_hi:[1,0]
	v_pk_mul_f32 v[116:117], v[116:117], v[252:253] op_sel_hi:[1,0]
	v_pk_mul_f32 v[118:119], v[118:119], v[252:253] op_sel_hi:[1,0]
	v_exp_f32_e32 v124, v124
	v_exp_f32_e32 v125, v125
	v_exp_f32_e32 v126, v126
	v_exp_f32_e32 v127, v127
	v_exp_f32_e32 v116, v116
	v_exp_f32_e32 v117, v117
	v_exp_f32_e32 v118, v118
	v_exp_f32_e32 v119, v119
	v_pk_add_f32 v[124:125], v[124:125], 1.0 op_sel_hi:[1,0]
	v_pk_add_f32 v[126:127], v[126:127], 1.0 op_sel_hi:[1,0]
	v_pk_add_f32 v[116:117], v[116:117], 1.0 op_sel_hi:[1,0]
	v_pk_add_f32 v[118:119], v[118:119], 1.0 op_sel_hi:[1,0]
	v_rcp_f32_e32 v124, v124
	v_rcp_f32_e32 v125, v125
	v_rcp_f32_e32 v126, v126
	v_rcp_f32_e32 v127, v127
	v_rcp_f32_e32 v116, v116
	v_rcp_f32_e32 v117, v117
	v_rcp_f32_e32 v118, v118
	v_rcp_f32_e32 v119, v119
	v_pk_mul_f32 v[120:121], v[120:121], v[254:255] op_sel_hi:[1,0]
	v_pk_mul_f32 v[122:123], v[122:123], v[254:255] op_sel_hi:[1,0]
	v_pk_mul_f32 v[112:113], v[112:113], v[254:255] op_sel_hi:[1,0]
	v_pk_mul_f32 v[114:115], v[114:115], v[254:255] op_sel_hi:[1,0]
	v_pk_mul_f32 v[120:121], v[120:121], v[124:125]
	v_pk_mul_f32 v[122:123], v[122:123], v[126:127]
	v_pk_mul_f32 v[112:113], v[112:113], v[116:117]
	v_pk_mul_f32 v[114:115], v[114:115], v[118:119]
	v_cvt_pk_bf16_f32 v120, v120, v121
	v_cvt_pk_bf16_f32 v121, v122, v123
	v_cvt_pk_bf16_f32 v122, v112, v113
	v_cvt_pk_bf16_f32 v123, v114, v115
	global_store_dwordx4 v235, v[120:123], s[14:15]
	v_add_u32_e32 v234, 0x16000, v235
	v_mul_f32_e32 v252, 0xbfb8aa3b, v240
	v_mul_f32_e32 v254, v240, v240
	v_pk_mul_f32 v[104:105], v[108:109], v[104:105]
	v_pk_mul_f32 v[106:107], v[110:111], v[106:107]
	v_pk_mul_f32 v[96:97], v[100:101], v[96:97]
	v_pk_mul_f32 v[98:99], v[102:103], v[98:99]
	v_pk_mul_f32 v[108:109], v[108:109], v[252:253] op_sel_hi:[1,0]
	v_pk_mul_f32 v[110:111], v[110:111], v[252:253] op_sel_hi:[1,0]
	v_pk_mul_f32 v[100:101], v[100:101], v[252:253] op_sel_hi:[1,0]
	v_pk_mul_f32 v[102:103], v[102:103], v[252:253] op_sel_hi:[1,0]
	v_exp_f32_e32 v108, v108
	v_exp_f32_e32 v109, v109
	v_exp_f32_e32 v110, v110
	v_exp_f32_e32 v111, v111
	v_exp_f32_e32 v100, v100
	v_exp_f32_e32 v101, v101
	v_exp_f32_e32 v102, v102
	v_exp_f32_e32 v103, v103
	v_pk_add_f32 v[108:109], v[108:109], 1.0 op_sel_hi:[1,0]
	v_pk_add_f32 v[110:111], v[110:111], 1.0 op_sel_hi:[1,0]
	v_pk_add_f32 v[100:101], v[100:101], 1.0 op_sel_hi:[1,0]
	v_pk_add_f32 v[102:103], v[102:103], 1.0 op_sel_hi:[1,0]
	v_rcp_f32_e32 v108, v108
	v_rcp_f32_e32 v109, v109
	v_rcp_f32_e32 v110, v110
	v_rcp_f32_e32 v111, v111
	v_rcp_f32_e32 v100, v100
	v_rcp_f32_e32 v101, v101
	v_rcp_f32_e32 v102, v102
	v_rcp_f32_e32 v103, v103
	v_pk_mul_f32 v[104:105], v[104:105], v[254:255] op_sel_hi:[1,0]
	v_pk_mul_f32 v[106:107], v[106:107], v[254:255] op_sel_hi:[1,0]
	v_pk_mul_f32 v[96:97], v[96:97], v[254:255] op_sel_hi:[1,0]
	v_pk_mul_f32 v[98:99], v[98:99], v[254:255] op_sel_hi:[1,0]
	v_pk_mul_f32 v[104:105], v[104:105], v[108:109]
	v_pk_mul_f32 v[106:107], v[106:107], v[110:111]
	v_pk_mul_f32 v[96:97], v[96:97], v[100:101]
	v_pk_mul_f32 v[98:99], v[98:99], v[102:103]
	v_cvt_pk_bf16_f32 v104, v104, v105
	v_cvt_pk_bf16_f32 v105, v106, v107
	v_cvt_pk_bf16_f32 v106, v96, v97
	v_cvt_pk_bf16_f32 v107, v98, v99
	global_store_dwordx4 v234, v[104:107], s[14:15]
	v_add_u32_e32 v235, 0x16000, v234
	v_mul_f32_e32 v252, 0xbfb8aa3b, v244
	v_mul_f32_e32 v254, v244, v244
	v_pk_mul_f32 v[88:89], v[92:93], v[88:89]
	v_pk_mul_f32 v[90:91], v[94:95], v[90:91]
	v_pk_mul_f32 v[80:81], v[84:85], v[80:81]
	v_pk_mul_f32 v[82:83], v[86:87], v[82:83]
	v_pk_mul_f32 v[92:93], v[92:93], v[252:253] op_sel_hi:[1,0]
	v_pk_mul_f32 v[94:95], v[94:95], v[252:253] op_sel_hi:[1,0]
	v_pk_mul_f32 v[84:85], v[84:85], v[252:253] op_sel_hi:[1,0]
	v_pk_mul_f32 v[86:87], v[86:87], v[252:253] op_sel_hi:[1,0]
	v_exp_f32_e32 v92, v92
	v_exp_f32_e32 v93, v93
	v_exp_f32_e32 v94, v94
	v_exp_f32_e32 v95, v95
	v_exp_f32_e32 v84, v84
	v_exp_f32_e32 v85, v85
	v_exp_f32_e32 v86, v86
	v_exp_f32_e32 v87, v87
	v_pk_add_f32 v[92:93], v[92:93], 1.0 op_sel_hi:[1,0]
	v_pk_add_f32 v[94:95], v[94:95], 1.0 op_sel_hi:[1,0]
	v_pk_add_f32 v[84:85], v[84:85], 1.0 op_sel_hi:[1,0]
	v_pk_add_f32 v[86:87], v[86:87], 1.0 op_sel_hi:[1,0]
	v_rcp_f32_e32 v92, v92
	v_rcp_f32_e32 v93, v93
	v_rcp_f32_e32 v94, v94
	v_rcp_f32_e32 v95, v95
	v_rcp_f32_e32 v84, v84
	v_rcp_f32_e32 v85, v85
	v_rcp_f32_e32 v86, v86
	v_rcp_f32_e32 v87, v87
	v_pk_mul_f32 v[88:89], v[88:89], v[254:255] op_sel_hi:[1,0]
	v_pk_mul_f32 v[90:91], v[90:91], v[254:255] op_sel_hi:[1,0]
	v_pk_mul_f32 v[80:81], v[80:81], v[254:255] op_sel_hi:[1,0]
	v_pk_mul_f32 v[82:83], v[82:83], v[254:255] op_sel_hi:[1,0]
	v_pk_mul_f32 v[88:89], v[88:89], v[92:93]
	v_pk_mul_f32 v[90:91], v[90:91], v[94:95]
	v_pk_mul_f32 v[80:81], v[80:81], v[84:85]
	v_pk_mul_f32 v[82:83], v[82:83], v[86:87]
	v_cvt_pk_bf16_f32 v88, v88, v89
	v_cvt_pk_bf16_f32 v89, v90, v91
	v_cvt_pk_bf16_f32 v90, v80, v81
	v_cvt_pk_bf16_f32 v91, v82, v83
	global_store_dwordx4 v235, v[88:91], s[14:15]
	v_add_u32_e32 v234, 0x16000, v235
	v_mul_f32_e32 v252, 0xbfb8aa3b, v248
	v_mul_f32_e32 v254, v248, v248
	v_pk_mul_f32 v[72:73], v[76:77], v[72:73]
	v_pk_mul_f32 v[74:75], v[78:79], v[74:75]
	v_pk_mul_f32 v[64:65], v[68:69], v[64:65]
	v_pk_mul_f32 v[66:67], v[70:71], v[66:67]
	v_pk_mul_f32 v[76:77], v[76:77], v[252:253] op_sel_hi:[1,0]
	v_pk_mul_f32 v[78:79], v[78:79], v[252:253] op_sel_hi:[1,0]
	v_pk_mul_f32 v[68:69], v[68:69], v[252:253] op_sel_hi:[1,0]
	v_pk_mul_f32 v[70:71], v[70:71], v[252:253] op_sel_hi:[1,0]
	v_exp_f32_e32 v76, v76
	v_exp_f32_e32 v77, v77
	v_exp_f32_e32 v78, v78
	v_exp_f32_e32 v79, v79
	v_exp_f32_e32 v68, v68
	v_exp_f32_e32 v69, v69
	v_exp_f32_e32 v70, v70
	v_exp_f32_e32 v71, v71
	v_pk_add_f32 v[76:77], v[76:77], 1.0 op_sel_hi:[1,0]
	v_pk_add_f32 v[78:79], v[78:79], 1.0 op_sel_hi:[1,0]
	v_pk_add_f32 v[68:69], v[68:69], 1.0 op_sel_hi:[1,0]
	v_pk_add_f32 v[70:71], v[70:71], 1.0 op_sel_hi:[1,0]
	v_rcp_f32_e32 v76, v76
	v_rcp_f32_e32 v77, v77
	v_rcp_f32_e32 v78, v78
	v_rcp_f32_e32 v79, v79
	v_rcp_f32_e32 v68, v68
	v_rcp_f32_e32 v69, v69
	v_rcp_f32_e32 v70, v70
	v_rcp_f32_e32 v71, v71
	v_pk_mul_f32 v[72:73], v[72:73], v[254:255] op_sel_hi:[1,0]
	v_pk_mul_f32 v[74:75], v[74:75], v[254:255] op_sel_hi:[1,0]
	v_pk_mul_f32 v[64:65], v[64:65], v[254:255] op_sel_hi:[1,0]
	v_pk_mul_f32 v[66:67], v[66:67], v[254:255] op_sel_hi:[1,0]
	v_pk_mul_f32 v[72:73], v[72:73], v[76:77]
	v_pk_mul_f32 v[74:75], v[74:75], v[78:79]
	v_pk_mul_f32 v[64:65], v[64:65], v[68:69]
	v_pk_mul_f32 v[66:67], v[66:67], v[70:71]
	v_cvt_pk_bf16_f32 v72, v72, v73
	v_cvt_pk_bf16_f32 v73, v74, v75
	v_cvt_pk_bf16_f32 v74, v64, v65
	v_cvt_pk_bf16_f32 v75, v66, v67
	global_store_dwordx4 v234, v[72:75], s[14:15]
	s_waitcnt vmcnt(12)
	s_waitcnt lgkmcnt(0)
	s_barrier
	s_setprio 1
	s_waitcnt lgkmcnt(0)
	v_mfma_f32_16x16x32_bf16 v[60:63], v[160:163], v[194:197], v[60:63]
	v_mfma_f32_16x16x32_bf16 v[60:63], v[164:167], v[198:201], v[60:63]
	v_mfma_f32_16x16x32_bf16 v[52:55], v[168:171], v[194:197], v[52:55]
	v_mfma_f32_16x16x32_bf16 v[52:55], v[172:175], v[198:201], v[52:55]
	v_mfma_f32_16x16x32_bf16 v[44:47], v[160:163], v[202:205], v[44:47]
	v_mfma_f32_16x16x32_bf16 v[44:47], v[164:167], v[206:209], v[44:47]
	v_mfma_f32_16x16x32_bf16 v[36:39], v[168:171], v[202:205], v[36:39]
	v_mfma_f32_16x16x32_bf16 v[36:39], v[172:175], v[206:209], v[36:39]
	v_mfma_f32_16x16x32_bf16 v[28:31], v[160:163], v[210:213], v[28:31]
	v_mfma_f32_16x16x32_bf16 v[28:31], v[164:167], v[214:217], v[28:31]
	v_mfma_f32_16x16x32_bf16 v[20:23], v[168:171], v[210:213], v[20:23]
	v_mfma_f32_16x16x32_bf16 v[20:23], v[172:175], v[214:217], v[20:23]
	v_mfma_f32_16x16x32_bf16 v[12:15], v[160:163], v[218:221], v[12:15]
	v_mfma_f32_16x16x32_bf16 v[12:15], v[164:167], v[222:225], v[12:15]
	v_mfma_f32_16x16x32_bf16 v[4:7], v[168:171], v[218:221], v[4:7]
	v_mfma_f32_16x16x32_bf16 v[4:7], v[172:175], v[222:225], v[4:7]
	s_setprio 0
	s_setprio 1
	v_mfma_f32_16x16x32_bf16 v[56:59], v[176:179], v[194:197], v[56:59]
	v_mfma_f32_16x16x32_bf16 v[56:59], v[180:183], v[198:201], v[56:59]
	v_mfma_f32_16x16x32_bf16 v[48:51], v[186:189], v[194:197], v[48:51]
	v_mfma_f32_16x16x32_bf16 v[48:51], v[190:193], v[198:201], v[48:51]
	v_mfma_f32_16x16x32_bf16 v[40:43], v[176:179], v[202:205], v[40:43]
	v_mfma_f32_16x16x32_bf16 v[40:43], v[180:183], v[206:209], v[40:43]
	v_mfma_f32_16x16x32_bf16 v[32:35], v[186:189], v[202:205], v[32:35]
	v_mfma_f32_16x16x32_bf16 v[32:35], v[190:193], v[206:209], v[32:35]
	v_mfma_f32_16x16x32_bf16 v[24:27], v[176:179], v[210:213], v[24:27]
	v_mfma_f32_16x16x32_bf16 v[24:27], v[180:183], v[214:217], v[24:27]
	v_mfma_f32_16x16x32_bf16 v[16:19], v[186:189], v[210:213], v[16:19]
	v_mfma_f32_16x16x32_bf16 v[16:19], v[190:193], v[214:217], v[16:19]
	v_mfma_f32_16x16x32_bf16 v[8:11], v[176:179], v[218:221], v[8:11]
	v_mfma_f32_16x16x32_bf16 v[8:11], v[180:183], v[222:225], v[8:11]
	v_mfma_f32_16x16x32_bf16 v[0:3], v[186:189], v[218:221], v[0:3]
	v_mfma_f32_16x16x32_bf16 v[0:3], v[190:193], v[222:225], v[0:3]
	s_setprio 0
	s_barrier
	s_add_i32 s75, s75, 2
	s_add_u32 s73, s73, 0x100
	s_addc_u32 s74, s74, 0
	s_add_u32 s46, s46, 0x100
	s_addc_u32 s47, s47, 0

.LBB0_609:
	s_add_u32 s79, s56, 0x100
	s_addc_u32 s80, s57, 0
	s_mov_b32 s81, -2
	s_waitcnt lgkmcnt(0)
	s_cmp_eq_u32 s70, 1
	s_cbranch_scc1 .Lfa_5
	ds_read_b128 v[128:131], v189
	v_xor_b32_e32 v253, 64, v189
	ds_read_b128 v[132:135], v253
	ds_read_b128 v[136:139], v189 offset:2048
	ds_read_b128 v[140:143], v253 offset:2048
	ds_read_b128 v[144:147], v190
	v_xor_b32_e32 v253, 64, v190
	ds_read_b128 v[148:151], v253
	ds_read_b128 v[172:175], v190 offset:2048
	ds_read_b128 v[176:179], v253 offset:2048
	s_add_u32 s56, s54, 0x100
	s_addc_u32 s57, s55, 0
	s_cmp_eq_u32 s81, 40
	s_cselect_b32 s61, s17, s57
	s_cselect_b32 s60, s16, s56
	s_cselect_b32 s59, s53, s80
	s_cselect_b32 s58, s52, s79
	v_lshl_add_u64 v[222:223], s[54:55], 0, v[166:167]
	s_add_i32 m0, s66, 0xc000
	ds_read_b128 v[180:183], v191
	v_xor_b32_e32 v253, 64, v191
	ds_read_b128 v[194:197], v253
	ds_read_b128 v[198:201], v191 offset:2048
	ds_read_b128 v[202:205], v253 offset:2048
	ds_read_b128 v[206:209], v191 offset:4096
	ds_read_b128 v[210:213], v253 offset:4096
	ds_read_b128 v[214:217], v191 offset:6144
	ds_read_b128 v[218:221], v253 offset:6144
	global_load_lds_dwordx4 v[222:223], off
	v_lshl_add_u64 v[222:223], s[54:55], 0, v[164:165]
	s_add_i32 m0, s66, 0xe000
	s_nop 0
	global_load_lds_dwordx4 v[222:223], off
	s_waitcnt vmcnt(24)
	s_waitcnt lgkmcnt(0)
	s_barrier
	s_setprio 1
	s_waitcnt lgkmcnt(0)
	v_mfma_f32_16x16x32_bf16 v[124:127], v[128:131], v[180:183], 0
	v_mfma_f32_16x16x32_bf16 v[120:123], v[136:139], v[180:183], 0
	v_mfma_f32_16x16x32_bf16 v[108:111], v[128:131], v[198:201], 0
	v_mfma_f32_16x16x32_bf16 v[104:107], v[136:139], v[198:201], 0
	v_mfma_f32_16x16x32_bf16 v[92:95], v[128:131], v[206:209], 0
	v_mfma_f32_16x16x32_bf16 v[88:91], v[136:139], v[206:209], 0
	v_mfma_f32_16x16x32_bf16 v[76:79], v[128:131], v[214:217], 0
	v_mfma_f32_16x16x32_bf16 v[72:75], v[136:139], v[214:217], 0
	v_mfma_f32_16x16x32_bf16 v[124:127], v[132:135], v[194:197], v[124:127]
	v_mfma_f32_16x16x32_bf16 v[120:123], v[140:143], v[194:197], v[120:123]
	v_mfma_f32_16x16x32_bf16 v[108:111], v[132:135], v[202:205], v[108:111]
	v_mfma_f32_16x16x32_bf16 v[104:107], v[140:143], v[202:205], v[104:107]
	v_mfma_f32_16x16x32_bf16 v[92:95], v[132:135], v[210:213], v[92:95]
	v_mfma_f32_16x16x32_bf16 v[88:91], v[140:143], v[210:213], v[88:91]
	v_mfma_f32_16x16x32_bf16 v[76:79], v[132:135], v[218:221], v[76:79]
	v_mfma_f32_16x16x32_bf16 v[72:75], v[140:143], v[218:221], v[72:75]
	s_setprio 0
	s_setprio 1
	v_mfma_f32_16x16x32_bf16 v[116:119], v[144:147], v[180:183], 0
	v_mfma_f32_16x16x32_bf16 v[112:115], v[172:175], v[180:183], 0
	v_mfma_f32_16x16x32_bf16 v[100:103], v[144:147], v[198:201], 0
	v_mfma_f32_16x16x32_bf16 v[96:99], v[172:175], v[198:201], 0
	v_mfma_f32_16x16x32_bf16 v[84:87], v[144:147], v[206:209], 0
	v_mfma_f32_16x16x32_bf16 v[80:83], v[172:175], v[206:209], 0
	v_mfma_f32_16x16x32_bf16 v[68:71], v[144:147], v[214:217], 0
	v_mfma_f32_16x16x32_bf16 v[64:67], v[172:175], v[214:217], 0
	v_mfma_f32_16x16x32_bf16 v[116:119], v[148:151], v[194:197], v[116:119]
	v_mfma_f32_16x16x32_bf16 v[112:115], v[176:179], v[194:197], v[112:115]
	v_mfma_f32_16x16x32_bf16 v[100:103], v[148:151], v[202:205], v[100:103]
	v_mfma_f32_16x16x32_bf16 v[96:99], v[176:179], v[202:205], v[96:99]
	v_mfma_f32_16x16x32_bf16 v[84:87], v[148:151], v[210:213], v[84:87]
	v_mfma_f32_16x16x32_bf16 v[80:83], v[176:179], v[210:213], v[80:83]
	v_mfma_f32_16x16x32_bf16 v[68:71], v[148:151], v[218:221], v[68:71]
	v_mfma_f32_16x16x32_bf16 v[64:67], v[176:179], v[218:221], v[64:67]
	s_setprio 0
	s_barrier
	s_add_i32 s54, s75, s65
	v_lshl_add_u64 v[222:223], s[58:59], 0, v[154:155]
	s_mov_b32 m0, s54
	ds_read_b128 v[180:183], v191 offset:16384
	v_xor_b32_e32 v253, 64, v191
	ds_read_b128 v[194:197], v253 offset:16384
	ds_read_b128 v[198:201], v191 offset:18432
	ds_read_b128 v[202:205], v253 offset:18432
	ds_read_b128 v[206:209], v191 offset:20480
	ds_read_b128 v[210:213], v253 offset:20480
	ds_read_b128 v[214:217], v191 offset:22528
	ds_read_b128 v[218:221], v253 offset:22528
	global_load_lds_dwordx4 v[222:223], off
	s_add_i32 m0, s54, 0x2000
	s_add_u32 s54, s58, 0xb0000
	v_lshl_add_u64 v[224:225], s[58:59], 0, v[162:163]
	s_addc_u32 s55, s59, 0
	s_add_i32 s82, s76, s65
	global_load_lds_dwordx4 v[224:225], off
	v_lshl_add_u64 v[226:227], s[54:55], 0, v[154:155]
	s_mov_b32 m0, s82
	v_lshl_add_u64 v[228:229], s[60:61], 0, v[160:161]
	global_load_lds_dwordx4 v[226:227], off
	v_lshl_add_u64 v[226:227], s[54:55], 0, v[162:163]
	s_add_i32 m0, s82, 0x2000
	s_nop 0
	global_load_lds_dwordx4 v[226:227], off
	v_lshl_add_u64 v[226:227], s[60:61], 0, v[152:153]
	s_mov_b32 m0, s66
	s_nop 0
	global_load_lds_dwordx4 v[226:227], off
	s_mov_b32 m0, s67
	s_nop 0
	global_load_lds_dwordx4 v[228:229], off
	s_waitcnt vmcnt(24)
	s_waitcnt lgkmcnt(0)
	s_barrier
	s_setprio 1
	s_waitcnt lgkmcnt(0)
	v_mfma_f32_16x16x32_bf16 v[60:63], v[128:131], v[180:183], 0
	v_mfma_f32_16x16x32_bf16 v[56:59], v[136:139], v[180:183], 0
	v_mfma_f32_16x16x32_bf16 v[44:47], v[128:131], v[198:201], 0
	v_mfma_f32_16x16x32_bf16 v[40:43], v[136:139], v[198:201], 0
	v_mfma_f32_16x16x32_bf16 v[28:31], v[128:131], v[206:209], 0
	v_mfma_f32_16x16x32_bf16 v[24:27], v[136:139], v[206:209], 0
	v_mfma_f32_16x16x32_bf16 v[12:15], v[128:131], v[214:217], 0
	v_mfma_f32_16x16x32_bf16 v[8:11], v[136:139], v[214:217], 0
	v_mfma_f32_16x16x32_bf16 v[60:63], v[132:135], v[194:197], v[60:63]
	v_mfma_f32_16x16x32_bf16 v[56:59], v[140:143], v[194:197], v[56:59]
	v_mfma_f32_16x16x32_bf16 v[44:47], v[132:135], v[202:205], v[44:47]
	v_mfma_f32_16x16x32_bf16 v[40:43], v[140:143], v[202:205], v[40:43]
	v_mfma_f32_16x16x32_bf16 v[28:31], v[132:135], v[210:213], v[28:31]
	v_mfma_f32_16x16x32_bf16 v[24:27], v[140:143], v[210:213], v[24:27]
	v_mfma_f32_16x16x32_bf16 v[12:15], v[132:135], v[218:221], v[12:15]
	v_mfma_f32_16x16x32_bf16 v[8:11], v[140:143], v[218:221], v[8:11]
	s_setprio 0
	s_setprio 1
	v_mfma_f32_16x16x32_bf16 v[52:55], v[144:147], v[180:183], 0
	v_mfma_f32_16x16x32_bf16 v[48:51], v[172:175], v[180:183], 0
	v_mfma_f32_16x16x32_bf16 v[36:39], v[144:147], v[198:201], 0
	v_mfma_f32_16x16x32_bf16 v[32:35], v[172:175], v[198:201], 0
	v_mfma_f32_16x16x32_bf16 v[20:23], v[144:147], v[206:209], 0
	v_mfma_f32_16x16x32_bf16 v[16:19], v[172:175], v[206:209], 0
	v_mfma_f32_16x16x32_bf16 v[4:7], v[144:147], v[214:217], 0
	v_mfma_f32_16x16x32_bf16 v[0:3], v[172:175], v[214:217], 0
	v_mfma_f32_16x16x32_bf16 v[52:55], v[148:151], v[194:197], v[52:55]
	v_mfma_f32_16x16x32_bf16 v[48:51], v[176:179], v[194:197], v[48:51]
	v_mfma_f32_16x16x32_bf16 v[36:39], v[148:151], v[202:205], v[36:39]
	v_mfma_f32_16x16x32_bf16 v[32:35], v[176:179], v[202:205], v[32:35]
	v_mfma_f32_16x16x32_bf16 v[20:23], v[148:151], v[210:213], v[20:23]
	v_mfma_f32_16x16x32_bf16 v[16:19], v[176:179], v[210:213], v[16:19]
	v_mfma_f32_16x16x32_bf16 v[4:7], v[148:151], v[218:221], v[4:7]
	v_mfma_f32_16x16x32_bf16 v[0:3], v[176:179], v[218:221], v[0:3]
	s_setprio 0
	s_barrier
	s_add_i32 s82, 0, 0x18000
	s_add_i32 s83, 0, 0x1c000
	v_add_u32_e32 v140, s82, v186
	v_add_u32_e32 v176, s83, v186
	ds_read_b128 v[128:131], v140
	v_xor_b32_e32 v253, 64, v140
	ds_read_b128 v[132:135], v253
	ds_read_b128 v[136:139], v140 offset:2048
	ds_read_b128 v[140:143], v253 offset:2048
	ds_read_b128 v[144:147], v176
	v_xor_b32_e32 v253, 64, v176
	ds_read_b128 v[148:151], v253
	ds_read_b128 v[172:175], v176 offset:2048
	ds_read_b128 v[176:179], v253 offset:2048
	s_add_u32 s54, s60, 0xb0000
	s_addc_u32 s55, s61, 0
	s_mov_b32 m0, s68
	v_lshl_add_u64 v[230:231], s[54:55], 0, v[152:153]
	ds_read_b128 v[180:183], v191 offset:32768
	v_xor_b32_e32 v253, 64, v191
	ds_read_b128 v[194:197], v253 offset:32768
	ds_read_b128 v[198:201], v191 offset:34816
	ds_read_b128 v[202:205], v253 offset:34816
	ds_read_b128 v[206:209], v191 offset:36864
	ds_read_b128 v[210:213], v253 offset:36864
	ds_read_b128 v[214:217], v191 offset:38912
	ds_read_b128 v[218:221], v253 offset:38912
	global_load_lds_dwordx4 v[230:231], off
	v_lshl_add_u64 v[230:231], s[54:55], 0, v[160:161]
	s_mov_b32 m0, s69
	s_nop 0
	global_load_lds_dwordx4 v[230:231], off
	s_waitcnt vmcnt(8)
	s_waitcnt lgkmcnt(0)
	s_barrier
	s_setprio 1
	s_waitcnt lgkmcnt(0)
	v_mfma_f32_16x16x32_bf16 v[124:127], v[128:131], v[180:183], v[124:127]
	v_mfma_f32_16x16x32_bf16 v[124:127], v[132:135], v[194:197], v[124:127]
	v_mfma_f32_16x16x32_bf16 v[120:123], v[136:139], v[180:183], v[120:123]
	v_mfma_f32_16x16x32_bf16 v[120:123], v[140:143], v[194:197], v[120:123]
	v_mfma_f32_16x16x32_bf16 v[108:111], v[128:131], v[198:201], v[108:111]
	v_mfma_f32_16x16x32_bf16 v[108:111], v[132:135], v[202:205], v[108:111]
	v_mfma_f32_16x16x32_bf16 v[104:107], v[136:139], v[198:201], v[104:107]
	v_mfma_f32_16x16x32_bf16 v[104:107], v[140:143], v[202:205], v[104:107]
	v_mfma_f32_16x16x32_bf16 v[92:95], v[128:131], v[206:209], v[92:95]
	v_mfma_f32_16x16x32_bf16 v[92:95], v[132:135], v[210:213], v[92:95]
	v_mfma_f32_16x16x32_bf16 v[88:91], v[136:139], v[206:209], v[88:91]
	v_mfma_f32_16x16x32_bf16 v[88:91], v[140:143], v[210:213], v[88:91]
	v_mfma_f32_16x16x32_bf16 v[76:79], v[128:131], v[214:217], v[76:79]
	v_mfma_f32_16x16x32_bf16 v[76:79], v[132:135], v[218:221], v[76:79]
	v_mfma_f32_16x16x32_bf16 v[72:75], v[136:139], v[214:217], v[72:75]
	v_mfma_f32_16x16x32_bf16 v[72:75], v[140:143], v[218:221], v[72:75]
	s_setprio 0
	s_setprio 1
	v_mfma_f32_16x16x32_bf16 v[116:119], v[144:147], v[180:183], v[116:119]
	v_mfma_f32_16x16x32_bf16 v[116:119], v[148:151], v[194:197], v[116:119]
	v_mfma_f32_16x16x32_bf16 v[112:115], v[172:175], v[180:183], v[112:115]
	v_mfma_f32_16x16x32_bf16 v[112:115], v[176:179], v[194:197], v[112:115]
	v_mfma_f32_16x16x32_bf16 v[100:103], v[144:147], v[198:201], v[100:103]
	v_mfma_f32_16x16x32_bf16 v[100:103], v[148:151], v[202:205], v[100:103]
	v_mfma_f32_16x16x32_bf16 v[96:99], v[172:175], v[198:201], v[96:99]
	v_mfma_f32_16x16x32_bf16 v[96:99], v[176:179], v[202:205], v[96:99]
	v_mfma_f32_16x16x32_bf16 v[84:87], v[144:147], v[206:209], v[84:87]
	v_mfma_f32_16x16x32_bf16 v[84:87], v[148:151], v[210:213], v[84:87]
	v_mfma_f32_16x16x32_bf16 v[80:83], v[172:175], v[206:209], v[80:83]
	v_mfma_f32_16x16x32_bf16 v[80:83], v[176:179], v[210:213], v[80:83]
	v_mfma_f32_16x16x32_bf16 v[68:71], v[144:147], v[214:217], v[68:71]
	v_mfma_f32_16x16x32_bf16 v[68:71], v[148:151], v[218:221], v[68:71]
	v_mfma_f32_16x16x32_bf16 v[64:67], v[172:175], v[214:217], v[64:67]
	v_mfma_f32_16x16x32_bf16 v[64:67], v[176:179], v[218:221], v[64:67]
	s_setprio 0
	s_barrier
	s_add_i32 s54, s82, s65
	v_lshl_add_u64 v[222:223], v[222:223], 0, s[28:29]
	s_mov_b32 m0, s54
	ds_read_b128 v[180:183], v191 offset:49152
	v_xor_b32_e32 v253, 64, v191
	ds_read_b128 v[194:197], v253 offset:49152
	ds_read_b128 v[198:201], v191 offset:51200
	ds_read_b128 v[202:205], v253 offset:51200
	ds_read_b128 v[206:209], v191 offset:53248
	ds_read_b128 v[210:213], v253 offset:53248
	ds_read_b128 v[214:217], v191 offset:55296
	ds_read_b128 v[218:221], v253 offset:55296
	global_load_lds_dwordx4 v[222:223], off
	s_add_i32 m0, s54, 0x2000
	s_add_u32 s54, s58, 0xb0080
	v_lshl_add_u64 v[222:223], v[224:225], 0, s[28:29]
	s_addc_u32 s55, s59, 0
	s_add_i32 s58, s83, s65
	global_load_lds_dwordx4 v[222:223], off
	v_lshl_add_u64 v[222:223], s[54:55], 0, v[154:155]
	s_mov_b32 m0, s58
	s_nop 0
	global_load_lds_dwordx4 v[222:223], off
	v_lshl_add_u64 v[222:223], s[54:55], 0, v[162:163]
	s_add_i32 m0, s58, 0x2000
	s_nop 0
	global_load_lds_dwordx4 v[222:223], off
	v_lshl_add_u64 v[222:223], v[226:227], 0, s[28:29]
	s_mov_b32 m0, s3
	s_nop 0
	global_load_lds_dwordx4 v[222:223], off
	v_lshl_add_u64 v[222:223], v[228:229], 0, s[28:29]
	s_mov_b32 m0, s71
	s_nop 0
	global_load_lds_dwordx4 v[222:223], off
	s_waitcnt vmcnt(8)
	s_waitcnt lgkmcnt(0)
	s_barrier
	s_setprio 1
	s_waitcnt lgkmcnt(0)
	v_mfma_f32_16x16x32_bf16 v[60:63], v[128:131], v[180:183], v[60:63]
	v_mfma_f32_16x16x32_bf16 v[60:63], v[132:135], v[194:197], v[60:63]
	v_mfma_f32_16x16x32_bf16 v[56:59], v[136:139], v[180:183], v[56:59]
	v_mfma_f32_16x16x32_bf16 v[56:59], v[140:143], v[194:197], v[56:59]
	v_mfma_f32_16x16x32_bf16 v[44:47], v[128:131], v[198:201], v[44:47]
	v_mfma_f32_16x16x32_bf16 v[44:47], v[132:135], v[202:205], v[44:47]
	v_mfma_f32_16x16x32_bf16 v[40:43], v[136:139], v[198:201], v[40:43]
	v_mfma_f32_16x16x32_bf16 v[40:43], v[140:143], v[202:205], v[40:43]
	v_mfma_f32_16x16x32_bf16 v[28:31], v[128:131], v[206:209], v[28:31]
	v_mfma_f32_16x16x32_bf16 v[28:31], v[132:135], v[210:213], v[28:31]
	v_mfma_f32_16x16x32_bf16 v[24:27], v[136:139], v[206:209], v[24:27]
	v_mfma_f32_16x16x32_bf16 v[24:27], v[140:143], v[210:213], v[24:27]
	v_mfma_f32_16x16x32_bf16 v[12:15], v[128:131], v[214:217], v[12:15]
	v_mfma_f32_16x16x32_bf16 v[12:15], v[132:135], v[218:221], v[12:15]
	v_mfma_f32_16x16x32_bf16 v[8:11], v[136:139], v[214:217], v[8:11]
	v_mfma_f32_16x16x32_bf16 v[8:11], v[140:143], v[218:221], v[8:11]
	s_setprio 0
	s_setprio 1
	v_mfma_f32_16x16x32_bf16 v[52:55], v[144:147], v[180:183], v[52:55]
	v_mfma_f32_16x16x32_bf16 v[52:55], v[148:151], v[194:197], v[52:55]
	v_mfma_f32_16x16x32_bf16 v[48:51], v[172:175], v[180:183], v[48:51]
	v_mfma_f32_16x16x32_bf16 v[48:51], v[176:179], v[194:197], v[48:51]
	v_mfma_f32_16x16x32_bf16 v[36:39], v[144:147], v[198:201], v[36:39]
	v_mfma_f32_16x16x32_bf16 v[36:39], v[148:151], v[202:205], v[36:39]
	v_mfma_f32_16x16x32_bf16 v[32:35], v[172:175], v[198:201], v[32:35]
	v_mfma_f32_16x16x32_bf16 v[32:35], v[176:179], v[202:205], v[32:35]
	v_mfma_f32_16x16x32_bf16 v[20:23], v[144:147], v[206:209], v[20:23]
	v_mfma_f32_16x16x32_bf16 v[20:23], v[148:151], v[210:213], v[20:23]
	v_mfma_f32_16x16x32_bf16 v[16:19], v[172:175], v[206:209], v[16:19]
	v_mfma_f32_16x16x32_bf16 v[16:19], v[176:179], v[210:213], v[16:19]
	v_mfma_f32_16x16x32_bf16 v[4:7], v[144:147], v[214:217], v[4:7]
	v_mfma_f32_16x16x32_bf16 v[4:7], v[148:151], v[218:221], v[4:7]
	v_mfma_f32_16x16x32_bf16 v[0:3], v[172:175], v[214:217], v[0:3]
	v_mfma_f32_16x16x32_bf16 v[0:3], v[176:179], v[218:221], v[0:3]
	s_setprio 0
	s_barrier
	s_add_i32 s81, s81, 2
	s_add_u32 s79, s79, 0x100
	s_addc_u32 s80, s80, 0
	s_cmp_gt_u32 s81, 41
	s_mov_b64 s[54:55], s[56:57]
	s_branch .LBB0_610
.Lfa_5:
	ds_read_b128 v[128:131], v189
	v_xor_b32_e32 v253, 64, v189
	ds_read_b128 v[132:135], v253
	ds_read_b128 v[136:139], v189 offset:2048
	ds_read_b128 v[140:143], v253 offset:2048
	ds_read_b128 v[144:147], v190
	v_xor_b32_e32 v253, 64, v190
	ds_read_b128 v[148:151], v253
	ds_read_b128 v[172:175], v190 offset:2048
	ds_read_b128 v[176:179], v253 offset:2048
	s_add_u32 s56, s54, 0x100
	s_addc_u32 s57, s55, 0
	s_cmp_eq_u32 s81, 40
	s_cselect_b32 s61, s17, s57
	s_cselect_b32 s60, s16, s56
	s_cselect_b32 s59, s53, s80
	s_cselect_b32 s58, s52, s79
	v_lshl_add_u64 v[222:223], s[54:55], 0, v[166:167]
	s_add_i32 m0, s66, 0xc000
	ds_read_b128 v[180:183], v191
	v_xor_b32_e32 v253, 64, v191
	ds_read_b128 v[194:197], v253
	ds_read_b128 v[198:201], v191 offset:2048
	ds_read_b128 v[202:205], v253 offset:2048
	ds_read_b128 v[206:209], v191 offset:4096
	ds_read_b128 v[210:213], v253 offset:4096
	ds_read_b128 v[214:217], v191 offset:6144
	ds_read_b128 v[218:221], v253 offset:6144
	global_load_lds_dwordx4 v[222:223], off
	v_lshl_add_u64 v[222:223], s[54:55], 0, v[164:165]
	s_add_i32 m0, s66, 0xe000
	s_nop 0
	global_load_lds_dwordx4 v[222:223], off
	s_waitcnt vmcnt(8)
	s_waitcnt lgkmcnt(0)
	s_barrier
	s_setprio 1
	s_waitcnt lgkmcnt(0)
	v_mfma_f32_16x16x32_bf16 v[124:127], v[128:131], v[180:183], 0
	v_mfma_f32_16x16x32_bf16 v[120:123], v[136:139], v[180:183], 0
	v_mfma_f32_16x16x32_bf16 v[108:111], v[128:131], v[198:201], 0
	v_mfma_f32_16x16x32_bf16 v[104:107], v[136:139], v[198:201], 0
	v_mfma_f32_16x16x32_bf16 v[92:95], v[128:131], v[206:209], 0
	v_mfma_f32_16x16x32_bf16 v[88:91], v[136:139], v[206:209], 0
	v_mfma_f32_16x16x32_bf16 v[76:79], v[128:131], v[214:217], 0
	v_mfma_f32_16x16x32_bf16 v[72:75], v[136:139], v[214:217], 0
	v_mfma_f32_16x16x32_bf16 v[124:127], v[132:135], v[194:197], v[124:127]
	v_mfma_f32_16x16x32_bf16 v[120:123], v[140:143], v[194:197], v[120:123]
	v_mfma_f32_16x16x32_bf16 v[108:111], v[132:135], v[202:205], v[108:111]
	v_mfma_f32_16x16x32_bf16 v[104:107], v[140:143], v[202:205], v[104:107]
	v_mfma_f32_16x16x32_bf16 v[92:95], v[132:135], v[210:213], v[92:95]
	v_mfma_f32_16x16x32_bf16 v[88:91], v[140:143], v[210:213], v[88:91]
	v_mfma_f32_16x16x32_bf16 v[76:79], v[132:135], v[218:221], v[76:79]
	v_mfma_f32_16x16x32_bf16 v[72:75], v[140:143], v[218:221], v[72:75]
	s_setprio 0
	s_setprio 1
	v_mfma_f32_16x16x32_bf16 v[116:119], v[144:147], v[180:183], 0
	v_mfma_f32_16x16x32_bf16 v[112:115], v[172:175], v[180:183], 0
	v_mfma_f32_16x16x32_bf16 v[100:103], v[144:147], v[198:201], 0
	v_mfma_f32_16x16x32_bf16 v[96:99], v[172:175], v[198:201], 0
	v_mfma_f32_16x16x32_bf16 v[84:87], v[144:147], v[206:209], 0
	v_mfma_f32_16x16x32_bf16 v[80:83], v[172:175], v[206:209], 0
	v_mfma_f32_16x16x32_bf16 v[68:71], v[144:147], v[214:217], 0
	v_mfma_f32_16x16x32_bf16 v[64:67], v[172:175], v[214:217], 0
	v_mfma_f32_16x16x32_bf16 v[116:119], v[148:151], v[194:197], v[116:119]
	v_mfma_f32_16x16x32_bf16 v[112:115], v[176:179], v[194:197], v[112:115]
	v_mfma_f32_16x16x32_bf16 v[100:103], v[148:151], v[202:205], v[100:103]
	v_mfma_f32_16x16x32_bf16 v[96:99], v[176:179], v[202:205], v[96:99]
	v_mfma_f32_16x16x32_bf16 v[84:87], v[148:151], v[210:213], v[84:87]
	v_mfma_f32_16x16x32_bf16 v[80:83], v[176:179], v[210:213], v[80:83]
	v_mfma_f32_16x16x32_bf16 v[68:71], v[148:151], v[218:221], v[68:71]
	v_mfma_f32_16x16x32_bf16 v[64:67], v[176:179], v[218:221], v[64:67]
	s_setprio 0
	s_barrier
	s_add_i32 s54, s75, s65
	v_lshl_add_u64 v[222:223], s[58:59], 0, v[154:155]
	s_mov_b32 m0, s54
	ds_read_b128 v[180:183], v191 offset:16384
	v_xor_b32_e32 v253, 64, v191
	ds_read_b128 v[194:197], v253 offset:16384
	ds_read_b128 v[198:201], v191 offset:18432
	ds_read_b128 v[202:205], v253 offset:18432
	ds_read_b128 v[206:209], v191 offset:20480
	ds_read_b128 v[210:213], v253 offset:20480
	ds_read_b128 v[214:217], v191 offset:22528
	ds_read_b128 v[218:221], v253 offset:22528
	global_load_lds_dwordx4 v[222:223], off
	s_add_i32 m0, s54, 0x2000
	s_add_u32 s54, s58, 0xb0000
	v_lshl_add_u64 v[224:225], s[58:59], 0, v[162:163]
	s_addc_u32 s55, s59, 0
	s_add_i32 s82, s76, s65
	global_load_lds_dwordx4 v[224:225], off
	v_lshl_add_u64 v[226:227], s[54:55], 0, v[154:155]
	s_mov_b32 m0, s82
	v_lshl_add_u64 v[228:229], s[60:61], 0, v[160:161]
	global_load_lds_dwordx4 v[226:227], off
	v_lshl_add_u64 v[226:227], s[54:55], 0, v[162:163]
	s_add_i32 m0, s82, 0x2000
	s_nop 0
	global_load_lds_dwordx4 v[226:227], off
	v_lshl_add_u64 v[226:227], s[60:61], 0, v[152:153]
	s_mov_b32 m0, s66
	s_nop 0
	global_load_lds_dwordx4 v[226:227], off
	s_mov_b32 m0, s67
	s_nop 0
	global_load_lds_dwordx4 v[228:229], off
	s_waitcnt vmcnt(8)
	s_waitcnt lgkmcnt(0)
	s_barrier
	s_setprio 1
	s_waitcnt lgkmcnt(0)
	v_mfma_f32_16x16x32_bf16 v[60:63], v[128:131], v[180:183], 0
	v_mfma_f32_16x16x32_bf16 v[56:59], v[136:139], v[180:183], 0
	v_mfma_f32_16x16x32_bf16 v[44:47], v[128:131], v[198:201], 0
	v_mfma_f32_16x16x32_bf16 v[40:43], v[136:139], v[198:201], 0
	v_mfma_f32_16x16x32_bf16 v[28:31], v[128:131], v[206:209], 0
	v_mfma_f32_16x16x32_bf16 v[24:27], v[136:139], v[206:209], 0
	v_mfma_f32_16x16x32_bf16 v[12:15], v[128:131], v[214:217], 0
	v_mfma_f32_16x16x32_bf16 v[8:11], v[136:139], v[214:217], 0
	v_mfma_f32_16x16x32_bf16 v[60:63], v[132:135], v[194:197], v[60:63]
	v_mfma_f32_16x16x32_bf16 v[56:59], v[140:143], v[194:197], v[56:59]
	v_mfma_f32_16x16x32_bf16 v[44:47], v[132:135], v[202:205], v[44:47]
	v_mfma_f32_16x16x32_bf16 v[40:43], v[140:143], v[202:205], v[40:43]
	v_mfma_f32_16x16x32_bf16 v[28:31], v[132:135], v[210:213], v[28:31]
	v_mfma_f32_16x16x32_bf16 v[24:27], v[140:143], v[210:213], v[24:27]
	v_mfma_f32_16x16x32_bf16 v[12:15], v[132:135], v[218:221], v[12:15]
	v_mfma_f32_16x16x32_bf16 v[8:11], v[140:143], v[218:221], v[8:11]
	s_setprio 0
	s_setprio 1
	v_mfma_f32_16x16x32_bf16 v[52:55], v[144:147], v[180:183], 0
	v_mfma_f32_16x16x32_bf16 v[48:51], v[172:175], v[180:183], 0
	v_mfma_f32_16x16x32_bf16 v[36:39], v[144:147], v[198:201], 0
	v_mfma_f32_16x16x32_bf16 v[32:35], v[172:175], v[198:201], 0
	v_mfma_f32_16x16x32_bf16 v[20:23], v[144:147], v[206:209], 0
	v_mfma_f32_16x16x32_bf16 v[16:19], v[172:175], v[206:209], 0
	v_mfma_f32_16x16x32_bf16 v[4:7], v[144:147], v[214:217], 0
	v_mfma_f32_16x16x32_bf16 v[0:3], v[172:175], v[214:217], 0
	v_mfma_f32_16x16x32_bf16 v[52:55], v[148:151], v[194:197], v[52:55]
	v_mfma_f32_16x16x32_bf16 v[48:51], v[176:179], v[194:197], v[48:51]
	v_mfma_f32_16x16x32_bf16 v[36:39], v[148:151], v[202:205], v[36:39]
	v_mfma_f32_16x16x32_bf16 v[32:35], v[176:179], v[202:205], v[32:35]
	v_mfma_f32_16x16x32_bf16 v[20:23], v[148:151], v[210:213], v[20:23]
	v_mfma_f32_16x16x32_bf16 v[16:19], v[176:179], v[210:213], v[16:19]
	v_mfma_f32_16x16x32_bf16 v[4:7], v[148:151], v[218:221], v[4:7]
	v_mfma_f32_16x16x32_bf16 v[0:3], v[176:179], v[218:221], v[0:3]
	s_setprio 0
	s_barrier
	s_add_i32 s82, 0, 0x18000
	s_add_i32 s83, 0, 0x1c000
	v_add_u32_e32 v140, s82, v186
	v_add_u32_e32 v176, s83, v186
	ds_read_b128 v[128:131], v140
	v_xor_b32_e32 v253, 64, v140
	ds_read_b128 v[132:135], v253
	ds_read_b128 v[136:139], v140 offset:2048
	ds_read_b128 v[140:143], v253 offset:2048
	ds_read_b128 v[144:147], v176
	v_xor_b32_e32 v253, 64, v176
	ds_read_b128 v[148:151], v253
	ds_read_b128 v[172:175], v176 offset:2048
	ds_read_b128 v[176:179], v253 offset:2048
	s_add_u32 s54, s60, 0xb0000
	s_addc_u32 s55, s61, 0
	s_mov_b32 m0, s68
	v_lshl_add_u64 v[230:231], s[54:55], 0, v[152:153]
	ds_read_b128 v[180:183], v191 offset:32768
	v_xor_b32_e32 v253, 64, v191
	ds_read_b128 v[194:197], v253 offset:32768
	ds_read_b128 v[198:201], v191 offset:34816
	ds_read_b128 v[202:205], v253 offset:34816
	ds_read_b128 v[206:209], v191 offset:36864
	ds_read_b128 v[210:213], v253 offset:36864
	ds_read_b128 v[214:217], v191 offset:38912
	ds_read_b128 v[218:221], v253 offset:38912
	global_load_lds_dwordx4 v[230:231], off
	v_lshl_add_u64 v[230:231], s[54:55], 0, v[160:161]
	s_mov_b32 m0, s69
	s_nop 0
	global_load_lds_dwordx4 v[230:231], off
	s_waitcnt vmcnt(8)
	s_waitcnt lgkmcnt(0)
	s_barrier
	s_setprio 1
	s_waitcnt lgkmcnt(0)
	v_mfma_f32_16x16x32_bf16 v[124:127], v[128:131], v[180:183], v[124:127]
	v_mfma_f32_16x16x32_bf16 v[124:127], v[132:135], v[194:197], v[124:127]
	v_mfma_f32_16x16x32_bf16 v[120:123], v[136:139], v[180:183], v[120:123]
	v_mfma_f32_16x16x32_bf16 v[120:123], v[140:143], v[194:197], v[120:123]
	v_mfma_f32_16x16x32_bf16 v[108:111], v[128:131], v[198:201], v[108:111]
	v_mfma_f32_16x16x32_bf16 v[108:111], v[132:135], v[202:205], v[108:111]
	v_mfma_f32_16x16x32_bf16 v[104:107], v[136:139], v[198:201], v[104:107]
	v_mfma_f32_16x16x32_bf16 v[104:107], v[140:143], v[202:205], v[104:107]
	v_mfma_f32_16x16x32_bf16 v[92:95], v[128:131], v[206:209], v[92:95]
	v_mfma_f32_16x16x32_bf16 v[92:95], v[132:135], v[210:213], v[92:95]
	v_mfma_f32_16x16x32_bf16 v[88:91], v[136:139], v[206:209], v[88:91]
	v_mfma_f32_16x16x32_bf16 v[88:91], v[140:143], v[210:213], v[88:91]
	v_mfma_f32_16x16x32_bf16 v[76:79], v[128:131], v[214:217], v[76:79]
	v_mfma_f32_16x16x32_bf16 v[76:79], v[132:135], v[218:221], v[76:79]
	v_mfma_f32_16x16x32_bf16 v[72:75], v[136:139], v[214:217], v[72:75]
	v_mfma_f32_16x16x32_bf16 v[72:75], v[140:143], v[218:221], v[72:75]
	s_setprio 0
	s_setprio 1
	v_mfma_f32_16x16x32_bf16 v[116:119], v[144:147], v[180:183], v[116:119]
	v_mfma_f32_16x16x32_bf16 v[116:119], v[148:151], v[194:197], v[116:119]
	v_mfma_f32_16x16x32_bf16 v[112:115], v[172:175], v[180:183], v[112:115]
	v_mfma_f32_16x16x32_bf16 v[112:115], v[176:179], v[194:197], v[112:115]
	v_mfma_f32_16x16x32_bf16 v[100:103], v[144:147], v[198:201], v[100:103]
	v_mfma_f32_16x16x32_bf16 v[100:103], v[148:151], v[202:205], v[100:103]
	v_mfma_f32_16x16x32_bf16 v[96:99], v[172:175], v[198:201], v[96:99]
	v_mfma_f32_16x16x32_bf16 v[96:99], v[176:179], v[202:205], v[96:99]
	v_mfma_f32_16x16x32_bf16 v[84:87], v[144:147], v[206:209], v[84:87]
	v_mfma_f32_16x16x32_bf16 v[84:87], v[148:151], v[210:213], v[84:87]
	v_mfma_f32_16x16x32_bf16 v[80:83], v[172:175], v[206:209], v[80:83]
	v_mfma_f32_16x16x32_bf16 v[80:83], v[176:179], v[210:213], v[80:83]
	v_mfma_f32_16x16x32_bf16 v[68:71], v[144:147], v[214:217], v[68:71]
	v_mfma_f32_16x16x32_bf16 v[68:71], v[148:151], v[218:221], v[68:71]
	v_mfma_f32_16x16x32_bf16 v[64:67], v[172:175], v[214:217], v[64:67]
	v_mfma_f32_16x16x32_bf16 v[64:67], v[176:179], v[218:221], v[64:67]
	s_setprio 0
	s_barrier
	s_add_i32 s54, s82, s65
	v_lshl_add_u64 v[222:223], v[222:223], 0, s[28:29]
	s_mov_b32 m0, s54
	ds_read_b128 v[180:183], v191 offset:49152
	v_xor_b32_e32 v253, 64, v191
	ds_read_b128 v[194:197], v253 offset:49152
	ds_read_b128 v[198:201], v191 offset:51200
	ds_read_b128 v[202:205], v253 offset:51200
	ds_read_b128 v[206:209], v191 offset:53248
	ds_read_b128 v[210:213], v253 offset:53248
	ds_read_b128 v[214:217], v191 offset:55296
	ds_read_b128 v[218:221], v253 offset:55296
	global_load_lds_dwordx4 v[222:223], off
	s_add_i32 m0, s54, 0x2000
	s_add_u32 s54, s58, 0xb0080
	v_lshl_add_u64 v[222:223], v[224:225], 0, s[28:29]
	s_addc_u32 s55, s59, 0
	s_add_i32 s58, s83, s65
	global_load_lds_dwordx4 v[222:223], off
	v_lshl_add_u64 v[222:223], s[54:55], 0, v[154:155]
	s_mov_b32 m0, s58
	s_nop 0
	global_load_lds_dwordx4 v[222:223], off
	v_lshl_add_u64 v[222:223], s[54:55], 0, v[162:163]
	s_add_i32 m0, s58, 0x2000
	s_nop 0
	global_load_lds_dwordx4 v[222:223], off
	v_lshl_add_u64 v[222:223], v[226:227], 0, s[28:29]
	s_mov_b32 m0, s3
	s_nop 0
	global_load_lds_dwordx4 v[222:223], off
	v_lshl_add_u64 v[222:223], v[228:229], 0, s[28:29]
	s_mov_b32 m0, s71
	s_nop 0
	global_load_lds_dwordx4 v[222:223], off
	s_waitcnt vmcnt(8)
	s_waitcnt lgkmcnt(0)
	s_barrier
	s_setprio 1
	s_waitcnt lgkmcnt(0)
	v_mfma_f32_16x16x32_bf16 v[60:63], v[128:131], v[180:183], v[60:63]
	v_mfma_f32_16x16x32_bf16 v[60:63], v[132:135], v[194:197], v[60:63]
	v_mfma_f32_16x16x32_bf16 v[56:59], v[136:139], v[180:183], v[56:59]
	v_mfma_f32_16x16x32_bf16 v[56:59], v[140:143], v[194:197], v[56:59]
	v_mfma_f32_16x16x32_bf16 v[44:47], v[128:131], v[198:201], v[44:47]
	v_mfma_f32_16x16x32_bf16 v[44:47], v[132:135], v[202:205], v[44:47]
	v_mfma_f32_16x16x32_bf16 v[40:43], v[136:139], v[198:201], v[40:43]
	v_mfma_f32_16x16x32_bf16 v[40:43], v[140:143], v[202:205], v[40:43]
	v_mfma_f32_16x16x32_bf16 v[28:31], v[128:131], v[206:209], v[28:31]
	v_mfma_f32_16x16x32_bf16 v[28:31], v[132:135], v[210:213], v[28:31]
	v_mfma_f32_16x16x32_bf16 v[24:27], v[136:139], v[206:209], v[24:27]
	v_mfma_f32_16x16x32_bf16 v[24:27], v[140:143], v[210:213], v[24:27]
	v_mfma_f32_16x16x32_bf16 v[12:15], v[128:131], v[214:217], v[12:15]
	v_mfma_f32_16x16x32_bf16 v[12:15], v[132:135], v[218:221], v[12:15]
	v_mfma_f32_16x16x32_bf16 v[8:11], v[136:139], v[214:217], v[8:11]
	v_mfma_f32_16x16x32_bf16 v[8:11], v[140:143], v[218:221], v[8:11]
	s_setprio 0
	s_setprio 1
	v_mfma_f32_16x16x32_bf16 v[52:55], v[144:147], v[180:183], v[52:55]
	v_mfma_f32_16x16x32_bf16 v[52:55], v[148:151], v[194:197], v[52:55]
	v_mfma_f32_16x16x32_bf16 v[48:51], v[172:175], v[180:183], v[48:51]
	v_mfma_f32_16x16x32_bf16 v[48:51], v[176:179], v[194:197], v[48:51]
	v_mfma_f32_16x16x32_bf16 v[36:39], v[144:147], v[198:201], v[36:39]
	v_mfma_f32_16x16x32_bf16 v[36:39], v[148:151], v[202:205], v[36:39]
	v_mfma_f32_16x16x32_bf16 v[32:35], v[172:175], v[198:201], v[32:35]
	v_mfma_f32_16x16x32_bf16 v[32:35], v[176:179], v[202:205], v[32:35]
	v_mfma_f32_16x16x32_bf16 v[20:23], v[144:147], v[206:209], v[20:23]
	v_mfma_f32_16x16x32_bf16 v[20:23], v[148:151], v[210:213], v[20:23]
	v_mfma_f32_16x16x32_bf16 v[16:19], v[172:175], v[206:209], v[16:19]
	v_mfma_f32_16x16x32_bf16 v[16:19], v[176:179], v[210:213], v[16:19]
	v_mfma_f32_16x16x32_bf16 v[4:7], v[144:147], v[214:217], v[4:7]
	v_mfma_f32_16x16x32_bf16 v[4:7], v[148:151], v[218:221], v[4:7]
	v_mfma_f32_16x16x32_bf16 v[0:3], v[172:175], v[214:217], v[0:3]
	v_mfma_f32_16x16x32_bf16 v[0:3], v[176:179], v[218:221], v[0:3]
	s_setprio 0
	s_barrier
	s_add_i32 s81, s81, 2
	s_add_u32 s79, s79, 0x100
	s_addc_u32 s80, s80, 0
	s_cmp_gt_u32 s81, 41
	s_mov_b64 s[54:55], s[56:57]
.LBB0_610:
	ds_read_b128 v[128:131], v189
	v_xor_b32_e32 v253, 64, v189
	ds_read_b128 v[132:135], v253
	ds_read_b128 v[136:139], v189 offset:2048
	ds_read_b128 v[140:143], v253 offset:2048
	ds_read_b128 v[144:147], v190
	v_xor_b32_e32 v253, 64, v190
	ds_read_b128 v[148:151], v253
	ds_read_b128 v[172:175], v190 offset:2048
	ds_read_b128 v[176:179], v253 offset:2048
	s_add_u32 s56, s54, 0x100
	s_addc_u32 s57, s55, 0
	s_cmp_eq_u32 s81, 40
	s_cselect_b32 s61, s17, s57
	s_cselect_b32 s60, s16, s56
	s_cselect_b32 s59, s53, s80
	s_cselect_b32 s58, s52, s79
	v_lshl_add_u64 v[222:223], s[54:55], 0, v[166:167]
	s_add_i32 m0, s66, 0xc000
	ds_read_b128 v[180:183], v191
	v_xor_b32_e32 v253, 64, v191
	ds_read_b128 v[194:197], v253
	ds_read_b128 v[198:201], v191 offset:2048
	ds_read_b128 v[202:205], v253 offset:2048
	ds_read_b128 v[206:209], v191 offset:4096
	ds_read_b128 v[210:213], v253 offset:4096
	ds_read_b128 v[214:217], v191 offset:6144
	ds_read_b128 v[218:221], v253 offset:6144
	global_load_lds_dwordx4 v[222:223], off
	v_lshl_add_u64 v[222:223], s[54:55], 0, v[164:165]
	s_add_i32 m0, s66, 0xe000
	s_nop 0
	global_load_lds_dwordx4 v[222:223], off
	s_waitcnt vmcnt(8)
	s_waitcnt lgkmcnt(0)
	s_barrier
	s_setprio 1
	s_waitcnt lgkmcnt(0)
	v_mfma_f32_16x16x32_bf16 v[124:127], v[128:131], v[180:183], v[124:127]
	v_mfma_f32_16x16x32_bf16 v[124:127], v[132:135], v[194:197], v[124:127]
	v_mfma_f32_16x16x32_bf16 v[120:123], v[136:139], v[180:183], v[120:123]
	v_mfma_f32_16x16x32_bf16 v[120:123], v[140:143], v[194:197], v[120:123]
	v_mfma_f32_16x16x32_bf16 v[108:111], v[128:131], v[198:201], v[108:111]
	v_mfma_f32_16x16x32_bf16 v[108:111], v[132:135], v[202:205], v[108:111]
	v_mfma_f32_16x16x32_bf16 v[104:107], v[136:139], v[198:201], v[104:107]
	v_mfma_f32_16x16x32_bf16 v[104:107], v[140:143], v[202:205], v[104:107]
	v_mfma_f32_16x16x32_bf16 v[92:95], v[128:131], v[206:209], v[92:95]
	v_mfma_f32_16x16x32_bf16 v[92:95], v[132:135], v[210:213], v[92:95]
	v_mfma_f32_16x16x32_bf16 v[88:91], v[136:139], v[206:209], v[88:91]
	v_mfma_f32_16x16x32_bf16 v[88:91], v[140:143], v[210:213], v[88:91]
	v_mfma_f32_16x16x32_bf16 v[76:79], v[128:131], v[214:217], v[76:79]
	v_mfma_f32_16x16x32_bf16 v[76:79], v[132:135], v[218:221], v[76:79]
	v_mfma_f32_16x16x32_bf16 v[72:75], v[136:139], v[214:217], v[72:75]
	v_mfma_f32_16x16x32_bf16 v[72:75], v[140:143], v[218:221], v[72:75]
	s_setprio 0
	s_setprio 1
	v_mfma_f32_16x16x32_bf16 v[116:119], v[144:147], v[180:183], v[116:119]
	v_mfma_f32_16x16x32_bf16 v[116:119], v[148:151], v[194:197], v[116:119]
	v_mfma_f32_16x16x32_bf16 v[112:115], v[172:175], v[180:183], v[112:115]
	v_mfma_f32_16x16x32_bf16 v[112:115], v[176:179], v[194:197], v[112:115]
	v_mfma_f32_16x16x32_bf16 v[100:103], v[144:147], v[198:201], v[100:103]
	v_mfma_f32_16x16x32_bf16 v[100:103], v[148:151], v[202:205], v[100:103]
	v_mfma_f32_16x16x32_bf16 v[96:99], v[172:175], v[198:201], v[96:99]
	v_mfma_f32_16x16x32_bf16 v[96:99], v[176:179], v[202:205], v[96:99]
	v_mfma_f32_16x16x32_bf16 v[84:87], v[144:147], v[206:209], v[84:87]
	v_mfma_f32_16x16x32_bf16 v[84:87], v[148:151], v[210:213], v[84:87]
	v_mfma_f32_16x16x32_bf16 v[80:83], v[172:175], v[206:209], v[80:83]
	v_mfma_f32_16x16x32_bf16 v[80:83], v[176:179], v[210:213], v[80:83]
	v_mfma_f32_16x16x32_bf16 v[68:71], v[144:147], v[214:217], v[68:71]
	v_mfma_f32_16x16x32_bf16 v[68:71], v[148:151], v[218:221], v[68:71]
	v_mfma_f32_16x16x32_bf16 v[64:67], v[172:175], v[214:217], v[64:67]
	v_mfma_f32_16x16x32_bf16 v[64:67], v[176:179], v[218:221], v[64:67]
	s_setprio 0
	s_barrier
	s_add_i32 s54, s75, s65
	v_lshl_add_u64 v[222:223], s[58:59], 0, v[154:155]
	s_mov_b32 m0, s54
	ds_read_b128 v[180:183], v191 offset:16384
	v_xor_b32_e32 v253, 64, v191
	ds_read_b128 v[194:197], v253 offset:16384
	ds_read_b128 v[198:201], v191 offset:18432
	ds_read_b128 v[202:205], v253 offset:18432
	ds_read_b128 v[206:209], v191 offset:20480
	ds_read_b128 v[210:213], v253 offset:20480
	ds_read_b128 v[214:217], v191 offset:22528
	ds_read_b128 v[218:221], v253 offset:22528
	global_load_lds_dwordx4 v[222:223], off
	s_add_i32 m0, s54, 0x2000
	s_add_u32 s54, s58, 0xb0000
	v_lshl_add_u64 v[224:225], s[58:59], 0, v[162:163]
	s_addc_u32 s55, s59, 0
	s_add_i32 s82, s76, s65
	global_load_lds_dwordx4 v[224:225], off
	v_lshl_add_u64 v[226:227], s[54:55], 0, v[154:155]
	s_mov_b32 m0, s82
	v_lshl_add_u64 v[228:229], s[60:61], 0, v[160:161]
	global_load_lds_dwordx4 v[226:227], off
	v_lshl_add_u64 v[226:227], s[54:55], 0, v[162:163]
	s_add_i32 m0, s82, 0x2000
	s_nop 0
	global_load_lds_dwordx4 v[226:227], off
	v_lshl_add_u64 v[226:227], s[60:61], 0, v[152:153]
	s_mov_b32 m0, s66
	s_nop 0
	global_load_lds_dwordx4 v[226:227], off
	s_mov_b32 m0, s67
	s_nop 0
	global_load_lds_dwordx4 v[228:229], off
	s_waitcnt vmcnt(8)
	s_waitcnt lgkmcnt(0)
	s_barrier
	s_setprio 1
	s_waitcnt lgkmcnt(0)
	v_mfma_f32_16x16x32_bf16 v[60:63], v[128:131], v[180:183], v[60:63]
	v_mfma_f32_16x16x32_bf16 v[60:63], v[132:135], v[194:197], v[60:63]
	v_mfma_f32_16x16x32_bf16 v[56:59], v[136:139], v[180:183], v[56:59]
	v_mfma_f32_16x16x32_bf16 v[56:59], v[140:143], v[194:197], v[56:59]
	v_mfma_f32_16x16x32_bf16 v[44:47], v[128:131], v[198:201], v[44:47]
	v_mfma_f32_16x16x32_bf16 v[44:47], v[132:135], v[202:205], v[44:47]
	v_mfma_f32_16x16x32_bf16 v[40:43], v[136:139], v[198:201], v[40:43]
	v_mfma_f32_16x16x32_bf16 v[40:43], v[140:143], v[202:205], v[40:43]
	v_mfma_f32_16x16x32_bf16 v[28:31], v[128:131], v[206:209], v[28:31]
	v_mfma_f32_16x16x32_bf16 v[28:31], v[132:135], v[210:213], v[28:31]
	v_mfma_f32_16x16x32_bf16 v[24:27], v[136:139], v[206:209], v[24:27]
	v_mfma_f32_16x16x32_bf16 v[24:27], v[140:143], v[210:213], v[24:27]
	v_mfma_f32_16x16x32_bf16 v[12:15], v[128:131], v[214:217], v[12:15]
	v_mfma_f32_16x16x32_bf16 v[12:15], v[132:135], v[218:221], v[12:15]
	v_mfma_f32_16x16x32_bf16 v[8:11], v[136:139], v[214:217], v[8:11]
	v_mfma_f32_16x16x32_bf16 v[8:11], v[140:143], v[218:221], v[8:11]
	s_setprio 0
	s_setprio 1
	v_mfma_f32_16x16x32_bf16 v[52:55], v[144:147], v[180:183], v[52:55]
	v_mfma_f32_16x16x32_bf16 v[52:55], v[148:151], v[194:197], v[52:55]
	v_mfma_f32_16x16x32_bf16 v[48:51], v[172:175], v[180:183], v[48:51]
	v_mfma_f32_16x16x32_bf16 v[48:51], v[176:179], v[194:197], v[48:51]
	v_mfma_f32_16x16x32_bf16 v[36:39], v[144:147], v[198:201], v[36:39]
	v_mfma_f32_16x16x32_bf16 v[36:39], v[148:151], v[202:205], v[36:39]
	v_mfma_f32_16x16x32_bf16 v[32:35], v[172:175], v[198:201], v[32:35]
	v_mfma_f32_16x16x32_bf16 v[32:35], v[176:179], v[202:205], v[32:35]
	v_mfma_f32_16x16x32_bf16 v[20:23], v[144:147], v[206:209], v[20:23]
	v_mfma_f32_16x16x32_bf16 v[20:23], v[148:151], v[210:213], v[20:23]
	v_mfma_f32_16x16x32_bf16 v[16:19], v[172:175], v[206:209], v[16:19]
	v_mfma_f32_16x16x32_bf16 v[16:19], v[176:179], v[210:213], v[16:19]
	v_mfma_f32_16x16x32_bf16 v[4:7], v[144:147], v[214:217], v[4:7]
	v_mfma_f32_16x16x32_bf16 v[4:7], v[148:151], v[218:221], v[4:7]
	v_mfma_f32_16x16x32_bf16 v[0:3], v[172:175], v[214:217], v[0:3]
	v_mfma_f32_16x16x32_bf16 v[0:3], v[176:179], v[218:221], v[0:3]
	s_setprio 0
	s_barrier
	s_add_i32 s82, 0, 0x18000
	s_add_i32 s83, 0, 0x1c000
	v_add_u32_e32 v140, s82, v186
	v_add_u32_e32 v176, s83, v186
	ds_read_b128 v[128:131], v140
	v_xor_b32_e32 v253, 64, v140
	ds_read_b128 v[132:135], v253
	ds_read_b128 v[136:139], v140 offset:2048
	ds_read_b128 v[140:143], v253 offset:2048
	ds_read_b128 v[144:147], v176
	v_xor_b32_e32 v253, 64, v176
	ds_read_b128 v[148:151], v253
	ds_read_b128 v[172:175], v176 offset:2048
	ds_read_b128 v[176:179], v253 offset:2048
	s_add_u32 s54, s60, 0xb0000
	s_addc_u32 s55, s61, 0
	s_mov_b32 m0, s68
	v_lshl_add_u64 v[230:231], s[54:55], 0, v[152:153]
	ds_read_b128 v[180:183], v191 offset:32768
	v_xor_b32_e32 v253, 64, v191
	ds_read_b128 v[194:197], v253 offset:32768
	ds_read_b128 v[198:201], v191 offset:34816
	ds_read_b128 v[202:205], v253 offset:34816
	ds_read_b128 v[206:209], v191 offset:36864
	ds_read_b128 v[210:213], v253 offset:36864
	ds_read_b128 v[214:217], v191 offset:38912
	ds_read_b128 v[218:221], v253 offset:38912
	global_load_lds_dwordx4 v[230:231], off
	v_lshl_add_u64 v[230:231], s[54:55], 0, v[160:161]
	s_mov_b32 m0, s69
	s_nop 0
	global_load_lds_dwordx4 v[230:231], off
	s_waitcnt vmcnt(8)
	s_waitcnt lgkmcnt(0)
	s_barrier
	s_setprio 1
	s_waitcnt lgkmcnt(0)
	v_mfma_f32_16x16x32_bf16 v[124:127], v[128:131], v[180:183], v[124:127]
	v_mfma_f32_16x16x32_bf16 v[124:127], v[132:135], v[194:197], v[124:127]
	v_mfma_f32_16x16x32_bf16 v[120:123], v[136:139], v[180:183], v[120:123]
	v_mfma_f32_16x16x32_bf16 v[120:123], v[140:143], v[194:197], v[120:123]
	v_mfma_f32_16x16x32_bf16 v[108:111], v[128:131], v[198:201], v[108:111]
	v_mfma_f32_16x16x32_bf16 v[108:111], v[132:135], v[202:205], v[108:111]
	v_mfma_f32_16x16x32_bf16 v[104:107], v[136:139], v[198:201], v[104:107]
	v_mfma_f32_16x16x32_bf16 v[104:107], v[140:143], v[202:205], v[104:107]
	v_mfma_f32_16x16x32_bf16 v[92:95], v[128:131], v[206:209], v[92:95]
	v_mfma_f32_16x16x32_bf16 v[92:95], v[132:135], v[210:213], v[92:95]
	v_mfma_f32_16x16x32_bf16 v[88:91], v[136:139], v[206:209], v[88:91]
	v_mfma_f32_16x16x32_bf16 v[88:91], v[140:143], v[210:213], v[88:91]
	v_mfma_f32_16x16x32_bf16 v[76:79], v[128:131], v[214:217], v[76:79]
	v_mfma_f32_16x16x32_bf16 v[76:79], v[132:135], v[218:221], v[76:79]
	v_mfma_f32_16x16x32_bf16 v[72:75], v[136:139], v[214:217], v[72:75]
	v_mfma_f32_16x16x32_bf16 v[72:75], v[140:143], v[218:221], v[72:75]
	s_setprio 0
	s_setprio 1
	v_mfma_f32_16x16x32_bf16 v[116:119], v[144:147], v[180:183], v[116:119]
	v_mfma_f32_16x16x32_bf16 v[116:119], v[148:151], v[194:197], v[116:119]
	v_mfma_f32_16x16x32_bf16 v[112:115], v[172:175], v[180:183], v[112:115]
	v_mfma_f32_16x16x32_bf16 v[112:115], v[176:179], v[194:197], v[112:115]
	v_mfma_f32_16x16x32_bf16 v[100:103], v[144:147], v[198:201], v[100:103]
	v_mfma_f32_16x16x32_bf16 v[100:103], v[148:151], v[202:205], v[100:103]
	v_mfma_f32_16x16x32_bf16 v[96:99], v[172:175], v[198:201], v[96:99]
	v_mfma_f32_16x16x32_bf16 v[96:99], v[176:179], v[202:205], v[96:99]
	v_mfma_f32_16x16x32_bf16 v[84:87], v[144:147], v[206:209], v[84:87]
	v_mfma_f32_16x16x32_bf16 v[84:87], v[148:151], v[210:213], v[84:87]
	v_mfma_f32_16x16x32_bf16 v[80:83], v[172:175], v[206:209], v[80:83]
	v_mfma_f32_16x16x32_bf16 v[80:83], v[176:179], v[210:213], v[80:83]
	v_mfma_f32_16x16x32_bf16 v[68:71], v[144:147], v[214:217], v[68:71]
	v_mfma_f32_16x16x32_bf16 v[68:71], v[148:151], v[218:221], v[68:71]
	v_mfma_f32_16x16x32_bf16 v[64:67], v[172:175], v[214:217], v[64:67]
	v_mfma_f32_16x16x32_bf16 v[64:67], v[176:179], v[218:221], v[64:67]
	s_setprio 0
	s_barrier
	s_add_i32 s54, s82, s65
	v_lshl_add_u64 v[222:223], v[222:223], 0, s[28:29]
	s_mov_b32 m0, s54
	ds_read_b128 v[180:183], v191 offset:49152
	v_xor_b32_e32 v253, 64, v191
	ds_read_b128 v[194:197], v253 offset:49152
	ds_read_b128 v[198:201], v191 offset:51200
	ds_read_b128 v[202:205], v253 offset:51200
	ds_read_b128 v[206:209], v191 offset:53248
	ds_read_b128 v[210:213], v253 offset:53248
	ds_read_b128 v[214:217], v191 offset:55296
	ds_read_b128 v[218:221], v253 offset:55296
	global_load_lds_dwordx4 v[222:223], off
	s_add_i32 m0, s54, 0x2000
	s_add_u32 s54, s58, 0xb0080
	v_lshl_add_u64 v[222:223], v[224:225], 0, s[28:29]
	s_addc_u32 s55, s59, 0
	s_add_i32 s58, s83, s65
	global_load_lds_dwordx4 v[222:223], off
	v_lshl_add_u64 v[222:223], s[54:55], 0, v[154:155]
	s_mov_b32 m0, s58
	s_nop 0
	global_load_lds_dwordx4 v[222:223], off
	v_lshl_add_u64 v[222:223], s[54:55], 0, v[162:163]
	s_add_i32 m0, s58, 0x2000
	s_nop 0
	global_load_lds_dwordx4 v[222:223], off
	v_lshl_add_u64 v[222:223], v[226:227], 0, s[28:29]
	s_mov_b32 m0, s3
	s_nop 0
	global_load_lds_dwordx4 v[222:223], off
	v_lshl_add_u64 v[222:223], v[228:229], 0, s[28:29]
	s_mov_b32 m0, s71
	s_nop 0
	global_load_lds_dwordx4 v[222:223], off
	s_waitcnt vmcnt(8)
	s_waitcnt lgkmcnt(0)
	s_barrier
	s_setprio 1
	s_waitcnt lgkmcnt(0)
	v_mfma_f32_16x16x32_bf16 v[60:63], v[128:131], v[180:183], v[60:63]
	v_mfma_f32_16x16x32_bf16 v[60:63], v[132:135], v[194:197], v[60:63]
	v_mfma_f32_16x16x32_bf16 v[56:59], v[136:139], v[180:183], v[56:59]
	v_mfma_f32_16x16x32_bf16 v[56:59], v[140:143], v[194:197], v[56:59]
	v_mfma_f32_16x16x32_bf16 v[44:47], v[128:131], v[198:201], v[44:47]
	v_mfma_f32_16x16x32_bf16 v[44:47], v[132:135], v[202:205], v[44:47]
	v_mfma_f32_16x16x32_bf16 v[40:43], v[136:139], v[198:201], v[40:43]
	v_mfma_f32_16x16x32_bf16 v[40:43], v[140:143], v[202:205], v[40:43]
	v_mfma_f32_16x16x32_bf16 v[28:31], v[128:131], v[206:209], v[28:31]
	v_mfma_f32_16x16x32_bf16 v[28:31], v[132:135], v[210:213], v[28:31]
	v_mfma_f32_16x16x32_bf16 v[24:27], v[136:139], v[206:209], v[24:27]
	v_mfma_f32_16x16x32_bf16 v[24:27], v[140:143], v[210:213], v[24:27]
	v_mfma_f32_16x16x32_bf16 v[12:15], v[128:131], v[214:217], v[12:15]
	v_mfma_f32_16x16x32_bf16 v[12:15], v[132:135], v[218:221], v[12:15]
	v_mfma_f32_16x16x32_bf16 v[8:11], v[136:139], v[214:217], v[8:11]
	v_mfma_f32_16x16x32_bf16 v[8:11], v[140:143], v[218:221], v[8:11]
	s_setprio 0
	s_setprio 1
	v_mfma_f32_16x16x32_bf16 v[52:55], v[144:147], v[180:183], v[52:55]
	v_mfma_f32_16x16x32_bf16 v[52:55], v[148:151], v[194:197], v[52:55]
	v_mfma_f32_16x16x32_bf16 v[48:51], v[172:175], v[180:183], v[48:51]
	v_mfma_f32_16x16x32_bf16 v[48:51], v[176:179], v[194:197], v[48:51]
	v_mfma_f32_16x16x32_bf16 v[36:39], v[144:147], v[198:201], v[36:39]
	v_mfma_f32_16x16x32_bf16 v[36:39], v[148:151], v[202:205], v[36:39]
	v_mfma_f32_16x16x32_bf16 v[32:35], v[172:175], v[198:201], v[32:35]
	v_mfma_f32_16x16x32_bf16 v[32:35], v[176:179], v[202:205], v[32:35]
	v_mfma_f32_16x16x32_bf16 v[20:23], v[144:147], v[206:209], v[20:23]
	v_mfma_f32_16x16x32_bf16 v[20:23], v[148:151], v[210:213], v[20:23]
	v_mfma_f32_16x16x32_bf16 v[16:19], v[172:175], v[206:209], v[16:19]
	v_mfma_f32_16x16x32_bf16 v[16:19], v[176:179], v[210:213], v[16:19]
	v_mfma_f32_16x16x32_bf16 v[4:7], v[144:147], v[214:217], v[4:7]
	v_mfma_f32_16x16x32_bf16 v[4:7], v[148:151], v[218:221], v[4:7]
	v_mfma_f32_16x16x32_bf16 v[0:3], v[172:175], v[214:217], v[0:3]
	v_mfma_f32_16x16x32_bf16 v[0:3], v[176:179], v[218:221], v[0:3]
	s_setprio 0
	s_barrier
	s_add_i32 s81, s81, 2
	s_add_u32 s79, s79, 0x100
	s_addc_u32 s80, s80, 0
	s_cmp_gt_u32 s81, 41
	s_mov_b64 s[54:55], s[56:57]
	s_cbranch_scc0 .LBB0_610
	s_and_b64 vcc, exec, s[30:31]
	s_cbranch_vccz .LBB0_613
	s_barrier

.LBB0_873:
	s_ashr_i32 s49, s48, 31
	s_lshl_b64 s[50:51], s[48:49], 19
	s_add_u32 s50, s35, s50
	s_addc_u32 s51, s60, s51
	s_and_b64 s[52:53], s[10:11], exec
	s_cselect_b32 s49, s51, s59
	s_cselect_b32 s80, s50, s58
	s_ashr_i32 s47, s46, 31
	s_lshl_b64 s[52:53], s[46:47], 19
	s_add_u32 s52, s61, s52
	s_addc_u32 s53, s62, s53
	s_and_b64 s[82:83], s[10:11], exec
	s_cselect_b32 s81, s53, s57
	s_cselect_b32 s82, s52, s56
	s_lshl_b32 s47, s54, 8
	v_add_u32_e32 v0, s47, v151
	s_add_u32 s83, s56, 0x100
	v_ashrrev_i32_e32 v1, 31, v0
	s_addc_u32 s84, s57, 0
	v_lshl_add_u64 v[144:145], v[0:1], 4, s[20:21]
	s_add_u32 s54, s58, 0x40080
	s_addc_u32 s55, s59, 0
	s_mov_b32 s85, -2
	s_mov_b64 s[56:57], 0
	s_cmp_eq_u32 s68, 1
	s_cbranch_scc1 .Lfa_8
	v_add_u32_e32 v146, s73, v149
	ds_read_b128 v[162:165], v146
	v_xor_b32_e32 v253, 64, v146
	ds_read_b128 v[166:169], v253
	ds_read_b128 v[170:173], v146 offset:2048
	ds_read_b128 v[174:177], v253 offset:2048
	v_add_u32_e32 v146, s74, v149
	ds_read_b128 v[178:181], v146
	v_xor_b32_e32 v253, 64, v146
	ds_read_b128 v[186:189], v253
	ds_read_b128 v[190:193], v146 offset:2048
	ds_read_b128 v[194:197], v253 offset:2048
	s_add_u32 s58, s54, 0xfffc0080
	s_addc_u32 s59, s55, -1
	s_and_b64 s[56:57], s[56:57], exec
	s_cselect_b32 s59, s49, s59
	s_cselect_b32 s58, s80, s58
	s_cselect_b32 s57, s81, s84
	s_cselect_b32 s56, s82, s83
	v_lshl_add_u64 v[182:183], s[54:55], 0, v[138:139]
	s_add_i32 m0, s64, 0xc000
	ds_read_b128 v[198:201], v154
	v_xor_b32_e32 v253, 64, v154
	ds_read_b128 v[202:205], v253
	ds_read_b128 v[206:209], v154 offset:2048
	ds_read_b128 v[210:213], v253 offset:2048
	ds_read_b128 v[214:217], v154 offset:4096
	ds_read_b128 v[218:221], v253 offset:4096
	ds_read_b128 v[222:225], v154 offset:6144
	ds_read_b128 v[226:229], v253 offset:6144
	global_load_lds_dwordx4 v[182:183], off
	v_lshl_add_u64 v[182:183], s[54:55], 0, v[136:137]
	s_add_i32 m0, s64, 0xe000
	s_nop 0
	global_load_lds_dwordx4 v[182:183], off
	s_waitcnt vmcnt(24)
	s_waitcnt lgkmcnt(0)
	s_barrier
	s_setprio 1
	s_waitcnt lgkmcnt(0)
	v_mfma_f32_16x16x32_bf16 v[124:127], v[162:165], v[198:201], 0
	v_mfma_f32_16x16x32_bf16 v[120:123], v[170:173], v[198:201], 0
	v_mfma_f32_16x16x32_bf16 v[112:115], v[162:165], v[206:209], 0
	v_mfma_f32_16x16x32_bf16 v[104:107], v[170:173], v[206:209], 0
	v_mfma_f32_16x16x32_bf16 v[96:99], v[162:165], v[214:217], 0
	v_mfma_f32_16x16x32_bf16 v[88:91], v[170:173], v[214:217], 0
	v_mfma_f32_16x16x32_bf16 v[80:83], v[162:165], v[222:225], 0
	v_mfma_f32_16x16x32_bf16 v[72:75], v[170:173], v[222:225], 0
	v_mfma_f32_16x16x32_bf16 v[124:127], v[166:169], v[202:205], v[124:127]
	v_mfma_f32_16x16x32_bf16 v[120:123], v[174:177], v[202:205], v[120:123]
	v_mfma_f32_16x16x32_bf16 v[112:115], v[166:169], v[210:213], v[112:115]
	v_mfma_f32_16x16x32_bf16 v[104:107], v[174:177], v[210:213], v[104:107]
	v_mfma_f32_16x16x32_bf16 v[96:99], v[166:169], v[218:221], v[96:99]
	v_mfma_f32_16x16x32_bf16 v[88:91], v[174:177], v[218:221], v[88:91]
	v_mfma_f32_16x16x32_bf16 v[80:83], v[166:169], v[226:229], v[80:83]
	v_mfma_f32_16x16x32_bf16 v[72:75], v[174:177], v[226:229], v[72:75]
	s_setprio 0
	s_setprio 1
	v_mfma_f32_16x16x32_bf16 v[116:119], v[178:181], v[198:201], 0
	v_mfma_f32_16x16x32_bf16 v[108:111], v[190:193], v[198:201], 0
	v_mfma_f32_16x16x32_bf16 v[100:103], v[178:181], v[206:209], 0
	v_mfma_f32_16x16x32_bf16 v[92:95], v[190:193], v[206:209], 0
	v_mfma_f32_16x16x32_bf16 v[84:87], v[178:181], v[214:217], 0
	v_mfma_f32_16x16x32_bf16 v[76:79], v[190:193], v[214:217], 0
	v_mfma_f32_16x16x32_bf16 v[68:71], v[178:181], v[222:225], 0
	v_mfma_f32_16x16x32_bf16 v[64:67], v[190:193], v[222:225], 0
	v_mfma_f32_16x16x32_bf16 v[116:119], v[186:189], v[202:205], v[116:119]
	v_mfma_f32_16x16x32_bf16 v[108:111], v[194:197], v[202:205], v[108:111]
	v_mfma_f32_16x16x32_bf16 v[100:103], v[186:189], v[210:213], v[100:103]
	v_mfma_f32_16x16x32_bf16 v[92:95], v[194:197], v[210:213], v[92:95]
	v_mfma_f32_16x16x32_bf16 v[84:87], v[186:189], v[218:221], v[84:87]
	v_mfma_f32_16x16x32_bf16 v[76:79], v[194:197], v[218:221], v[76:79]
	v_mfma_f32_16x16x32_bf16 v[68:71], v[186:189], v[226:229], v[68:71]
	v_mfma_f32_16x16x32_bf16 v[64:67], v[194:197], v[226:229], v[64:67]
	s_setprio 0
	s_barrier
	s_add_i32 s86, s73, s63
	v_lshl_add_u64 v[182:183], s[56:57], 0, v[130:131]
	s_mov_b32 m0, s86
	ds_read_b128 v[198:201], v154 offset:16384
	v_xor_b32_e32 v253, 64, v154
	ds_read_b128 v[202:205], v253 offset:16384
	ds_read_b128 v[206:209], v154 offset:18432
	ds_read_b128 v[210:213], v253 offset:18432
	ds_read_b128 v[214:217], v154 offset:20480
	ds_read_b128 v[218:221], v253 offset:20480
	ds_read_b128 v[222:225], v154 offset:22528
	ds_read_b128 v[226:229], v253 offset:22528
	global_load_lds_dwordx4 v[182:183], off
	s_add_i32 m0, s86, 0x2000
	s_add_u32 s86, s56, 0x40000
	v_lshl_add_u64 v[230:231], s[56:57], 0, v[134:135]
	s_addc_u32 s87, s57, 0
	s_add_i32 s88, s74, s63
	global_load_lds_dwordx4 v[230:231], off
	v_lshl_add_u64 v[232:233], s[86:87], 0, v[130:131]
	s_mov_b32 m0, s88
	v_lshl_add_u64 v[234:235], s[58:59], 0, v[132:133]
	global_load_lds_dwordx4 v[232:233], off
	v_lshl_add_u64 v[232:233], s[86:87], 0, v[134:135]
	s_add_i32 m0, s88, 0x2000
	s_nop 0
	global_load_lds_dwordx4 v[232:233], off
	v_lshl_add_u64 v[232:233], s[58:59], 0, v[128:129]
	s_mov_b32 m0, s64
	s_nop 0
	global_load_lds_dwordx4 v[232:233], off
	s_mov_b32 m0, s65
	s_nop 0
	global_load_lds_dwordx4 v[234:235], off
	s_waitcnt vmcnt(24)
	s_waitcnt lgkmcnt(0)
	s_barrier
	s_setprio 1
	s_waitcnt lgkmcnt(0)
	v_mfma_f32_16x16x32_bf16 v[60:63], v[162:165], v[198:201], 0
	v_mfma_f32_16x16x32_bf16 v[56:59], v[170:173], v[198:201], 0
	v_mfma_f32_16x16x32_bf16 v[48:51], v[162:165], v[206:209], 0
	v_mfma_f32_16x16x32_bf16 v[40:43], v[170:173], v[206:209], 0
	v_mfma_f32_16x16x32_bf16 v[32:35], v[162:165], v[214:217], 0
	v_mfma_f32_16x16x32_bf16 v[24:27], v[170:173], v[214:217], 0
	v_mfma_f32_16x16x32_bf16 v[16:19], v[162:165], v[222:225], 0
	v_mfma_f32_16x16x32_bf16 v[8:11], v[170:173], v[222:225], 0
	v_mfma_f32_16x16x32_bf16 v[60:63], v[166:169], v[202:205], v[60:63]
	v_mfma_f32_16x16x32_bf16 v[56:59], v[174:177], v[202:205], v[56:59]
	v_mfma_f32_16x16x32_bf16 v[48:51], v[166:169], v[210:213], v[48:51]
	v_mfma_f32_16x16x32_bf16 v[40:43], v[174:177], v[210:213], v[40:43]
	v_mfma_f32_16x16x32_bf16 v[32:35], v[166:169], v[218:221], v[32:35]
	v_mfma_f32_16x16x32_bf16 v[24:27], v[174:177], v[218:221], v[24:27]
	v_mfma_f32_16x16x32_bf16 v[16:19], v[166:169], v[226:229], v[16:19]
	v_mfma_f32_16x16x32_bf16 v[8:11], v[174:177], v[226:229], v[8:11]
	s_setprio 0
	s_setprio 1
	v_mfma_f32_16x16x32_bf16 v[52:55], v[178:181], v[198:201], 0
	v_mfma_f32_16x16x32_bf16 v[44:47], v[190:193], v[198:201], 0
	v_mfma_f32_16x16x32_bf16 v[36:39], v[178:181], v[206:209], 0
	v_mfma_f32_16x16x32_bf16 v[28:31], v[190:193], v[206:209], 0
	v_mfma_f32_16x16x32_bf16 v[20:23], v[178:181], v[214:217], 0
	v_mfma_f32_16x16x32_bf16 v[12:15], v[190:193], v[214:217], 0
	v_mfma_f32_16x16x32_bf16 v[4:7], v[178:181], v[222:225], 0
	v_mfma_f32_16x16x32_bf16 v[0:3], v[190:193], v[222:225], 0
	v_mfma_f32_16x16x32_bf16 v[52:55], v[186:189], v[202:205], v[52:55]
	v_mfma_f32_16x16x32_bf16 v[44:47], v[194:197], v[202:205], v[44:47]
	v_mfma_f32_16x16x32_bf16 v[36:39], v[186:189], v[210:213], v[36:39]
	v_mfma_f32_16x16x32_bf16 v[28:31], v[194:197], v[210:213], v[28:31]
	v_mfma_f32_16x16x32_bf16 v[20:23], v[186:189], v[218:221], v[20:23]
	v_mfma_f32_16x16x32_bf16 v[12:15], v[194:197], v[218:221], v[12:15]
	v_mfma_f32_16x16x32_bf16 v[4:7], v[186:189], v[226:229], v[4:7]
	v_mfma_f32_16x16x32_bf16 v[0:3], v[194:197], v[226:229], v[0:3]
	s_setprio 0
	s_barrier
	s_add_i32 s86, 0, 0x18000
	v_add_u32_e32 v146, s86, v149
	s_add_i32 s87, 0, 0x1c000
	ds_read_b128 v[162:165], v146
	v_xor_b32_e32 v253, 64, v146
	ds_read_b128 v[166:169], v253
	ds_read_b128 v[170:173], v146 offset:2048
	ds_read_b128 v[174:177], v253 offset:2048
	v_add_u32_e32 v146, s87, v149
	ds_read_b128 v[178:181], v146
	v_xor_b32_e32 v253, 64, v146
	ds_read_b128 v[186:189], v253
	ds_read_b128 v[190:193], v146 offset:2048
	ds_read_b128 v[194:197], v253 offset:2048
	s_add_u32 s58, s58, 0x40000
	s_addc_u32 s59, s59, 0
	s_mov_b32 m0, s66
	v_lshl_add_u64 v[236:237], s[58:59], 0, v[128:129]
	ds_read_b128 v[198:201], v154 offset:32768
	v_xor_b32_e32 v253, 64, v154
	ds_read_b128 v[202:205], v253 offset:32768
	ds_read_b128 v[206:209], v154 offset:34816
	ds_read_b128 v[210:213], v253 offset:34816
	ds_read_b128 v[214:217], v154 offset:36864
	ds_read_b128 v[218:221], v253 offset:36864
	ds_read_b128 v[222:225], v154 offset:38912
	ds_read_b128 v[226:229], v253 offset:38912
	global_load_lds_dwordx4 v[236:237], off
	v_lshl_add_u64 v[236:237], s[58:59], 0, v[132:133]
	s_mov_b32 m0, s67
	s_nop 0
	global_load_lds_dwordx4 v[236:237], off
	s_waitcnt vmcnt(8)
	s_waitcnt lgkmcnt(0)
	s_barrier
	s_setprio 1
	s_waitcnt lgkmcnt(0)
	v_mfma_f32_16x16x32_bf16 v[124:127], v[162:165], v[198:201], v[124:127]
	v_mfma_f32_16x16x32_bf16 v[124:127], v[166:169], v[202:205], v[124:127]
	v_mfma_f32_16x16x32_bf16 v[120:123], v[170:173], v[198:201], v[120:123]
	v_mfma_f32_16x16x32_bf16 v[120:123], v[174:177], v[202:205], v[120:123]
	v_mfma_f32_16x16x32_bf16 v[112:115], v[162:165], v[206:209], v[112:115]
	v_mfma_f32_16x16x32_bf16 v[112:115], v[166:169], v[210:213], v[112:115]
	v_mfma_f32_16x16x32_bf16 v[104:107], v[170:173], v[206:209], v[104:107]
	v_mfma_f32_16x16x32_bf16 v[104:107], v[174:177], v[210:213], v[104:107]
	v_mfma_f32_16x16x32_bf16 v[96:99], v[162:165], v[214:217], v[96:99]
	v_mfma_f32_16x16x32_bf16 v[96:99], v[166:169], v[218:221], v[96:99]
	v_mfma_f32_16x16x32_bf16 v[88:91], v[170:173], v[214:217], v[88:91]
	v_mfma_f32_16x16x32_bf16 v[88:91], v[174:177], v[218:221], v[88:91]
	v_mfma_f32_16x16x32_bf16 v[80:83], v[162:165], v[222:225], v[80:83]
	v_mfma_f32_16x16x32_bf16 v[80:83], v[166:169], v[226:229], v[80:83]
	v_mfma_f32_16x16x32_bf16 v[72:75], v[170:173], v[222:225], v[72:75]
	v_mfma_f32_16x16x32_bf16 v[72:75], v[174:177], v[226:229], v[72:75]
	s_setprio 0
	s_setprio 1
	v_mfma_f32_16x16x32_bf16 v[116:119], v[178:181], v[198:201], v[116:119]
	v_mfma_f32_16x16x32_bf16 v[116:119], v[186:189], v[202:205], v[116:119]
	v_mfma_f32_16x16x32_bf16 v[108:111], v[190:193], v[198:201], v[108:111]
	v_mfma_f32_16x16x32_bf16 v[108:111], v[194:197], v[202:205], v[108:111]
	v_mfma_f32_16x16x32_bf16 v[100:103], v[178:181], v[206:209], v[100:103]
	v_mfma_f32_16x16x32_bf16 v[100:103], v[186:189], v[210:213], v[100:103]
	v_mfma_f32_16x16x32_bf16 v[92:95], v[190:193], v[206:209], v[92:95]
	v_mfma_f32_16x16x32_bf16 v[92:95], v[194:197], v[210:213], v[92:95]
	v_mfma_f32_16x16x32_bf16 v[84:87], v[178:181], v[214:217], v[84:87]
	v_mfma_f32_16x16x32_bf16 v[84:87], v[186:189], v[218:221], v[84:87]
	v_mfma_f32_16x16x32_bf16 v[76:79], v[190:193], v[214:217], v[76:79]
	v_mfma_f32_16x16x32_bf16 v[76:79], v[194:197], v[218:221], v[76:79]
	v_mfma_f32_16x16x32_bf16 v[68:71], v[178:181], v[222:225], v[68:71]
	v_mfma_f32_16x16x32_bf16 v[68:71], v[186:189], v[226:229], v[68:71]
	v_mfma_f32_16x16x32_bf16 v[64:67], v[190:193], v[222:225], v[64:67]
	v_mfma_f32_16x16x32_bf16 v[64:67], v[194:197], v[226:229], v[64:67]
	s_setprio 0
	s_barrier
	s_add_i32 s58, s86, s63
	v_lshl_add_u64 v[182:183], v[182:183], 0, s[22:23]
	s_mov_b32 m0, s58
	ds_read_b128 v[198:201], v154 offset:49152
	v_xor_b32_e32 v253, 64, v154
	ds_read_b128 v[202:205], v253 offset:49152
	ds_read_b128 v[206:209], v154 offset:51200
	ds_read_b128 v[210:213], v253 offset:51200
	ds_read_b128 v[214:217], v154 offset:53248
	ds_read_b128 v[218:221], v253 offset:53248
	ds_read_b128 v[222:225], v154 offset:55296
	ds_read_b128 v[226:229], v253 offset:55296
	global_load_lds_dwordx4 v[182:183], off
	s_add_i32 m0, s58, 0x2000
	s_add_u32 s56, s56, 0x40080
	v_lshl_add_u64 v[182:183], v[230:231], 0, s[22:23]
	s_addc_u32 s57, s57, 0
	s_add_i32 s58, s87, s63
	global_load_lds_dwordx4 v[182:183], off
	v_lshl_add_u64 v[182:183], s[56:57], 0, v[130:131]
	s_mov_b32 m0, s58
	s_nop 0
	global_load_lds_dwordx4 v[182:183], off
	v_lshl_add_u64 v[182:183], s[56:57], 0, v[134:135]
	s_add_i32 m0, s58, 0x2000
	s_nop 0
	global_load_lds_dwordx4 v[182:183], off
	v_lshl_add_u64 v[182:183], v[232:233], 0, s[22:23]
	s_mov_b32 m0, s69
	s_nop 0
	global_load_lds_dwordx4 v[182:183], off
	v_lshl_add_u64 v[182:183], v[234:235], 0, s[22:23]
	s_mov_b32 m0, s70
	s_nop 0
	global_load_lds_dwordx4 v[182:183], off
	s_waitcnt vmcnt(8)
	s_waitcnt lgkmcnt(0)
	s_barrier
	s_setprio 1
	s_waitcnt lgkmcnt(0)
	v_mfma_f32_16x16x32_bf16 v[60:63], v[162:165], v[198:201], v[60:63]
	v_mfma_f32_16x16x32_bf16 v[60:63], v[166:169], v[202:205], v[60:63]
	v_mfma_f32_16x16x32_bf16 v[56:59], v[170:173], v[198:201], v[56:59]
	v_mfma_f32_16x16x32_bf16 v[56:59], v[174:177], v[202:205], v[56:59]
	v_mfma_f32_16x16x32_bf16 v[48:51], v[162:165], v[206:209], v[48:51]
	v_mfma_f32_16x16x32_bf16 v[48:51], v[166:169], v[210:213], v[48:51]
	v_mfma_f32_16x16x32_bf16 v[40:43], v[170:173], v[206:209], v[40:43]
	v_mfma_f32_16x16x32_bf16 v[40:43], v[174:177], v[210:213], v[40:43]
	v_mfma_f32_16x16x32_bf16 v[32:35], v[162:165], v[214:217], v[32:35]
	v_mfma_f32_16x16x32_bf16 v[32:35], v[166:169], v[218:221], v[32:35]
	v_mfma_f32_16x16x32_bf16 v[24:27], v[170:173], v[214:217], v[24:27]
	v_mfma_f32_16x16x32_bf16 v[24:27], v[174:177], v[218:221], v[24:27]
	v_mfma_f32_16x16x32_bf16 v[16:19], v[162:165], v[222:225], v[16:19]
	v_mfma_f32_16x16x32_bf16 v[16:19], v[166:169], v[226:229], v[16:19]
	v_mfma_f32_16x16x32_bf16 v[8:11], v[170:173], v[222:225], v[8:11]
	v_mfma_f32_16x16x32_bf16 v[8:11], v[174:177], v[226:229], v[8:11]
	s_setprio 0
	s_setprio 1
	v_mfma_f32_16x16x32_bf16 v[52:55], v[178:181], v[198:201], v[52:55]
	v_mfma_f32_16x16x32_bf16 v[52:55], v[186:189], v[202:205], v[52:55]
	v_mfma_f32_16x16x32_bf16 v[44:47], v[190:193], v[198:201], v[44:47]
	v_mfma_f32_16x16x32_bf16 v[44:47], v[194:197], v[202:205], v[44:47]
	v_mfma_f32_16x16x32_bf16 v[36:39], v[178:181], v[206:209], v[36:39]
	v_mfma_f32_16x16x32_bf16 v[36:39], v[186:189], v[210:213], v[36:39]
	v_mfma_f32_16x16x32_bf16 v[28:31], v[190:193], v[206:209], v[28:31]
	v_mfma_f32_16x16x32_bf16 v[28:31], v[194:197], v[210:213], v[28:31]
	v_mfma_f32_16x16x32_bf16 v[20:23], v[178:181], v[214:217], v[20:23]
	v_mfma_f32_16x16x32_bf16 v[20:23], v[186:189], v[218:221], v[20:23]
	v_mfma_f32_16x16x32_bf16 v[12:15], v[190:193], v[214:217], v[12:15]
	v_mfma_f32_16x16x32_bf16 v[12:15], v[194:197], v[218:221], v[12:15]
	v_mfma_f32_16x16x32_bf16 v[4:7], v[178:181], v[222:225], v[4:7]
	v_mfma_f32_16x16x32_bf16 v[4:7], v[186:189], v[226:229], v[4:7]
	v_mfma_f32_16x16x32_bf16 v[0:3], v[190:193], v[222:225], v[0:3]
	v_mfma_f32_16x16x32_bf16 v[0:3], v[194:197], v[226:229], v[0:3]
	s_setprio 0
	s_barrier
	s_add_i32 s85, s85, 2
	s_add_u32 s83, s83, 0x100
	s_addc_u32 s84, s84, 0
	s_add_u32 s54, s54, 0x100
	s_addc_u32 s55, s55, 0
	s_branch .LBB0_875
.Lfa_8:
	v_add_u32_e32 v146, s73, v149
	ds_read_b128 v[162:165], v146
	v_xor_b32_e32 v253, 64, v146
	ds_read_b128 v[166:169], v253
	ds_read_b128 v[170:173], v146 offset:2048
	ds_read_b128 v[174:177], v253 offset:2048
	v_add_u32_e32 v146, s74, v149
	ds_read_b128 v[178:181], v146
	v_xor_b32_e32 v253, 64, v146
	ds_read_b128 v[186:189], v253
	ds_read_b128 v[190:193], v146 offset:2048
	ds_read_b128 v[194:197], v253 offset:2048
	s_add_u32 s58, s54, 0xfffc0080
	s_addc_u32 s59, s55, -1
	s_and_b64 s[56:57], s[56:57], exec
	s_cselect_b32 s59, s49, s59
	s_cselect_b32 s58, s80, s58
	s_cselect_b32 s57, s81, s84
	s_cselect_b32 s56, s82, s83
	v_lshl_add_u64 v[182:183], s[54:55], 0, v[138:139]
	s_add_i32 m0, s64, 0xc000
	ds_read_b128 v[198:201], v154
	v_xor_b32_e32 v253, 64, v154
	ds_read_b128 v[202:205], v253
	ds_read_b128 v[206:209], v154 offset:2048
	ds_read_b128 v[210:213], v253 offset:2048
	ds_read_b128 v[214:217], v154 offset:4096
	ds_read_b128 v[218:221], v253 offset:4096
	ds_read_b128 v[222:225], v154 offset:6144
	ds_read_b128 v[226:229], v253 offset:6144
	global_load_lds_dwordx4 v[182:183], off
	v_lshl_add_u64 v[182:183], s[54:55], 0, v[136:137]
	s_add_i32 m0, s64, 0xe000
	s_nop 0
	global_load_lds_dwordx4 v[182:183], off
	s_waitcnt vmcnt(8)
	s_waitcnt lgkmcnt(0)
	s_barrier
	s_setprio 1
	s_waitcnt lgkmcnt(0)
	v_mfma_f32_16x16x32_bf16 v[124:127], v[162:165], v[198:201], 0
	v_mfma_f32_16x16x32_bf16 v[120:123], v[170:173], v[198:201], 0
	v_mfma_f32_16x16x32_bf16 v[112:115], v[162:165], v[206:209], 0
	v_mfma_f32_16x16x32_bf16 v[104:107], v[170:173], v[206:209], 0
	v_mfma_f32_16x16x32_bf16 v[96:99], v[162:165], v[214:217], 0
	v_mfma_f32_16x16x32_bf16 v[88:91], v[170:173], v[214:217], 0
	v_mfma_f32_16x16x32_bf16 v[80:83], v[162:165], v[222:225], 0
	v_mfma_f32_16x16x32_bf16 v[72:75], v[170:173], v[222:225], 0
	v_mfma_f32_16x16x32_bf16 v[124:127], v[166:169], v[202:205], v[124:127]
	v_mfma_f32_16x16x32_bf16 v[120:123], v[174:177], v[202:205], v[120:123]
	v_mfma_f32_16x16x32_bf16 v[112:115], v[166:169], v[210:213], v[112:115]
	v_mfma_f32_16x16x32_bf16 v[104:107], v[174:177], v[210:213], v[104:107]
	v_mfma_f32_16x16x32_bf16 v[96:99], v[166:169], v[218:221], v[96:99]
	v_mfma_f32_16x16x32_bf16 v[88:91], v[174:177], v[218:221], v[88:91]
	v_mfma_f32_16x16x32_bf16 v[80:83], v[166:169], v[226:229], v[80:83]
	v_mfma_f32_16x16x32_bf16 v[72:75], v[174:177], v[226:229], v[72:75]
	s_setprio 0
	s_setprio 1
	v_mfma_f32_16x16x32_bf16 v[116:119], v[178:181], v[198:201], 0
	v_mfma_f32_16x16x32_bf16 v[108:111], v[190:193], v[198:201], 0
	v_mfma_f32_16x16x32_bf16 v[100:103], v[178:181], v[206:209], 0
	v_mfma_f32_16x16x32_bf16 v[92:95], v[190:193], v[206:209], 0
	v_mfma_f32_16x16x32_bf16 v[84:87], v[178:181], v[214:217], 0
	v_mfma_f32_16x16x32_bf16 v[76:79], v[190:193], v[214:217], 0
	v_mfma_f32_16x16x32_bf16 v[68:71], v[178:181], v[222:225], 0
	v_mfma_f32_16x16x32_bf16 v[64:67], v[190:193], v[222:225], 0
	v_mfma_f32_16x16x32_bf16 v[116:119], v[186:189], v[202:205], v[116:119]
	v_mfma_f32_16x16x32_bf16 v[108:111], v[194:197], v[202:205], v[108:111]
	v_mfma_f32_16x16x32_bf16 v[100:103], v[186:189], v[210:213], v[100:103]
	v_mfma_f32_16x16x32_bf16 v[92:95], v[194:197], v[210:213], v[92:95]
	v_mfma_f32_16x16x32_bf16 v[84:87], v[186:189], v[218:221], v[84:87]
	v_mfma_f32_16x16x32_bf16 v[76:79], v[194:197], v[218:221], v[76:79]
	v_mfma_f32_16x16x32_bf16 v[68:71], v[186:189], v[226:229], v[68:71]
	v_mfma_f32_16x16x32_bf16 v[64:67], v[194:197], v[226:229], v[64:67]
	s_setprio 0
	s_barrier
	s_add_i32 s86, s73, s63
	v_lshl_add_u64 v[182:183], s[56:57], 0, v[130:131]
	s_mov_b32 m0, s86
	ds_read_b128 v[198:201], v154 offset:16384
	v_xor_b32_e32 v253, 64, v154
	ds_read_b128 v[202:205], v253 offset:16384
	ds_read_b128 v[206:209], v154 offset:18432
	ds_read_b128 v[210:213], v253 offset:18432
	ds_read_b128 v[214:217], v154 offset:20480
	ds_read_b128 v[218:221], v253 offset:20480
	ds_read_b128 v[222:225], v154 offset:22528
	ds_read_b128 v[226:229], v253 offset:22528
	global_load_lds_dwordx4 v[182:183], off
	s_add_i32 m0, s86, 0x2000
	s_add_u32 s86, s56, 0x40000
	v_lshl_add_u64 v[230:231], s[56:57], 0, v[134:135]
	s_addc_u32 s87, s57, 0
	s_add_i32 s88, s74, s63
	global_load_lds_dwordx4 v[230:231], off
	v_lshl_add_u64 v[232:233], s[86:87], 0, v[130:131]
	s_mov_b32 m0, s88
	v_lshl_add_u64 v[234:235], s[58:59], 0, v[132:133]
	global_load_lds_dwordx4 v[232:233], off
	v_lshl_add_u64 v[232:233], s[86:87], 0, v[134:135]
	s_add_i32 m0, s88, 0x2000
	s_nop 0
	global_load_lds_dwordx4 v[232:233], off
	v_lshl_add_u64 v[232:233], s[58:59], 0, v[128:129]
	s_mov_b32 m0, s64
	s_nop 0
	global_load_lds_dwordx4 v[232:233], off
	s_mov_b32 m0, s65
	s_nop 0
	global_load_lds_dwordx4 v[234:235], off
	s_waitcnt vmcnt(8)
	s_waitcnt lgkmcnt(0)
	s_barrier
	s_setprio 1
	s_waitcnt lgkmcnt(0)
	v_mfma_f32_16x16x32_bf16 v[60:63], v[162:165], v[198:201], 0
	v_mfma_f32_16x16x32_bf16 v[56:59], v[170:173], v[198:201], 0
	v_mfma_f32_16x16x32_bf16 v[48:51], v[162:165], v[206:209], 0
	v_mfma_f32_16x16x32_bf16 v[40:43], v[170:173], v[206:209], 0
	v_mfma_f32_16x16x32_bf16 v[32:35], v[162:165], v[214:217], 0
	v_mfma_f32_16x16x32_bf16 v[24:27], v[170:173], v[214:217], 0
	v_mfma_f32_16x16x32_bf16 v[16:19], v[162:165], v[222:225], 0
	v_mfma_f32_16x16x32_bf16 v[8:11], v[170:173], v[222:225], 0
	v_mfma_f32_16x16x32_bf16 v[60:63], v[166:169], v[202:205], v[60:63]
	v_mfma_f32_16x16x32_bf16 v[56:59], v[174:177], v[202:205], v[56:59]
	v_mfma_f32_16x16x32_bf16 v[48:51], v[166:169], v[210:213], v[48:51]
	v_mfma_f32_16x16x32_bf16 v[40:43], v[174:177], v[210:213], v[40:43]
	v_mfma_f32_16x16x32_bf16 v[32:35], v[166:169], v[218:221], v[32:35]
	v_mfma_f32_16x16x32_bf16 v[24:27], v[174:177], v[218:221], v[24:27]
	v_mfma_f32_16x16x32_bf16 v[16:19], v[166:169], v[226:229], v[16:19]
	v_mfma_f32_16x16x32_bf16 v[8:11], v[174:177], v[226:229], v[8:11]
	s_setprio 0
	s_setprio 1
	v_mfma_f32_16x16x32_bf16 v[52:55], v[178:181], v[198:201], 0
	v_mfma_f32_16x16x32_bf16 v[44:47], v[190:193], v[198:201], 0
	v_mfma_f32_16x16x32_bf16 v[36:39], v[178:181], v[206:209], 0
	v_mfma_f32_16x16x32_bf16 v[28:31], v[190:193], v[206:209], 0
	v_mfma_f32_16x16x32_bf16 v[20:23], v[178:181], v[214:217], 0
	v_mfma_f32_16x16x32_bf16 v[12:15], v[190:193], v[214:217], 0
	v_mfma_f32_16x16x32_bf16 v[4:7], v[178:181], v[222:225], 0
	v_mfma_f32_16x16x32_bf16 v[0:3], v[190:193], v[222:225], 0
	v_mfma_f32_16x16x32_bf16 v[52:55], v[186:189], v[202:205], v[52:55]
	v_mfma_f32_16x16x32_bf16 v[44:47], v[194:197], v[202:205], v[44:47]
	v_mfma_f32_16x16x32_bf16 v[36:39], v[186:189], v[210:213], v[36:39]
	v_mfma_f32_16x16x32_bf16 v[28:31], v[194:197], v[210:213], v[28:31]
	v_mfma_f32_16x16x32_bf16 v[20:23], v[186:189], v[218:221], v[20:23]
	v_mfma_f32_16x16x32_bf16 v[12:15], v[194:197], v[218:221], v[12:15]
	v_mfma_f32_16x16x32_bf16 v[4:7], v[186:189], v[226:229], v[4:7]
	v_mfma_f32_16x16x32_bf16 v[0:3], v[194:197], v[226:229], v[0:3]
	s_setprio 0
	s_barrier
	s_add_i32 s86, 0, 0x18000
	v_add_u32_e32 v146, s86, v149
	s_add_i32 s87, 0, 0x1c000
	ds_read_b128 v[162:165], v146
	v_xor_b32_e32 v253, 64, v146
	ds_read_b128 v[166:169], v253
	ds_read_b128 v[170:173], v146 offset:2048
	ds_read_b128 v[174:177], v253 offset:2048
	v_add_u32_e32 v146, s87, v149
	ds_read_b128 v[178:181], v146
	v_xor_b32_e32 v253, 64, v146
	ds_read_b128 v[186:189], v253
	ds_read_b128 v[190:193], v146 offset:2048
	ds_read_b128 v[194:197], v253 offset:2048
	s_add_u32 s58, s58, 0x40000
	s_addc_u32 s59, s59, 0
	s_mov_b32 m0, s66
	v_lshl_add_u64 v[236:237], s[58:59], 0, v[128:129]
	ds_read_b128 v[198:201], v154 offset:32768
	v_xor_b32_e32 v253, 64, v154
	ds_read_b128 v[202:205], v253 offset:32768
	ds_read_b128 v[206:209], v154 offset:34816
	ds_read_b128 v[210:213], v253 offset:34816
	ds_read_b128 v[214:217], v154 offset:36864
	ds_read_b128 v[218:221], v253 offset:36864
	ds_read_b128 v[222:225], v154 offset:38912
	ds_read_b128 v[226:229], v253 offset:38912
	global_load_lds_dwordx4 v[236:237], off
	v_lshl_add_u64 v[236:237], s[58:59], 0, v[132:133]
	s_mov_b32 m0, s67
	s_nop 0
	global_load_lds_dwordx4 v[236:237], off
	s_waitcnt vmcnt(8)
	s_waitcnt lgkmcnt(0)
	s_barrier
	s_setprio 1
	s_waitcnt lgkmcnt(0)
	v_mfma_f32_16x16x32_bf16 v[124:127], v[162:165], v[198:201], v[124:127]
	v_mfma_f32_16x16x32_bf16 v[124:127], v[166:169], v[202:205], v[124:127]
	v_mfma_f32_16x16x32_bf16 v[120:123], v[170:173], v[198:201], v[120:123]
	v_mfma_f32_16x16x32_bf16 v[120:123], v[174:177], v[202:205], v[120:123]
	v_mfma_f32_16x16x32_bf16 v[112:115], v[162:165], v[206:209], v[112:115]
	v_mfma_f32_16x16x32_bf16 v[112:115], v[166:169], v[210:213], v[112:115]
	v_mfma_f32_16x16x32_bf16 v[104:107], v[170:173], v[206:209], v[104:107]
	v_mfma_f32_16x16x32_bf16 v[104:107], v[174:177], v[210:213], v[104:107]
	v_mfma_f32_16x16x32_bf16 v[96:99], v[162:165], v[214:217], v[96:99]
	v_mfma_f32_16x16x32_bf16 v[96:99], v[166:169], v[218:221], v[96:99]
	v_mfma_f32_16x16x32_bf16 v[88:91], v[170:173], v[214:217], v[88:91]
	v_mfma_f32_16x16x32_bf16 v[88:91], v[174:177], v[218:221], v[88:91]
	v_mfma_f32_16x16x32_bf16 v[80:83], v[162:165], v[222:225], v[80:83]
	v_mfma_f32_16x16x32_bf16 v[80:83], v[166:169], v[226:229], v[80:83]
	v_mfma_f32_16x16x32_bf16 v[72:75], v[170:173], v[222:225], v[72:75]
	v_mfma_f32_16x16x32_bf16 v[72:75], v[174:177], v[226:229], v[72:75]
	s_setprio 0
	s_setprio 1
	v_mfma_f32_16x16x32_bf16 v[116:119], v[178:181], v[198:201], v[116:119]
	v_mfma_f32_16x16x32_bf16 v[116:119], v[186:189], v[202:205], v[116:119]
	v_mfma_f32_16x16x32_bf16 v[108:111], v[190:193], v[198:201], v[108:111]
	v_mfma_f32_16x16x32_bf16 v[108:111], v[194:197], v[202:205], v[108:111]
	v_mfma_f32_16x16x32_bf16 v[100:103], v[178:181], v[206:209], v[100:103]
	v_mfma_f32_16x16x32_bf16 v[100:103], v[186:189], v[210:213], v[100:103]
	v_mfma_f32_16x16x32_bf16 v[92:95], v[190:193], v[206:209], v[92:95]
	v_mfma_f32_16x16x32_bf16 v[92:95], v[194:197], v[210:213], v[92:95]
	v_mfma_f32_16x16x32_bf16 v[84:87], v[178:181], v[214:217], v[84:87]
	v_mfma_f32_16x16x32_bf16 v[84:87], v[186:189], v[218:221], v[84:87]
	v_mfma_f32_16x16x32_bf16 v[76:79], v[190:193], v[214:217], v[76:79]
	v_mfma_f32_16x16x32_bf16 v[76:79], v[194:197], v[218:221], v[76:79]
	v_mfma_f32_16x16x32_bf16 v[68:71], v[178:181], v[222:225], v[68:71]
	v_mfma_f32_16x16x32_bf16 v[68:71], v[186:189], v[226:229], v[68:71]
	v_mfma_f32_16x16x32_bf16 v[64:67], v[190:193], v[222:225], v[64:67]
	v_mfma_f32_16x16x32_bf16 v[64:67], v[194:197], v[226:229], v[64:67]
	s_setprio 0
	s_barrier
	s_add_i32 s58, s86, s63
	v_lshl_add_u64 v[182:183], v[182:183], 0, s[22:23]
	s_mov_b32 m0, s58
	ds_read_b128 v[198:201], v154 offset:49152
	v_xor_b32_e32 v253, 64, v154
	ds_read_b128 v[202:205], v253 offset:49152
	ds_read_b128 v[206:209], v154 offset:51200
	ds_read_b128 v[210:213], v253 offset:51200
	ds_read_b128 v[214:217], v154 offset:53248
	ds_read_b128 v[218:221], v253 offset:53248
	ds_read_b128 v[222:225], v154 offset:55296
	ds_read_b128 v[226:229], v253 offset:55296
	global_load_lds_dwordx4 v[182:183], off
	s_add_i32 m0, s58, 0x2000
	s_add_u32 s56, s56, 0x40080
	v_lshl_add_u64 v[182:183], v[230:231], 0, s[22:23]
	s_addc_u32 s57, s57, 0
	s_add_i32 s58, s87, s63
	global_load_lds_dwordx4 v[182:183], off
	v_lshl_add_u64 v[182:183], s[56:57], 0, v[130:131]
	s_mov_b32 m0, s58
	s_nop 0
	global_load_lds_dwordx4 v[182:183], off
	v_lshl_add_u64 v[182:183], s[56:57], 0, v[134:135]
	s_add_i32 m0, s58, 0x2000
	s_nop 0
	global_load_lds_dwordx4 v[182:183], off
	v_lshl_add_u64 v[182:183], v[232:233], 0, s[22:23]
	s_mov_b32 m0, s69
	s_nop 0
	global_load_lds_dwordx4 v[182:183], off
	v_lshl_add_u64 v[182:183], v[234:235], 0, s[22:23]
	s_mov_b32 m0, s70
	s_nop 0
	global_load_lds_dwordx4 v[182:183], off
	s_waitcnt vmcnt(8)
	s_waitcnt lgkmcnt(0)
	s_barrier
	s_setprio 1
	s_waitcnt lgkmcnt(0)
	v_mfma_f32_16x16x32_bf16 v[60:63], v[162:165], v[198:201], v[60:63]
	v_mfma_f32_16x16x32_bf16 v[60:63], v[166:169], v[202:205], v[60:63]
	v_mfma_f32_16x16x32_bf16 v[56:59], v[170:173], v[198:201], v[56:59]
	v_mfma_f32_16x16x32_bf16 v[56:59], v[174:177], v[202:205], v[56:59]
	v_mfma_f32_16x16x32_bf16 v[48:51], v[162:165], v[206:209], v[48:51]
	v_mfma_f32_16x16x32_bf16 v[48:51], v[166:169], v[210:213], v[48:51]
	v_mfma_f32_16x16x32_bf16 v[40:43], v[170:173], v[206:209], v[40:43]
	v_mfma_f32_16x16x32_bf16 v[40:43], v[174:177], v[210:213], v[40:43]
	v_mfma_f32_16x16x32_bf16 v[32:35], v[162:165], v[214:217], v[32:35]
	v_mfma_f32_16x16x32_bf16 v[32:35], v[166:169], v[218:221], v[32:35]
	v_mfma_f32_16x16x32_bf16 v[24:27], v[170:173], v[214:217], v[24:27]
	v_mfma_f32_16x16x32_bf16 v[24:27], v[174:177], v[218:221], v[24:27]
	v_mfma_f32_16x16x32_bf16 v[16:19], v[162:165], v[222:225], v[16:19]
	v_mfma_f32_16x16x32_bf16 v[16:19], v[166:169], v[226:229], v[16:19]
	v_mfma_f32_16x16x32_bf16 v[8:11], v[170:173], v[222:225], v[8:11]
	v_mfma_f32_16x16x32_bf16 v[8:11], v[174:177], v[226:229], v[8:11]
	s_setprio 0
	s_setprio 1
	v_mfma_f32_16x16x32_bf16 v[52:55], v[178:181], v[198:201], v[52:55]
	v_mfma_f32_16x16x32_bf16 v[52:55], v[186:189], v[202:205], v[52:55]
	v_mfma_f32_16x16x32_bf16 v[44:47], v[190:193], v[198:201], v[44:47]
	v_mfma_f32_16x16x32_bf16 v[44:47], v[194:197], v[202:205], v[44:47]
	v_mfma_f32_16x16x32_bf16 v[36:39], v[178:181], v[206:209], v[36:39]
	v_mfma_f32_16x16x32_bf16 v[36:39], v[186:189], v[210:213], v[36:39]
	v_mfma_f32_16x16x32_bf16 v[28:31], v[190:193], v[206:209], v[28:31]
	v_mfma_f32_16x16x32_bf16 v[28:31], v[194:197], v[210:213], v[28:31]
	v_mfma_f32_16x16x32_bf16 v[20:23], v[178:181], v[214:217], v[20:23]
	v_mfma_f32_16x16x32_bf16 v[20:23], v[186:189], v[218:221], v[20:23]
	v_mfma_f32_16x16x32_bf16 v[12:15], v[190:193], v[214:217], v[12:15]
	v_mfma_f32_16x16x32_bf16 v[12:15], v[194:197], v[218:221], v[12:15]
	v_mfma_f32_16x16x32_bf16 v[4:7], v[178:181], v[222:225], v[4:7]
	v_mfma_f32_16x16x32_bf16 v[4:7], v[186:189], v[226:229], v[4:7]
	v_mfma_f32_16x16x32_bf16 v[0:3], v[190:193], v[222:225], v[0:3]
	v_mfma_f32_16x16x32_bf16 v[0:3], v[194:197], v[226:229], v[0:3]
	s_setprio 0
	s_barrier
	s_add_i32 s85, s85, 2
	s_add_u32 s83, s83, 0x100
	s_addc_u32 s84, s84, 0
	s_add_u32 s54, s54, 0x100
	s_addc_u32 s55, s55, 0
	s_branch .LBB0_875
.LBB0_874:
	v_add_u32_e32 v146, s73, v149
	ds_read_b128 v[162:165], v146
	v_xor_b32_e32 v253, 64, v146
	ds_read_b128 v[166:169], v253
	ds_read_b128 v[170:173], v146 offset:2048
	ds_read_b128 v[174:177], v253 offset:2048
	v_add_u32_e32 v146, s74, v149
	ds_read_b128 v[178:181], v146
	v_xor_b32_e32 v253, 64, v146
	ds_read_b128 v[186:189], v253
	ds_read_b128 v[190:193], v146 offset:2048
	ds_read_b128 v[194:197], v253 offset:2048
	s_add_u32 s58, s54, 0xfffc0080
	s_addc_u32 s59, s55, -1
	s_and_b64 s[56:57], s[56:57], exec
	s_cselect_b32 s59, s49, s59
	s_cselect_b32 s58, s80, s58
	s_cselect_b32 s57, s81, s84
	s_cselect_b32 s56, s82, s83
	v_lshl_add_u64 v[182:183], s[54:55], 0, v[138:139]
	s_add_i32 m0, s64, 0xc000
	ds_read_b128 v[198:201], v154
	v_xor_b32_e32 v253, 64, v154
	ds_read_b128 v[202:205], v253
	ds_read_b128 v[206:209], v154 offset:2048
	ds_read_b128 v[210:213], v253 offset:2048
	ds_read_b128 v[214:217], v154 offset:4096
	ds_read_b128 v[218:221], v253 offset:4096
	ds_read_b128 v[222:225], v154 offset:6144
	ds_read_b128 v[226:229], v253 offset:6144
	global_load_lds_dwordx4 v[182:183], off
	v_lshl_add_u64 v[182:183], s[54:55], 0, v[136:137]
	s_add_i32 m0, s64, 0xe000
	s_nop 0
	global_load_lds_dwordx4 v[182:183], off
	s_waitcnt vmcnt(8)
	s_waitcnt lgkmcnt(0)
	s_barrier
	s_setprio 1
	s_waitcnt lgkmcnt(0)
	v_mfma_f32_16x16x32_bf16 v[124:127], v[162:165], v[198:201], v[124:127]
	v_mfma_f32_16x16x32_bf16 v[124:127], v[166:169], v[202:205], v[124:127]
	v_mfma_f32_16x16x32_bf16 v[120:123], v[170:173], v[198:201], v[120:123]
	v_mfma_f32_16x16x32_bf16 v[120:123], v[174:177], v[202:205], v[120:123]
	v_mfma_f32_16x16x32_bf16 v[112:115], v[162:165], v[206:209], v[112:115]
	v_mfma_f32_16x16x32_bf16 v[112:115], v[166:169], v[210:213], v[112:115]
	v_mfma_f32_16x16x32_bf16 v[104:107], v[170:173], v[206:209], v[104:107]
	v_mfma_f32_16x16x32_bf16 v[104:107], v[174:177], v[210:213], v[104:107]
	v_mfma_f32_16x16x32_bf16 v[96:99], v[162:165], v[214:217], v[96:99]
	v_mfma_f32_16x16x32_bf16 v[96:99], v[166:169], v[218:221], v[96:99]
	v_mfma_f32_16x16x32_bf16 v[88:91], v[170:173], v[214:217], v[88:91]
	v_mfma_f32_16x16x32_bf16 v[88:91], v[174:177], v[218:221], v[88:91]
	v_mfma_f32_16x16x32_bf16 v[80:83], v[162:165], v[222:225], v[80:83]
	v_mfma_f32_16x16x32_bf16 v[80:83], v[166:169], v[226:229], v[80:83]
	v_mfma_f32_16x16x32_bf16 v[72:75], v[170:173], v[222:225], v[72:75]
	v_mfma_f32_16x16x32_bf16 v[72:75], v[174:177], v[226:229], v[72:75]
	s_setprio 0
	s_setprio 1
	v_mfma_f32_16x16x32_bf16 v[116:119], v[178:181], v[198:201], v[116:119]
	v_mfma_f32_16x16x32_bf16 v[116:119], v[186:189], v[202:205], v[116:119]
	v_mfma_f32_16x16x32_bf16 v[108:111], v[190:193], v[198:201], v[108:111]
	v_mfma_f32_16x16x32_bf16 v[108:111], v[194:197], v[202:205], v[108:111]
	v_mfma_f32_16x16x32_bf16 v[100:103], v[178:181], v[206:209], v[100:103]
	v_mfma_f32_16x16x32_bf16 v[100:103], v[186:189], v[210:213], v[100:103]
	v_mfma_f32_16x16x32_bf16 v[92:95], v[190:193], v[206:209], v[92:95]
	v_mfma_f32_16x16x32_bf16 v[92:95], v[194:197], v[210:213], v[92:95]
	v_mfma_f32_16x16x32_bf16 v[84:87], v[178:181], v[214:217], v[84:87]
	v_mfma_f32_16x16x32_bf16 v[84:87], v[186:189], v[218:221], v[84:87]
	v_mfma_f32_16x16x32_bf16 v[76:79], v[190:193], v[214:217], v[76:79]
	v_mfma_f32_16x16x32_bf16 v[76:79], v[194:197], v[218:221], v[76:79]
	v_mfma_f32_16x16x32_bf16 v[68:71], v[178:181], v[222:225], v[68:71]
	v_mfma_f32_16x16x32_bf16 v[68:71], v[186:189], v[226:229], v[68:71]
	v_mfma_f32_16x16x32_bf16 v[64:67], v[190:193], v[222:225], v[64:67]
	v_mfma_f32_16x16x32_bf16 v[64:67], v[194:197], v[226:229], v[64:67]
	s_setprio 0
	s_barrier
	s_add_i32 s86, s73, s63
	v_lshl_add_u64 v[182:183], s[56:57], 0, v[130:131]
	s_mov_b32 m0, s86
	ds_read_b128 v[198:201], v154 offset:16384
	v_xor_b32_e32 v253, 64, v154
	ds_read_b128 v[202:205], v253 offset:16384
	ds_read_b128 v[206:209], v154 offset:18432
	ds_read_b128 v[210:213], v253 offset:18432
	ds_read_b128 v[214:217], v154 offset:20480
	ds_read_b128 v[218:221], v253 offset:20480
	ds_read_b128 v[222:225], v154 offset:22528
	ds_read_b128 v[226:229], v253 offset:22528
	global_load_lds_dwordx4 v[182:183], off
	s_add_i32 m0, s86, 0x2000
	s_add_u32 s86, s56, 0x40000
	v_lshl_add_u64 v[230:231], s[56:57], 0, v[134:135]
	s_addc_u32 s87, s57, 0
	s_add_i32 s88, s74, s63
	global_load_lds_dwordx4 v[230:231], off
	v_lshl_add_u64 v[232:233], s[86:87], 0, v[130:131]
	s_mov_b32 m0, s88
	v_lshl_add_u64 v[234:235], s[58:59], 0, v[132:133]
	global_load_lds_dwordx4 v[232:233], off
	v_lshl_add_u64 v[232:233], s[86:87], 0, v[134:135]
	s_add_i32 m0, s88, 0x2000
	s_nop 0
	global_load_lds_dwordx4 v[232:233], off
	v_lshl_add_u64 v[232:233], s[58:59], 0, v[128:129]
	s_mov_b32 m0, s64
	s_nop 0
	global_load_lds_dwordx4 v[232:233], off
	s_mov_b32 m0, s65
	s_nop 0
	global_load_lds_dwordx4 v[234:235], off
	s_waitcnt vmcnt(8)
	s_waitcnt lgkmcnt(0)
	s_barrier
	s_setprio 1
	s_waitcnt lgkmcnt(0)
	v_mfma_f32_16x16x32_bf16 v[60:63], v[162:165], v[198:201], v[60:63]
	v_mfma_f32_16x16x32_bf16 v[60:63], v[166:169], v[202:205], v[60:63]
	v_mfma_f32_16x16x32_bf16 v[56:59], v[170:173], v[198:201], v[56:59]
	v_mfma_f32_16x16x32_bf16 v[56:59], v[174:177], v[202:205], v[56:59]
	v_mfma_f32_16x16x32_bf16 v[48:51], v[162:165], v[206:209], v[48:51]
	v_mfma_f32_16x16x32_bf16 v[48:51], v[166:169], v[210:213], v[48:51]
	v_mfma_f32_16x16x32_bf16 v[40:43], v[170:173], v[206:209], v[40:43]
	v_mfma_f32_16x16x32_bf16 v[40:43], v[174:177], v[210:213], v[40:43]
	v_mfma_f32_16x16x32_bf16 v[32:35], v[162:165], v[214:217], v[32:35]
	v_mfma_f32_16x16x32_bf16 v[32:35], v[166:169], v[218:221], v[32:35]
	v_mfma_f32_16x16x32_bf16 v[24:27], v[170:173], v[214:217], v[24:27]
	v_mfma_f32_16x16x32_bf16 v[24:27], v[174:177], v[218:221], v[24:27]
	v_mfma_f32_16x16x32_bf16 v[16:19], v[162:165], v[222:225], v[16:19]
	v_mfma_f32_16x16x32_bf16 v[16:19], v[166:169], v[226:229], v[16:19]
	v_mfma_f32_16x16x32_bf16 v[8:11], v[170:173], v[222:225], v[8:11]
	v_mfma_f32_16x16x32_bf16 v[8:11], v[174:177], v[226:229], v[8:11]
	s_setprio 0
	s_setprio 1
	v_mfma_f32_16x16x32_bf16 v[52:55], v[178:181], v[198:201], v[52:55]
	v_mfma_f32_16x16x32_bf16 v[52:55], v[186:189], v[202:205], v[52:55]
	v_mfma_f32_16x16x32_bf16 v[44:47], v[190:193], v[198:201], v[44:47]
	v_mfma_f32_16x16x32_bf16 v[44:47], v[194:197], v[202:205], v[44:47]
	v_mfma_f32_16x16x32_bf16 v[36:39], v[178:181], v[206:209], v[36:39]
	v_mfma_f32_16x16x32_bf16 v[36:39], v[186:189], v[210:213], v[36:39]
	v_mfma_f32_16x16x32_bf16 v[28:31], v[190:193], v[206:209], v[28:31]
	v_mfma_f32_16x16x32_bf16 v[28:31], v[194:197], v[210:213], v[28:31]
	v_mfma_f32_16x16x32_bf16 v[20:23], v[178:181], v[214:217], v[20:23]
	v_mfma_f32_16x16x32_bf16 v[20:23], v[186:189], v[218:221], v[20:23]
	v_mfma_f32_16x16x32_bf16 v[12:15], v[190:193], v[214:217], v[12:15]
	v_mfma_f32_16x16x32_bf16 v[12:15], v[194:197], v[218:221], v[12:15]
	v_mfma_f32_16x16x32_bf16 v[4:7], v[178:181], v[222:225], v[4:7]
	v_mfma_f32_16x16x32_bf16 v[4:7], v[186:189], v[226:229], v[4:7]
	v_mfma_f32_16x16x32_bf16 v[0:3], v[190:193], v[222:225], v[0:3]
	v_mfma_f32_16x16x32_bf16 v[0:3], v[194:197], v[226:229], v[0:3]
	s_setprio 0
	s_barrier
	s_add_i32 s86, 0, 0x18000
	v_add_u32_e32 v146, s86, v149
	s_add_i32 s87, 0, 0x1c000
	ds_read_b128 v[162:165], v146
	v_xor_b32_e32 v253, 64, v146
	ds_read_b128 v[166:169], v253
	ds_read_b128 v[170:173], v146 offset:2048
	ds_read_b128 v[174:177], v253 offset:2048
	v_add_u32_e32 v146, s87, v149
	ds_read_b128 v[178:181], v146
	v_xor_b32_e32 v253, 64, v146
	ds_read_b128 v[186:189], v253
	ds_read_b128 v[190:193], v146 offset:2048
	ds_read_b128 v[194:197], v253 offset:2048
	s_add_u32 s58, s58, 0x40000
	s_addc_u32 s59, s59, 0
	s_mov_b32 m0, s66
	v_lshl_add_u64 v[236:237], s[58:59], 0, v[128:129]
	ds_read_b128 v[198:201], v154 offset:32768
	v_xor_b32_e32 v253, 64, v154
	ds_read_b128 v[202:205], v253 offset:32768
	ds_read_b128 v[206:209], v154 offset:34816
	ds_read_b128 v[210:213], v253 offset:34816
	ds_read_b128 v[214:217], v154 offset:36864
	ds_read_b128 v[218:221], v253 offset:36864
	ds_read_b128 v[222:225], v154 offset:38912
	ds_read_b128 v[226:229], v253 offset:38912
	global_load_lds_dwordx4 v[236:237], off
	v_lshl_add_u64 v[236:237], s[58:59], 0, v[132:133]
	s_mov_b32 m0, s67
	s_nop 0
	global_load_lds_dwordx4 v[236:237], off
	s_waitcnt vmcnt(8)
	s_waitcnt lgkmcnt(0)
	s_barrier
	s_setprio 1
	s_waitcnt lgkmcnt(0)
	v_mfma_f32_16x16x32_bf16 v[124:127], v[162:165], v[198:201], v[124:127]
	v_mfma_f32_16x16x32_bf16 v[124:127], v[166:169], v[202:205], v[124:127]
	v_mfma_f32_16x16x32_bf16 v[120:123], v[170:173], v[198:201], v[120:123]
	v_mfma_f32_16x16x32_bf16 v[120:123], v[174:177], v[202:205], v[120:123]
	v_mfma_f32_16x16x32_bf16 v[112:115], v[162:165], v[206:209], v[112:115]
	v_mfma_f32_16x16x32_bf16 v[112:115], v[166:169], v[210:213], v[112:115]
	v_mfma_f32_16x16x32_bf16 v[104:107], v[170:173], v[206:209], v[104:107]
	v_mfma_f32_16x16x32_bf16 v[104:107], v[174:177], v[210:213], v[104:107]
	v_mfma_f32_16x16x32_bf16 v[96:99], v[162:165], v[214:217], v[96:99]
	v_mfma_f32_16x16x32_bf16 v[96:99], v[166:169], v[218:221], v[96:99]
	v_mfma_f32_16x16x32_bf16 v[88:91], v[170:173], v[214:217], v[88:91]
	v_mfma_f32_16x16x32_bf16 v[88:91], v[174:177], v[218:221], v[88:91]
	v_mfma_f32_16x16x32_bf16 v[80:83], v[162:165], v[222:225], v[80:83]
	v_mfma_f32_16x16x32_bf16 v[80:83], v[166:169], v[226:229], v[80:83]
	v_mfma_f32_16x16x32_bf16 v[72:75], v[170:173], v[222:225], v[72:75]
	v_mfma_f32_16x16x32_bf16 v[72:75], v[174:177], v[226:229], v[72:75]
	s_setprio 0
	s_setprio 1
	v_mfma_f32_16x16x32_bf16 v[116:119], v[178:181], v[198:201], v[116:119]
	v_mfma_f32_16x16x32_bf16 v[116:119], v[186:189], v[202:205], v[116:119]
	v_mfma_f32_16x16x32_bf16 v[108:111], v[190:193], v[198:201], v[108:111]
	v_mfma_f32_16x16x32_bf16 v[108:111], v[194:197], v[202:205], v[108:111]
	v_mfma_f32_16x16x32_bf16 v[100:103], v[178:181], v[206:209], v[100:103]
	v_mfma_f32_16x16x32_bf16 v[100:103], v[186:189], v[210:213], v[100:103]
	v_mfma_f32_16x16x32_bf16 v[92:95], v[190:193], v[206:209], v[92:95]
	v_mfma_f32_16x16x32_bf16 v[92:95], v[194:197], v[210:213], v[92:95]
	v_mfma_f32_16x16x32_bf16 v[84:87], v[178:181], v[214:217], v[84:87]
	v_mfma_f32_16x16x32_bf16 v[84:87], v[186:189], v[218:221], v[84:87]
	v_mfma_f32_16x16x32_bf16 v[76:79], v[190:193], v[214:217], v[76:79]
	v_mfma_f32_16x16x32_bf16 v[76:79], v[194:197], v[218:221], v[76:79]
	v_mfma_f32_16x16x32_bf16 v[68:71], v[178:181], v[222:225], v[68:71]
	v_mfma_f32_16x16x32_bf16 v[68:71], v[186:189], v[226:229], v[68:71]
	v_mfma_f32_16x16x32_bf16 v[64:67], v[190:193], v[222:225], v[64:67]
	v_mfma_f32_16x16x32_bf16 v[64:67], v[194:197], v[226:229], v[64:67]
	s_setprio 0
	s_barrier
	s_add_i32 s58, s86, s63
	v_lshl_add_u64 v[182:183], v[182:183], 0, s[22:23]
	s_mov_b32 m0, s58
	ds_read_b128 v[198:201], v154 offset:49152
	v_xor_b32_e32 v253, 64, v154
	ds_read_b128 v[202:205], v253 offset:49152
	ds_read_b128 v[206:209], v154 offset:51200
	ds_read_b128 v[210:213], v253 offset:51200
	ds_read_b128 v[214:217], v154 offset:53248
	ds_read_b128 v[218:221], v253 offset:53248
	ds_read_b128 v[222:225], v154 offset:55296
	ds_read_b128 v[226:229], v253 offset:55296
	global_load_lds_dwordx4 v[182:183], off
	s_add_i32 m0, s58, 0x2000
	s_add_u32 s56, s56, 0x40080
	v_lshl_add_u64 v[182:183], v[230:231], 0, s[22:23]
	s_addc_u32 s57, s57, 0
	s_add_i32 s58, s87, s63
	global_load_lds_dwordx4 v[182:183], off
	v_lshl_add_u64 v[182:183], s[56:57], 0, v[130:131]
	s_mov_b32 m0, s58
	s_nop 0
	global_load_lds_dwordx4 v[182:183], off
	v_lshl_add_u64 v[182:183], s[56:57], 0, v[134:135]
	s_add_i32 m0, s58, 0x2000
	s_nop 0
	global_load_lds_dwordx4 v[182:183], off
	v_lshl_add_u64 v[182:183], v[232:233], 0, s[22:23]
	s_mov_b32 m0, s69
	s_nop 0
	global_load_lds_dwordx4 v[182:183], off
	v_lshl_add_u64 v[182:183], v[234:235], 0, s[22:23]
	s_mov_b32 m0, s70
	s_nop 0
	global_load_lds_dwordx4 v[182:183], off
	s_waitcnt vmcnt(8)
	s_waitcnt lgkmcnt(0)
	s_barrier
	s_setprio 1
	s_waitcnt lgkmcnt(0)
	v_mfma_f32_16x16x32_bf16 v[60:63], v[162:165], v[198:201], v[60:63]
	v_mfma_f32_16x16x32_bf16 v[60:63], v[166:169], v[202:205], v[60:63]
	v_mfma_f32_16x16x32_bf16 v[56:59], v[170:173], v[198:201], v[56:59]
	v_mfma_f32_16x16x32_bf16 v[56:59], v[174:177], v[202:205], v[56:59]
	v_mfma_f32_16x16x32_bf16 v[48:51], v[162:165], v[206:209], v[48:51]
	v_mfma_f32_16x16x32_bf16 v[48:51], v[166:169], v[210:213], v[48:51]
	v_mfma_f32_16x16x32_bf16 v[40:43], v[170:173], v[206:209], v[40:43]
	v_mfma_f32_16x16x32_bf16 v[40:43], v[174:177], v[210:213], v[40:43]
	v_mfma_f32_16x16x32_bf16 v[32:35], v[162:165], v[214:217], v[32:35]
	v_mfma_f32_16x16x32_bf16 v[32:35], v[166:169], v[218:221], v[32:35]
	v_mfma_f32_16x16x32_bf16 v[24:27], v[170:173], v[214:217], v[24:27]
	v_mfma_f32_16x16x32_bf16 v[24:27], v[174:177], v[218:221], v[24:27]
	v_mfma_f32_16x16x32_bf16 v[16:19], v[162:165], v[222:225], v[16:19]
	v_mfma_f32_16x16x32_bf16 v[16:19], v[166:169], v[226:229], v[16:19]
	v_mfma_f32_16x16x32_bf16 v[8:11], v[170:173], v[222:225], v[8:11]
	v_mfma_f32_16x16x32_bf16 v[8:11], v[174:177], v[226:229], v[8:11]
	s_setprio 0
	s_setprio 1
	v_mfma_f32_16x16x32_bf16 v[52:55], v[178:181], v[198:201], v[52:55]
	v_mfma_f32_16x16x32_bf16 v[52:55], v[186:189], v[202:205], v[52:55]
	v_mfma_f32_16x16x32_bf16 v[44:47], v[190:193], v[198:201], v[44:47]
	v_mfma_f32_16x16x32_bf16 v[44:47], v[194:197], v[202:205], v[44:47]
	v_mfma_f32_16x16x32_bf16 v[36:39], v[178:181], v[206:209], v[36:39]
	v_mfma_f32_16x16x32_bf16 v[36:39], v[186:189], v[210:213], v[36:39]
	v_mfma_f32_16x16x32_bf16 v[28:31], v[190:193], v[206:209], v[28:31]
	v_mfma_f32_16x16x32_bf16 v[28:31], v[194:197], v[210:213], v[28:31]
	v_mfma_f32_16x16x32_bf16 v[20:23], v[178:181], v[214:217], v[20:23]
	v_mfma_f32_16x16x32_bf16 v[20:23], v[186:189], v[218:221], v[20:23]
	v_mfma_f32_16x16x32_bf16 v[12:15], v[190:193], v[214:217], v[12:15]
	v_mfma_f32_16x16x32_bf16 v[12:15], v[194:197], v[218:221], v[12:15]
	v_mfma_f32_16x16x32_bf16 v[4:7], v[178:181], v[222:225], v[4:7]
	v_mfma_f32_16x16x32_bf16 v[4:7], v[186:189], v[226:229], v[4:7]
	v_mfma_f32_16x16x32_bf16 v[0:3], v[190:193], v[222:225], v[0:3]
	v_mfma_f32_16x16x32_bf16 v[0:3], v[194:197], v[226:229], v[0:3]
	s_setprio 0
	s_barrier
	s_add_i32 s85, s85, 2
	s_add_u32 s83, s83, 0x100
	s_addc_u32 s84, s84, 0
	s_add_u32 s54, s54, 0x100
	s_addc_u32 s55, s55, 0
	s_cmp_gt_u32 s85, 13
	s_cbranch_scc1 .LBB0_877

.LBB0_1010:
	s_ashr_i32 s51, s50, 31
	s_lshl_b64 s[52:53], s[50:51], 19
	s_add_u32 s52, s33, s52
	s_addc_u32 s53, s35, s53
	s_and_b64 s[54:55], s[12:13], exec
	s_cselect_b32 s15, s53, s61
	s_cselect_b32 s51, s52, s60
	s_ashr_i32 s49, s48, 31
	s_lshl_b64 s[54:55], s[48:49], 19
	s_add_u32 s54, s64, s54
	s_addc_u32 s55, s65, s55
	s_and_b64 s[62:63], s[12:13], exec
	s_cselect_b32 s49, s55, s59
	s_cselect_b32 s57, s54, s58
	s_add_u32 s78, s58, 0x100
	s_addc_u32 s79, s59, 0
	s_add_u32 s58, s60, 0x40080
	s_addc_u32 s59, s61, 0
	s_mov_b32 s80, -2
	s_waitcnt lgkmcnt(0)
	s_cmp_eq_u32 s71, 1
	s_cbranch_scc1 .Lfa_9
	ds_read_b128 v[128:131], v188
	v_xor_b32_e32 v253, 64, v188
	ds_read_b128 v[132:135], v253
	ds_read_b128 v[136:139], v188 offset:2048
	ds_read_b128 v[140:143], v253 offset:2048
	ds_read_b128 v[144:147], v189
	v_xor_b32_e32 v253, 64, v189
	ds_read_b128 v[148:151], v253
	ds_read_b128 v[172:175], v189 offset:2048
	ds_read_b128 v[176:179], v253 offset:2048
	s_add_u32 s60, s58, 0xfffc0080
	s_addc_u32 s61, s59, -1
	s_cmp_eq_u32 s80, 12
	s_cselect_b32 s63, s15, s61
	s_cselect_b32 s62, s51, s60
	s_cselect_b32 s61, s49, s79
	s_cselect_b32 s60, s57, s78
	v_lshl_add_u64 v[220:221], s[58:59], 0, v[166:167]
	s_add_i32 m0, s67, 0xc000
	ds_read_b128 v[180:183], v190
	v_xor_b32_e32 v253, 64, v190
	ds_read_b128 v[192:195], v253
	ds_read_b128 v[196:199], v190 offset:2048
	ds_read_b128 v[200:203], v253 offset:2048
	ds_read_b128 v[204:207], v190 offset:4096
	ds_read_b128 v[208:211], v253 offset:4096
	ds_read_b128 v[212:215], v190 offset:6144
	ds_read_b128 v[216:219], v253 offset:6144
	global_load_lds_dwordx4 v[220:221], off
	v_lshl_add_u64 v[220:221], s[58:59], 0, v[164:165]
	s_add_i32 m0, s67, 0xe000
	s_nop 0
	global_load_lds_dwordx4 v[220:221], off
	s_waitcnt vmcnt(24)
	s_waitcnt lgkmcnt(0)
	s_barrier
	s_setprio 1
	s_waitcnt lgkmcnt(0)
	v_mfma_f32_16x16x32_bf16 v[124:127], v[128:131], v[180:183], 0
	v_mfma_f32_16x16x32_bf16 v[120:123], v[136:139], v[180:183], 0
	v_mfma_f32_16x16x32_bf16 v[108:111], v[128:131], v[196:199], 0
	v_mfma_f32_16x16x32_bf16 v[104:107], v[136:139], v[196:199], 0
	v_mfma_f32_16x16x32_bf16 v[92:95], v[128:131], v[204:207], 0
	v_mfma_f32_16x16x32_bf16 v[88:91], v[136:139], v[204:207], 0
	v_mfma_f32_16x16x32_bf16 v[76:79], v[128:131], v[212:215], 0
	v_mfma_f32_16x16x32_bf16 v[72:75], v[136:139], v[212:215], 0
	v_mfma_f32_16x16x32_bf16 v[124:127], v[132:135], v[192:195], v[124:127]
	v_mfma_f32_16x16x32_bf16 v[120:123], v[140:143], v[192:195], v[120:123]
	v_mfma_f32_16x16x32_bf16 v[108:111], v[132:135], v[200:203], v[108:111]
	v_mfma_f32_16x16x32_bf16 v[104:107], v[140:143], v[200:203], v[104:107]
	v_mfma_f32_16x16x32_bf16 v[92:95], v[132:135], v[208:211], v[92:95]
	v_mfma_f32_16x16x32_bf16 v[88:91], v[140:143], v[208:211], v[88:91]
	v_mfma_f32_16x16x32_bf16 v[76:79], v[132:135], v[216:219], v[76:79]
	v_mfma_f32_16x16x32_bf16 v[72:75], v[140:143], v[216:219], v[72:75]
	s_setprio 0
	s_setprio 1
	v_mfma_f32_16x16x32_bf16 v[116:119], v[144:147], v[180:183], 0
	v_mfma_f32_16x16x32_bf16 v[112:115], v[172:175], v[180:183], 0
	v_mfma_f32_16x16x32_bf16 v[100:103], v[144:147], v[196:199], 0
	v_mfma_f32_16x16x32_bf16 v[96:99], v[172:175], v[196:199], 0
	v_mfma_f32_16x16x32_bf16 v[84:87], v[144:147], v[204:207], 0
	v_mfma_f32_16x16x32_bf16 v[80:83], v[172:175], v[204:207], 0
	v_mfma_f32_16x16x32_bf16 v[68:71], v[144:147], v[212:215], 0
	v_mfma_f32_16x16x32_bf16 v[64:67], v[172:175], v[212:215], 0
	v_mfma_f32_16x16x32_bf16 v[116:119], v[148:151], v[192:195], v[116:119]
	v_mfma_f32_16x16x32_bf16 v[112:115], v[176:179], v[192:195], v[112:115]
	v_mfma_f32_16x16x32_bf16 v[100:103], v[148:151], v[200:203], v[100:103]
	v_mfma_f32_16x16x32_bf16 v[96:99], v[176:179], v[200:203], v[96:99]
	v_mfma_f32_16x16x32_bf16 v[84:87], v[148:151], v[208:211], v[84:87]
	v_mfma_f32_16x16x32_bf16 v[80:83], v[176:179], v[208:211], v[80:83]
	v_mfma_f32_16x16x32_bf16 v[68:71], v[148:151], v[216:219], v[68:71]
	v_mfma_f32_16x16x32_bf16 v[64:67], v[176:179], v[216:219], v[64:67]
	s_setprio 0
	s_barrier
	s_add_i32 s81, s76, s66
	v_lshl_add_u64 v[220:221], s[60:61], 0, v[154:155]
	s_mov_b32 m0, s81
	ds_read_b128 v[180:183], v190 offset:16384
	v_xor_b32_e32 v253, 64, v190
	ds_read_b128 v[192:195], v253 offset:16384
	ds_read_b128 v[196:199], v190 offset:18432
	ds_read_b128 v[200:203], v253 offset:18432
	ds_read_b128 v[204:207], v190 offset:20480
	ds_read_b128 v[208:211], v253 offset:20480
	ds_read_b128 v[212:215], v190 offset:22528
	ds_read_b128 v[216:219], v253 offset:22528
	global_load_lds_dwordx4 v[220:221], off
	s_add_i32 m0, s81, 0x2000
	s_add_u32 s82, s60, 0x40000
	v_lshl_add_u64 v[222:223], s[60:61], 0, v[162:163]
	s_addc_u32 s83, s61, 0
	s_add_i32 s81, s77, s66
	global_load_lds_dwordx4 v[222:223], off
	v_lshl_add_u64 v[224:225], s[82:83], 0, v[154:155]
	s_mov_b32 m0, s81
	v_lshl_add_u64 v[226:227], s[62:63], 0, v[160:161]
	global_load_lds_dwordx4 v[224:225], off
	v_lshl_add_u64 v[224:225], s[82:83], 0, v[162:163]
	s_add_i32 m0, s81, 0x2000
	s_nop 0
	global_load_lds_dwordx4 v[224:225], off
	v_lshl_add_u64 v[224:225], s[62:63], 0, v[152:153]
	s_mov_b32 m0, s67
	s_nop 0
	global_load_lds_dwordx4 v[224:225], off
	s_mov_b32 m0, s68
	s_nop 0
	global_load_lds_dwordx4 v[226:227], off
	s_waitcnt vmcnt(24)
	s_waitcnt lgkmcnt(0)
	s_barrier
	s_setprio 1
	s_waitcnt lgkmcnt(0)
	v_mfma_f32_16x16x32_bf16 v[60:63], v[128:131], v[180:183], 0
	v_mfma_f32_16x16x32_bf16 v[56:59], v[136:139], v[180:183], 0
	v_mfma_f32_16x16x32_bf16 v[44:47], v[128:131], v[196:199], 0
	v_mfma_f32_16x16x32_bf16 v[40:43], v[136:139], v[196:199], 0
	v_mfma_f32_16x16x32_bf16 v[28:31], v[128:131], v[204:207], 0
	v_mfma_f32_16x16x32_bf16 v[24:27], v[136:139], v[204:207], 0
	v_mfma_f32_16x16x32_bf16 v[12:15], v[128:131], v[212:215], 0
	v_mfma_f32_16x16x32_bf16 v[8:11], v[136:139], v[212:215], 0
	v_mfma_f32_16x16x32_bf16 v[60:63], v[132:135], v[192:195], v[60:63]
	v_mfma_f32_16x16x32_bf16 v[56:59], v[140:143], v[192:195], v[56:59]
	v_mfma_f32_16x16x32_bf16 v[44:47], v[132:135], v[200:203], v[44:47]
	v_mfma_f32_16x16x32_bf16 v[40:43], v[140:143], v[200:203], v[40:43]
	v_mfma_f32_16x16x32_bf16 v[28:31], v[132:135], v[208:211], v[28:31]
	v_mfma_f32_16x16x32_bf16 v[24:27], v[140:143], v[208:211], v[24:27]
	v_mfma_f32_16x16x32_bf16 v[12:15], v[132:135], v[216:219], v[12:15]
	v_mfma_f32_16x16x32_bf16 v[8:11], v[140:143], v[216:219], v[8:11]
	s_setprio 0
	s_setprio 1
	v_mfma_f32_16x16x32_bf16 v[52:55], v[144:147], v[180:183], 0
	v_mfma_f32_16x16x32_bf16 v[48:51], v[172:175], v[180:183], 0
	v_mfma_f32_16x16x32_bf16 v[36:39], v[144:147], v[196:199], 0
	v_mfma_f32_16x16x32_bf16 v[32:35], v[172:175], v[196:199], 0
	v_mfma_f32_16x16x32_bf16 v[20:23], v[144:147], v[204:207], 0
	v_mfma_f32_16x16x32_bf16 v[16:19], v[172:175], v[204:207], 0
	v_mfma_f32_16x16x32_bf16 v[4:7], v[144:147], v[212:215], 0
	v_mfma_f32_16x16x32_bf16 v[0:3], v[172:175], v[212:215], 0
	v_mfma_f32_16x16x32_bf16 v[52:55], v[148:151], v[192:195], v[52:55]
	v_mfma_f32_16x16x32_bf16 v[48:51], v[176:179], v[192:195], v[48:51]
	v_mfma_f32_16x16x32_bf16 v[36:39], v[148:151], v[200:203], v[36:39]
	v_mfma_f32_16x16x32_bf16 v[32:35], v[176:179], v[200:203], v[32:35]
	v_mfma_f32_16x16x32_bf16 v[20:23], v[148:151], v[208:211], v[20:23]
	v_mfma_f32_16x16x32_bf16 v[16:19], v[176:179], v[208:211], v[16:19]
	v_mfma_f32_16x16x32_bf16 v[4:7], v[148:151], v[216:219], v[4:7]
	v_mfma_f32_16x16x32_bf16 v[0:3], v[176:179], v[216:219], v[0:3]
	s_setprio 0
	s_barrier
	s_add_i32 s81, 0, 0x18000
	s_add_i32 s82, 0, 0x1c000
	v_add_u32_e32 v140, s81, v185
	v_add_u32_e32 v176, s82, v185
	ds_read_b128 v[128:131], v140
	v_xor_b32_e32 v253, 64, v140
	ds_read_b128 v[132:135], v253
	ds_read_b128 v[136:139], v140 offset:2048
	ds_read_b128 v[140:143], v253 offset:2048
	ds_read_b128 v[144:147], v176
	v_xor_b32_e32 v253, 64, v176
	ds_read_b128 v[148:151], v253
	ds_read_b128 v[172:175], v176 offset:2048
	ds_read_b128 v[176:179], v253 offset:2048
	s_add_u32 s62, s62, 0x40000
	s_addc_u32 s63, s63, 0
	s_mov_b32 m0, s69
	v_lshl_add_u64 v[228:229], s[62:63], 0, v[152:153]
	ds_read_b128 v[180:183], v190 offset:32768
	v_xor_b32_e32 v253, 64, v190
	ds_read_b128 v[192:195], v253 offset:32768
	ds_read_b128 v[196:199], v190 offset:34816
	ds_read_b128 v[200:203], v253 offset:34816
	ds_read_b128 v[204:207], v190 offset:36864
	ds_read_b128 v[208:211], v253 offset:36864
	ds_read_b128 v[212:215], v190 offset:38912
	ds_read_b128 v[216:219], v253 offset:38912
	global_load_lds_dwordx4 v[228:229], off
	v_lshl_add_u64 v[228:229], s[62:63], 0, v[160:161]
	s_mov_b32 m0, s70
	s_nop 0
	global_load_lds_dwordx4 v[228:229], off
	s_waitcnt vmcnt(8)
	s_waitcnt lgkmcnt(0)
	s_barrier
	s_setprio 1
	s_waitcnt lgkmcnt(0)
	v_mfma_f32_16x16x32_bf16 v[124:127], v[128:131], v[180:183], v[124:127]
	v_mfma_f32_16x16x32_bf16 v[124:127], v[132:135], v[192:195], v[124:127]
	v_mfma_f32_16x16x32_bf16 v[120:123], v[136:139], v[180:183], v[120:123]
	v_mfma_f32_16x16x32_bf16 v[120:123], v[140:143], v[192:195], v[120:123]
	v_mfma_f32_16x16x32_bf16 v[108:111], v[128:131], v[196:199], v[108:111]
	v_mfma_f32_16x16x32_bf16 v[108:111], v[132:135], v[200:203], v[108:111]
	v_mfma_f32_16x16x32_bf16 v[104:107], v[136:139], v[196:199], v[104:107]
	v_mfma_f32_16x16x32_bf16 v[104:107], v[140:143], v[200:203], v[104:107]
	v_mfma_f32_16x16x32_bf16 v[92:95], v[128:131], v[204:207], v[92:95]
	v_mfma_f32_16x16x32_bf16 v[92:95], v[132:135], v[208:211], v[92:95]
	v_mfma_f32_16x16x32_bf16 v[88:91], v[136:139], v[204:207], v[88:91]
	v_mfma_f32_16x16x32_bf16 v[88:91], v[140:143], v[208:211], v[88:91]
	v_mfma_f32_16x16x32_bf16 v[76:79], v[128:131], v[212:215], v[76:79]
	v_mfma_f32_16x16x32_bf16 v[76:79], v[132:135], v[216:219], v[76:79]
	v_mfma_f32_16x16x32_bf16 v[72:75], v[136:139], v[212:215], v[72:75]
	v_mfma_f32_16x16x32_bf16 v[72:75], v[140:143], v[216:219], v[72:75]
	s_setprio 0
	s_setprio 1
	v_mfma_f32_16x16x32_bf16 v[116:119], v[144:147], v[180:183], v[116:119]
	v_mfma_f32_16x16x32_bf16 v[116:119], v[148:151], v[192:195], v[116:119]
	v_mfma_f32_16x16x32_bf16 v[112:115], v[172:175], v[180:183], v[112:115]
	v_mfma_f32_16x16x32_bf16 v[112:115], v[176:179], v[192:195], v[112:115]
	v_mfma_f32_16x16x32_bf16 v[100:103], v[144:147], v[196:199], v[100:103]
	v_mfma_f32_16x16x32_bf16 v[100:103], v[148:151], v[200:203], v[100:103]
	v_mfma_f32_16x16x32_bf16 v[96:99], v[172:175], v[196:199], v[96:99]
	v_mfma_f32_16x16x32_bf16 v[96:99], v[176:179], v[200:203], v[96:99]
	v_mfma_f32_16x16x32_bf16 v[84:87], v[144:147], v[204:207], v[84:87]
	v_mfma_f32_16x16x32_bf16 v[84:87], v[148:151], v[208:211], v[84:87]
	v_mfma_f32_16x16x32_bf16 v[80:83], v[172:175], v[204:207], v[80:83]
	v_mfma_f32_16x16x32_bf16 v[80:83], v[176:179], v[208:211], v[80:83]
	v_mfma_f32_16x16x32_bf16 v[68:71], v[144:147], v[212:215], v[68:71]
	v_mfma_f32_16x16x32_bf16 v[68:71], v[148:151], v[216:219], v[68:71]
	v_mfma_f32_16x16x32_bf16 v[64:67], v[172:175], v[212:215], v[64:67]
	v_mfma_f32_16x16x32_bf16 v[64:67], v[176:179], v[216:219], v[64:67]
	s_setprio 0
	s_barrier
	s_add_i32 s62, s81, s66
	v_lshl_add_u64 v[220:221], v[220:221], 0, s[26:27]
	s_mov_b32 m0, s62
	ds_read_b128 v[180:183], v190 offset:49152
	v_xor_b32_e32 v253, 64, v190
	ds_read_b128 v[192:195], v253 offset:49152
	ds_read_b128 v[196:199], v190 offset:51200
	ds_read_b128 v[200:203], v253 offset:51200
	ds_read_b128 v[204:207], v190 offset:53248
	ds_read_b128 v[208:211], v253 offset:53248
	ds_read_b128 v[212:215], v190 offset:55296
	ds_read_b128 v[216:219], v253 offset:55296
	global_load_lds_dwordx4 v[220:221], off
	s_add_i32 m0, s62, 0x2000
	s_add_u32 s60, s60, 0x40080
	v_lshl_add_u64 v[220:221], v[222:223], 0, s[26:27]
	s_addc_u32 s61, s61, 0
	s_add_i32 s62, s82, s66
	global_load_lds_dwordx4 v[220:221], off
	v_lshl_add_u64 v[220:221], s[60:61], 0, v[154:155]
	s_mov_b32 m0, s62
	s_nop 0
	global_load_lds_dwordx4 v[220:221], off
	v_lshl_add_u64 v[220:221], s[60:61], 0, v[162:163]
	s_add_i32 m0, s62, 0x2000
	s_nop 0
	global_load_lds_dwordx4 v[220:221], off
	v_lshl_add_u64 v[220:221], v[224:225], 0, s[26:27]
	s_mov_b32 m0, s3
	s_nop 0
	global_load_lds_dwordx4 v[220:221], off
	v_lshl_add_u64 v[220:221], v[226:227], 0, s[26:27]
	s_mov_b32 m0, s72
	s_nop 0
	global_load_lds_dwordx4 v[220:221], off
	s_waitcnt vmcnt(8)
	s_waitcnt lgkmcnt(0)
	s_barrier
	s_setprio 1
	s_waitcnt lgkmcnt(0)
	v_mfma_f32_16x16x32_bf16 v[60:63], v[128:131], v[180:183], v[60:63]
	v_mfma_f32_16x16x32_bf16 v[60:63], v[132:135], v[192:195], v[60:63]
	v_mfma_f32_16x16x32_bf16 v[56:59], v[136:139], v[180:183], v[56:59]
	v_mfma_f32_16x16x32_bf16 v[56:59], v[140:143], v[192:195], v[56:59]
	v_mfma_f32_16x16x32_bf16 v[44:47], v[128:131], v[196:199], v[44:47]
	v_mfma_f32_16x16x32_bf16 v[44:47], v[132:135], v[200:203], v[44:47]
	v_mfma_f32_16x16x32_bf16 v[40:43], v[136:139], v[196:199], v[40:43]
	v_mfma_f32_16x16x32_bf16 v[40:43], v[140:143], v[200:203], v[40:43]
	v_mfma_f32_16x16x32_bf16 v[28:31], v[128:131], v[204:207], v[28:31]
	v_mfma_f32_16x16x32_bf16 v[28:31], v[132:135], v[208:211], v[28:31]
	v_mfma_f32_16x16x32_bf16 v[24:27], v[136:139], v[204:207], v[24:27]
	v_mfma_f32_16x16x32_bf16 v[24:27], v[140:143], v[208:211], v[24:27]
	v_mfma_f32_16x16x32_bf16 v[12:15], v[128:131], v[212:215], v[12:15]
	v_mfma_f32_16x16x32_bf16 v[12:15], v[132:135], v[216:219], v[12:15]
	v_mfma_f32_16x16x32_bf16 v[8:11], v[136:139], v[212:215], v[8:11]
	v_mfma_f32_16x16x32_bf16 v[8:11], v[140:143], v[216:219], v[8:11]
	s_setprio 0
	s_setprio 1
	v_mfma_f32_16x16x32_bf16 v[52:55], v[144:147], v[180:183], v[52:55]
	v_mfma_f32_16x16x32_bf16 v[52:55], v[148:151], v[192:195], v[52:55]
	v_mfma_f32_16x16x32_bf16 v[48:51], v[172:175], v[180:183], v[48:51]
	v_mfma_f32_16x16x32_bf16 v[48:51], v[176:179], v[192:195], v[48:51]
	v_mfma_f32_16x16x32_bf16 v[36:39], v[144:147], v[196:199], v[36:39]
	v_mfma_f32_16x16x32_bf16 v[36:39], v[148:151], v[200:203], v[36:39]
	v_mfma_f32_16x16x32_bf16 v[32:35], v[172:175], v[196:199], v[32:35]
	v_mfma_f32_16x16x32_bf16 v[32:35], v[176:179], v[200:203], v[32:35]
	v_mfma_f32_16x16x32_bf16 v[20:23], v[144:147], v[204:207], v[20:23]
	v_mfma_f32_16x16x32_bf16 v[20:23], v[148:151], v[208:211], v[20:23]
	v_mfma_f32_16x16x32_bf16 v[16:19], v[172:175], v[204:207], v[16:19]
	v_mfma_f32_16x16x32_bf16 v[16:19], v[176:179], v[208:211], v[16:19]
	v_mfma_f32_16x16x32_bf16 v[4:7], v[144:147], v[212:215], v[4:7]
	v_mfma_f32_16x16x32_bf16 v[4:7], v[148:151], v[216:219], v[4:7]
	v_mfma_f32_16x16x32_bf16 v[0:3], v[172:175], v[212:215], v[0:3]
	v_mfma_f32_16x16x32_bf16 v[0:3], v[176:179], v[216:219], v[0:3]
	s_setprio 0
	s_barrier
	s_add_i32 s80, s80, 2
	s_add_u32 s78, s78, 0x100
	s_addc_u32 s79, s79, 0
	s_add_u32 s58, s58, 0x100
	s_addc_u32 s59, s59, 0
	s_cmp_gt_u32 s80, 13
	s_branch .LBB0_1011
.Lfa_9:
	ds_read_b128 v[128:131], v188
	v_xor_b32_e32 v253, 64, v188
	ds_read_b128 v[132:135], v253
	ds_read_b128 v[136:139], v188 offset:2048
	ds_read_b128 v[140:143], v253 offset:2048
	ds_read_b128 v[144:147], v189
	v_xor_b32_e32 v253, 64, v189
	ds_read_b128 v[148:151], v253
	ds_read_b128 v[172:175], v189 offset:2048
	ds_read_b128 v[176:179], v253 offset:2048
	s_add_u32 s60, s58, 0xfffc0080
	s_addc_u32 s61, s59, -1
	s_cmp_eq_u32 s80, 12
	s_cselect_b32 s63, s15, s61
	s_cselect_b32 s62, s51, s60
	s_cselect_b32 s61, s49, s79
	s_cselect_b32 s60, s57, s78
	v_lshl_add_u64 v[220:221], s[58:59], 0, v[166:167]
	s_add_i32 m0, s67, 0xc000
	ds_read_b128 v[180:183], v190
	v_xor_b32_e32 v253, 64, v190
	ds_read_b128 v[192:195], v253
	ds_read_b128 v[196:199], v190 offset:2048
	ds_read_b128 v[200:203], v253 offset:2048
	ds_read_b128 v[204:207], v190 offset:4096
	ds_read_b128 v[208:211], v253 offset:4096
	ds_read_b128 v[212:215], v190 offset:6144
	ds_read_b128 v[216:219], v253 offset:6144
	global_load_lds_dwordx4 v[220:221], off
	v_lshl_add_u64 v[220:221], s[58:59], 0, v[164:165]
	s_add_i32 m0, s67, 0xe000
	s_nop 0
	global_load_lds_dwordx4 v[220:221], off
	s_waitcnt vmcnt(8)
	s_waitcnt lgkmcnt(0)
	s_barrier
	s_setprio 1
	s_waitcnt lgkmcnt(0)
	v_mfma_f32_16x16x32_bf16 v[124:127], v[128:131], v[180:183], 0
	v_mfma_f32_16x16x32_bf16 v[120:123], v[136:139], v[180:183], 0
	v_mfma_f32_16x16x32_bf16 v[108:111], v[128:131], v[196:199], 0
	v_mfma_f32_16x16x32_bf16 v[104:107], v[136:139], v[196:199], 0
	v_mfma_f32_16x16x32_bf16 v[92:95], v[128:131], v[204:207], 0
	v_mfma_f32_16x16x32_bf16 v[88:91], v[136:139], v[204:207], 0
	v_mfma_f32_16x16x32_bf16 v[76:79], v[128:131], v[212:215], 0
	v_mfma_f32_16x16x32_bf16 v[72:75], v[136:139], v[212:215], 0
	v_mfma_f32_16x16x32_bf16 v[124:127], v[132:135], v[192:195], v[124:127]
	v_mfma_f32_16x16x32_bf16 v[120:123], v[140:143], v[192:195], v[120:123]
	v_mfma_f32_16x16x32_bf16 v[108:111], v[132:135], v[200:203], v[108:111]
	v_mfma_f32_16x16x32_bf16 v[104:107], v[140:143], v[200:203], v[104:107]
	v_mfma_f32_16x16x32_bf16 v[92:95], v[132:135], v[208:211], v[92:95]
	v_mfma_f32_16x16x32_bf16 v[88:91], v[140:143], v[208:211], v[88:91]
	v_mfma_f32_16x16x32_bf16 v[76:79], v[132:135], v[216:219], v[76:79]
	v_mfma_f32_16x16x32_bf16 v[72:75], v[140:143], v[216:219], v[72:75]
	s_setprio 0
	s_setprio 1
	v_mfma_f32_16x16x32_bf16 v[116:119], v[144:147], v[180:183], 0
	v_mfma_f32_16x16x32_bf16 v[112:115], v[172:175], v[180:183], 0
	v_mfma_f32_16x16x32_bf16 v[100:103], v[144:147], v[196:199], 0
	v_mfma_f32_16x16x32_bf16 v[96:99], v[172:175], v[196:199], 0
	v_mfma_f32_16x16x32_bf16 v[84:87], v[144:147], v[204:207], 0
	v_mfma_f32_16x16x32_bf16 v[80:83], v[172:175], v[204:207], 0
	v_mfma_f32_16x16x32_bf16 v[68:71], v[144:147], v[212:215], 0
	v_mfma_f32_16x16x32_bf16 v[64:67], v[172:175], v[212:215], 0
	v_mfma_f32_16x16x32_bf16 v[116:119], v[148:151], v[192:195], v[116:119]
	v_mfma_f32_16x16x32_bf16 v[112:115], v[176:179], v[192:195], v[112:115]
	v_mfma_f32_16x16x32_bf16 v[100:103], v[148:151], v[200:203], v[100:103]
	v_mfma_f32_16x16x32_bf16 v[96:99], v[176:179], v[200:203], v[96:99]
	v_mfma_f32_16x16x32_bf16 v[84:87], v[148:151], v[208:211], v[84:87]
	v_mfma_f32_16x16x32_bf16 v[80:83], v[176:179], v[208:211], v[80:83]
	v_mfma_f32_16x16x32_bf16 v[68:71], v[148:151], v[216:219], v[68:71]
	v_mfma_f32_16x16x32_bf16 v[64:67], v[176:179], v[216:219], v[64:67]
	s_setprio 0
	s_barrier
	s_add_i32 s81, s76, s66
	v_lshl_add_u64 v[220:221], s[60:61], 0, v[154:155]
	s_mov_b32 m0, s81
	ds_read_b128 v[180:183], v190 offset:16384
	v_xor_b32_e32 v253, 64, v190
	ds_read_b128 v[192:195], v253 offset:16384
	ds_read_b128 v[196:199], v190 offset:18432
	ds_read_b128 v[200:203], v253 offset:18432
	ds_read_b128 v[204:207], v190 offset:20480
	ds_read_b128 v[208:211], v253 offset:20480
	ds_read_b128 v[212:215], v190 offset:22528
	ds_read_b128 v[216:219], v253 offset:22528
	global_load_lds_dwordx4 v[220:221], off
	s_add_i32 m0, s81, 0x2000
	s_add_u32 s82, s60, 0x40000
	v_lshl_add_u64 v[222:223], s[60:61], 0, v[162:163]
	s_addc_u32 s83, s61, 0
	s_add_i32 s81, s77, s66
	global_load_lds_dwordx4 v[222:223], off
	v_lshl_add_u64 v[224:225], s[82:83], 0, v[154:155]
	s_mov_b32 m0, s81
	v_lshl_add_u64 v[226:227], s[62:63], 0, v[160:161]
	global_load_lds_dwordx4 v[224:225], off
	v_lshl_add_u64 v[224:225], s[82:83], 0, v[162:163]
	s_add_i32 m0, s81, 0x2000
	s_nop 0
	global_load_lds_dwordx4 v[224:225], off
	v_lshl_add_u64 v[224:225], s[62:63], 0, v[152:153]
	s_mov_b32 m0, s67
	s_nop 0
	global_load_lds_dwordx4 v[224:225], off
	s_mov_b32 m0, s68
	s_nop 0
	global_load_lds_dwordx4 v[226:227], off
	s_waitcnt vmcnt(8)
	s_waitcnt lgkmcnt(0)
	s_barrier
	s_setprio 1
	s_waitcnt lgkmcnt(0)
	v_mfma_f32_16x16x32_bf16 v[60:63], v[128:131], v[180:183], 0
	v_mfma_f32_16x16x32_bf16 v[56:59], v[136:139], v[180:183], 0
	v_mfma_f32_16x16x32_bf16 v[44:47], v[128:131], v[196:199], 0
	v_mfma_f32_16x16x32_bf16 v[40:43], v[136:139], v[196:199], 0
	v_mfma_f32_16x16x32_bf16 v[28:31], v[128:131], v[204:207], 0
	v_mfma_f32_16x16x32_bf16 v[24:27], v[136:139], v[204:207], 0
	v_mfma_f32_16x16x32_bf16 v[12:15], v[128:131], v[212:215], 0
	v_mfma_f32_16x16x32_bf16 v[8:11], v[136:139], v[212:215], 0
	v_mfma_f32_16x16x32_bf16 v[60:63], v[132:135], v[192:195], v[60:63]
	v_mfma_f32_16x16x32_bf16 v[56:59], v[140:143], v[192:195], v[56:59]
	v_mfma_f32_16x16x32_bf16 v[44:47], v[132:135], v[200:203], v[44:47]
	v_mfma_f32_16x16x32_bf16 v[40:43], v[140:143], v[200:203], v[40:43]
	v_mfma_f32_16x16x32_bf16 v[28:31], v[132:135], v[208:211], v[28:31]
	v_mfma_f32_16x16x32_bf16 v[24:27], v[140:143], v[208:211], v[24:27]
	v_mfma_f32_16x16x32_bf16 v[12:15], v[132:135], v[216:219], v[12:15]
	v_mfma_f32_16x16x32_bf16 v[8:11], v[140:143], v[216:219], v[8:11]
	s_setprio 0
	s_setprio 1
	v_mfma_f32_16x16x32_bf16 v[52:55], v[144:147], v[180:183], 0
	v_mfma_f32_16x16x32_bf16 v[48:51], v[172:175], v[180:183], 0
	v_mfma_f32_16x16x32_bf16 v[36:39], v[144:147], v[196:199], 0
	v_mfma_f32_16x16x32_bf16 v[32:35], v[172:175], v[196:199], 0
	v_mfma_f32_16x16x32_bf16 v[20:23], v[144:147], v[204:207], 0
	v_mfma_f32_16x16x32_bf16 v[16:19], v[172:175], v[204:207], 0
	v_mfma_f32_16x16x32_bf16 v[4:7], v[144:147], v[212:215], 0
	v_mfma_f32_16x16x32_bf16 v[0:3], v[172:175], v[212:215], 0
	v_mfma_f32_16x16x32_bf16 v[52:55], v[148:151], v[192:195], v[52:55]
	v_mfma_f32_16x16x32_bf16 v[48:51], v[176:179], v[192:195], v[48:51]
	v_mfma_f32_16x16x32_bf16 v[36:39], v[148:151], v[200:203], v[36:39]
	v_mfma_f32_16x16x32_bf16 v[32:35], v[176:179], v[200:203], v[32:35]
	v_mfma_f32_16x16x32_bf16 v[20:23], v[148:151], v[208:211], v[20:23]
	v_mfma_f32_16x16x32_bf16 v[16:19], v[176:179], v[208:211], v[16:19]
	v_mfma_f32_16x16x32_bf16 v[4:7], v[148:151], v[216:219], v[4:7]
	v_mfma_f32_16x16x32_bf16 v[0:3], v[176:179], v[216:219], v[0:3]
	s_setprio 0
	s_barrier
	s_add_i32 s81, 0, 0x18000
	s_add_i32 s82, 0, 0x1c000
	v_add_u32_e32 v140, s81, v185
	v_add_u32_e32 v176, s82, v185
	ds_read_b128 v[128:131], v140
	v_xor_b32_e32 v253, 64, v140
	ds_read_b128 v[132:135], v253
	ds_read_b128 v[136:139], v140 offset:2048
	ds_read_b128 v[140:143], v253 offset:2048
	ds_read_b128 v[144:147], v176
	v_xor_b32_e32 v253, 64, v176
	ds_read_b128 v[148:151], v253
	ds_read_b128 v[172:175], v176 offset:2048
	ds_read_b128 v[176:179], v253 offset:2048
	s_add_u32 s62, s62, 0x40000
	s_addc_u32 s63, s63, 0
	s_mov_b32 m0, s69
	v_lshl_add_u64 v[228:229], s[62:63], 0, v[152:153]
	ds_read_b128 v[180:183], v190 offset:32768
	v_xor_b32_e32 v253, 64, v190
	ds_read_b128 v[192:195], v253 offset:32768
	ds_read_b128 v[196:199], v190 offset:34816
	ds_read_b128 v[200:203], v253 offset:34816
	ds_read_b128 v[204:207], v190 offset:36864
	ds_read_b128 v[208:211], v253 offset:36864
	ds_read_b128 v[212:215], v190 offset:38912
	ds_read_b128 v[216:219], v253 offset:38912
	global_load_lds_dwordx4 v[228:229], off
	v_lshl_add_u64 v[228:229], s[62:63], 0, v[160:161]
	s_mov_b32 m0, s70
	s_nop 0
	global_load_lds_dwordx4 v[228:229], off
	s_waitcnt vmcnt(8)
	s_waitcnt lgkmcnt(0)
	s_barrier
	s_setprio 1
	s_waitcnt lgkmcnt(0)
	v_mfma_f32_16x16x32_bf16 v[124:127], v[128:131], v[180:183], v[124:127]
	v_mfma_f32_16x16x32_bf16 v[124:127], v[132:135], v[192:195], v[124:127]
	v_mfma_f32_16x16x32_bf16 v[120:123], v[136:139], v[180:183], v[120:123]
	v_mfma_f32_16x16x32_bf16 v[120:123], v[140:143], v[192:195], v[120:123]
	v_mfma_f32_16x16x32_bf16 v[108:111], v[128:131], v[196:199], v[108:111]
	v_mfma_f32_16x16x32_bf16 v[108:111], v[132:135], v[200:203], v[108:111]
	v_mfma_f32_16x16x32_bf16 v[104:107], v[136:139], v[196:199], v[104:107]
	v_mfma_f32_16x16x32_bf16 v[104:107], v[140:143], v[200:203], v[104:107]
	v_mfma_f32_16x16x32_bf16 v[92:95], v[128:131], v[204:207], v[92:95]
	v_mfma_f32_16x16x32_bf16 v[92:95], v[132:135], v[208:211], v[92:95]
	v_mfma_f32_16x16x32_bf16 v[88:91], v[136:139], v[204:207], v[88:91]
	v_mfma_f32_16x16x32_bf16 v[88:91], v[140:143], v[208:211], v[88:91]
	v_mfma_f32_16x16x32_bf16 v[76:79], v[128:131], v[212:215], v[76:79]
	v_mfma_f32_16x16x32_bf16 v[76:79], v[132:135], v[216:219], v[76:79]
	v_mfma_f32_16x16x32_bf16 v[72:75], v[136:139], v[212:215], v[72:75]
	v_mfma_f32_16x16x32_bf16 v[72:75], v[140:143], v[216:219], v[72:75]
	s_setprio 0
	s_setprio 1
	v_mfma_f32_16x16x32_bf16 v[116:119], v[144:147], v[180:183], v[116:119]
	v_mfma_f32_16x16x32_bf16 v[116:119], v[148:151], v[192:195], v[116:119]
	v_mfma_f32_16x16x32_bf16 v[112:115], v[172:175], v[180:183], v[112:115]
	v_mfma_f32_16x16x32_bf16 v[112:115], v[176:179], v[192:195], v[112:115]
	v_mfma_f32_16x16x32_bf16 v[100:103], v[144:147], v[196:199], v[100:103]
	v_mfma_f32_16x16x32_bf16 v[100:103], v[148:151], v[200:203], v[100:103]
	v_mfma_f32_16x16x32_bf16 v[96:99], v[172:175], v[196:199], v[96:99]
	v_mfma_f32_16x16x32_bf16 v[96:99], v[176:179], v[200:203], v[96:99]
	v_mfma_f32_16x16x32_bf16 v[84:87], v[144:147], v[204:207], v[84:87]
	v_mfma_f32_16x16x32_bf16 v[84:87], v[148:151], v[208:211], v[84:87]
	v_mfma_f32_16x16x32_bf16 v[80:83], v[172:175], v[204:207], v[80:83]
	v_mfma_f32_16x16x32_bf16 v[80:83], v[176:179], v[208:211], v[80:83]
	v_mfma_f32_16x16x32_bf16 v[68:71], v[144:147], v[212:215], v[68:71]
	v_mfma_f32_16x16x32_bf16 v[68:71], v[148:151], v[216:219], v[68:71]
	v_mfma_f32_16x16x32_bf16 v[64:67], v[172:175], v[212:215], v[64:67]
	v_mfma_f32_16x16x32_bf16 v[64:67], v[176:179], v[216:219], v[64:67]
	s_setprio 0
	s_barrier
	s_add_i32 s62, s81, s66
	v_lshl_add_u64 v[220:221], v[220:221], 0, s[26:27]
	s_mov_b32 m0, s62
	ds_read_b128 v[180:183], v190 offset:49152
	v_xor_b32_e32 v253, 64, v190
	ds_read_b128 v[192:195], v253 offset:49152
	ds_read_b128 v[196:199], v190 offset:51200
	ds_read_b128 v[200:203], v253 offset:51200
	ds_read_b128 v[204:207], v190 offset:53248
	ds_read_b128 v[208:211], v253 offset:53248
	ds_read_b128 v[212:215], v190 offset:55296
	ds_read_b128 v[216:219], v253 offset:55296
	global_load_lds_dwordx4 v[220:221], off
	s_add_i32 m0, s62, 0x2000
	s_add_u32 s60, s60, 0x40080
	v_lshl_add_u64 v[220:221], v[222:223], 0, s[26:27]
	s_addc_u32 s61, s61, 0
	s_add_i32 s62, s82, s66
	global_load_lds_dwordx4 v[220:221], off
	v_lshl_add_u64 v[220:221], s[60:61], 0, v[154:155]
	s_mov_b32 m0, s62
	s_nop 0
	global_load_lds_dwordx4 v[220:221], off
	v_lshl_add_u64 v[220:221], s[60:61], 0, v[162:163]
	s_add_i32 m0, s62, 0x2000
	s_nop 0
	global_load_lds_dwordx4 v[220:221], off
	v_lshl_add_u64 v[220:221], v[224:225], 0, s[26:27]
	s_mov_b32 m0, s3
	s_nop 0
	global_load_lds_dwordx4 v[220:221], off
	v_lshl_add_u64 v[220:221], v[226:227], 0, s[26:27]
	s_mov_b32 m0, s72
	s_nop 0
	global_load_lds_dwordx4 v[220:221], off
	s_waitcnt vmcnt(8)
	s_waitcnt lgkmcnt(0)
	s_barrier
	s_setprio 1
	s_waitcnt lgkmcnt(0)
	v_mfma_f32_16x16x32_bf16 v[60:63], v[128:131], v[180:183], v[60:63]
	v_mfma_f32_16x16x32_bf16 v[60:63], v[132:135], v[192:195], v[60:63]
	v_mfma_f32_16x16x32_bf16 v[56:59], v[136:139], v[180:183], v[56:59]
	v_mfma_f32_16x16x32_bf16 v[56:59], v[140:143], v[192:195], v[56:59]
	v_mfma_f32_16x16x32_bf16 v[44:47], v[128:131], v[196:199], v[44:47]
	v_mfma_f32_16x16x32_bf16 v[44:47], v[132:135], v[200:203], v[44:47]
	v_mfma_f32_16x16x32_bf16 v[40:43], v[136:139], v[196:199], v[40:43]
	v_mfma_f32_16x16x32_bf16 v[40:43], v[140:143], v[200:203], v[40:43]
	v_mfma_f32_16x16x32_bf16 v[28:31], v[128:131], v[204:207], v[28:31]
	v_mfma_f32_16x16x32_bf16 v[28:31], v[132:135], v[208:211], v[28:31]
	v_mfma_f32_16x16x32_bf16 v[24:27], v[136:139], v[204:207], v[24:27]
	v_mfma_f32_16x16x32_bf16 v[24:27], v[140:143], v[208:211], v[24:27]
	v_mfma_f32_16x16x32_bf16 v[12:15], v[128:131], v[212:215], v[12:15]
	v_mfma_f32_16x16x32_bf16 v[12:15], v[132:135], v[216:219], v[12:15]
	v_mfma_f32_16x16x32_bf16 v[8:11], v[136:139], v[212:215], v[8:11]
	v_mfma_f32_16x16x32_bf16 v[8:11], v[140:143], v[216:219], v[8:11]
	s_setprio 0
	s_setprio 1
	v_mfma_f32_16x16x32_bf16 v[52:55], v[144:147], v[180:183], v[52:55]
	v_mfma_f32_16x16x32_bf16 v[52:55], v[148:151], v[192:195], v[52:55]
	v_mfma_f32_16x16x32_bf16 v[48:51], v[172:175], v[180:183], v[48:51]
	v_mfma_f32_16x16x32_bf16 v[48:51], v[176:179], v[192:195], v[48:51]
	v_mfma_f32_16x16x32_bf16 v[36:39], v[144:147], v[196:199], v[36:39]
	v_mfma_f32_16x16x32_bf16 v[36:39], v[148:151], v[200:203], v[36:39]
	v_mfma_f32_16x16x32_bf16 v[32:35], v[172:175], v[196:199], v[32:35]
	v_mfma_f32_16x16x32_bf16 v[32:35], v[176:179], v[200:203], v[32:35]
	v_mfma_f32_16x16x32_bf16 v[20:23], v[144:147], v[204:207], v[20:23]
	v_mfma_f32_16x16x32_bf16 v[20:23], v[148:151], v[208:211], v[20:23]
	v_mfma_f32_16x16x32_bf16 v[16:19], v[172:175], v[204:207], v[16:19]
	v_mfma_f32_16x16x32_bf16 v[16:19], v[176:179], v[208:211], v[16:19]
	v_mfma_f32_16x16x32_bf16 v[4:7], v[144:147], v[212:215], v[4:7]
	v_mfma_f32_16x16x32_bf16 v[4:7], v[148:151], v[216:219], v[4:7]
	v_mfma_f32_16x16x32_bf16 v[0:3], v[172:175], v[212:215], v[0:3]
	v_mfma_f32_16x16x32_bf16 v[0:3], v[176:179], v[216:219], v[0:3]
	s_setprio 0
	s_barrier
	s_add_i32 s80, s80, 2
	s_add_u32 s78, s78, 0x100
	s_addc_u32 s79, s79, 0
	s_add_u32 s58, s58, 0x100
	s_addc_u32 s59, s59, 0
	s_cmp_gt_u32 s80, 13
.LBB0_1011:
	ds_read_b128 v[128:131], v188
	v_xor_b32_e32 v253, 64, v188
	ds_read_b128 v[132:135], v253
	ds_read_b128 v[136:139], v188 offset:2048
	ds_read_b128 v[140:143], v253 offset:2048
	ds_read_b128 v[144:147], v189
	v_xor_b32_e32 v253, 64, v189
	ds_read_b128 v[148:151], v253
	ds_read_b128 v[172:175], v189 offset:2048
	ds_read_b128 v[176:179], v253 offset:2048
	s_add_u32 s60, s58, 0xfffc0080
	s_addc_u32 s61, s59, -1
	s_cmp_eq_u32 s80, 12
	s_cselect_b32 s63, s15, s61
	s_cselect_b32 s62, s51, s60
	s_cselect_b32 s61, s49, s79
	s_cselect_b32 s60, s57, s78
	v_lshl_add_u64 v[220:221], s[58:59], 0, v[166:167]
	s_add_i32 m0, s67, 0xc000
	ds_read_b128 v[180:183], v190
	v_xor_b32_e32 v253, 64, v190
	ds_read_b128 v[192:195], v253
	ds_read_b128 v[196:199], v190 offset:2048
	ds_read_b128 v[200:203], v253 offset:2048
	ds_read_b128 v[204:207], v190 offset:4096
	ds_read_b128 v[208:211], v253 offset:4096
	ds_read_b128 v[212:215], v190 offset:6144
	ds_read_b128 v[216:219], v253 offset:6144
	global_load_lds_dwordx4 v[220:221], off
	v_lshl_add_u64 v[220:221], s[58:59], 0, v[164:165]
	s_add_i32 m0, s67, 0xe000
	s_nop 0
	global_load_lds_dwordx4 v[220:221], off
	s_waitcnt vmcnt(8)
	s_waitcnt lgkmcnt(0)
	s_barrier
	s_setprio 1
	s_waitcnt lgkmcnt(0)
	v_mfma_f32_16x16x32_bf16 v[124:127], v[128:131], v[180:183], v[124:127]
	v_mfma_f32_16x16x32_bf16 v[124:127], v[132:135], v[192:195], v[124:127]
	v_mfma_f32_16x16x32_bf16 v[120:123], v[136:139], v[180:183], v[120:123]
	v_mfma_f32_16x16x32_bf16 v[120:123], v[140:143], v[192:195], v[120:123]
	v_mfma_f32_16x16x32_bf16 v[108:111], v[128:131], v[196:199], v[108:111]
	v_mfma_f32_16x16x32_bf16 v[108:111], v[132:135], v[200:203], v[108:111]
	v_mfma_f32_16x16x32_bf16 v[104:107], v[136:139], v[196:199], v[104:107]
	v_mfma_f32_16x16x32_bf16 v[104:107], v[140:143], v[200:203], v[104:107]
	v_mfma_f32_16x16x32_bf16 v[92:95], v[128:131], v[204:207], v[92:95]
	v_mfma_f32_16x16x32_bf16 v[92:95], v[132:135], v[208:211], v[92:95]
	v_mfma_f32_16x16x32_bf16 v[88:91], v[136:139], v[204:207], v[88:91]
	v_mfma_f32_16x16x32_bf16 v[88:91], v[140:143], v[208:211], v[88:91]
	v_mfma_f32_16x16x32_bf16 v[76:79], v[128:131], v[212:215], v[76:79]
	v_mfma_f32_16x16x32_bf16 v[76:79], v[132:135], v[216:219], v[76:79]
	v_mfma_f32_16x16x32_bf16 v[72:75], v[136:139], v[212:215], v[72:75]
	v_mfma_f32_16x16x32_bf16 v[72:75], v[140:143], v[216:219], v[72:75]
	s_setprio 0
	s_setprio 1
	v_mfma_f32_16x16x32_bf16 v[116:119], v[144:147], v[180:183], v[116:119]
	v_mfma_f32_16x16x32_bf16 v[116:119], v[148:151], v[192:195], v[116:119]
	v_mfma_f32_16x16x32_bf16 v[112:115], v[172:175], v[180:183], v[112:115]
	v_mfma_f32_16x16x32_bf16 v[112:115], v[176:179], v[192:195], v[112:115]
	v_mfma_f32_16x16x32_bf16 v[100:103], v[144:147], v[196:199], v[100:103]
	v_mfma_f32_16x16x32_bf16 v[100:103], v[148:151], v[200:203], v[100:103]
	v_mfma_f32_16x16x32_bf16 v[96:99], v[172:175], v[196:199], v[96:99]
	v_mfma_f32_16x16x32_bf16 v[96:99], v[176:179], v[200:203], v[96:99]
	v_mfma_f32_16x16x32_bf16 v[84:87], v[144:147], v[204:207], v[84:87]
	v_mfma_f32_16x16x32_bf16 v[84:87], v[148:151], v[208:211], v[84:87]
	v_mfma_f32_16x16x32_bf16 v[80:83], v[172:175], v[204:207], v[80:83]
	v_mfma_f32_16x16x32_bf16 v[80:83], v[176:179], v[208:211], v[80:83]
	v_mfma_f32_16x16x32_bf16 v[68:71], v[144:147], v[212:215], v[68:71]
	v_mfma_f32_16x16x32_bf16 v[68:71], v[148:151], v[216:219], v[68:71]
	v_mfma_f32_16x16x32_bf16 v[64:67], v[172:175], v[212:215], v[64:67]
	v_mfma_f32_16x16x32_bf16 v[64:67], v[176:179], v[216:219], v[64:67]
	s_setprio 0
	s_barrier
	s_add_i32 s81, s76, s66
	v_lshl_add_u64 v[220:221], s[60:61], 0, v[154:155]
	s_mov_b32 m0, s81
	ds_read_b128 v[180:183], v190 offset:16384
	v_xor_b32_e32 v253, 64, v190
	ds_read_b128 v[192:195], v253 offset:16384
	ds_read_b128 v[196:199], v190 offset:18432
	ds_read_b128 v[200:203], v253 offset:18432
	ds_read_b128 v[204:207], v190 offset:20480
	ds_read_b128 v[208:211], v253 offset:20480
	ds_read_b128 v[212:215], v190 offset:22528
	ds_read_b128 v[216:219], v253 offset:22528
	global_load_lds_dwordx4 v[220:221], off
	s_add_i32 m0, s81, 0x2000
	s_add_u32 s82, s60, 0x40000
	v_lshl_add_u64 v[222:223], s[60:61], 0, v[162:163]
	s_addc_u32 s83, s61, 0
	s_add_i32 s81, s77, s66
	global_load_lds_dwordx4 v[222:223], off
	v_lshl_add_u64 v[224:225], s[82:83], 0, v[154:155]
	s_mov_b32 m0, s81
	v_lshl_add_u64 v[226:227], s[62:63], 0, v[160:161]
	global_load_lds_dwordx4 v[224:225], off
	v_lshl_add_u64 v[224:225], s[82:83], 0, v[162:163]
	s_add_i32 m0, s81, 0x2000
	s_nop 0
	global_load_lds_dwordx4 v[224:225], off
	v_lshl_add_u64 v[224:225], s[62:63], 0, v[152:153]
	s_mov_b32 m0, s67
	s_nop 0
	global_load_lds_dwordx4 v[224:225], off
	s_mov_b32 m0, s68
	s_nop 0
	global_load_lds_dwordx4 v[226:227], off
	s_waitcnt vmcnt(8)
	s_waitcnt lgkmcnt(0)
	s_barrier
	s_setprio 1
	s_waitcnt lgkmcnt(0)
	v_mfma_f32_16x16x32_bf16 v[60:63], v[128:131], v[180:183], v[60:63]
	v_mfma_f32_16x16x32_bf16 v[60:63], v[132:135], v[192:195], v[60:63]
	v_mfma_f32_16x16x32_bf16 v[56:59], v[136:139], v[180:183], v[56:59]
	v_mfma_f32_16x16x32_bf16 v[56:59], v[140:143], v[192:195], v[56:59]
	v_mfma_f32_16x16x32_bf16 v[44:47], v[128:131], v[196:199], v[44:47]
	v_mfma_f32_16x16x32_bf16 v[44:47], v[132:135], v[200:203], v[44:47]
	v_mfma_f32_16x16x32_bf16 v[40:43], v[136:139], v[196:199], v[40:43]
	v_mfma_f32_16x16x32_bf16 v[40:43], v[140:143], v[200:203], v[40:43]
	v_mfma_f32_16x16x32_bf16 v[28:31], v[128:131], v[204:207], v[28:31]
	v_mfma_f32_16x16x32_bf16 v[28:31], v[132:135], v[208:211], v[28:31]
	v_mfma_f32_16x16x32_bf16 v[24:27], v[136:139], v[204:207], v[24:27]
	v_mfma_f32_16x16x32_bf16 v[24:27], v[140:143], v[208:211], v[24:27]
	v_mfma_f32_16x16x32_bf16 v[12:15], v[128:131], v[212:215], v[12:15]
	v_mfma_f32_16x16x32_bf16 v[12:15], v[132:135], v[216:219], v[12:15]
	v_mfma_f32_16x16x32_bf16 v[8:11], v[136:139], v[212:215], v[8:11]
	v_mfma_f32_16x16x32_bf16 v[8:11], v[140:143], v[216:219], v[8:11]
	s_setprio 0
	s_setprio 1
	v_mfma_f32_16x16x32_bf16 v[52:55], v[144:147], v[180:183], v[52:55]
	v_mfma_f32_16x16x32_bf16 v[52:55], v[148:151], v[192:195], v[52:55]
	v_mfma_f32_16x16x32_bf16 v[48:51], v[172:175], v[180:183], v[48:51]
	v_mfma_f32_16x16x32_bf16 v[48:51], v[176:179], v[192:195], v[48:51]
	v_mfma_f32_16x16x32_bf16 v[36:39], v[144:147], v[196:199], v[36:39]
	v_mfma_f32_16x16x32_bf16 v[36:39], v[148:151], v[200:203], v[36:39]
	v_mfma_f32_16x16x32_bf16 v[32:35], v[172:175], v[196:199], v[32:35]
	v_mfma_f32_16x16x32_bf16 v[32:35], v[176:179], v[200:203], v[32:35]
	v_mfma_f32_16x16x32_bf16 v[20:23], v[144:147], v[204:207], v[20:23]
	v_mfma_f32_16x16x32_bf16 v[20:23], v[148:151], v[208:211], v[20:23]
	v_mfma_f32_16x16x32_bf16 v[16:19], v[172:175], v[204:207], v[16:19]
	v_mfma_f32_16x16x32_bf16 v[16:19], v[176:179], v[208:211], v[16:19]
	v_mfma_f32_16x16x32_bf16 v[4:7], v[144:147], v[212:215], v[4:7]
	v_mfma_f32_16x16x32_bf16 v[4:7], v[148:151], v[216:219], v[4:7]
	v_mfma_f32_16x16x32_bf16 v[0:3], v[172:175], v[212:215], v[0:3]
	v_mfma_f32_16x16x32_bf16 v[0:3], v[176:179], v[216:219], v[0:3]
	s_setprio 0
	s_barrier
	s_add_i32 s81, 0, 0x18000
	s_add_i32 s82, 0, 0x1c000
	v_add_u32_e32 v140, s81, v185
	v_add_u32_e32 v176, s82, v185
	ds_read_b128 v[128:131], v140
	v_xor_b32_e32 v253, 64, v140
	ds_read_b128 v[132:135], v253
	ds_read_b128 v[136:139], v140 offset:2048
	ds_read_b128 v[140:143], v253 offset:2048
	ds_read_b128 v[144:147], v176
	v_xor_b32_e32 v253, 64, v176
	ds_read_b128 v[148:151], v253
	ds_read_b128 v[172:175], v176 offset:2048
	ds_read_b128 v[176:179], v253 offset:2048
	s_add_u32 s62, s62, 0x40000
	s_addc_u32 s63, s63, 0
	s_mov_b32 m0, s69
	v_lshl_add_u64 v[228:229], s[62:63], 0, v[152:153]
	ds_read_b128 v[180:183], v190 offset:32768
	v_xor_b32_e32 v253, 64, v190
	ds_read_b128 v[192:195], v253 offset:32768
	ds_read_b128 v[196:199], v190 offset:34816
	ds_read_b128 v[200:203], v253 offset:34816
	ds_read_b128 v[204:207], v190 offset:36864
	ds_read_b128 v[208:211], v253 offset:36864
	ds_read_b128 v[212:215], v190 offset:38912
	ds_read_b128 v[216:219], v253 offset:38912
	global_load_lds_dwordx4 v[228:229], off
	v_lshl_add_u64 v[228:229], s[62:63], 0, v[160:161]
	s_mov_b32 m0, s70
	s_nop 0
	global_load_lds_dwordx4 v[228:229], off
	s_waitcnt vmcnt(8)
	s_waitcnt lgkmcnt(0)
	s_barrier
	s_setprio 1
	s_waitcnt lgkmcnt(0)
	v_mfma_f32_16x16x32_bf16 v[124:127], v[128:131], v[180:183], v[124:127]
	v_mfma_f32_16x16x32_bf16 v[124:127], v[132:135], v[192:195], v[124:127]
	v_mfma_f32_16x16x32_bf16 v[120:123], v[136:139], v[180:183], v[120:123]
	v_mfma_f32_16x16x32_bf16 v[120:123], v[140:143], v[192:195], v[120:123]
	v_mfma_f32_16x16x32_bf16 v[108:111], v[128:131], v[196:199], v[108:111]
	v_mfma_f32_16x16x32_bf16 v[108:111], v[132:135], v[200:203], v[108:111]
	v_mfma_f32_16x16x32_bf16 v[104:107], v[136:139], v[196:199], v[104:107]
	v_mfma_f32_16x16x32_bf16 v[104:107], v[140:143], v[200:203], v[104:107]
	v_mfma_f32_16x16x32_bf16 v[92:95], v[128:131], v[204:207], v[92:95]
	v_mfma_f32_16x16x32_bf16 v[92:95], v[132:135], v[208:211], v[92:95]
	v_mfma_f32_16x16x32_bf16 v[88:91], v[136:139], v[204:207], v[88:91]
	v_mfma_f32_16x16x32_bf16 v[88:91], v[140:143], v[208:211], v[88:91]
	v_mfma_f32_16x16x32_bf16 v[76:79], v[128:131], v[212:215], v[76:79]
	v_mfma_f32_16x16x32_bf16 v[76:79], v[132:135], v[216:219], v[76:79]
	v_mfma_f32_16x16x32_bf16 v[72:75], v[136:139], v[212:215], v[72:75]
	v_mfma_f32_16x16x32_bf16 v[72:75], v[140:143], v[216:219], v[72:75]
	s_setprio 0
	s_setprio 1
	v_mfma_f32_16x16x32_bf16 v[116:119], v[144:147], v[180:183], v[116:119]
	v_mfma_f32_16x16x32_bf16 v[116:119], v[148:151], v[192:195], v[116:119]
	v_mfma_f32_16x16x32_bf16 v[112:115], v[172:175], v[180:183], v[112:115]
	v_mfma_f32_16x16x32_bf16 v[112:115], v[176:179], v[192:195], v[112:115]
	v_mfma_f32_16x16x32_bf16 v[100:103], v[144:147], v[196:199], v[100:103]
	v_mfma_f32_16x16x32_bf16 v[100:103], v[148:151], v[200:203], v[100:103]
	v_mfma_f32_16x16x32_bf16 v[96:99], v[172:175], v[196:199], v[96:99]
	v_mfma_f32_16x16x32_bf16 v[96:99], v[176:179], v[200:203], v[96:99]
	v_mfma_f32_16x16x32_bf16 v[84:87], v[144:147], v[204:207], v[84:87]
	v_mfma_f32_16x16x32_bf16 v[84:87], v[148:151], v[208:211], v[84:87]
	v_mfma_f32_16x16x32_bf16 v[80:83], v[172:175], v[204:207], v[80:83]
	v_mfma_f32_16x16x32_bf16 v[80:83], v[176:179], v[208:211], v[80:83]
	v_mfma_f32_16x16x32_bf16 v[68:71], v[144:147], v[212:215], v[68:71]
	v_mfma_f32_16x16x32_bf16 v[68:71], v[148:151], v[216:219], v[68:71]
	v_mfma_f32_16x16x32_bf16 v[64:67], v[172:175], v[212:215], v[64:67]
	v_mfma_f32_16x16x32_bf16 v[64:67], v[176:179], v[216:219], v[64:67]
	s_setprio 0
	s_barrier
	s_add_i32 s62, s81, s66
	v_lshl_add_u64 v[220:221], v[220:221], 0, s[26:27]
	s_mov_b32 m0, s62
	ds_read_b128 v[180:183], v190 offset:49152
	v_xor_b32_e32 v253, 64, v190
	ds_read_b128 v[192:195], v253 offset:49152
	ds_read_b128 v[196:199], v190 offset:51200
	ds_read_b128 v[200:203], v253 offset:51200
	ds_read_b128 v[204:207], v190 offset:53248
	ds_read_b128 v[208:211], v253 offset:53248
	ds_read_b128 v[212:215], v190 offset:55296
	ds_read_b128 v[216:219], v253 offset:55296
	global_load_lds_dwordx4 v[220:221], off
	s_add_i32 m0, s62, 0x2000
	s_add_u32 s60, s60, 0x40080
	v_lshl_add_u64 v[220:221], v[222:223], 0, s[26:27]
	s_addc_u32 s61, s61, 0
	s_add_i32 s62, s82, s66
	global_load_lds_dwordx4 v[220:221], off
	v_lshl_add_u64 v[220:221], s[60:61], 0, v[154:155]
	s_mov_b32 m0, s62
	s_nop 0
	global_load_lds_dwordx4 v[220:221], off
	v_lshl_add_u64 v[220:221], s[60:61], 0, v[162:163]
	s_add_i32 m0, s62, 0x2000
	s_nop 0
	global_load_lds_dwordx4 v[220:221], off
	v_lshl_add_u64 v[220:221], v[224:225], 0, s[26:27]
	s_mov_b32 m0, s3
	s_nop 0
	global_load_lds_dwordx4 v[220:221], off
	v_lshl_add_u64 v[220:221], v[226:227], 0, s[26:27]
	s_mov_b32 m0, s72
	s_nop 0
	global_load_lds_dwordx4 v[220:221], off
	s_waitcnt vmcnt(8)
	s_waitcnt lgkmcnt(0)
	s_barrier
	s_setprio 1
	s_waitcnt lgkmcnt(0)
	v_mfma_f32_16x16x32_bf16 v[60:63], v[128:131], v[180:183], v[60:63]
	v_mfma_f32_16x16x32_bf16 v[60:63], v[132:135], v[192:195], v[60:63]
	v_mfma_f32_16x16x32_bf16 v[56:59], v[136:139], v[180:183], v[56:59]
	v_mfma_f32_16x16x32_bf16 v[56:59], v[140:143], v[192:195], v[56:59]
	v_mfma_f32_16x16x32_bf16 v[44:47], v[128:131], v[196:199], v[44:47]
	v_mfma_f32_16x16x32_bf16 v[44:47], v[132:135], v[200:203], v[44:47]
	v_mfma_f32_16x16x32_bf16 v[40:43], v[136:139], v[196:199], v[40:43]
	v_mfma_f32_16x16x32_bf16 v[40:43], v[140:143], v[200:203], v[40:43]
	v_mfma_f32_16x16x32_bf16 v[28:31], v[128:131], v[204:207], v[28:31]
	v_mfma_f32_16x16x32_bf16 v[28:31], v[132:135], v[208:211], v[28:31]
	v_mfma_f32_16x16x32_bf16 v[24:27], v[136:139], v[204:207], v[24:27]
	v_mfma_f32_16x16x32_bf16 v[24:27], v[140:143], v[208:211], v[24:27]
	v_mfma_f32_16x16x32_bf16 v[12:15], v[128:131], v[212:215], v[12:15]
	v_mfma_f32_16x16x32_bf16 v[12:15], v[132:135], v[216:219], v[12:15]
	v_mfma_f32_16x16x32_bf16 v[8:11], v[136:139], v[212:215], v[8:11]
	v_mfma_f32_16x16x32_bf16 v[8:11], v[140:143], v[216:219], v[8:11]
	s_setprio 0
	s_setprio 1
	v_mfma_f32_16x16x32_bf16 v[52:55], v[144:147], v[180:183], v[52:55]
	v_mfma_f32_16x16x32_bf16 v[52:55], v[148:151], v[192:195], v[52:55]
	v_mfma_f32_16x16x32_bf16 v[48:51], v[172:175], v[180:183], v[48:51]
	v_mfma_f32_16x16x32_bf16 v[48:51], v[176:179], v[192:195], v[48:51]
	v_mfma_f32_16x16x32_bf16 v[36:39], v[144:147], v[196:199], v[36:39]
	v_mfma_f32_16x16x32_bf16 v[36:39], v[148:151], v[200:203], v[36:39]
	v_mfma_f32_16x16x32_bf16 v[32:35], v[172:175], v[196:199], v[32:35]
	v_mfma_f32_16x16x32_bf16 v[32:35], v[176:179], v[200:203], v[32:35]
	v_mfma_f32_16x16x32_bf16 v[20:23], v[144:147], v[204:207], v[20:23]
	v_mfma_f32_16x16x32_bf16 v[20:23], v[148:151], v[208:211], v[20:23]
	v_mfma_f32_16x16x32_bf16 v[16:19], v[172:175], v[204:207], v[16:19]
	v_mfma_f32_16x16x32_bf16 v[16:19], v[176:179], v[208:211], v[16:19]
	v_mfma_f32_16x16x32_bf16 v[4:7], v[144:147], v[212:215], v[4:7]
	v_mfma_f32_16x16x32_bf16 v[4:7], v[148:151], v[216:219], v[4:7]
	v_mfma_f32_16x16x32_bf16 v[0:3], v[172:175], v[212:215], v[0:3]
	v_mfma_f32_16x16x32_bf16 v[0:3], v[176:179], v[216:219], v[0:3]
	s_setprio 0
	s_barrier
	s_add_i32 s80, s80, 2
	s_add_u32 s78, s78, 0x100
	s_addc_u32 s79, s79, 0
	s_add_u32 s58, s58, 0x100
	s_addc_u32 s59, s59, 0
	s_cmp_gt_u32 s80, 13
	s_cbranch_scc0 .LBB0_1011
	s_and_b64 vcc, exec, s[28:29]
	s_cbranch_vccz .LBB0_1014
	s_barrier

.LBB0_1096:
	s_ashr_i32 s25, s24, 31
	s_lshl_b64 s[26:27], s[24:25], 19
	s_add_u32 s26, s3, s26
	s_addc_u32 s27, s33, s27
	s_and_b64 s[28:29], s[6:7], exec
	s_cselect_b32 s25, s27, s47
	s_cselect_b32 s65, s26, s46
	s_ashr_i32 s23, s22, 31
	s_lshl_b64 s[28:29], s[22:23], 19
	s_add_u32 s28, s35, s28
	s_addc_u32 s29, s48, s29
	s_and_b64 s[66:67], s[6:7], exec
	s_cselect_b32 s66, s29, s45
	s_cselect_b32 s67, s28, s44
	s_lshl_b32 s23, s30, 8
	v_add_u32_e32 v0, s23, v148
	s_add_u32 s68, s44, 0x100
	v_ashrrev_i32_e32 v1, 31, v0
	s_addc_u32 s69, s45, 0
	v_lshl_add_u64 v[144:145], v[0:1], 4, s[12:13]
	s_add_u32 s30, s46, 0x40080
	s_addc_u32 s31, s47, 0
	s_mov_b32 s70, -2
	s_mov_b64 s[44:45], 0
	s_cmp_eq_u32 s56, 1
	s_cbranch_scc1 .Lfa_10
	v_add_u32_e32 v153, s61, v147
	ds_read_b128 v[160:163], v153
	v_xor_b32_e32 v253, 64, v153
	ds_read_b128 v[164:167], v253
	ds_read_b128 v[168:171], v153 offset:2048
	ds_read_b128 v[172:175], v253 offset:2048
	v_add_u32_e32 v153, s62, v147
	ds_read_b128 v[176:179], v153
	v_xor_b32_e32 v253, 64, v153
	ds_read_b128 v[180:183], v253
	ds_read_b128 v[184:187], v153 offset:2048
	ds_read_b128 v[188:191], v253 offset:2048
	s_add_u32 s46, s30, 0xfffc0080
	s_addc_u32 s47, s31, -1
	s_and_b64 s[44:45], s[44:45], exec
	s_cselect_b32 s47, s25, s47
	s_cselect_b32 s46, s65, s46
	s_cselect_b32 s45, s66, s69
	s_cselect_b32 s44, s67, s68
	v_lshl_add_u64 v[154:155], s[30:31], 0, v[138:139]
	s_add_i32 m0, s52, 0xc000
	ds_read_b128 v[192:195], v150
	v_xor_b32_e32 v253, 64, v150
	ds_read_b128 v[196:199], v253
	ds_read_b128 v[200:203], v150 offset:2048
	ds_read_b128 v[204:207], v253 offset:2048
	ds_read_b128 v[208:211], v150 offset:4096
	ds_read_b128 v[212:215], v253 offset:4096
	ds_read_b128 v[216:219], v150 offset:6144
	ds_read_b128 v[220:223], v253 offset:6144
	global_load_lds_dwordx4 v[154:155], off
	v_lshl_add_u64 v[154:155], s[30:31], 0, v[136:137]
	s_add_i32 m0, s52, 0xe000
	s_nop 0
	global_load_lds_dwordx4 v[154:155], off
	s_waitcnt vmcnt(16)
	s_waitcnt lgkmcnt(0)
	s_barrier
	s_setprio 1
	s_waitcnt lgkmcnt(0)
	v_mfma_f32_16x16x32_bf16 v[124:127], v[160:163], v[192:195], 0
	v_mfma_f32_16x16x32_bf16 v[116:119], v[168:171], v[192:195], 0
	v_mfma_f32_16x16x32_bf16 v[108:111], v[160:163], v[200:203], 0
	v_mfma_f32_16x16x32_bf16 v[100:103], v[168:171], v[200:203], 0
	v_mfma_f32_16x16x32_bf16 v[92:95], v[160:163], v[208:211], 0
	v_mfma_f32_16x16x32_bf16 v[84:87], v[168:171], v[208:211], 0
	v_mfma_f32_16x16x32_bf16 v[76:79], v[160:163], v[216:219], 0
	v_mfma_f32_16x16x32_bf16 v[68:71], v[168:171], v[216:219], 0
	v_mfma_f32_16x16x32_bf16 v[124:127], v[164:167], v[196:199], v[124:127]
	v_mfma_f32_16x16x32_bf16 v[116:119], v[172:175], v[196:199], v[116:119]
	v_mfma_f32_16x16x32_bf16 v[108:111], v[164:167], v[204:207], v[108:111]
	v_mfma_f32_16x16x32_bf16 v[100:103], v[172:175], v[204:207], v[100:103]
	v_mfma_f32_16x16x32_bf16 v[92:95], v[164:167], v[212:215], v[92:95]
	v_mfma_f32_16x16x32_bf16 v[84:87], v[172:175], v[212:215], v[84:87]
	v_mfma_f32_16x16x32_bf16 v[76:79], v[164:167], v[220:223], v[76:79]
	v_mfma_f32_16x16x32_bf16 v[68:71], v[172:175], v[220:223], v[68:71]
	s_setprio 0
	s_setprio 1
	v_mfma_f32_16x16x32_bf16 v[120:123], v[176:179], v[192:195], 0
	v_mfma_f32_16x16x32_bf16 v[112:115], v[184:187], v[192:195], 0
	v_mfma_f32_16x16x32_bf16 v[104:107], v[176:179], v[200:203], 0
	v_mfma_f32_16x16x32_bf16 v[96:99], v[184:187], v[200:203], 0
	v_mfma_f32_16x16x32_bf16 v[88:91], v[176:179], v[208:211], 0
	v_mfma_f32_16x16x32_bf16 v[80:83], v[184:187], v[208:211], 0
	v_mfma_f32_16x16x32_bf16 v[72:75], v[176:179], v[216:219], 0
	v_mfma_f32_16x16x32_bf16 v[64:67], v[184:187], v[216:219], 0
	v_mfma_f32_16x16x32_bf16 v[120:123], v[180:183], v[196:199], v[120:123]
	v_mfma_f32_16x16x32_bf16 v[112:115], v[188:191], v[196:199], v[112:115]
	v_mfma_f32_16x16x32_bf16 v[104:107], v[180:183], v[204:207], v[104:107]
	v_mfma_f32_16x16x32_bf16 v[96:99], v[188:191], v[204:207], v[96:99]
	v_mfma_f32_16x16x32_bf16 v[88:91], v[180:183], v[212:215], v[88:91]
	v_mfma_f32_16x16x32_bf16 v[80:83], v[188:191], v[212:215], v[80:83]
	v_mfma_f32_16x16x32_bf16 v[72:75], v[180:183], v[220:223], v[72:75]
	v_mfma_f32_16x16x32_bf16 v[64:67], v[188:191], v[220:223], v[64:67]
	s_setprio 0
	s_barrier
	s_add_i32 s71, s61, s49
	v_lshl_add_u64 v[154:155], s[44:45], 0, v[132:133]
	s_mov_b32 m0, s71
	ds_read_b128 v[192:195], v150 offset:16384
	v_xor_b32_e32 v253, 64, v150
	ds_read_b128 v[196:199], v253 offset:16384
	ds_read_b128 v[200:203], v150 offset:18432
	ds_read_b128 v[204:207], v253 offset:18432
	ds_read_b128 v[208:211], v150 offset:20480
	ds_read_b128 v[212:215], v253 offset:20480
	ds_read_b128 v[216:219], v150 offset:22528
	ds_read_b128 v[220:223], v253 offset:22528
	global_load_lds_dwordx4 v[154:155], off
	s_add_i32 m0, s71, 0x2000
	s_add_u32 s72, s44, 0x40000
	v_lshl_add_u64 v[224:225], s[44:45], 0, v[128:129]
	s_addc_u32 s73, s45, 0
	s_add_i32 s71, s62, s49
	global_load_lds_dwordx4 v[224:225], off
	v_lshl_add_u64 v[226:227], s[72:73], 0, v[132:133]
	s_mov_b32 m0, s71
	v_lshl_add_u64 v[228:229], s[46:47], 0, v[130:131]
	global_load_lds_dwordx4 v[226:227], off
	v_lshl_add_u64 v[226:227], s[72:73], 0, v[128:129]
	s_add_i32 m0, s71, 0x2000
	s_nop 0
	global_load_lds_dwordx4 v[226:227], off
	v_lshl_add_u64 v[226:227], s[46:47], 0, v[134:135]
	s_mov_b32 m0, s52
	s_nop 0
	global_load_lds_dwordx4 v[226:227], off
	s_mov_b32 m0, s53
	s_nop 0
	global_load_lds_dwordx4 v[228:229], off
	s_waitcnt vmcnt(16)
	s_waitcnt lgkmcnt(0)
	s_barrier
	s_setprio 1
	s_waitcnt lgkmcnt(0)
	v_mfma_f32_16x16x32_bf16 v[60:63], v[160:163], v[192:195], 0
	v_mfma_f32_16x16x32_bf16 v[52:55], v[168:171], v[192:195], 0
	v_mfma_f32_16x16x32_bf16 v[44:47], v[160:163], v[200:203], 0
	v_mfma_f32_16x16x32_bf16 v[36:39], v[168:171], v[200:203], 0
	v_mfma_f32_16x16x32_bf16 v[28:31], v[160:163], v[208:211], 0
	v_mfma_f32_16x16x32_bf16 v[20:23], v[168:171], v[208:211], 0
	v_mfma_f32_16x16x32_bf16 v[12:15], v[160:163], v[216:219], 0
	v_mfma_f32_16x16x32_bf16 v[4:7], v[168:171], v[216:219], 0
	v_mfma_f32_16x16x32_bf16 v[60:63], v[164:167], v[196:199], v[60:63]
	v_mfma_f32_16x16x32_bf16 v[52:55], v[172:175], v[196:199], v[52:55]
	v_mfma_f32_16x16x32_bf16 v[44:47], v[164:167], v[204:207], v[44:47]
	v_mfma_f32_16x16x32_bf16 v[36:39], v[172:175], v[204:207], v[36:39]
	v_mfma_f32_16x16x32_bf16 v[28:31], v[164:167], v[212:215], v[28:31]
	v_mfma_f32_16x16x32_bf16 v[20:23], v[172:175], v[212:215], v[20:23]
	v_mfma_f32_16x16x32_bf16 v[12:15], v[164:167], v[220:223], v[12:15]
	v_mfma_f32_16x16x32_bf16 v[4:7], v[172:175], v[220:223], v[4:7]
	s_setprio 0
	s_setprio 1
	v_mfma_f32_16x16x32_bf16 v[56:59], v[176:179], v[192:195], 0
	v_mfma_f32_16x16x32_bf16 v[48:51], v[184:187], v[192:195], 0
	v_mfma_f32_16x16x32_bf16 v[40:43], v[176:179], v[200:203], 0
	v_mfma_f32_16x16x32_bf16 v[32:35], v[184:187], v[200:203], 0
	v_mfma_f32_16x16x32_bf16 v[24:27], v[176:179], v[208:211], 0
	v_mfma_f32_16x16x32_bf16 v[16:19], v[184:187], v[208:211], 0
	v_mfma_f32_16x16x32_bf16 v[8:11], v[176:179], v[216:219], 0
	v_mfma_f32_16x16x32_bf16 v[0:3], v[184:187], v[216:219], 0
	v_mfma_f32_16x16x32_bf16 v[56:59], v[180:183], v[196:199], v[56:59]
	v_mfma_f32_16x16x32_bf16 v[48:51], v[188:191], v[196:199], v[48:51]
	v_mfma_f32_16x16x32_bf16 v[40:43], v[180:183], v[204:207], v[40:43]
	v_mfma_f32_16x16x32_bf16 v[32:35], v[188:191], v[204:207], v[32:35]
	v_mfma_f32_16x16x32_bf16 v[24:27], v[180:183], v[212:215], v[24:27]
	v_mfma_f32_16x16x32_bf16 v[16:19], v[188:191], v[212:215], v[16:19]
	v_mfma_f32_16x16x32_bf16 v[8:11], v[180:183], v[220:223], v[8:11]
	v_mfma_f32_16x16x32_bf16 v[0:3], v[188:191], v[220:223], v[0:3]
	s_setprio 0
	s_barrier
	s_add_i32 s71, 0, 0x18000
	v_add_u32_e32 v153, s71, v147
	s_add_i32 s72, 0, 0x1c000
	ds_read_b128 v[160:163], v153
	v_xor_b32_e32 v253, 64, v153
	ds_read_b128 v[164:167], v253
	ds_read_b128 v[168:171], v153 offset:2048
	ds_read_b128 v[172:175], v253 offset:2048
	v_add_u32_e32 v153, s72, v147
	ds_read_b128 v[176:179], v153
	v_xor_b32_e32 v253, 64, v153
	ds_read_b128 v[180:183], v253
	ds_read_b128 v[184:187], v153 offset:2048
	ds_read_b128 v[188:191], v253 offset:2048
	s_add_u32 s46, s46, 0x40000
	s_addc_u32 s47, s47, 0
	s_mov_b32 m0, s54
	v_lshl_add_u64 v[230:231], s[46:47], 0, v[134:135]
	ds_read_b128 v[192:195], v150 offset:32768
	v_xor_b32_e32 v253, 64, v150
	ds_read_b128 v[196:199], v253 offset:32768
	ds_read_b128 v[200:203], v150 offset:34816
	ds_read_b128 v[204:207], v253 offset:34816
	ds_read_b128 v[208:211], v150 offset:36864
	ds_read_b128 v[212:215], v253 offset:36864
	ds_read_b128 v[216:219], v150 offset:38912
	ds_read_b128 v[220:223], v253 offset:38912
	global_load_lds_dwordx4 v[230:231], off
	v_lshl_add_u64 v[230:231], s[46:47], 0, v[130:131]
	s_mov_b32 m0, s55
	s_nop 0
	global_load_lds_dwordx4 v[230:231], off
	s_waitcnt vmcnt(8)
	s_waitcnt lgkmcnt(0)
	s_barrier
	s_setprio 1
	s_waitcnt lgkmcnt(0)
	v_mfma_f32_16x16x32_bf16 v[124:127], v[160:163], v[192:195], v[124:127]
	v_mfma_f32_16x16x32_bf16 v[124:127], v[164:167], v[196:199], v[124:127]
	v_mfma_f32_16x16x32_bf16 v[116:119], v[168:171], v[192:195], v[116:119]
	v_mfma_f32_16x16x32_bf16 v[116:119], v[172:175], v[196:199], v[116:119]
	v_mfma_f32_16x16x32_bf16 v[108:111], v[160:163], v[200:203], v[108:111]
	v_mfma_f32_16x16x32_bf16 v[108:111], v[164:167], v[204:207], v[108:111]
	v_mfma_f32_16x16x32_bf16 v[100:103], v[168:171], v[200:203], v[100:103]
	v_mfma_f32_16x16x32_bf16 v[100:103], v[172:175], v[204:207], v[100:103]
	v_mfma_f32_16x16x32_bf16 v[92:95], v[160:163], v[208:211], v[92:95]
	v_mfma_f32_16x16x32_bf16 v[92:95], v[164:167], v[212:215], v[92:95]
	v_mfma_f32_16x16x32_bf16 v[84:87], v[168:171], v[208:211], v[84:87]
	v_mfma_f32_16x16x32_bf16 v[84:87], v[172:175], v[212:215], v[84:87]
	v_mfma_f32_16x16x32_bf16 v[76:79], v[160:163], v[216:219], v[76:79]
	v_mfma_f32_16x16x32_bf16 v[76:79], v[164:167], v[220:223], v[76:79]
	v_mfma_f32_16x16x32_bf16 v[68:71], v[168:171], v[216:219], v[68:71]
	v_mfma_f32_16x16x32_bf16 v[68:71], v[172:175], v[220:223], v[68:71]
	s_setprio 0
	s_setprio 1
	v_mfma_f32_16x16x32_bf16 v[120:123], v[176:179], v[192:195], v[120:123]
	v_mfma_f32_16x16x32_bf16 v[120:123], v[180:183], v[196:199], v[120:123]
	v_mfma_f32_16x16x32_bf16 v[112:115], v[184:187], v[192:195], v[112:115]
	v_mfma_f32_16x16x32_bf16 v[112:115], v[188:191], v[196:199], v[112:115]
	v_mfma_f32_16x16x32_bf16 v[104:107], v[176:179], v[200:203], v[104:107]
	v_mfma_f32_16x16x32_bf16 v[104:107], v[180:183], v[204:207], v[104:107]
	v_mfma_f32_16x16x32_bf16 v[96:99], v[184:187], v[200:203], v[96:99]
	v_mfma_f32_16x16x32_bf16 v[96:99], v[188:191], v[204:207], v[96:99]
	v_mfma_f32_16x16x32_bf16 v[88:91], v[176:179], v[208:211], v[88:91]
	v_mfma_f32_16x16x32_bf16 v[88:91], v[180:183], v[212:215], v[88:91]
	v_mfma_f32_16x16x32_bf16 v[80:83], v[184:187], v[208:211], v[80:83]
	v_mfma_f32_16x16x32_bf16 v[80:83], v[188:191], v[212:215], v[80:83]
	v_mfma_f32_16x16x32_bf16 v[72:75], v[176:179], v[216:219], v[72:75]
	v_mfma_f32_16x16x32_bf16 v[72:75], v[180:183], v[220:223], v[72:75]
	v_mfma_f32_16x16x32_bf16 v[64:67], v[184:187], v[216:219], v[64:67]
	v_mfma_f32_16x16x32_bf16 v[64:67], v[188:191], v[220:223], v[64:67]
	s_setprio 0
	s_barrier
	s_add_i32 s46, s71, s49
	v_lshl_add_u64 v[154:155], v[154:155], 0, s[14:15]
	s_mov_b32 m0, s46
	ds_read_b128 v[192:195], v150 offset:49152
	v_xor_b32_e32 v253, 64, v150
	ds_read_b128 v[196:199], v253 offset:49152
	ds_read_b128 v[200:203], v150 offset:51200
	ds_read_b128 v[204:207], v253 offset:51200
	ds_read_b128 v[208:211], v150 offset:53248
	ds_read_b128 v[212:215], v253 offset:53248
	ds_read_b128 v[216:219], v150 offset:55296
	ds_read_b128 v[220:223], v253 offset:55296
	global_load_lds_dwordx4 v[154:155], off
	s_add_i32 m0, s46, 0x2000
	s_add_u32 s44, s44, 0x40080
	v_lshl_add_u64 v[154:155], v[224:225], 0, s[14:15]
	s_addc_u32 s45, s45, 0
	s_add_i32 s46, s72, s49
	global_load_lds_dwordx4 v[154:155], off
	v_lshl_add_u64 v[154:155], s[44:45], 0, v[132:133]
	s_mov_b32 m0, s46
	s_nop 0
	global_load_lds_dwordx4 v[154:155], off
	v_lshl_add_u64 v[154:155], s[44:45], 0, v[128:129]
	s_add_i32 m0, s46, 0x2000
	s_nop 0
	global_load_lds_dwordx4 v[154:155], off
	v_lshl_add_u64 v[154:155], v[226:227], 0, s[14:15]
	s_mov_b32 m0, s57
	s_nop 0
	global_load_lds_dwordx4 v[154:155], off
	v_lshl_add_u64 v[154:155], v[228:229], 0, s[14:15]
	s_mov_b32 m0, s58
	s_nop 0
	global_load_lds_dwordx4 v[154:155], off
	s_waitcnt vmcnt(8)
	s_waitcnt lgkmcnt(0)
	s_barrier
	s_setprio 1
	s_waitcnt lgkmcnt(0)
	v_mfma_f32_16x16x32_bf16 v[60:63], v[160:163], v[192:195], v[60:63]
	v_mfma_f32_16x16x32_bf16 v[60:63], v[164:167], v[196:199], v[60:63]
	v_mfma_f32_16x16x32_bf16 v[52:55], v[168:171], v[192:195], v[52:55]
	v_mfma_f32_16x16x32_bf16 v[52:55], v[172:175], v[196:199], v[52:55]
	v_mfma_f32_16x16x32_bf16 v[44:47], v[160:163], v[200:203], v[44:47]
	v_mfma_f32_16x16x32_bf16 v[44:47], v[164:167], v[204:207], v[44:47]
	v_mfma_f32_16x16x32_bf16 v[36:39], v[168:171], v[200:203], v[36:39]
	v_mfma_f32_16x16x32_bf16 v[36:39], v[172:175], v[204:207], v[36:39]
	v_mfma_f32_16x16x32_bf16 v[28:31], v[160:163], v[208:211], v[28:31]
	v_mfma_f32_16x16x32_bf16 v[28:31], v[164:167], v[212:215], v[28:31]
	v_mfma_f32_16x16x32_bf16 v[20:23], v[168:171], v[208:211], v[20:23]
	v_mfma_f32_16x16x32_bf16 v[20:23], v[172:175], v[212:215], v[20:23]
	v_mfma_f32_16x16x32_bf16 v[12:15], v[160:163], v[216:219], v[12:15]
	v_mfma_f32_16x16x32_bf16 v[12:15], v[164:167], v[220:223], v[12:15]
	v_mfma_f32_16x16x32_bf16 v[4:7], v[168:171], v[216:219], v[4:7]
	v_mfma_f32_16x16x32_bf16 v[4:7], v[172:175], v[220:223], v[4:7]
	s_setprio 0
	s_setprio 1
	v_mfma_f32_16x16x32_bf16 v[56:59], v[176:179], v[192:195], v[56:59]
	v_mfma_f32_16x16x32_bf16 v[56:59], v[180:183], v[196:199], v[56:59]
	v_mfma_f32_16x16x32_bf16 v[48:51], v[184:187], v[192:195], v[48:51]
	v_mfma_f32_16x16x32_bf16 v[48:51], v[188:191], v[196:199], v[48:51]
	v_mfma_f32_16x16x32_bf16 v[40:43], v[176:179], v[200:203], v[40:43]
	v_mfma_f32_16x16x32_bf16 v[40:43], v[180:183], v[204:207], v[40:43]
	v_mfma_f32_16x16x32_bf16 v[32:35], v[184:187], v[200:203], v[32:35]
	v_mfma_f32_16x16x32_bf16 v[32:35], v[188:191], v[204:207], v[32:35]
	v_mfma_f32_16x16x32_bf16 v[24:27], v[176:179], v[208:211], v[24:27]
	v_mfma_f32_16x16x32_bf16 v[24:27], v[180:183], v[212:215], v[24:27]
	v_mfma_f32_16x16x32_bf16 v[16:19], v[184:187], v[208:211], v[16:19]
	v_mfma_f32_16x16x32_bf16 v[16:19], v[188:191], v[212:215], v[16:19]
	v_mfma_f32_16x16x32_bf16 v[8:11], v[176:179], v[216:219], v[8:11]
	v_mfma_f32_16x16x32_bf16 v[8:11], v[180:183], v[220:223], v[8:11]
	v_mfma_f32_16x16x32_bf16 v[0:3], v[184:187], v[216:219], v[0:3]
	v_mfma_f32_16x16x32_bf16 v[0:3], v[188:191], v[220:223], v[0:3]
	s_setprio 0
	s_barrier
	s_add_i32 s70, s70, 2
	s_add_u32 s68, s68, 0x100
	s_addc_u32 s69, s69, 0
	s_add_u32 s30, s30, 0x100
	s_addc_u32 s31, s31, 0
	s_branch .LBB0_1098
.Lfa_10:
	v_add_u32_e32 v153, s61, v147
	ds_read_b128 v[160:163], v153
	v_xor_b32_e32 v253, 64, v153
	ds_read_b128 v[164:167], v253
	ds_read_b128 v[168:171], v153 offset:2048
	ds_read_b128 v[172:175], v253 offset:2048
	v_add_u32_e32 v153, s62, v147
	ds_read_b128 v[176:179], v153
	v_xor_b32_e32 v253, 64, v153
	ds_read_b128 v[180:183], v253
	ds_read_b128 v[184:187], v153 offset:2048
	ds_read_b128 v[188:191], v253 offset:2048
	s_add_u32 s46, s30, 0xfffc0080
	s_addc_u32 s47, s31, -1
	s_and_b64 s[44:45], s[44:45], exec
	s_cselect_b32 s47, s25, s47
	s_cselect_b32 s46, s65, s46
	s_cselect_b32 s45, s66, s69
	s_cselect_b32 s44, s67, s68
	v_lshl_add_u64 v[154:155], s[30:31], 0, v[138:139]
	s_add_i32 m0, s52, 0xc000
	ds_read_b128 v[192:195], v150
	v_xor_b32_e32 v253, 64, v150
	ds_read_b128 v[196:199], v253
	ds_read_b128 v[200:203], v150 offset:2048
	ds_read_b128 v[204:207], v253 offset:2048
	ds_read_b128 v[208:211], v150 offset:4096
	ds_read_b128 v[212:215], v253 offset:4096
	ds_read_b128 v[216:219], v150 offset:6144
	ds_read_b128 v[220:223], v253 offset:6144
	global_load_lds_dwordx4 v[154:155], off
	v_lshl_add_u64 v[154:155], s[30:31], 0, v[136:137]
	s_add_i32 m0, s52, 0xe000
	s_nop 0
	global_load_lds_dwordx4 v[154:155], off
	s_waitcnt vmcnt(8)
	s_waitcnt lgkmcnt(0)
	s_barrier
	s_setprio 1
	s_waitcnt lgkmcnt(0)
	v_mfma_f32_16x16x32_bf16 v[124:127], v[160:163], v[192:195], 0
	v_mfma_f32_16x16x32_bf16 v[116:119], v[168:171], v[192:195], 0
	v_mfma_f32_16x16x32_bf16 v[108:111], v[160:163], v[200:203], 0
	v_mfma_f32_16x16x32_bf16 v[100:103], v[168:171], v[200:203], 0
	v_mfma_f32_16x16x32_bf16 v[92:95], v[160:163], v[208:211], 0
	v_mfma_f32_16x16x32_bf16 v[84:87], v[168:171], v[208:211], 0
	v_mfma_f32_16x16x32_bf16 v[76:79], v[160:163], v[216:219], 0
	v_mfma_f32_16x16x32_bf16 v[68:71], v[168:171], v[216:219], 0
	v_mfma_f32_16x16x32_bf16 v[124:127], v[164:167], v[196:199], v[124:127]
	v_mfma_f32_16x16x32_bf16 v[116:119], v[172:175], v[196:199], v[116:119]
	v_mfma_f32_16x16x32_bf16 v[108:111], v[164:167], v[204:207], v[108:111]
	v_mfma_f32_16x16x32_bf16 v[100:103], v[172:175], v[204:207], v[100:103]
	v_mfma_f32_16x16x32_bf16 v[92:95], v[164:167], v[212:215], v[92:95]
	v_mfma_f32_16x16x32_bf16 v[84:87], v[172:175], v[212:215], v[84:87]
	v_mfma_f32_16x16x32_bf16 v[76:79], v[164:167], v[220:223], v[76:79]
	v_mfma_f32_16x16x32_bf16 v[68:71], v[172:175], v[220:223], v[68:71]
	s_setprio 0
	s_setprio 1
	v_mfma_f32_16x16x32_bf16 v[120:123], v[176:179], v[192:195], 0
	v_mfma_f32_16x16x32_bf16 v[112:115], v[184:187], v[192:195], 0
	v_mfma_f32_16x16x32_bf16 v[104:107], v[176:179], v[200:203], 0
	v_mfma_f32_16x16x32_bf16 v[96:99], v[184:187], v[200:203], 0
	v_mfma_f32_16x16x32_bf16 v[88:91], v[176:179], v[208:211], 0
	v_mfma_f32_16x16x32_bf16 v[80:83], v[184:187], v[208:211], 0
	v_mfma_f32_16x16x32_bf16 v[72:75], v[176:179], v[216:219], 0
	v_mfma_f32_16x16x32_bf16 v[64:67], v[184:187], v[216:219], 0
	v_mfma_f32_16x16x32_bf16 v[120:123], v[180:183], v[196:199], v[120:123]
	v_mfma_f32_16x16x32_bf16 v[112:115], v[188:191], v[196:199], v[112:115]
	v_mfma_f32_16x16x32_bf16 v[104:107], v[180:183], v[204:207], v[104:107]
	v_mfma_f32_16x16x32_bf16 v[96:99], v[188:191], v[204:207], v[96:99]
	v_mfma_f32_16x16x32_bf16 v[88:91], v[180:183], v[212:215], v[88:91]
	v_mfma_f32_16x16x32_bf16 v[80:83], v[188:191], v[212:215], v[80:83]
	v_mfma_f32_16x16x32_bf16 v[72:75], v[180:183], v[220:223], v[72:75]
	v_mfma_f32_16x16x32_bf16 v[64:67], v[188:191], v[220:223], v[64:67]
	s_setprio 0
	s_barrier
	s_add_i32 s71, s61, s49
	v_lshl_add_u64 v[154:155], s[44:45], 0, v[132:133]
	s_mov_b32 m0, s71
	ds_read_b128 v[192:195], v150 offset:16384
	v_xor_b32_e32 v253, 64, v150
	ds_read_b128 v[196:199], v253 offset:16384
	ds_read_b128 v[200:203], v150 offset:18432
	ds_read_b128 v[204:207], v253 offset:18432
	ds_read_b128 v[208:211], v150 offset:20480
	ds_read_b128 v[212:215], v253 offset:20480
	ds_read_b128 v[216:219], v150 offset:22528
	ds_read_b128 v[220:223], v253 offset:22528
	global_load_lds_dwordx4 v[154:155], off
	s_add_i32 m0, s71, 0x2000
	s_add_u32 s72, s44, 0x40000
	v_lshl_add_u64 v[224:225], s[44:45], 0, v[128:129]
	s_addc_u32 s73, s45, 0
	s_add_i32 s71, s62, s49
	global_load_lds_dwordx4 v[224:225], off
	v_lshl_add_u64 v[226:227], s[72:73], 0, v[132:133]
	s_mov_b32 m0, s71
	v_lshl_add_u64 v[228:229], s[46:47], 0, v[130:131]
	global_load_lds_dwordx4 v[226:227], off
	v_lshl_add_u64 v[226:227], s[72:73], 0, v[128:129]
	s_add_i32 m0, s71, 0x2000
	s_nop 0
	global_load_lds_dwordx4 v[226:227], off
	v_lshl_add_u64 v[226:227], s[46:47], 0, v[134:135]
	s_mov_b32 m0, s52
	s_nop 0
	global_load_lds_dwordx4 v[226:227], off
	s_mov_b32 m0, s53
	s_nop 0
	global_load_lds_dwordx4 v[228:229], off
	s_waitcnt vmcnt(8)
	s_waitcnt lgkmcnt(0)
	s_barrier
	s_setprio 1
	s_waitcnt lgkmcnt(0)
	v_mfma_f32_16x16x32_bf16 v[60:63], v[160:163], v[192:195], 0
	v_mfma_f32_16x16x32_bf16 v[52:55], v[168:171], v[192:195], 0
	v_mfma_f32_16x16x32_bf16 v[44:47], v[160:163], v[200:203], 0
	v_mfma_f32_16x16x32_bf16 v[36:39], v[168:171], v[200:203], 0
	v_mfma_f32_16x16x32_bf16 v[28:31], v[160:163], v[208:211], 0
	v_mfma_f32_16x16x32_bf16 v[20:23], v[168:171], v[208:211], 0
	v_mfma_f32_16x16x32_bf16 v[12:15], v[160:163], v[216:219], 0
	v_mfma_f32_16x16x32_bf16 v[4:7], v[168:171], v[216:219], 0
	v_mfma_f32_16x16x32_bf16 v[60:63], v[164:167], v[196:199], v[60:63]
	v_mfma_f32_16x16x32_bf16 v[52:55], v[172:175], v[196:199], v[52:55]
	v_mfma_f32_16x16x32_bf16 v[44:47], v[164:167], v[204:207], v[44:47]
	v_mfma_f32_16x16x32_bf16 v[36:39], v[172:175], v[204:207], v[36:39]
	v_mfma_f32_16x16x32_bf16 v[28:31], v[164:167], v[212:215], v[28:31]
	v_mfma_f32_16x16x32_bf16 v[20:23], v[172:175], v[212:215], v[20:23]
	v_mfma_f32_16x16x32_bf16 v[12:15], v[164:167], v[220:223], v[12:15]
	v_mfma_f32_16x16x32_bf16 v[4:7], v[172:175], v[220:223], v[4:7]
	s_setprio 0
	s_setprio 1
	v_mfma_f32_16x16x32_bf16 v[56:59], v[176:179], v[192:195], 0
	v_mfma_f32_16x16x32_bf16 v[48:51], v[184:187], v[192:195], 0
	v_mfma_f32_16x16x32_bf16 v[40:43], v[176:179], v[200:203], 0
	v_mfma_f32_16x16x32_bf16 v[32:35], v[184:187], v[200:203], 0
	v_mfma_f32_16x16x32_bf16 v[24:27], v[176:179], v[208:211], 0
	v_mfma_f32_16x16x32_bf16 v[16:19], v[184:187], v[208:211], 0
	v_mfma_f32_16x16x32_bf16 v[8:11], v[176:179], v[216:219], 0
	v_mfma_f32_16x16x32_bf16 v[0:3], v[184:187], v[216:219], 0
	v_mfma_f32_16x16x32_bf16 v[56:59], v[180:183], v[196:199], v[56:59]
	v_mfma_f32_16x16x32_bf16 v[48:51], v[188:191], v[196:199], v[48:51]
	v_mfma_f32_16x16x32_bf16 v[40:43], v[180:183], v[204:207], v[40:43]
	v_mfma_f32_16x16x32_bf16 v[32:35], v[188:191], v[204:207], v[32:35]
	v_mfma_f32_16x16x32_bf16 v[24:27], v[180:183], v[212:215], v[24:27]
	v_mfma_f32_16x16x32_bf16 v[16:19], v[188:191], v[212:215], v[16:19]
	v_mfma_f32_16x16x32_bf16 v[8:11], v[180:183], v[220:223], v[8:11]
	v_mfma_f32_16x16x32_bf16 v[0:3], v[188:191], v[220:223], v[0:3]
	s_setprio 0
	s_barrier
	s_add_i32 s71, 0, 0x18000
	v_add_u32_e32 v153, s71, v147
	s_add_i32 s72, 0, 0x1c000
	ds_read_b128 v[160:163], v153
	v_xor_b32_e32 v253, 64, v153
	ds_read_b128 v[164:167], v253
	ds_read_b128 v[168:171], v153 offset:2048
	ds_read_b128 v[172:175], v253 offset:2048
	v_add_u32_e32 v153, s72, v147
	ds_read_b128 v[176:179], v153
	v_xor_b32_e32 v253, 64, v153
	ds_read_b128 v[180:183], v253
	ds_read_b128 v[184:187], v153 offset:2048
	ds_read_b128 v[188:191], v253 offset:2048
	s_add_u32 s46, s46, 0x40000
	s_addc_u32 s47, s47, 0
	s_mov_b32 m0, s54
	v_lshl_add_u64 v[230:231], s[46:47], 0, v[134:135]
	ds_read_b128 v[192:195], v150 offset:32768
	v_xor_b32_e32 v253, 64, v150
	ds_read_b128 v[196:199], v253 offset:32768
	ds_read_b128 v[200:203], v150 offset:34816
	ds_read_b128 v[204:207], v253 offset:34816
	ds_read_b128 v[208:211], v150 offset:36864
	ds_read_b128 v[212:215], v253 offset:36864
	ds_read_b128 v[216:219], v150 offset:38912
	ds_read_b128 v[220:223], v253 offset:38912
	global_load_lds_dwordx4 v[230:231], off
	v_lshl_add_u64 v[230:231], s[46:47], 0, v[130:131]
	s_mov_b32 m0, s55
	s_nop 0
	global_load_lds_dwordx4 v[230:231], off
	s_waitcnt vmcnt(8)
	s_waitcnt lgkmcnt(0)
	s_barrier
	s_setprio 1
	s_waitcnt lgkmcnt(0)
	v_mfma_f32_16x16x32_bf16 v[124:127], v[160:163], v[192:195], v[124:127]
	v_mfma_f32_16x16x32_bf16 v[124:127], v[164:167], v[196:199], v[124:127]
	v_mfma_f32_16x16x32_bf16 v[116:119], v[168:171], v[192:195], v[116:119]
	v_mfma_f32_16x16x32_bf16 v[116:119], v[172:175], v[196:199], v[116:119]
	v_mfma_f32_16x16x32_bf16 v[108:111], v[160:163], v[200:203], v[108:111]
	v_mfma_f32_16x16x32_bf16 v[108:111], v[164:167], v[204:207], v[108:111]
	v_mfma_f32_16x16x32_bf16 v[100:103], v[168:171], v[200:203], v[100:103]
	v_mfma_f32_16x16x32_bf16 v[100:103], v[172:175], v[204:207], v[100:103]
	v_mfma_f32_16x16x32_bf16 v[92:95], v[160:163], v[208:211], v[92:95]
	v_mfma_f32_16x16x32_bf16 v[92:95], v[164:167], v[212:215], v[92:95]
	v_mfma_f32_16x16x32_bf16 v[84:87], v[168:171], v[208:211], v[84:87]
	v_mfma_f32_16x16x32_bf16 v[84:87], v[172:175], v[212:215], v[84:87]
	v_mfma_f32_16x16x32_bf16 v[76:79], v[160:163], v[216:219], v[76:79]
	v_mfma_f32_16x16x32_bf16 v[76:79], v[164:167], v[220:223], v[76:79]
	v_mfma_f32_16x16x32_bf16 v[68:71], v[168:171], v[216:219], v[68:71]
	v_mfma_f32_16x16x32_bf16 v[68:71], v[172:175], v[220:223], v[68:71]
	s_setprio 0
	s_setprio 1
	v_mfma_f32_16x16x32_bf16 v[120:123], v[176:179], v[192:195], v[120:123]
	v_mfma_f32_16x16x32_bf16 v[120:123], v[180:183], v[196:199], v[120:123]
	v_mfma_f32_16x16x32_bf16 v[112:115], v[184:187], v[192:195], v[112:115]
	v_mfma_f32_16x16x32_bf16 v[112:115], v[188:191], v[196:199], v[112:115]
	v_mfma_f32_16x16x32_bf16 v[104:107], v[176:179], v[200:203], v[104:107]
	v_mfma_f32_16x16x32_bf16 v[104:107], v[180:183], v[204:207], v[104:107]
	v_mfma_f32_16x16x32_bf16 v[96:99], v[184:187], v[200:203], v[96:99]
	v_mfma_f32_16x16x32_bf16 v[96:99], v[188:191], v[204:207], v[96:99]
	v_mfma_f32_16x16x32_bf16 v[88:91], v[176:179], v[208:211], v[88:91]
	v_mfma_f32_16x16x32_bf16 v[88:91], v[180:183], v[212:215], v[88:91]
	v_mfma_f32_16x16x32_bf16 v[80:83], v[184:187], v[208:211], v[80:83]
	v_mfma_f32_16x16x32_bf16 v[80:83], v[188:191], v[212:215], v[80:83]
	v_mfma_f32_16x16x32_bf16 v[72:75], v[176:179], v[216:219], v[72:75]
	v_mfma_f32_16x16x32_bf16 v[72:75], v[180:183], v[220:223], v[72:75]
	v_mfma_f32_16x16x32_bf16 v[64:67], v[184:187], v[216:219], v[64:67]
	v_mfma_f32_16x16x32_bf16 v[64:67], v[188:191], v[220:223], v[64:67]
	s_setprio 0
	s_barrier
	s_add_i32 s46, s71, s49
	v_lshl_add_u64 v[154:155], v[154:155], 0, s[14:15]
	s_mov_b32 m0, s46
	ds_read_b128 v[192:195], v150 offset:49152
	v_xor_b32_e32 v253, 64, v150
	ds_read_b128 v[196:199], v253 offset:49152
	ds_read_b128 v[200:203], v150 offset:51200
	ds_read_b128 v[204:207], v253 offset:51200
	ds_read_b128 v[208:211], v150 offset:53248
	ds_read_b128 v[212:215], v253 offset:53248
	ds_read_b128 v[216:219], v150 offset:55296
	ds_read_b128 v[220:223], v253 offset:55296
	global_load_lds_dwordx4 v[154:155], off
	s_add_i32 m0, s46, 0x2000
	s_add_u32 s44, s44, 0x40080
	v_lshl_add_u64 v[154:155], v[224:225], 0, s[14:15]
	s_addc_u32 s45, s45, 0
	s_add_i32 s46, s72, s49
	global_load_lds_dwordx4 v[154:155], off
	v_lshl_add_u64 v[154:155], s[44:45], 0, v[132:133]
	s_mov_b32 m0, s46
	s_nop 0
	global_load_lds_dwordx4 v[154:155], off
	v_lshl_add_u64 v[154:155], s[44:45], 0, v[128:129]
	s_add_i32 m0, s46, 0x2000
	s_nop 0
	global_load_lds_dwordx4 v[154:155], off
	v_lshl_add_u64 v[154:155], v[226:227], 0, s[14:15]
	s_mov_b32 m0, s57
	s_nop 0
	global_load_lds_dwordx4 v[154:155], off
	v_lshl_add_u64 v[154:155], v[228:229], 0, s[14:15]
	s_mov_b32 m0, s58
	s_nop 0
	global_load_lds_dwordx4 v[154:155], off
	s_waitcnt vmcnt(8)
	s_waitcnt lgkmcnt(0)
	s_barrier
	s_setprio 1
	s_waitcnt lgkmcnt(0)
	v_mfma_f32_16x16x32_bf16 v[60:63], v[160:163], v[192:195], v[60:63]
	v_mfma_f32_16x16x32_bf16 v[60:63], v[164:167], v[196:199], v[60:63]
	v_mfma_f32_16x16x32_bf16 v[52:55], v[168:171], v[192:195], v[52:55]
	v_mfma_f32_16x16x32_bf16 v[52:55], v[172:175], v[196:199], v[52:55]
	v_mfma_f32_16x16x32_bf16 v[44:47], v[160:163], v[200:203], v[44:47]
	v_mfma_f32_16x16x32_bf16 v[44:47], v[164:167], v[204:207], v[44:47]
	v_mfma_f32_16x16x32_bf16 v[36:39], v[168:171], v[200:203], v[36:39]
	v_mfma_f32_16x16x32_bf16 v[36:39], v[172:175], v[204:207], v[36:39]
	v_mfma_f32_16x16x32_bf16 v[28:31], v[160:163], v[208:211], v[28:31]
	v_mfma_f32_16x16x32_bf16 v[28:31], v[164:167], v[212:215], v[28:31]
	v_mfma_f32_16x16x32_bf16 v[20:23], v[168:171], v[208:211], v[20:23]
	v_mfma_f32_16x16x32_bf16 v[20:23], v[172:175], v[212:215], v[20:23]
	v_mfma_f32_16x16x32_bf16 v[12:15], v[160:163], v[216:219], v[12:15]
	v_mfma_f32_16x16x32_bf16 v[12:15], v[164:167], v[220:223], v[12:15]
	v_mfma_f32_16x16x32_bf16 v[4:7], v[168:171], v[216:219], v[4:7]
	v_mfma_f32_16x16x32_bf16 v[4:7], v[172:175], v[220:223], v[4:7]
	s_setprio 0
	s_setprio 1
	v_mfma_f32_16x16x32_bf16 v[56:59], v[176:179], v[192:195], v[56:59]
	v_mfma_f32_16x16x32_bf16 v[56:59], v[180:183], v[196:199], v[56:59]
	v_mfma_f32_16x16x32_bf16 v[48:51], v[184:187], v[192:195], v[48:51]
	v_mfma_f32_16x16x32_bf16 v[48:51], v[188:191], v[196:199], v[48:51]
	v_mfma_f32_16x16x32_bf16 v[40:43], v[176:179], v[200:203], v[40:43]
	v_mfma_f32_16x16x32_bf16 v[40:43], v[180:183], v[204:207], v[40:43]
	v_mfma_f32_16x16x32_bf16 v[32:35], v[184:187], v[200:203], v[32:35]
	v_mfma_f32_16x16x32_bf16 v[32:35], v[188:191], v[204:207], v[32:35]
	v_mfma_f32_16x16x32_bf16 v[24:27], v[176:179], v[208:211], v[24:27]
	v_mfma_f32_16x16x32_bf16 v[24:27], v[180:183], v[212:215], v[24:27]
	v_mfma_f32_16x16x32_bf16 v[16:19], v[184:187], v[208:211], v[16:19]
	v_mfma_f32_16x16x32_bf16 v[16:19], v[188:191], v[212:215], v[16:19]
	v_mfma_f32_16x16x32_bf16 v[8:11], v[176:179], v[216:219], v[8:11]
	v_mfma_f32_16x16x32_bf16 v[8:11], v[180:183], v[220:223], v[8:11]
	v_mfma_f32_16x16x32_bf16 v[0:3], v[184:187], v[216:219], v[0:3]
	v_mfma_f32_16x16x32_bf16 v[0:3], v[188:191], v[220:223], v[0:3]
	s_setprio 0
	s_barrier
	s_add_i32 s70, s70, 2
	s_add_u32 s68, s68, 0x100
	s_addc_u32 s69, s69, 0
	s_add_u32 s30, s30, 0x100
	s_addc_u32 s31, s31, 0
	s_branch .LBB0_1098
.LBB0_1097:
	v_add_u32_e32 v153, s61, v147
	ds_read_b128 v[160:163], v153
	v_xor_b32_e32 v253, 64, v153
	ds_read_b128 v[164:167], v253
	ds_read_b128 v[168:171], v153 offset:2048
	ds_read_b128 v[172:175], v253 offset:2048
	v_add_u32_e32 v153, s62, v147
	ds_read_b128 v[176:179], v153
	v_xor_b32_e32 v253, 64, v153
	ds_read_b128 v[180:183], v253
	ds_read_b128 v[184:187], v153 offset:2048
	ds_read_b128 v[188:191], v253 offset:2048
	s_add_u32 s46, s30, 0xfffc0080
	s_addc_u32 s47, s31, -1
	s_and_b64 s[44:45], s[44:45], exec
	s_cselect_b32 s47, s25, s47
	s_cselect_b32 s46, s65, s46
	s_cselect_b32 s45, s66, s69
	s_cselect_b32 s44, s67, s68
	v_lshl_add_u64 v[154:155], s[30:31], 0, v[138:139]
	s_add_i32 m0, s52, 0xc000
	ds_read_b128 v[192:195], v150
	v_xor_b32_e32 v253, 64, v150
	ds_read_b128 v[196:199], v253
	ds_read_b128 v[200:203], v150 offset:2048
	ds_read_b128 v[204:207], v253 offset:2048
	ds_read_b128 v[208:211], v150 offset:4096
	ds_read_b128 v[212:215], v253 offset:4096
	ds_read_b128 v[216:219], v150 offset:6144
	ds_read_b128 v[220:223], v253 offset:6144
	global_load_lds_dwordx4 v[154:155], off
	v_lshl_add_u64 v[154:155], s[30:31], 0, v[136:137]
	s_add_i32 m0, s52, 0xe000
	s_nop 0
	global_load_lds_dwordx4 v[154:155], off
	s_waitcnt vmcnt(8)
	s_waitcnt lgkmcnt(0)
	s_barrier
	s_setprio 1
	s_waitcnt lgkmcnt(0)
	v_mfma_f32_16x16x32_bf16 v[124:127], v[160:163], v[192:195], v[124:127]
	v_mfma_f32_16x16x32_bf16 v[124:127], v[164:167], v[196:199], v[124:127]
	v_mfma_f32_16x16x32_bf16 v[116:119], v[168:171], v[192:195], v[116:119]
	v_mfma_f32_16x16x32_bf16 v[116:119], v[172:175], v[196:199], v[116:119]
	v_mfma_f32_16x16x32_bf16 v[108:111], v[160:163], v[200:203], v[108:111]
	v_mfma_f32_16x16x32_bf16 v[108:111], v[164:167], v[204:207], v[108:111]
	v_mfma_f32_16x16x32_bf16 v[100:103], v[168:171], v[200:203], v[100:103]
	v_mfma_f32_16x16x32_bf16 v[100:103], v[172:175], v[204:207], v[100:103]
	v_mfma_f32_16x16x32_bf16 v[92:95], v[160:163], v[208:211], v[92:95]
	v_mfma_f32_16x16x32_bf16 v[92:95], v[164:167], v[212:215], v[92:95]
	v_mfma_f32_16x16x32_bf16 v[84:87], v[168:171], v[208:211], v[84:87]
	v_mfma_f32_16x16x32_bf16 v[84:87], v[172:175], v[212:215], v[84:87]
	v_mfma_f32_16x16x32_bf16 v[76:79], v[160:163], v[216:219], v[76:79]
	v_mfma_f32_16x16x32_bf16 v[76:79], v[164:167], v[220:223], v[76:79]
	v_mfma_f32_16x16x32_bf16 v[68:71], v[168:171], v[216:219], v[68:71]
	v_mfma_f32_16x16x32_bf16 v[68:71], v[172:175], v[220:223], v[68:71]
	s_setprio 0
	s_setprio 1
	v_mfma_f32_16x16x32_bf16 v[120:123], v[176:179], v[192:195], v[120:123]
	v_mfma_f32_16x16x32_bf16 v[120:123], v[180:183], v[196:199], v[120:123]
	v_mfma_f32_16x16x32_bf16 v[112:115], v[184:187], v[192:195], v[112:115]
	v_mfma_f32_16x16x32_bf16 v[112:115], v[188:191], v[196:199], v[112:115]
	v_mfma_f32_16x16x32_bf16 v[104:107], v[176:179], v[200:203], v[104:107]
	v_mfma_f32_16x16x32_bf16 v[104:107], v[180:183], v[204:207], v[104:107]
	v_mfma_f32_16x16x32_bf16 v[96:99], v[184:187], v[200:203], v[96:99]
	v_mfma_f32_16x16x32_bf16 v[96:99], v[188:191], v[204:207], v[96:99]
	v_mfma_f32_16x16x32_bf16 v[88:91], v[176:179], v[208:211], v[88:91]
	v_mfma_f32_16x16x32_bf16 v[88:91], v[180:183], v[212:215], v[88:91]
	v_mfma_f32_16x16x32_bf16 v[80:83], v[184:187], v[208:211], v[80:83]
	v_mfma_f32_16x16x32_bf16 v[80:83], v[188:191], v[212:215], v[80:83]
	v_mfma_f32_16x16x32_bf16 v[72:75], v[176:179], v[216:219], v[72:75]
	v_mfma_f32_16x16x32_bf16 v[72:75], v[180:183], v[220:223], v[72:75]
	v_mfma_f32_16x16x32_bf16 v[64:67], v[184:187], v[216:219], v[64:67]
	v_mfma_f32_16x16x32_bf16 v[64:67], v[188:191], v[220:223], v[64:67]
	s_setprio 0
	s_barrier
	s_add_i32 s71, s61, s49
	v_lshl_add_u64 v[154:155], s[44:45], 0, v[132:133]
	s_mov_b32 m0, s71
	ds_read_b128 v[192:195], v150 offset:16384
	v_xor_b32_e32 v253, 64, v150
	ds_read_b128 v[196:199], v253 offset:16384
	ds_read_b128 v[200:203], v150 offset:18432
	ds_read_b128 v[204:207], v253 offset:18432
	ds_read_b128 v[208:211], v150 offset:20480
	ds_read_b128 v[212:215], v253 offset:20480
	ds_read_b128 v[216:219], v150 offset:22528
	ds_read_b128 v[220:223], v253 offset:22528
	global_load_lds_dwordx4 v[154:155], off
	s_add_i32 m0, s71, 0x2000
	s_add_u32 s72, s44, 0x40000
	v_lshl_add_u64 v[224:225], s[44:45], 0, v[128:129]
	s_addc_u32 s73, s45, 0
	s_add_i32 s71, s62, s49
	global_load_lds_dwordx4 v[224:225], off
	v_lshl_add_u64 v[226:227], s[72:73], 0, v[132:133]
	s_mov_b32 m0, s71
	v_lshl_add_u64 v[228:229], s[46:47], 0, v[130:131]
	global_load_lds_dwordx4 v[226:227], off
	v_lshl_add_u64 v[226:227], s[72:73], 0, v[128:129]
	s_add_i32 m0, s71, 0x2000
	s_nop 0
	global_load_lds_dwordx4 v[226:227], off
	v_lshl_add_u64 v[226:227], s[46:47], 0, v[134:135]
	s_mov_b32 m0, s52
	s_nop 0
	global_load_lds_dwordx4 v[226:227], off
	s_mov_b32 m0, s53
	s_nop 0
	global_load_lds_dwordx4 v[228:229], off
	s_waitcnt vmcnt(8)
	s_waitcnt lgkmcnt(0)
	s_barrier
	s_setprio 1
	s_waitcnt lgkmcnt(0)
	v_mfma_f32_16x16x32_bf16 v[60:63], v[160:163], v[192:195], v[60:63]
	v_mfma_f32_16x16x32_bf16 v[60:63], v[164:167], v[196:199], v[60:63]
	v_mfma_f32_16x16x32_bf16 v[52:55], v[168:171], v[192:195], v[52:55]
	v_mfma_f32_16x16x32_bf16 v[52:55], v[172:175], v[196:199], v[52:55]
	v_mfma_f32_16x16x32_bf16 v[44:47], v[160:163], v[200:203], v[44:47]
	v_mfma_f32_16x16x32_bf16 v[44:47], v[164:167], v[204:207], v[44:47]
	v_mfma_f32_16x16x32_bf16 v[36:39], v[168:171], v[200:203], v[36:39]
	v_mfma_f32_16x16x32_bf16 v[36:39], v[172:175], v[204:207], v[36:39]
	v_mfma_f32_16x16x32_bf16 v[28:31], v[160:163], v[208:211], v[28:31]
	v_mfma_f32_16x16x32_bf16 v[28:31], v[164:167], v[212:215], v[28:31]
	v_mfma_f32_16x16x32_bf16 v[20:23], v[168:171], v[208:211], v[20:23]
	v_mfma_f32_16x16x32_bf16 v[20:23], v[172:175], v[212:215], v[20:23]
	v_mfma_f32_16x16x32_bf16 v[12:15], v[160:163], v[216:219], v[12:15]
	v_mfma_f32_16x16x32_bf16 v[12:15], v[164:167], v[220:223], v[12:15]
	v_mfma_f32_16x16x32_bf16 v[4:7], v[168:171], v[216:219], v[4:7]
	v_mfma_f32_16x16x32_bf16 v[4:7], v[172:175], v[220:223], v[4:7]
	s_setprio 0
	s_setprio 1
	v_mfma_f32_16x16x32_bf16 v[56:59], v[176:179], v[192:195], v[56:59]
	v_mfma_f32_16x16x32_bf16 v[56:59], v[180:183], v[196:199], v[56:59]
	v_mfma_f32_16x16x32_bf16 v[48:51], v[184:187], v[192:195], v[48:51]
	v_mfma_f32_16x16x32_bf16 v[48:51], v[188:191], v[196:199], v[48:51]
	v_mfma_f32_16x16x32_bf16 v[40:43], v[176:179], v[200:203], v[40:43]
	v_mfma_f32_16x16x32_bf16 v[40:43], v[180:183], v[204:207], v[40:43]
	v_mfma_f32_16x16x32_bf16 v[32:35], v[184:187], v[200:203], v[32:35]
	v_mfma_f32_16x16x32_bf16 v[32:35], v[188:191], v[204:207], v[32:35]
	v_mfma_f32_16x16x32_bf16 v[24:27], v[176:179], v[208:211], v[24:27]
	v_mfma_f32_16x16x32_bf16 v[24:27], v[180:183], v[212:215], v[24:27]
	v_mfma_f32_16x16x32_bf16 v[16:19], v[184:187], v[208:211], v[16:19]
	v_mfma_f32_16x16x32_bf16 v[16:19], v[188:191], v[212:215], v[16:19]
	v_mfma_f32_16x16x32_bf16 v[8:11], v[176:179], v[216:219], v[8:11]
	v_mfma_f32_16x16x32_bf16 v[8:11], v[180:183], v[220:223], v[8:11]
	v_mfma_f32_16x16x32_bf16 v[0:3], v[184:187], v[216:219], v[0:3]
	v_mfma_f32_16x16x32_bf16 v[0:3], v[188:191], v[220:223], v[0:3]
	s_setprio 0
	s_barrier
	s_add_i32 s71, 0, 0x18000
	v_add_u32_e32 v153, s71, v147
	s_add_i32 s72, 0, 0x1c000
	ds_read_b128 v[160:163], v153
	v_xor_b32_e32 v253, 64, v153
	ds_read_b128 v[164:167], v253
	ds_read_b128 v[168:171], v153 offset:2048
	ds_read_b128 v[172:175], v253 offset:2048
	v_add_u32_e32 v153, s72, v147
	ds_read_b128 v[176:179], v153
	v_xor_b32_e32 v253, 64, v153
	ds_read_b128 v[180:183], v253
	ds_read_b128 v[184:187], v153 offset:2048
	ds_read_b128 v[188:191], v253 offset:2048
	s_add_u32 s46, s46, 0x40000
	s_addc_u32 s47, s47, 0
	s_mov_b32 m0, s54
	v_lshl_add_u64 v[230:231], s[46:47], 0, v[134:135]
	ds_read_b128 v[192:195], v150 offset:32768
	v_xor_b32_e32 v253, 64, v150
	ds_read_b128 v[196:199], v253 offset:32768
	ds_read_b128 v[200:203], v150 offset:34816
	ds_read_b128 v[204:207], v253 offset:34816
	ds_read_b128 v[208:211], v150 offset:36864
	ds_read_b128 v[212:215], v253 offset:36864
	ds_read_b128 v[216:219], v150 offset:38912
	ds_read_b128 v[220:223], v253 offset:38912
	global_load_lds_dwordx4 v[230:231], off
	v_lshl_add_u64 v[230:231], s[46:47], 0, v[130:131]
	s_mov_b32 m0, s55
	s_nop 0
	global_load_lds_dwordx4 v[230:231], off
	s_waitcnt vmcnt(8)
	s_waitcnt lgkmcnt(0)
	s_barrier
	s_setprio 1
	s_waitcnt lgkmcnt(0)
	v_mfma_f32_16x16x32_bf16 v[124:127], v[160:163], v[192:195], v[124:127]
	v_mfma_f32_16x16x32_bf16 v[124:127], v[164:167], v[196:199], v[124:127]
	v_mfma_f32_16x16x32_bf16 v[116:119], v[168:171], v[192:195], v[116:119]
	v_mfma_f32_16x16x32_bf16 v[116:119], v[172:175], v[196:199], v[116:119]
	v_mfma_f32_16x16x32_bf16 v[108:111], v[160:163], v[200:203], v[108:111]
	v_mfma_f32_16x16x32_bf16 v[108:111], v[164:167], v[204:207], v[108:111]
	v_mfma_f32_16x16x32_bf16 v[100:103], v[168:171], v[200:203], v[100:103]
	v_mfma_f32_16x16x32_bf16 v[100:103], v[172:175], v[204:207], v[100:103]
	v_mfma_f32_16x16x32_bf16 v[92:95], v[160:163], v[208:211], v[92:95]
	v_mfma_f32_16x16x32_bf16 v[92:95], v[164:167], v[212:215], v[92:95]
	v_mfma_f32_16x16x32_bf16 v[84:87], v[168:171], v[208:211], v[84:87]
	v_mfma_f32_16x16x32_bf16 v[84:87], v[172:175], v[212:215], v[84:87]
	v_mfma_f32_16x16x32_bf16 v[76:79], v[160:163], v[216:219], v[76:79]
	v_mfma_f32_16x16x32_bf16 v[76:79], v[164:167], v[220:223], v[76:79]
	v_mfma_f32_16x16x32_bf16 v[68:71], v[168:171], v[216:219], v[68:71]
	v_mfma_f32_16x16x32_bf16 v[68:71], v[172:175], v[220:223], v[68:71]
	s_setprio 0
	s_setprio 1
	v_mfma_f32_16x16x32_bf16 v[120:123], v[176:179], v[192:195], v[120:123]
	v_mfma_f32_16x16x32_bf16 v[120:123], v[180:183], v[196:199], v[120:123]
	v_mfma_f32_16x16x32_bf16 v[112:115], v[184:187], v[192:195], v[112:115]
	v_mfma_f32_16x16x32_bf16 v[112:115], v[188:191], v[196:199], v[112:115]
	v_mfma_f32_16x16x32_bf16 v[104:107], v[176:179], v[200:203], v[104:107]
	v_mfma_f32_16x16x32_bf16 v[104:107], v[180:183], v[204:207], v[104:107]
	v_mfma_f32_16x16x32_bf16 v[96:99], v[184:187], v[200:203], v[96:99]
	v_mfma_f32_16x16x32_bf16 v[96:99], v[188:191], v[204:207], v[96:99]
	v_mfma_f32_16x16x32_bf16 v[88:91], v[176:179], v[208:211], v[88:91]
	v_mfma_f32_16x16x32_bf16 v[88:91], v[180:183], v[212:215], v[88:91]
	v_mfma_f32_16x16x32_bf16 v[80:83], v[184:187], v[208:211], v[80:83]
	v_mfma_f32_16x16x32_bf16 v[80:83], v[188:191], v[212:215], v[80:83]
	v_mfma_f32_16x16x32_bf16 v[72:75], v[176:179], v[216:219], v[72:75]
	v_mfma_f32_16x16x32_bf16 v[72:75], v[180:183], v[220:223], v[72:75]
	v_mfma_f32_16x16x32_bf16 v[64:67], v[184:187], v[216:219], v[64:67]
	v_mfma_f32_16x16x32_bf16 v[64:67], v[188:191], v[220:223], v[64:67]
	s_setprio 0
	s_barrier
	s_add_i32 s46, s71, s49
	v_lshl_add_u64 v[154:155], v[154:155], 0, s[14:15]
	s_mov_b32 m0, s46
	ds_read_b128 v[192:195], v150 offset:49152
	v_xor_b32_e32 v253, 64, v150
	ds_read_b128 v[196:199], v253 offset:49152
	ds_read_b128 v[200:203], v150 offset:51200
	ds_read_b128 v[204:207], v253 offset:51200
	ds_read_b128 v[208:211], v150 offset:53248
	ds_read_b128 v[212:215], v253 offset:53248
	ds_read_b128 v[216:219], v150 offset:55296
	ds_read_b128 v[220:223], v253 offset:55296
	global_load_lds_dwordx4 v[154:155], off
	s_add_i32 m0, s46, 0x2000
	s_add_u32 s44, s44, 0x40080
	v_lshl_add_u64 v[154:155], v[224:225], 0, s[14:15]
	s_addc_u32 s45, s45, 0
	s_add_i32 s46, s72, s49
	global_load_lds_dwordx4 v[154:155], off
	v_lshl_add_u64 v[154:155], s[44:45], 0, v[132:133]
	s_mov_b32 m0, s46
	s_nop 0
	global_load_lds_dwordx4 v[154:155], off
	v_lshl_add_u64 v[154:155], s[44:45], 0, v[128:129]
	s_add_i32 m0, s46, 0x2000
	s_nop 0
	global_load_lds_dwordx4 v[154:155], off
	v_lshl_add_u64 v[154:155], v[226:227], 0, s[14:15]
	s_mov_b32 m0, s57
	s_nop 0
	global_load_lds_dwordx4 v[154:155], off
	v_lshl_add_u64 v[154:155], v[228:229], 0, s[14:15]
	s_mov_b32 m0, s58
	s_nop 0
	global_load_lds_dwordx4 v[154:155], off
	s_waitcnt vmcnt(8)
	s_waitcnt lgkmcnt(0)
	s_barrier
	s_setprio 1
	s_waitcnt lgkmcnt(0)
	v_mfma_f32_16x16x32_bf16 v[60:63], v[160:163], v[192:195], v[60:63]
	v_mfma_f32_16x16x32_bf16 v[60:63], v[164:167], v[196:199], v[60:63]
	v_mfma_f32_16x16x32_bf16 v[52:55], v[168:171], v[192:195], v[52:55]
	v_mfma_f32_16x16x32_bf16 v[52:55], v[172:175], v[196:199], v[52:55]
	v_mfma_f32_16x16x32_bf16 v[44:47], v[160:163], v[200:203], v[44:47]
	v_mfma_f32_16x16x32_bf16 v[44:47], v[164:167], v[204:207], v[44:47]
	v_mfma_f32_16x16x32_bf16 v[36:39], v[168:171], v[200:203], v[36:39]
	v_mfma_f32_16x16x32_bf16 v[36:39], v[172:175], v[204:207], v[36:39]
	v_mfma_f32_16x16x32_bf16 v[28:31], v[160:163], v[208:211], v[28:31]
	v_mfma_f32_16x16x32_bf16 v[28:31], v[164:167], v[212:215], v[28:31]
	v_mfma_f32_16x16x32_bf16 v[20:23], v[168:171], v[208:211], v[20:23]
	v_mfma_f32_16x16x32_bf16 v[20:23], v[172:175], v[212:215], v[20:23]
	v_mfma_f32_16x16x32_bf16 v[12:15], v[160:163], v[216:219], v[12:15]
	v_mfma_f32_16x16x32_bf16 v[12:15], v[164:167], v[220:223], v[12:15]
	v_mfma_f32_16x16x32_bf16 v[4:7], v[168:171], v[216:219], v[4:7]
	v_mfma_f32_16x16x32_bf16 v[4:7], v[172:175], v[220:223], v[4:7]
	s_setprio 0
	s_setprio 1
	v_mfma_f32_16x16x32_bf16 v[56:59], v[176:179], v[192:195], v[56:59]
	v_mfma_f32_16x16x32_bf16 v[56:59], v[180:183], v[196:199], v[56:59]
	v_mfma_f32_16x16x32_bf16 v[48:51], v[184:187], v[192:195], v[48:51]
	v_mfma_f32_16x16x32_bf16 v[48:51], v[188:191], v[196:199], v[48:51]
	v_mfma_f32_16x16x32_bf16 v[40:43], v[176:179], v[200:203], v[40:43]
	v_mfma_f32_16x16x32_bf16 v[40:43], v[180:183], v[204:207], v[40:43]
	v_mfma_f32_16x16x32_bf16 v[32:35], v[184:187], v[200:203], v[32:35]
	v_mfma_f32_16x16x32_bf16 v[32:35], v[188:191], v[204:207], v[32:35]
	v_mfma_f32_16x16x32_bf16 v[24:27], v[176:179], v[208:211], v[24:27]
	v_mfma_f32_16x16x32_bf16 v[24:27], v[180:183], v[212:215], v[24:27]
	v_mfma_f32_16x16x32_bf16 v[16:19], v[184:187], v[208:211], v[16:19]
	v_mfma_f32_16x16x32_bf16 v[16:19], v[188:191], v[212:215], v[16:19]
	v_mfma_f32_16x16x32_bf16 v[8:11], v[176:179], v[216:219], v[8:11]
	v_mfma_f32_16x16x32_bf16 v[8:11], v[180:183], v[220:223], v[8:11]
	v_mfma_f32_16x16x32_bf16 v[0:3], v[184:187], v[216:219], v[0:3]
	v_mfma_f32_16x16x32_bf16 v[0:3], v[188:191], v[220:223], v[0:3]
	s_setprio 0
	s_barrier
	s_add_i32 s70, s70, 2
	s_add_u32 s68, s68, 0x100
	s_addc_u32 s69, s69, 0
	s_add_u32 s30, s30, 0x100
	s_addc_u32 s31, s31, 0
	s_cmp_gt_u32 s70, 13
	s_cbranch_scc1 .LBB0_1100

.Llast_10:
	v_add_u32_e32 v153, s61, v147
	ds_read_b128 v[160:163], v153
	v_xor_b32_e32 v253, 64, v153
	ds_read_b128 v[164:167], v253
	ds_read_b128 v[168:171], v153 offset:2048
	ds_read_b128 v[172:175], v253 offset:2048
	v_add_u32_e32 v153, s62, v147
	ds_read_b128 v[176:179], v153
	v_xor_b32_e32 v253, 64, v153
	ds_read_b128 v[180:183], v253
	ds_read_b128 v[184:187], v153 offset:2048
	ds_read_b128 v[188:191], v253 offset:2048
	s_add_u32 s46, s30, 0xfffc0080
	s_addc_u32 s47, s31, -1
	s_and_b64 s[44:45], s[44:45], exec
	s_cselect_b32 s47, s25, s47
	s_cselect_b32 s46, s65, s46
	s_cselect_b32 s45, s66, s69
	s_cselect_b32 s44, s67, s68
	v_lshl_add_u64 v[154:155], s[30:31], 0, v[138:139]
	s_add_i32 m0, s52, 0xc000
	ds_read_b128 v[192:195], v150
	v_xor_b32_e32 v253, 64, v150
	ds_read_b128 v[196:199], v253
	ds_read_b128 v[200:203], v150 offset:2048
	ds_read_b128 v[204:207], v253 offset:2048
	ds_read_b128 v[208:211], v150 offset:4096
	ds_read_b128 v[212:215], v253 offset:4096
	ds_read_b128 v[216:219], v150 offset:6144
	ds_read_b128 v[220:223], v253 offset:6144
	global_load_lds_dwordx4 v[154:155], off
	v_lshl_add_u64 v[154:155], s[30:31], 0, v[136:137]
	s_add_i32 m0, s52, 0xe000
	s_nop 0
	global_load_lds_dwordx4 v[154:155], off
	s_waitcnt vmcnt(8)
	s_waitcnt lgkmcnt(0)
	s_barrier
	s_setprio 1
	s_waitcnt lgkmcnt(0)
	v_mfma_f32_16x16x32_bf16 v[124:127], v[160:163], v[192:195], v[124:127]
	v_mfma_f32_16x16x32_bf16 v[124:127], v[164:167], v[196:199], v[124:127]
	v_mfma_f32_16x16x32_bf16 v[116:119], v[168:171], v[192:195], v[116:119]
	v_mfma_f32_16x16x32_bf16 v[116:119], v[172:175], v[196:199], v[116:119]
	v_mfma_f32_16x16x32_bf16 v[108:111], v[160:163], v[200:203], v[108:111]
	v_mfma_f32_16x16x32_bf16 v[108:111], v[164:167], v[204:207], v[108:111]
	v_mfma_f32_16x16x32_bf16 v[100:103], v[168:171], v[200:203], v[100:103]
	v_mfma_f32_16x16x32_bf16 v[100:103], v[172:175], v[204:207], v[100:103]
	v_mfma_f32_16x16x32_bf16 v[92:95], v[160:163], v[208:211], v[92:95]
	v_mfma_f32_16x16x32_bf16 v[92:95], v[164:167], v[212:215], v[92:95]
	v_mfma_f32_16x16x32_bf16 v[84:87], v[168:171], v[208:211], v[84:87]
	v_mfma_f32_16x16x32_bf16 v[84:87], v[172:175], v[212:215], v[84:87]
	v_mfma_f32_16x16x32_bf16 v[76:79], v[160:163], v[216:219], v[76:79]
	v_mfma_f32_16x16x32_bf16 v[76:79], v[164:167], v[220:223], v[76:79]
	v_mfma_f32_16x16x32_bf16 v[68:71], v[168:171], v[216:219], v[68:71]
	v_mfma_f32_16x16x32_bf16 v[68:71], v[172:175], v[220:223], v[68:71]
	s_setprio 0
	s_setprio 1
	v_mfma_f32_16x16x32_bf16 v[120:123], v[176:179], v[192:195], v[120:123]
	v_mfma_f32_16x16x32_bf16 v[120:123], v[180:183], v[196:199], v[120:123]
	v_mfma_f32_16x16x32_bf16 v[112:115], v[184:187], v[192:195], v[112:115]
	v_mfma_f32_16x16x32_bf16 v[112:115], v[188:191], v[196:199], v[112:115]
	v_mfma_f32_16x16x32_bf16 v[104:107], v[176:179], v[200:203], v[104:107]
	v_mfma_f32_16x16x32_bf16 v[104:107], v[180:183], v[204:207], v[104:107]
	v_mfma_f32_16x16x32_bf16 v[96:99], v[184:187], v[200:203], v[96:99]
	v_mfma_f32_16x16x32_bf16 v[96:99], v[188:191], v[204:207], v[96:99]
	v_mfma_f32_16x16x32_bf16 v[88:91], v[176:179], v[208:211], v[88:91]
	v_mfma_f32_16x16x32_bf16 v[88:91], v[180:183], v[212:215], v[88:91]
	v_mfma_f32_16x16x32_bf16 v[80:83], v[184:187], v[208:211], v[80:83]
	v_mfma_f32_16x16x32_bf16 v[80:83], v[188:191], v[212:215], v[80:83]
	v_mfma_f32_16x16x32_bf16 v[72:75], v[176:179], v[216:219], v[72:75]
	v_mfma_f32_16x16x32_bf16 v[72:75], v[180:183], v[220:223], v[72:75]
	v_mfma_f32_16x16x32_bf16 v[64:67], v[184:187], v[216:219], v[64:67]
	v_mfma_f32_16x16x32_bf16 v[64:67], v[188:191], v[220:223], v[64:67]
	s_setprio 0
	s_barrier
	s_add_i32 s71, s61, s49
	v_lshl_add_u64 v[154:155], s[44:45], 0, v[132:133]
	s_mov_b32 m0, s71
	ds_read_b128 v[192:195], v150 offset:16384
	v_xor_b32_e32 v253, 64, v150
	ds_read_b128 v[196:199], v253 offset:16384
	ds_read_b128 v[200:203], v150 offset:18432
	ds_read_b128 v[204:207], v253 offset:18432
	ds_read_b128 v[208:211], v150 offset:20480
	ds_read_b128 v[212:215], v253 offset:20480
	ds_read_b128 v[216:219], v150 offset:22528
	ds_read_b128 v[220:223], v253 offset:22528
	global_load_lds_dwordx4 v[154:155], off
	s_add_i32 m0, s71, 0x2000
	s_add_u32 s72, s44, 0x40000
	v_lshl_add_u64 v[224:225], s[44:45], 0, v[128:129]
	s_addc_u32 s73, s45, 0
	s_add_i32 s71, s62, s49
	global_load_lds_dwordx4 v[224:225], off
	v_lshl_add_u64 v[226:227], s[72:73], 0, v[132:133]
	s_mov_b32 m0, s71
	v_lshl_add_u64 v[228:229], s[46:47], 0, v[130:131]
	global_load_lds_dwordx4 v[226:227], off
	v_lshl_add_u64 v[226:227], s[72:73], 0, v[128:129]
	s_add_i32 m0, s71, 0x2000
	s_nop 0
	global_load_lds_dwordx4 v[226:227], off
	v_lshl_add_u64 v[226:227], s[46:47], 0, v[134:135]
	s_mov_b32 m0, s52
	s_nop 0
	global_load_lds_dwordx4 v[226:227], off
	s_mov_b32 m0, s53
	s_nop 0
	global_load_lds_dwordx4 v[228:229], off
	s_waitcnt vmcnt(8)
	s_waitcnt lgkmcnt(0)
	s_barrier
	s_setprio 1
	s_waitcnt lgkmcnt(0)
	v_mfma_f32_16x16x32_bf16 v[60:63], v[160:163], v[192:195], v[60:63]
	v_mfma_f32_16x16x32_bf16 v[60:63], v[164:167], v[196:199], v[60:63]
	v_mfma_f32_16x16x32_bf16 v[52:55], v[168:171], v[192:195], v[52:55]
	v_mfma_f32_16x16x32_bf16 v[52:55], v[172:175], v[196:199], v[52:55]
	v_mfma_f32_16x16x32_bf16 v[44:47], v[160:163], v[200:203], v[44:47]
	v_mfma_f32_16x16x32_bf16 v[44:47], v[164:167], v[204:207], v[44:47]
	v_mfma_f32_16x16x32_bf16 v[36:39], v[168:171], v[200:203], v[36:39]
	v_mfma_f32_16x16x32_bf16 v[36:39], v[172:175], v[204:207], v[36:39]
	v_mfma_f32_16x16x32_bf16 v[28:31], v[160:163], v[208:211], v[28:31]
	v_mfma_f32_16x16x32_bf16 v[28:31], v[164:167], v[212:215], v[28:31]
	v_mfma_f32_16x16x32_bf16 v[20:23], v[168:171], v[208:211], v[20:23]
	v_mfma_f32_16x16x32_bf16 v[20:23], v[172:175], v[212:215], v[20:23]
	v_mfma_f32_16x16x32_bf16 v[12:15], v[160:163], v[216:219], v[12:15]
	v_mfma_f32_16x16x32_bf16 v[12:15], v[164:167], v[220:223], v[12:15]
	v_mfma_f32_16x16x32_bf16 v[4:7], v[168:171], v[216:219], v[4:7]
	v_mfma_f32_16x16x32_bf16 v[4:7], v[172:175], v[220:223], v[4:7]
	s_setprio 0
	s_setprio 1
	v_mfma_f32_16x16x32_bf16 v[56:59], v[176:179], v[192:195], v[56:59]
	v_mfma_f32_16x16x32_bf16 v[56:59], v[180:183], v[196:199], v[56:59]
	v_mfma_f32_16x16x32_bf16 v[48:51], v[184:187], v[192:195], v[48:51]
	v_mfma_f32_16x16x32_bf16 v[48:51], v[188:191], v[196:199], v[48:51]
	v_mfma_f32_16x16x32_bf16 v[40:43], v[176:179], v[200:203], v[40:43]
	v_mfma_f32_16x16x32_bf16 v[40:43], v[180:183], v[204:207], v[40:43]
	v_mfma_f32_16x16x32_bf16 v[32:35], v[184:187], v[200:203], v[32:35]
	v_mfma_f32_16x16x32_bf16 v[32:35], v[188:191], v[204:207], v[32:35]
	v_mfma_f32_16x16x32_bf16 v[24:27], v[176:179], v[208:211], v[24:27]
	v_mfma_f32_16x16x32_bf16 v[24:27], v[180:183], v[212:215], v[24:27]
	v_mfma_f32_16x16x32_bf16 v[16:19], v[184:187], v[208:211], v[16:19]
	v_mfma_f32_16x16x32_bf16 v[16:19], v[188:191], v[212:215], v[16:19]
	v_mfma_f32_16x16x32_bf16 v[8:11], v[176:179], v[216:219], v[8:11]
	v_mfma_f32_16x16x32_bf16 v[8:11], v[180:183], v[220:223], v[8:11]
	v_mfma_f32_16x16x32_bf16 v[0:3], v[184:187], v[216:219], v[0:3]
	v_mfma_f32_16x16x32_bf16 v[0:3], v[188:191], v[220:223], v[0:3]
	s_setprio 0
	s_barrier
	s_add_i32 s71, 0, 0x18000
	v_add_u32_e32 v153, s71, v147
	s_add_i32 s72, 0, 0x1c000
	ds_read_b128 v[160:163], v153
	v_xor_b32_e32 v253, 64, v153
	ds_read_b128 v[164:167], v253
	ds_read_b128 v[168:171], v153 offset:2048
	ds_read_b128 v[172:175], v253 offset:2048
	v_add_u32_e32 v153, s72, v147
	ds_read_b128 v[176:179], v153
	v_xor_b32_e32 v253, 64, v153
	ds_read_b128 v[180:183], v253
	ds_read_b128 v[184:187], v153 offset:2048
	ds_read_b128 v[188:191], v253 offset:2048
	s_add_u32 s46, s46, 0x40000
	s_addc_u32 s47, s47, 0
	s_mov_b32 m0, s54
	v_lshl_add_u64 v[230:231], s[46:47], 0, v[134:135]
	ds_read_b128 v[192:195], v150 offset:32768
	v_xor_b32_e32 v253, 64, v150
	ds_read_b128 v[196:199], v253 offset:32768
	ds_read_b128 v[200:203], v150 offset:34816
	ds_read_b128 v[204:207], v253 offset:34816
	ds_read_b128 v[208:211], v150 offset:36864
	ds_read_b128 v[212:215], v253 offset:36864
	ds_read_b128 v[216:219], v150 offset:38912
	ds_read_b128 v[220:223], v253 offset:38912
	global_load_lds_dwordx4 v[230:231], off
	v_lshl_add_u64 v[230:231], s[46:47], 0, v[130:131]
	s_mov_b32 m0, s55
	s_nop 0
	global_load_lds_dwordx4 v[230:231], off
	s_waitcnt vmcnt(8)
	s_waitcnt lgkmcnt(0)
	s_barrier
	s_setprio 1
	s_waitcnt lgkmcnt(0)
	v_mfma_f32_16x16x32_bf16 v[124:127], v[160:163], v[192:195], v[124:127]
	v_mfma_f32_16x16x32_bf16 v[124:127], v[164:167], v[196:199], v[124:127]
	v_mfma_f32_16x16x32_bf16 v[116:119], v[168:171], v[192:195], v[116:119]
	v_mfma_f32_16x16x32_bf16 v[116:119], v[172:175], v[196:199], v[116:119]
	v_mfma_f32_16x16x32_bf16 v[108:111], v[160:163], v[200:203], v[108:111]
	v_mfma_f32_16x16x32_bf16 v[108:111], v[164:167], v[204:207], v[108:111]
	v_mfma_f32_16x16x32_bf16 v[100:103], v[168:171], v[200:203], v[100:103]
	v_mfma_f32_16x16x32_bf16 v[100:103], v[172:175], v[204:207], v[100:103]
	v_mfma_f32_16x16x32_bf16 v[92:95], v[160:163], v[208:211], v[92:95]
	v_mfma_f32_16x16x32_bf16 v[92:95], v[164:167], v[212:215], v[92:95]
	v_mfma_f32_16x16x32_bf16 v[84:87], v[168:171], v[208:211], v[84:87]
	v_mfma_f32_16x16x32_bf16 v[84:87], v[172:175], v[212:215], v[84:87]
	v_mfma_f32_16x16x32_bf16 v[76:79], v[160:163], v[216:219], v[76:79]
	v_mfma_f32_16x16x32_bf16 v[76:79], v[164:167], v[220:223], v[76:79]
	v_mfma_f32_16x16x32_bf16 v[68:71], v[168:171], v[216:219], v[68:71]
	v_mfma_f32_16x16x32_bf16 v[68:71], v[172:175], v[220:223], v[68:71]
	s_setprio 0
	s_setprio 1
	v_mfma_f32_16x16x32_bf16 v[120:123], v[176:179], v[192:195], v[120:123]
	v_mfma_f32_16x16x32_bf16 v[120:123], v[180:183], v[196:199], v[120:123]
	v_mfma_f32_16x16x32_bf16 v[112:115], v[184:187], v[192:195], v[112:115]
	v_mfma_f32_16x16x32_bf16 v[112:115], v[188:191], v[196:199], v[112:115]
	v_mfma_f32_16x16x32_bf16 v[104:107], v[176:179], v[200:203], v[104:107]
	v_mfma_f32_16x16x32_bf16 v[104:107], v[180:183], v[204:207], v[104:107]
	v_mfma_f32_16x16x32_bf16 v[96:99], v[184:187], v[200:203], v[96:99]
	v_mfma_f32_16x16x32_bf16 v[96:99], v[188:191], v[204:207], v[96:99]
	v_mfma_f32_16x16x32_bf16 v[88:91], v[176:179], v[208:211], v[88:91]
	v_mfma_f32_16x16x32_bf16 v[88:91], v[180:183], v[212:215], v[88:91]
	v_mfma_f32_16x16x32_bf16 v[80:83], v[184:187], v[208:211], v[80:83]
	v_mfma_f32_16x16x32_bf16 v[80:83], v[188:191], v[212:215], v[80:83]
	v_mfma_f32_16x16x32_bf16 v[72:75], v[176:179], v[216:219], v[72:75]
	v_mfma_f32_16x16x32_bf16 v[72:75], v[180:183], v[220:223], v[72:75]
	v_mfma_f32_16x16x32_bf16 v[64:67], v[184:187], v[216:219], v[64:67]
	v_mfma_f32_16x16x32_bf16 v[64:67], v[188:191], v[220:223], v[64:67]
	s_setprio 0
	s_barrier
	v_add_u32_e32 v234, 0x21000, v151
	ds_read_b128 v[236:239], v234
	ds_read_b128 v[240:243], v234 offset:256
	ds_read_b128 v[244:247], v234 offset:512
	ds_read_b128 v[248:251], v234 offset:768
	v_add_u32_e32 v235, s23, v146
	v_mul_u32_u24_e32 v235, 0x1600, v235
	v_lshl_or_b32 v234, s64, 7, v149
	v_lshl_add_u32 v235, v234, 1, v235
	s_add_i32 s46, s71, s49
	v_lshl_add_u64 v[154:155], v[154:155], 0, s[14:15]
	s_mov_b32 m0, s46
	ds_read_b128 v[192:195], v150 offset:49152
	v_xor_b32_e32 v253, 64, v150
	ds_read_b128 v[196:199], v253 offset:49152
	ds_read_b128 v[200:203], v150 offset:51200
	ds_read_b128 v[204:207], v253 offset:51200
	ds_read_b128 v[208:211], v150 offset:53248
	ds_read_b128 v[212:215], v253 offset:53248
	ds_read_b128 v[216:219], v150 offset:55296
	ds_read_b128 v[220:223], v253 offset:55296
	global_load_lds_dwordx4 v[154:155], off
	s_add_i32 m0, s46, 0x2000
	s_add_u32 s44, s44, 0x40080
	v_lshl_add_u64 v[154:155], v[224:225], 0, s[14:15]
	s_addc_u32 s45, s45, 0
	s_add_i32 s46, s72, s49
	global_load_lds_dwordx4 v[154:155], off
	v_lshl_add_u64 v[154:155], s[44:45], 0, v[132:133]
	s_mov_b32 m0, s46
	s_nop 0
	global_load_lds_dwordx4 v[154:155], off
	v_lshl_add_u64 v[154:155], s[44:45], 0, v[128:129]
	s_add_i32 m0, s46, 0x2000
	s_nop 0
	global_load_lds_dwordx4 v[154:155], off
	v_lshl_add_u64 v[154:155], v[226:227], 0, s[14:15]
	s_mov_b32 m0, s57
	s_nop 0
	global_load_lds_dwordx4 v[154:155], off
	v_lshl_add_u64 v[154:155], v[228:229], 0, s[14:15]
	s_mov_b32 m0, s58
	s_nop 0
	global_load_lds_dwordx4 v[154:155], off
	s_waitcnt lgkmcnt(8)
	v_add_f32_e32 v236, v236, v237
	v_add_f32_e32 v238, v238, v239
	v_add_f32_e32 v240, v240, v241
	v_add_f32_e32 v242, v242, v243
	v_add_f32_e32 v244, v244, v245
	v_add_f32_e32 v246, v246, v247
	v_add_f32_e32 v248, v248, v249
	v_add_f32_e32 v250, v250, v251
	v_add_f32_e32 v236, v236, v238
	v_add_f32_e32 v240, v240, v242
	v_add_f32_e32 v244, v244, v246
	v_add_f32_e32 v248, v248, v250
	v_fmamk_f32 v236, v236, 0x3a800000, v152
	v_fmamk_f32 v240, v240, 0x3a800000, v152
	v_fmamk_f32 v244, v244, 0x3a800000, v152
	v_fmamk_f32 v248, v248, 0x3a800000, v152
	v_rsq_f32_e32 v236, v236
	v_rsq_f32_e32 v240, v240
	v_rsq_f32_e32 v244, v244
	v_rsq_f32_e32 v248, v248
	v_mul_f32_e32 v252, 0xbfb8aa3b, v236
	v_mul_f32_e32 v254, v236, v236
	v_pk_mul_f32 v[120:121], v[124:125], v[120:121]
	v_pk_mul_f32 v[122:123], v[126:127], v[122:123]
	v_pk_mul_f32 v[112:113], v[116:117], v[112:113]
	v_pk_mul_f32 v[114:115], v[118:119], v[114:115]
	v_pk_mul_f32 v[124:125], v[124:125], v[252:253] op_sel_hi:[1,0]
	v_pk_mul_f32 v[126:127], v[126:127], v[252:253] op_sel_hi:[1,0]
	v_pk_mul_f32 v[116:117], v[116:117], v[252:253] op_sel_hi:[1,0]
	v_pk_mul_f32 v[118:119], v[118:119], v[252:253] op_sel_hi:[1,0]
	v_exp_f32_e32 v124, v124
	v_exp_f32_e32 v125, v125
	v_exp_f32_e32 v126, v126
	v_exp_f32_e32 v127, v127
	v_exp_f32_e32 v116, v116
	v_exp_f32_e32 v117, v117
	v_exp_f32_e32 v118, v118
	v_exp_f32_e32 v119, v119
	v_pk_add_f32 v[124:125], v[124:125], 1.0 op_sel_hi:[1,0]
	v_pk_add_f32 v[126:127], v[126:127], 1.0 op_sel_hi:[1,0]
	v_pk_add_f32 v[116:117], v[116:117], 1.0 op_sel_hi:[1,0]
	v_pk_add_f32 v[118:119], v[118:119], 1.0 op_sel_hi:[1,0]
	v_rcp_f32_e32 v124, v124
	v_rcp_f32_e32 v125, v125
	v_rcp_f32_e32 v126, v126
	v_rcp_f32_e32 v127, v127
	v_rcp_f32_e32 v116, v116
	v_rcp_f32_e32 v117, v117
	v_rcp_f32_e32 v118, v118
	v_rcp_f32_e32 v119, v119
	v_pk_mul_f32 v[120:121], v[120:121], v[254:255] op_sel_hi:[1,0]
	v_pk_mul_f32 v[122:123], v[122:123], v[254:255] op_sel_hi:[1,0]
	v_pk_mul_f32 v[112:113], v[112:113], v[254:255] op_sel_hi:[1,0]
	v_pk_mul_f32 v[114:115], v[114:115], v[254:255] op_sel_hi:[1,0]
	v_pk_mul_f32 v[120:121], v[120:121], v[124:125]
	v_pk_mul_f32 v[122:123], v[122:123], v[126:127]
	v_pk_mul_f32 v[112:113], v[112:113], v[116:117]
	v_pk_mul_f32 v[114:115], v[114:115], v[118:119]
	v_cvt_pk_bf16_f32 v120, v120, v121
	v_cvt_pk_bf16_f32 v121, v122, v123
	v_cvt_pk_bf16_f32 v122, v112, v113
	v_cvt_pk_bf16_f32 v123, v114, v115
	global_store_dwordx4 v235, v[120:123], s[10:11]
	v_add_u32_e32 v234, 0x16000, v235
	v_mul_f32_e32 v252, 0xbfb8aa3b, v240
	v_mul_f32_e32 v254, v240, v240
	v_pk_mul_f32 v[104:105], v[108:109], v[104:105]
	v_pk_mul_f32 v[106:107], v[110:111], v[106:107]
	v_pk_mul_f32 v[96:97], v[100:101], v[96:97]
	v_pk_mul_f32 v[98:99], v[102:103], v[98:99]
	v_pk_mul_f32 v[108:109], v[108:109], v[252:253] op_sel_hi:[1,0]
	v_pk_mul_f32 v[110:111], v[110:111], v[252:253] op_sel_hi:[1,0]
	v_pk_mul_f32 v[100:101], v[100:101], v[252:253] op_sel_hi:[1,0]
	v_pk_mul_f32 v[102:103], v[102:103], v[252:253] op_sel_hi:[1,0]
	v_exp_f32_e32 v108, v108
	v_exp_f32_e32 v109, v109
	v_exp_f32_e32 v110, v110
	v_exp_f32_e32 v111, v111
	v_exp_f32_e32 v100, v100
	v_exp_f32_e32 v101, v101
	v_exp_f32_e32 v102, v102
	v_exp_f32_e32 v103, v103
	v_pk_add_f32 v[108:109], v[108:109], 1.0 op_sel_hi:[1,0]
	v_pk_add_f32 v[110:111], v[110:111], 1.0 op_sel_hi:[1,0]
	v_pk_add_f32 v[100:101], v[100:101], 1.0 op_sel_hi:[1,0]
	v_pk_add_f32 v[102:103], v[102:103], 1.0 op_sel_hi:[1,0]
	v_rcp_f32_e32 v108, v108
	v_rcp_f32_e32 v109, v109
	v_rcp_f32_e32 v110, v110
	v_rcp_f32_e32 v111, v111
	v_rcp_f32_e32 v100, v100
	v_rcp_f32_e32 v101, v101
	v_rcp_f32_e32 v102, v102
	v_rcp_f32_e32 v103, v103
	v_pk_mul_f32 v[104:105], v[104:105], v[254:255] op_sel_hi:[1,0]
	v_pk_mul_f32 v[106:107], v[106:107], v[254:255] op_sel_hi:[1,0]
	v_pk_mul_f32 v[96:97], v[96:97], v[254:255] op_sel_hi:[1,0]
	v_pk_mul_f32 v[98:99], v[98:99], v[254:255] op_sel_hi:[1,0]
	v_pk_mul_f32 v[104:105], v[104:105], v[108:109]
	v_pk_mul_f32 v[106:107], v[106:107], v[110:111]
	v_pk_mul_f32 v[96:97], v[96:97], v[100:101]
	v_pk_mul_f32 v[98:99], v[98:99], v[102:103]
	v_cvt_pk_bf16_f32 v104, v104, v105
	v_cvt_pk_bf16_f32 v105, v106, v107
	v_cvt_pk_bf16_f32 v106, v96, v97
	v_cvt_pk_bf16_f32 v107, v98, v99
	global_store_dwordx4 v234, v[104:107], s[10:11]
	v_add_u32_e32 v235, 0x16000, v234
	v_mul_f32_e32 v252, 0xbfb8aa3b, v244
	v_mul_f32_e32 v254, v244, v244
	v_pk_mul_f32 v[88:89], v[92:93], v[88:89]
	v_pk_mul_f32 v[90:91], v[94:95], v[90:91]
	v_pk_mul_f32 v[80:81], v[84:85], v[80:81]
	v_pk_mul_f32 v[82:83], v[86:87], v[82:83]
	v_pk_mul_f32 v[92:93], v[92:93], v[252:253] op_sel_hi:[1,0]
	v_pk_mul_f32 v[94:95], v[94:95], v[252:253] op_sel_hi:[1,0]
	v_pk_mul_f32 v[84:85], v[84:85], v[252:253] op_sel_hi:[1,0]
	v_pk_mul_f32 v[86:87], v[86:87], v[252:253] op_sel_hi:[1,0]
	v_exp_f32_e32 v92, v92
	v_exp_f32_e32 v93, v93
	v_exp_f32_e32 v94, v94
	v_exp_f32_e32 v95, v95
	v_exp_f32_e32 v84, v84
	v_exp_f32_e32 v85, v85
	v_exp_f32_e32 v86, v86
	v_exp_f32_e32 v87, v87
	v_pk_add_f32 v[92:93], v[92:93], 1.0 op_sel_hi:[1,0]
	v_pk_add_f32 v[94:95], v[94:95], 1.0 op_sel_hi:[1,0]
	v_pk_add_f32 v[84:85], v[84:85], 1.0 op_sel_hi:[1,0]
	v_pk_add_f32 v[86:87], v[86:87], 1.0 op_sel_hi:[1,0]
	v_rcp_f32_e32 v92, v92
	v_rcp_f32_e32 v93, v93
	v_rcp_f32_e32 v94, v94
	v_rcp_f32_e32 v95, v95
	v_rcp_f32_e32 v84, v84
	v_rcp_f32_e32 v85, v85
	v_rcp_f32_e32 v86, v86
	v_rcp_f32_e32 v87, v87
	v_pk_mul_f32 v[88:89], v[88:89], v[254:255] op_sel_hi:[1,0]
	v_pk_mul_f32 v[90:91], v[90:91], v[254:255] op_sel_hi:[1,0]
	v_pk_mul_f32 v[80:81], v[80:81], v[254:255] op_sel_hi:[1,0]
	v_pk_mul_f32 v[82:83], v[82:83], v[254:255] op_sel_hi:[1,0]
	v_pk_mul_f32 v[88:89], v[88:89], v[92:93]
	v_pk_mul_f32 v[90:91], v[90:91], v[94:95]
	v_pk_mul_f32 v[80:81], v[80:81], v[84:85]
	v_pk_mul_f32 v[82:83], v[82:83], v[86:87]
	v_cvt_pk_bf16_f32 v88, v88, v89
	v_cvt_pk_bf16_f32 v89, v90, v91
	v_cvt_pk_bf16_f32 v90, v80, v81
	v_cvt_pk_bf16_f32 v91, v82, v83
	global_store_dwordx4 v235, v[88:91], s[10:11]
	v_add_u32_e32 v234, 0x16000, v235
	v_mul_f32_e32 v252, 0xbfb8aa3b, v248
	v_mul_f32_e32 v254, v248, v248
	v_pk_mul_f32 v[72:73], v[76:77], v[72:73]
	v_pk_mul_f32 v[74:75], v[78:79], v[74:75]
	v_pk_mul_f32 v[64:65], v[68:69], v[64:65]
	v_pk_mul_f32 v[66:67], v[70:71], v[66:67]
	v_pk_mul_f32 v[76:77], v[76:77], v[252:253] op_sel_hi:[1,0]
	v_pk_mul_f32 v[78:79], v[78:79], v[252:253] op_sel_hi:[1,0]
	v_pk_mul_f32 v[68:69], v[68:69], v[252:253] op_sel_hi:[1,0]
	v_pk_mul_f32 v[70:71], v[70:71], v[252:253] op_sel_hi:[1,0]
	v_exp_f32_e32 v76, v76
	v_exp_f32_e32 v77, v77
	v_exp_f32_e32 v78, v78
	v_exp_f32_e32 v79, v79
	v_exp_f32_e32 v68, v68
	v_exp_f32_e32 v69, v69
	v_exp_f32_e32 v70, v70
	v_exp_f32_e32 v71, v71
	v_pk_add_f32 v[76:77], v[76:77], 1.0 op_sel_hi:[1,0]
	v_pk_add_f32 v[78:79], v[78:79], 1.0 op_sel_hi:[1,0]
	v_pk_add_f32 v[68:69], v[68:69], 1.0 op_sel_hi:[1,0]
	v_pk_add_f32 v[70:71], v[70:71], 1.0 op_sel_hi:[1,0]
	v_rcp_f32_e32 v76, v76
	v_rcp_f32_e32 v77, v77
	v_rcp_f32_e32 v78, v78
	v_rcp_f32_e32 v79, v79
	v_rcp_f32_e32 v68, v68
	v_rcp_f32_e32 v69, v69
	v_rcp_f32_e32 v70, v70
	v_rcp_f32_e32 v71, v71
	v_pk_mul_f32 v[72:73], v[72:73], v[254:255] op_sel_hi:[1,0]
	v_pk_mul_f32 v[74:75], v[74:75], v[254:255] op_sel_hi:[1,0]
	v_pk_mul_f32 v[64:65], v[64:65], v[254:255] op_sel_hi:[1,0]
	v_pk_mul_f32 v[66:67], v[66:67], v[254:255] op_sel_hi:[1,0]
	v_pk_mul_f32 v[72:73], v[72:73], v[76:77]
	v_pk_mul_f32 v[74:75], v[74:75], v[78:79]
	v_pk_mul_f32 v[64:65], v[64:65], v[68:69]
	v_pk_mul_f32 v[66:67], v[66:67], v[70:71]
	v_cvt_pk_bf16_f32 v72, v72, v73
	v_cvt_pk_bf16_f32 v73, v74, v75
	v_cvt_pk_bf16_f32 v74, v64, v65
	v_cvt_pk_bf16_f32 v75, v66, v67
	global_store_dwordx4 v234, v[72:75], s[10:11]
	s_waitcnt vmcnt(12)
	s_waitcnt lgkmcnt(0)
	s_barrier
	s_setprio 1
	s_waitcnt lgkmcnt(0)
	v_mfma_f32_16x16x32_bf16 v[60:63], v[160:163], v[192:195], v[60:63]
	v_mfma_f32_16x16x32_bf16 v[60:63], v[164:167], v[196:199], v[60:63]
	v_mfma_f32_16x16x32_bf16 v[52:55], v[168:171], v[192:195], v[52:55]
	v_mfma_f32_16x16x32_bf16 v[52:55], v[172:175], v[196:199], v[52:55]
	v_mfma_f32_16x16x32_bf16 v[44:47], v[160:163], v[200:203], v[44:47]
	v_mfma_f32_16x16x32_bf16 v[44:47], v[164:167], v[204:207], v[44:47]
	v_mfma_f32_16x16x32_bf16 v[36:39], v[168:171], v[200:203], v[36:39]
	v_mfma_f32_16x16x32_bf16 v[36:39], v[172:175], v[204:207], v[36:39]
	v_mfma_f32_16x16x32_bf16 v[28:31], v[160:163], v[208:211], v[28:31]
	v_mfma_f32_16x16x32_bf16 v[28:31], v[164:167], v[212:215], v[28:31]
	v_mfma_f32_16x16x32_bf16 v[20:23], v[168:171], v[208:211], v[20:23]
	v_mfma_f32_16x16x32_bf16 v[20:23], v[172:175], v[212:215], v[20:23]
	v_mfma_f32_16x16x32_bf16 v[12:15], v[160:163], v[216:219], v[12:15]
	v_mfma_f32_16x16x32_bf16 v[12:15], v[164:167], v[220:223], v[12:15]
	v_mfma_f32_16x16x32_bf16 v[4:7], v[168:171], v[216:219], v[4:7]
	v_mfma_f32_16x16x32_bf16 v[4:7], v[172:175], v[220:223], v[4:7]
	s_setprio 0
	s_setprio 1
	v_mfma_f32_16x16x32_bf16 v[56:59], v[176:179], v[192:195], v[56:59]
	v_mfma_f32_16x16x32_bf16 v[56:59], v[180:183], v[196:199], v[56:59]
	v_mfma_f32_16x16x32_bf16 v[48:51], v[184:187], v[192:195], v[48:51]
	v_mfma_f32_16x16x32_bf16 v[48:51], v[188:191], v[196:199], v[48:51]
	v_mfma_f32_16x16x32_bf16 v[40:43], v[176:179], v[200:203], v[40:43]
	v_mfma_f32_16x16x32_bf16 v[40:43], v[180:183], v[204:207], v[40:43]
	v_mfma_f32_16x16x32_bf16 v[32:35], v[184:187], v[200:203], v[32:35]
	v_mfma_f32_16x16x32_bf16 v[32:35], v[188:191], v[204:207], v[32:35]
	v_mfma_f32_16x16x32_bf16 v[24:27], v[176:179], v[208:211], v[24:27]
	v_mfma_f32_16x16x32_bf16 v[24:27], v[180:183], v[212:215], v[24:27]
	v_mfma_f32_16x16x32_bf16 v[16:19], v[184:187], v[208:211], v[16:19]
	v_mfma_f32_16x16x32_bf16 v[16:19], v[188:191], v[212:215], v[16:19]
	v_mfma_f32_16x16x32_bf16 v[8:11], v[176:179], v[216:219], v[8:11]
	v_mfma_f32_16x16x32_bf16 v[8:11], v[180:183], v[220:223], v[8:11]
	v_mfma_f32_16x16x32_bf16 v[0:3], v[184:187], v[216:219], v[0:3]
	v_mfma_f32_16x16x32_bf16 v[0:3], v[188:191], v[220:223], v[0:3]
	s_setprio 0
	s_barrier
	s_add_i32 s70, s70, 2
	s_add_u32 s68, s68, 0x100
	s_addc_u32 s69, s69, 0
	s_add_u32 s30, s30, 0x100
	s_addc_u32 s31, s31, 0

.LBB0_1180:
	s_add_u32 s72, s50, 0x100
	s_addc_u32 s73, s51, 0
	s_mov_b32 s74, -2
	s_waitcnt lgkmcnt(0)
	s_cmp_eq_u32 s63, 1
	s_cbranch_scc1 .Lfa_11
	ds_read_b128 v[128:131], v188
	v_xor_b32_e32 v253, 64, v188
	ds_read_b128 v[132:135], v253
	ds_read_b128 v[136:139], v188 offset:2048
	ds_read_b128 v[140:143], v253 offset:2048
	ds_read_b128 v[144:147], v189
	v_xor_b32_e32 v253, 64, v189
	ds_read_b128 v[148:151], v253
	ds_read_b128 v[172:175], v189 offset:2048
	ds_read_b128 v[176:179], v253 offset:2048
	s_add_u32 s50, s48, 0x100
	s_addc_u32 s51, s49, 0
	s_cmp_eq_u32 s74, 40
	s_cselect_b32 s55, s11, s51
	s_cselect_b32 s54, s10, s50
	s_cselect_b32 s53, s47, s73
	s_cselect_b32 s52, s46, s72
	v_lshl_add_u64 v[220:221], s[48:49], 0, v[166:167]
	s_add_i32 m0, s59, 0xc000
	ds_read_b128 v[180:183], v190
	v_xor_b32_e32 v253, 64, v190
	ds_read_b128 v[192:195], v253
	ds_read_b128 v[196:199], v190 offset:2048
	ds_read_b128 v[200:203], v253 offset:2048
	ds_read_b128 v[204:207], v190 offset:4096
	ds_read_b128 v[208:211], v253 offset:4096
	ds_read_b128 v[212:215], v190 offset:6144
	ds_read_b128 v[216:219], v253 offset:6144
	global_load_lds_dwordx4 v[220:221], off
	v_lshl_add_u64 v[220:221], s[48:49], 0, v[164:165]
	s_add_i32 m0, s59, 0xe000
	s_nop 0
	global_load_lds_dwordx4 v[220:221], off
	s_waitcnt vmcnt(24)
	s_waitcnt lgkmcnt(0)
	s_barrier
	s_setprio 1
	s_waitcnt lgkmcnt(0)
	v_mfma_f32_16x16x32_bf16 v[124:127], v[128:131], v[180:183], 0
	v_mfma_f32_16x16x32_bf16 v[120:123], v[136:139], v[180:183], 0
	v_mfma_f32_16x16x32_bf16 v[108:111], v[128:131], v[196:199], 0
	v_mfma_f32_16x16x32_bf16 v[104:107], v[136:139], v[196:199], 0
	v_mfma_f32_16x16x32_bf16 v[92:95], v[128:131], v[204:207], 0
	v_mfma_f32_16x16x32_bf16 v[88:91], v[136:139], v[204:207], 0
	v_mfma_f32_16x16x32_bf16 v[76:79], v[128:131], v[212:215], 0
	v_mfma_f32_16x16x32_bf16 v[72:75], v[136:139], v[212:215], 0
	v_mfma_f32_16x16x32_bf16 v[124:127], v[132:135], v[192:195], v[124:127]
	v_mfma_f32_16x16x32_bf16 v[120:123], v[140:143], v[192:195], v[120:123]
	v_mfma_f32_16x16x32_bf16 v[108:111], v[132:135], v[200:203], v[108:111]
	v_mfma_f32_16x16x32_bf16 v[104:107], v[140:143], v[200:203], v[104:107]
	v_mfma_f32_16x16x32_bf16 v[92:95], v[132:135], v[208:211], v[92:95]
	v_mfma_f32_16x16x32_bf16 v[88:91], v[140:143], v[208:211], v[88:91]
	v_mfma_f32_16x16x32_bf16 v[76:79], v[132:135], v[216:219], v[76:79]
	v_mfma_f32_16x16x32_bf16 v[72:75], v[140:143], v[216:219], v[72:75]
	s_setprio 0
	s_setprio 1
	v_mfma_f32_16x16x32_bf16 v[116:119], v[144:147], v[180:183], 0
	v_mfma_f32_16x16x32_bf16 v[112:115], v[172:175], v[180:183], 0
	v_mfma_f32_16x16x32_bf16 v[100:103], v[144:147], v[196:199], 0
	v_mfma_f32_16x16x32_bf16 v[96:99], v[172:175], v[196:199], 0
	v_mfma_f32_16x16x32_bf16 v[84:87], v[144:147], v[204:207], 0
	v_mfma_f32_16x16x32_bf16 v[80:83], v[172:175], v[204:207], 0
	v_mfma_f32_16x16x32_bf16 v[68:71], v[144:147], v[212:215], 0
	v_mfma_f32_16x16x32_bf16 v[64:67], v[172:175], v[212:215], 0
	v_mfma_f32_16x16x32_bf16 v[116:119], v[148:151], v[192:195], v[116:119]
	v_mfma_f32_16x16x32_bf16 v[112:115], v[176:179], v[192:195], v[112:115]
	v_mfma_f32_16x16x32_bf16 v[100:103], v[148:151], v[200:203], v[100:103]
	v_mfma_f32_16x16x32_bf16 v[96:99], v[176:179], v[200:203], v[96:99]
	v_mfma_f32_16x16x32_bf16 v[84:87], v[148:151], v[208:211], v[84:87]
	v_mfma_f32_16x16x32_bf16 v[80:83], v[176:179], v[208:211], v[80:83]
	v_mfma_f32_16x16x32_bf16 v[68:71], v[148:151], v[216:219], v[68:71]
	v_mfma_f32_16x16x32_bf16 v[64:67], v[176:179], v[216:219], v[64:67]
	s_setprio 0
	s_barrier
	s_add_i32 s48, s68, s58
	v_lshl_add_u64 v[220:221], s[52:53], 0, v[154:155]
	s_mov_b32 m0, s48
	ds_read_b128 v[180:183], v190 offset:16384
	v_xor_b32_e32 v253, 64, v190
	ds_read_b128 v[192:195], v253 offset:16384
	ds_read_b128 v[196:199], v190 offset:18432
	ds_read_b128 v[200:203], v253 offset:18432
	ds_read_b128 v[204:207], v190 offset:20480
	ds_read_b128 v[208:211], v253 offset:20480
	ds_read_b128 v[212:215], v190 offset:22528
	ds_read_b128 v[216:219], v253 offset:22528
	global_load_lds_dwordx4 v[220:221], off
	s_add_i32 m0, s48, 0x2000
	s_add_u32 s48, s52, 0xb0000
	v_lshl_add_u64 v[222:223], s[52:53], 0, v[162:163]
	s_addc_u32 s49, s53, 0
	s_add_i32 s75, s69, s58
	global_load_lds_dwordx4 v[222:223], off
	v_lshl_add_u64 v[224:225], s[48:49], 0, v[154:155]
	s_mov_b32 m0, s75
	v_lshl_add_u64 v[226:227], s[54:55], 0, v[160:161]
	global_load_lds_dwordx4 v[224:225], off
	v_lshl_add_u64 v[224:225], s[48:49], 0, v[162:163]
	s_add_i32 m0, s75, 0x2000
	s_nop 0
	global_load_lds_dwordx4 v[224:225], off
	v_lshl_add_u64 v[224:225], s[54:55], 0, v[152:153]
	s_mov_b32 m0, s59
	s_nop 0
	global_load_lds_dwordx4 v[224:225], off
	s_mov_b32 m0, s60
	s_nop 0
	global_load_lds_dwordx4 v[226:227], off
	s_waitcnt vmcnt(24)
	s_waitcnt lgkmcnt(0)
	s_barrier
	s_setprio 1
	s_waitcnt lgkmcnt(0)
	v_mfma_f32_16x16x32_bf16 v[60:63], v[128:131], v[180:183], 0
	v_mfma_f32_16x16x32_bf16 v[56:59], v[136:139], v[180:183], 0
	v_mfma_f32_16x16x32_bf16 v[44:47], v[128:131], v[196:199], 0
	v_mfma_f32_16x16x32_bf16 v[40:43], v[136:139], v[196:199], 0
	v_mfma_f32_16x16x32_bf16 v[28:31], v[128:131], v[204:207], 0
	v_mfma_f32_16x16x32_bf16 v[24:27], v[136:139], v[204:207], 0
	v_mfma_f32_16x16x32_bf16 v[12:15], v[128:131], v[212:215], 0
	v_mfma_f32_16x16x32_bf16 v[8:11], v[136:139], v[212:215], 0
	v_mfma_f32_16x16x32_bf16 v[60:63], v[132:135], v[192:195], v[60:63]
	v_mfma_f32_16x16x32_bf16 v[56:59], v[140:143], v[192:195], v[56:59]
	v_mfma_f32_16x16x32_bf16 v[44:47], v[132:135], v[200:203], v[44:47]
	v_mfma_f32_16x16x32_bf16 v[40:43], v[140:143], v[200:203], v[40:43]
	v_mfma_f32_16x16x32_bf16 v[28:31], v[132:135], v[208:211], v[28:31]
	v_mfma_f32_16x16x32_bf16 v[24:27], v[140:143], v[208:211], v[24:27]
	v_mfma_f32_16x16x32_bf16 v[12:15], v[132:135], v[216:219], v[12:15]
	v_mfma_f32_16x16x32_bf16 v[8:11], v[140:143], v[216:219], v[8:11]
	s_setprio 0
	s_setprio 1
	v_mfma_f32_16x16x32_bf16 v[52:55], v[144:147], v[180:183], 0
	v_mfma_f32_16x16x32_bf16 v[48:51], v[172:175], v[180:183], 0
	v_mfma_f32_16x16x32_bf16 v[36:39], v[144:147], v[196:199], 0
	v_mfma_f32_16x16x32_bf16 v[32:35], v[172:175], v[196:199], 0
	v_mfma_f32_16x16x32_bf16 v[20:23], v[144:147], v[204:207], 0
	v_mfma_f32_16x16x32_bf16 v[16:19], v[172:175], v[204:207], 0
	v_mfma_f32_16x16x32_bf16 v[4:7], v[144:147], v[212:215], 0
	v_mfma_f32_16x16x32_bf16 v[0:3], v[172:175], v[212:215], 0
	v_mfma_f32_16x16x32_bf16 v[52:55], v[148:151], v[192:195], v[52:55]
	v_mfma_f32_16x16x32_bf16 v[48:51], v[176:179], v[192:195], v[48:51]
	v_mfma_f32_16x16x32_bf16 v[36:39], v[148:151], v[200:203], v[36:39]
	v_mfma_f32_16x16x32_bf16 v[32:35], v[176:179], v[200:203], v[32:35]
	v_mfma_f32_16x16x32_bf16 v[20:23], v[148:151], v[208:211], v[20:23]
	v_mfma_f32_16x16x32_bf16 v[16:19], v[176:179], v[208:211], v[16:19]
	v_mfma_f32_16x16x32_bf16 v[4:7], v[148:151], v[216:219], v[4:7]
	v_mfma_f32_16x16x32_bf16 v[0:3], v[176:179], v[216:219], v[0:3]
	s_setprio 0
	s_barrier
	s_add_i32 s75, 0, 0x18000
	s_add_i32 s76, 0, 0x1c000
	v_add_u32_e32 v140, s75, v185
	v_add_u32_e32 v176, s76, v185
	ds_read_b128 v[128:131], v140
	v_xor_b32_e32 v253, 64, v140
	ds_read_b128 v[132:135], v253
	ds_read_b128 v[136:139], v140 offset:2048
	ds_read_b128 v[140:143], v253 offset:2048
	ds_read_b128 v[144:147], v176
	v_xor_b32_e32 v253, 64, v176
	ds_read_b128 v[148:151], v253
	ds_read_b128 v[172:175], v176 offset:2048
	ds_read_b128 v[176:179], v253 offset:2048
	s_add_u32 s48, s54, 0xb0000
	s_addc_u32 s49, s55, 0
	s_mov_b32 m0, s61
	v_lshl_add_u64 v[228:229], s[48:49], 0, v[152:153]
	ds_read_b128 v[180:183], v190 offset:32768
	v_xor_b32_e32 v253, 64, v190
	ds_read_b128 v[192:195], v253 offset:32768
	ds_read_b128 v[196:199], v190 offset:34816
	ds_read_b128 v[200:203], v253 offset:34816
	ds_read_b128 v[204:207], v190 offset:36864
	ds_read_b128 v[208:211], v253 offset:36864
	ds_read_b128 v[212:215], v190 offset:38912
	ds_read_b128 v[216:219], v253 offset:38912
	global_load_lds_dwordx4 v[228:229], off
	v_lshl_add_u64 v[228:229], s[48:49], 0, v[160:161]
	s_mov_b32 m0, s62
	s_nop 0
	global_load_lds_dwordx4 v[228:229], off
	s_waitcnt vmcnt(8)
	s_waitcnt lgkmcnt(0)
	s_barrier
	s_setprio 1
	s_waitcnt lgkmcnt(0)
	v_mfma_f32_16x16x32_bf16 v[124:127], v[128:131], v[180:183], v[124:127]
	v_mfma_f32_16x16x32_bf16 v[124:127], v[132:135], v[192:195], v[124:127]
	v_mfma_f32_16x16x32_bf16 v[120:123], v[136:139], v[180:183], v[120:123]
	v_mfma_f32_16x16x32_bf16 v[120:123], v[140:143], v[192:195], v[120:123]
	v_mfma_f32_16x16x32_bf16 v[108:111], v[128:131], v[196:199], v[108:111]
	v_mfma_f32_16x16x32_bf16 v[108:111], v[132:135], v[200:203], v[108:111]
	v_mfma_f32_16x16x32_bf16 v[104:107], v[136:139], v[196:199], v[104:107]
	v_mfma_f32_16x16x32_bf16 v[104:107], v[140:143], v[200:203], v[104:107]
	v_mfma_f32_16x16x32_bf16 v[92:95], v[128:131], v[204:207], v[92:95]
	v_mfma_f32_16x16x32_bf16 v[92:95], v[132:135], v[208:211], v[92:95]
	v_mfma_f32_16x16x32_bf16 v[88:91], v[136:139], v[204:207], v[88:91]
	v_mfma_f32_16x16x32_bf16 v[88:91], v[140:143], v[208:211], v[88:91]
	v_mfma_f32_16x16x32_bf16 v[76:79], v[128:131], v[212:215], v[76:79]
	v_mfma_f32_16x16x32_bf16 v[76:79], v[132:135], v[216:219], v[76:79]
	v_mfma_f32_16x16x32_bf16 v[72:75], v[136:139], v[212:215], v[72:75]
	v_mfma_f32_16x16x32_bf16 v[72:75], v[140:143], v[216:219], v[72:75]
	s_setprio 0
	s_setprio 1
	v_mfma_f32_16x16x32_bf16 v[116:119], v[144:147], v[180:183], v[116:119]
	v_mfma_f32_16x16x32_bf16 v[116:119], v[148:151], v[192:195], v[116:119]
	v_mfma_f32_16x16x32_bf16 v[112:115], v[172:175], v[180:183], v[112:115]
	v_mfma_f32_16x16x32_bf16 v[112:115], v[176:179], v[192:195], v[112:115]
	v_mfma_f32_16x16x32_bf16 v[100:103], v[144:147], v[196:199], v[100:103]
	v_mfma_f32_16x16x32_bf16 v[100:103], v[148:151], v[200:203], v[100:103]
	v_mfma_f32_16x16x32_bf16 v[96:99], v[172:175], v[196:199], v[96:99]
	v_mfma_f32_16x16x32_bf16 v[96:99], v[176:179], v[200:203], v[96:99]
	v_mfma_f32_16x16x32_bf16 v[84:87], v[144:147], v[204:207], v[84:87]
	v_mfma_f32_16x16x32_bf16 v[84:87], v[148:151], v[208:211], v[84:87]
	v_mfma_f32_16x16x32_bf16 v[80:83], v[172:175], v[204:207], v[80:83]
	v_mfma_f32_16x16x32_bf16 v[80:83], v[176:179], v[208:211], v[80:83]
	v_mfma_f32_16x16x32_bf16 v[68:71], v[144:147], v[212:215], v[68:71]
	v_mfma_f32_16x16x32_bf16 v[68:71], v[148:151], v[216:219], v[68:71]
	v_mfma_f32_16x16x32_bf16 v[64:67], v[172:175], v[212:215], v[64:67]
	v_mfma_f32_16x16x32_bf16 v[64:67], v[176:179], v[216:219], v[64:67]
	s_setprio 0
	s_barrier
	s_add_i32 s48, s75, s58
	v_lshl_add_u64 v[220:221], v[220:221], 0, s[22:23]
	s_mov_b32 m0, s48
	ds_read_b128 v[180:183], v190 offset:49152
	v_xor_b32_e32 v253, 64, v190
	ds_read_b128 v[192:195], v253 offset:49152
	ds_read_b128 v[196:199], v190 offset:51200
	ds_read_b128 v[200:203], v253 offset:51200
	ds_read_b128 v[204:207], v190 offset:53248
	ds_read_b128 v[208:211], v253 offset:53248
	ds_read_b128 v[212:215], v190 offset:55296
	ds_read_b128 v[216:219], v253 offset:55296
	global_load_lds_dwordx4 v[220:221], off
	s_add_i32 m0, s48, 0x2000
	s_add_u32 s48, s52, 0xb0080
	v_lshl_add_u64 v[220:221], v[222:223], 0, s[22:23]
	s_addc_u32 s49, s53, 0
	s_add_i32 s52, s76, s58
	global_load_lds_dwordx4 v[220:221], off
	v_lshl_add_u64 v[220:221], s[48:49], 0, v[154:155]
	s_mov_b32 m0, s52
	s_nop 0
	global_load_lds_dwordx4 v[220:221], off
	v_lshl_add_u64 v[220:221], s[48:49], 0, v[162:163]
	s_add_i32 m0, s52, 0x2000
	s_nop 0
	global_load_lds_dwordx4 v[220:221], off
	v_lshl_add_u64 v[220:221], v[224:225], 0, s[22:23]
	s_mov_b32 m0, s3
	s_nop 0
	global_load_lds_dwordx4 v[220:221], off
	v_lshl_add_u64 v[220:221], v[226:227], 0, s[22:23]
	s_mov_b32 m0, s64
	s_nop 0
	global_load_lds_dwordx4 v[220:221], off
	s_waitcnt vmcnt(8)
	s_waitcnt lgkmcnt(0)
	s_barrier
	s_setprio 1
	s_waitcnt lgkmcnt(0)
	v_mfma_f32_16x16x32_bf16 v[60:63], v[128:131], v[180:183], v[60:63]
	v_mfma_f32_16x16x32_bf16 v[60:63], v[132:135], v[192:195], v[60:63]
	v_mfma_f32_16x16x32_bf16 v[56:59], v[136:139], v[180:183], v[56:59]
	v_mfma_f32_16x16x32_bf16 v[56:59], v[140:143], v[192:195], v[56:59]
	v_mfma_f32_16x16x32_bf16 v[44:47], v[128:131], v[196:199], v[44:47]
	v_mfma_f32_16x16x32_bf16 v[44:47], v[132:135], v[200:203], v[44:47]
	v_mfma_f32_16x16x32_bf16 v[40:43], v[136:139], v[196:199], v[40:43]
	v_mfma_f32_16x16x32_bf16 v[40:43], v[140:143], v[200:203], v[40:43]
	v_mfma_f32_16x16x32_bf16 v[28:31], v[128:131], v[204:207], v[28:31]
	v_mfma_f32_16x16x32_bf16 v[28:31], v[132:135], v[208:211], v[28:31]
	v_mfma_f32_16x16x32_bf16 v[24:27], v[136:139], v[204:207], v[24:27]
	v_mfma_f32_16x16x32_bf16 v[24:27], v[140:143], v[208:211], v[24:27]
	v_mfma_f32_16x16x32_bf16 v[12:15], v[128:131], v[212:215], v[12:15]
	v_mfma_f32_16x16x32_bf16 v[12:15], v[132:135], v[216:219], v[12:15]
	v_mfma_f32_16x16x32_bf16 v[8:11], v[136:139], v[212:215], v[8:11]
	v_mfma_f32_16x16x32_bf16 v[8:11], v[140:143], v[216:219], v[8:11]
	s_setprio 0
	s_setprio 1
	v_mfma_f32_16x16x32_bf16 v[52:55], v[144:147], v[180:183], v[52:55]
	v_mfma_f32_16x16x32_bf16 v[52:55], v[148:151], v[192:195], v[52:55]
	v_mfma_f32_16x16x32_bf16 v[48:51], v[172:175], v[180:183], v[48:51]
	v_mfma_f32_16x16x32_bf16 v[48:51], v[176:179], v[192:195], v[48:51]
	v_mfma_f32_16x16x32_bf16 v[36:39], v[144:147], v[196:199], v[36:39]
	v_mfma_f32_16x16x32_bf16 v[36:39], v[148:151], v[200:203], v[36:39]
	v_mfma_f32_16x16x32_bf16 v[32:35], v[172:175], v[196:199], v[32:35]
	v_mfma_f32_16x16x32_bf16 v[32:35], v[176:179], v[200:203], v[32:35]
	v_mfma_f32_16x16x32_bf16 v[20:23], v[144:147], v[204:207], v[20:23]
	v_mfma_f32_16x16x32_bf16 v[20:23], v[148:151], v[208:211], v[20:23]
	v_mfma_f32_16x16x32_bf16 v[16:19], v[172:175], v[204:207], v[16:19]
	v_mfma_f32_16x16x32_bf16 v[16:19], v[176:179], v[208:211], v[16:19]
	v_mfma_f32_16x16x32_bf16 v[4:7], v[144:147], v[212:215], v[4:7]
	v_mfma_f32_16x16x32_bf16 v[4:7], v[148:151], v[216:219], v[4:7]
	v_mfma_f32_16x16x32_bf16 v[0:3], v[172:175], v[212:215], v[0:3]
	v_mfma_f32_16x16x32_bf16 v[0:3], v[176:179], v[216:219], v[0:3]
	s_setprio 0
	s_barrier
	s_add_i32 s74, s74, 2
	s_add_u32 s72, s72, 0x100
	s_addc_u32 s73, s73, 0
	s_cmp_gt_u32 s74, 41
	s_mov_b64 s[48:49], s[50:51]
	s_branch .LBB0_1181
.Lfa_11:
	ds_read_b128 v[128:131], v188
	v_xor_b32_e32 v253, 64, v188
	ds_read_b128 v[132:135], v253
	ds_read_b128 v[136:139], v188 offset:2048
	ds_read_b128 v[140:143], v253 offset:2048
	ds_read_b128 v[144:147], v189
	v_xor_b32_e32 v253, 64, v189
	ds_read_b128 v[148:151], v253
	ds_read_b128 v[172:175], v189 offset:2048
	ds_read_b128 v[176:179], v253 offset:2048
	s_add_u32 s50, s48, 0x100
	s_addc_u32 s51, s49, 0
	s_cmp_eq_u32 s74, 40
	s_cselect_b32 s55, s11, s51
	s_cselect_b32 s54, s10, s50
	s_cselect_b32 s53, s47, s73
	s_cselect_b32 s52, s46, s72
	v_lshl_add_u64 v[220:221], s[48:49], 0, v[166:167]
	s_add_i32 m0, s59, 0xc000
	ds_read_b128 v[180:183], v190
	v_xor_b32_e32 v253, 64, v190
	ds_read_b128 v[192:195], v253
	ds_read_b128 v[196:199], v190 offset:2048
	ds_read_b128 v[200:203], v253 offset:2048
	ds_read_b128 v[204:207], v190 offset:4096
	ds_read_b128 v[208:211], v253 offset:4096
	ds_read_b128 v[212:215], v190 offset:6144
	ds_read_b128 v[216:219], v253 offset:6144
	global_load_lds_dwordx4 v[220:221], off
	v_lshl_add_u64 v[220:221], s[48:49], 0, v[164:165]
	s_add_i32 m0, s59, 0xe000
	s_nop 0
	global_load_lds_dwordx4 v[220:221], off
	s_waitcnt vmcnt(8)
	s_waitcnt lgkmcnt(0)
	s_barrier
	s_setprio 1
	s_waitcnt lgkmcnt(0)
	v_mfma_f32_16x16x32_bf16 v[124:127], v[128:131], v[180:183], 0
	v_mfma_f32_16x16x32_bf16 v[120:123], v[136:139], v[180:183], 0
	v_mfma_f32_16x16x32_bf16 v[108:111], v[128:131], v[196:199], 0
	v_mfma_f32_16x16x32_bf16 v[104:107], v[136:139], v[196:199], 0
	v_mfma_f32_16x16x32_bf16 v[92:95], v[128:131], v[204:207], 0
	v_mfma_f32_16x16x32_bf16 v[88:91], v[136:139], v[204:207], 0
	v_mfma_f32_16x16x32_bf16 v[76:79], v[128:131], v[212:215], 0
	v_mfma_f32_16x16x32_bf16 v[72:75], v[136:139], v[212:215], 0
	v_mfma_f32_16x16x32_bf16 v[124:127], v[132:135], v[192:195], v[124:127]
	v_mfma_f32_16x16x32_bf16 v[120:123], v[140:143], v[192:195], v[120:123]
	v_mfma_f32_16x16x32_bf16 v[108:111], v[132:135], v[200:203], v[108:111]
	v_mfma_f32_16x16x32_bf16 v[104:107], v[140:143], v[200:203], v[104:107]
	v_mfma_f32_16x16x32_bf16 v[92:95], v[132:135], v[208:211], v[92:95]
	v_mfma_f32_16x16x32_bf16 v[88:91], v[140:143], v[208:211], v[88:91]
	v_mfma_f32_16x16x32_bf16 v[76:79], v[132:135], v[216:219], v[76:79]
	v_mfma_f32_16x16x32_bf16 v[72:75], v[140:143], v[216:219], v[72:75]
	s_setprio 0
	s_setprio 1
	v_mfma_f32_16x16x32_bf16 v[116:119], v[144:147], v[180:183], 0
	v_mfma_f32_16x16x32_bf16 v[112:115], v[172:175], v[180:183], 0
	v_mfma_f32_16x16x32_bf16 v[100:103], v[144:147], v[196:199], 0
	v_mfma_f32_16x16x32_bf16 v[96:99], v[172:175], v[196:199], 0
	v_mfma_f32_16x16x32_bf16 v[84:87], v[144:147], v[204:207], 0
	v_mfma_f32_16x16x32_bf16 v[80:83], v[172:175], v[204:207], 0
	v_mfma_f32_16x16x32_bf16 v[68:71], v[144:147], v[212:215], 0
	v_mfma_f32_16x16x32_bf16 v[64:67], v[172:175], v[212:215], 0
	v_mfma_f32_16x16x32_bf16 v[116:119], v[148:151], v[192:195], v[116:119]
	v_mfma_f32_16x16x32_bf16 v[112:115], v[176:179], v[192:195], v[112:115]
	v_mfma_f32_16x16x32_bf16 v[100:103], v[148:151], v[200:203], v[100:103]
	v_mfma_f32_16x16x32_bf16 v[96:99], v[176:179], v[200:203], v[96:99]
	v_mfma_f32_16x16x32_bf16 v[84:87], v[148:151], v[208:211], v[84:87]
	v_mfma_f32_16x16x32_bf16 v[80:83], v[176:179], v[208:211], v[80:83]
	v_mfma_f32_16x16x32_bf16 v[68:71], v[148:151], v[216:219], v[68:71]
	v_mfma_f32_16x16x32_bf16 v[64:67], v[176:179], v[216:219], v[64:67]
	s_setprio 0
	s_barrier
	s_add_i32 s48, s68, s58
	v_lshl_add_u64 v[220:221], s[52:53], 0, v[154:155]
	s_mov_b32 m0, s48
	ds_read_b128 v[180:183], v190 offset:16384
	v_xor_b32_e32 v253, 64, v190
	ds_read_b128 v[192:195], v253 offset:16384
	ds_read_b128 v[196:199], v190 offset:18432
	ds_read_b128 v[200:203], v253 offset:18432
	ds_read_b128 v[204:207], v190 offset:20480
	ds_read_b128 v[208:211], v253 offset:20480
	ds_read_b128 v[212:215], v190 offset:22528
	ds_read_b128 v[216:219], v253 offset:22528
	global_load_lds_dwordx4 v[220:221], off
	s_add_i32 m0, s48, 0x2000
	s_add_u32 s48, s52, 0xb0000
	v_lshl_add_u64 v[222:223], s[52:53], 0, v[162:163]
	s_addc_u32 s49, s53, 0
	s_add_i32 s75, s69, s58
	global_load_lds_dwordx4 v[222:223], off
	v_lshl_add_u64 v[224:225], s[48:49], 0, v[154:155]
	s_mov_b32 m0, s75
	v_lshl_add_u64 v[226:227], s[54:55], 0, v[160:161]
	global_load_lds_dwordx4 v[224:225], off
	v_lshl_add_u64 v[224:225], s[48:49], 0, v[162:163]
	s_add_i32 m0, s75, 0x2000
	s_nop 0
	global_load_lds_dwordx4 v[224:225], off
	v_lshl_add_u64 v[224:225], s[54:55], 0, v[152:153]
	s_mov_b32 m0, s59
	s_nop 0
	global_load_lds_dwordx4 v[224:225], off
	s_mov_b32 m0, s60
	s_nop 0
	global_load_lds_dwordx4 v[226:227], off
	s_waitcnt vmcnt(8)
	s_waitcnt lgkmcnt(0)
	s_barrier
	s_setprio 1
	s_waitcnt lgkmcnt(0)
	v_mfma_f32_16x16x32_bf16 v[60:63], v[128:131], v[180:183], 0
	v_mfma_f32_16x16x32_bf16 v[56:59], v[136:139], v[180:183], 0
	v_mfma_f32_16x16x32_bf16 v[44:47], v[128:131], v[196:199], 0
	v_mfma_f32_16x16x32_bf16 v[40:43], v[136:139], v[196:199], 0
	v_mfma_f32_16x16x32_bf16 v[28:31], v[128:131], v[204:207], 0
	v_mfma_f32_16x16x32_bf16 v[24:27], v[136:139], v[204:207], 0
	v_mfma_f32_16x16x32_bf16 v[12:15], v[128:131], v[212:215], 0
	v_mfma_f32_16x16x32_bf16 v[8:11], v[136:139], v[212:215], 0
	v_mfma_f32_16x16x32_bf16 v[60:63], v[132:135], v[192:195], v[60:63]
	v_mfma_f32_16x16x32_bf16 v[56:59], v[140:143], v[192:195], v[56:59]
	v_mfma_f32_16x16x32_bf16 v[44:47], v[132:135], v[200:203], v[44:47]
	v_mfma_f32_16x16x32_bf16 v[40:43], v[140:143], v[200:203], v[40:43]
	v_mfma_f32_16x16x32_bf16 v[28:31], v[132:135], v[208:211], v[28:31]
	v_mfma_f32_16x16x32_bf16 v[24:27], v[140:143], v[208:211], v[24:27]
	v_mfma_f32_16x16x32_bf16 v[12:15], v[132:135], v[216:219], v[12:15]
	v_mfma_f32_16x16x32_bf16 v[8:11], v[140:143], v[216:219], v[8:11]
	s_setprio 0
	s_setprio 1
	v_mfma_f32_16x16x32_bf16 v[52:55], v[144:147], v[180:183], 0
	v_mfma_f32_16x16x32_bf16 v[48:51], v[172:175], v[180:183], 0
	v_mfma_f32_16x16x32_bf16 v[36:39], v[144:147], v[196:199], 0
	v_mfma_f32_16x16x32_bf16 v[32:35], v[172:175], v[196:199], 0
	v_mfma_f32_16x16x32_bf16 v[20:23], v[144:147], v[204:207], 0
	v_mfma_f32_16x16x32_bf16 v[16:19], v[172:175], v[204:207], 0
	v_mfma_f32_16x16x32_bf16 v[4:7], v[144:147], v[212:215], 0
	v_mfma_f32_16x16x32_bf16 v[0:3], v[172:175], v[212:215], 0
	v_mfma_f32_16x16x32_bf16 v[52:55], v[148:151], v[192:195], v[52:55]
	v_mfma_f32_16x16x32_bf16 v[48:51], v[176:179], v[192:195], v[48:51]
	v_mfma_f32_16x16x32_bf16 v[36:39], v[148:151], v[200:203], v[36:39]
	v_mfma_f32_16x16x32_bf16 v[32:35], v[176:179], v[200:203], v[32:35]
	v_mfma_f32_16x16x32_bf16 v[20:23], v[148:151], v[208:211], v[20:23]
	v_mfma_f32_16x16x32_bf16 v[16:19], v[176:179], v[208:211], v[16:19]
	v_mfma_f32_16x16x32_bf16 v[4:7], v[148:151], v[216:219], v[4:7]
	v_mfma_f32_16x16x32_bf16 v[0:3], v[176:179], v[216:219], v[0:3]
	s_setprio 0
	s_barrier
	s_add_i32 s75, 0, 0x18000
	s_add_i32 s76, 0, 0x1c000
	v_add_u32_e32 v140, s75, v185
	v_add_u32_e32 v176, s76, v185
	ds_read_b128 v[128:131], v140
	v_xor_b32_e32 v253, 64, v140
	ds_read_b128 v[132:135], v253
	ds_read_b128 v[136:139], v140 offset:2048
	ds_read_b128 v[140:143], v253 offset:2048
	ds_read_b128 v[144:147], v176
	v_xor_b32_e32 v253, 64, v176
	ds_read_b128 v[148:151], v253
	ds_read_b128 v[172:175], v176 offset:2048
	ds_read_b128 v[176:179], v253 offset:2048
	s_add_u32 s48, s54, 0xb0000
	s_addc_u32 s49, s55, 0
	s_mov_b32 m0, s61
	v_lshl_add_u64 v[228:229], s[48:49], 0, v[152:153]
	ds_read_b128 v[180:183], v190 offset:32768
	v_xor_b32_e32 v253, 64, v190
	ds_read_b128 v[192:195], v253 offset:32768
	ds_read_b128 v[196:199], v190 offset:34816
	ds_read_b128 v[200:203], v253 offset:34816
	ds_read_b128 v[204:207], v190 offset:36864
	ds_read_b128 v[208:211], v253 offset:36864
	ds_read_b128 v[212:215], v190 offset:38912
	ds_read_b128 v[216:219], v253 offset:38912
	global_load_lds_dwordx4 v[228:229], off
	v_lshl_add_u64 v[228:229], s[48:49], 0, v[160:161]
	s_mov_b32 m0, s62
	s_nop 0
	global_load_lds_dwordx4 v[228:229], off
	s_waitcnt vmcnt(8)
	s_waitcnt lgkmcnt(0)
	s_barrier
	s_setprio 1
	s_waitcnt lgkmcnt(0)
	v_mfma_f32_16x16x32_bf16 v[124:127], v[128:131], v[180:183], v[124:127]
	v_mfma_f32_16x16x32_bf16 v[124:127], v[132:135], v[192:195], v[124:127]
	v_mfma_f32_16x16x32_bf16 v[120:123], v[136:139], v[180:183], v[120:123]
	v_mfma_f32_16x16x32_bf16 v[120:123], v[140:143], v[192:195], v[120:123]
	v_mfma_f32_16x16x32_bf16 v[108:111], v[128:131], v[196:199], v[108:111]
	v_mfma_f32_16x16x32_bf16 v[108:111], v[132:135], v[200:203], v[108:111]
	v_mfma_f32_16x16x32_bf16 v[104:107], v[136:139], v[196:199], v[104:107]
	v_mfma_f32_16x16x32_bf16 v[104:107], v[140:143], v[200:203], v[104:107]
	v_mfma_f32_16x16x32_bf16 v[92:95], v[128:131], v[204:207], v[92:95]
	v_mfma_f32_16x16x32_bf16 v[92:95], v[132:135], v[208:211], v[92:95]
	v_mfma_f32_16x16x32_bf16 v[88:91], v[136:139], v[204:207], v[88:91]
	v_mfma_f32_16x16x32_bf16 v[88:91], v[140:143], v[208:211], v[88:91]
	v_mfma_f32_16x16x32_bf16 v[76:79], v[128:131], v[212:215], v[76:79]
	v_mfma_f32_16x16x32_bf16 v[76:79], v[132:135], v[216:219], v[76:79]
	v_mfma_f32_16x16x32_bf16 v[72:75], v[136:139], v[212:215], v[72:75]
	v_mfma_f32_16x16x32_bf16 v[72:75], v[140:143], v[216:219], v[72:75]
	s_setprio 0
	s_setprio 1
	v_mfma_f32_16x16x32_bf16 v[116:119], v[144:147], v[180:183], v[116:119]
	v_mfma_f32_16x16x32_bf16 v[116:119], v[148:151], v[192:195], v[116:119]
	v_mfma_f32_16x16x32_bf16 v[112:115], v[172:175], v[180:183], v[112:115]
	v_mfma_f32_16x16x32_bf16 v[112:115], v[176:179], v[192:195], v[112:115]
	v_mfma_f32_16x16x32_bf16 v[100:103], v[144:147], v[196:199], v[100:103]
	v_mfma_f32_16x16x32_bf16 v[100:103], v[148:151], v[200:203], v[100:103]
	v_mfma_f32_16x16x32_bf16 v[96:99], v[172:175], v[196:199], v[96:99]
	v_mfma_f32_16x16x32_bf16 v[96:99], v[176:179], v[200:203], v[96:99]
	v_mfma_f32_16x16x32_bf16 v[84:87], v[144:147], v[204:207], v[84:87]
	v_mfma_f32_16x16x32_bf16 v[84:87], v[148:151], v[208:211], v[84:87]
	v_mfma_f32_16x16x32_bf16 v[80:83], v[172:175], v[204:207], v[80:83]
	v_mfma_f32_16x16x32_bf16 v[80:83], v[176:179], v[208:211], v[80:83]
	v_mfma_f32_16x16x32_bf16 v[68:71], v[144:147], v[212:215], v[68:71]
	v_mfma_f32_16x16x32_bf16 v[68:71], v[148:151], v[216:219], v[68:71]
	v_mfma_f32_16x16x32_bf16 v[64:67], v[172:175], v[212:215], v[64:67]
	v_mfma_f32_16x16x32_bf16 v[64:67], v[176:179], v[216:219], v[64:67]
	s_setprio 0
	s_barrier
	s_add_i32 s48, s75, s58
	v_lshl_add_u64 v[220:221], v[220:221], 0, s[22:23]
	s_mov_b32 m0, s48
	ds_read_b128 v[180:183], v190 offset:49152
	v_xor_b32_e32 v253, 64, v190
	ds_read_b128 v[192:195], v253 offset:49152
	ds_read_b128 v[196:199], v190 offset:51200
	ds_read_b128 v[200:203], v253 offset:51200
	ds_read_b128 v[204:207], v190 offset:53248
	ds_read_b128 v[208:211], v253 offset:53248
	ds_read_b128 v[212:215], v190 offset:55296
	ds_read_b128 v[216:219], v253 offset:55296
	global_load_lds_dwordx4 v[220:221], off
	s_add_i32 m0, s48, 0x2000
	s_add_u32 s48, s52, 0xb0080
	v_lshl_add_u64 v[220:221], v[222:223], 0, s[22:23]
	s_addc_u32 s49, s53, 0
	s_add_i32 s52, s76, s58
	global_load_lds_dwordx4 v[220:221], off
	v_lshl_add_u64 v[220:221], s[48:49], 0, v[154:155]
	s_mov_b32 m0, s52
	s_nop 0
	global_load_lds_dwordx4 v[220:221], off
	v_lshl_add_u64 v[220:221], s[48:49], 0, v[162:163]
	s_add_i32 m0, s52, 0x2000
	s_nop 0
	global_load_lds_dwordx4 v[220:221], off
	v_lshl_add_u64 v[220:221], v[224:225], 0, s[22:23]
	s_mov_b32 m0, s3
	s_nop 0
	global_load_lds_dwordx4 v[220:221], off
	v_lshl_add_u64 v[220:221], v[226:227], 0, s[22:23]
	s_mov_b32 m0, s64
	s_nop 0
	global_load_lds_dwordx4 v[220:221], off
	s_waitcnt vmcnt(8)
	s_waitcnt lgkmcnt(0)
	s_barrier
	s_setprio 1
	s_waitcnt lgkmcnt(0)
	v_mfma_f32_16x16x32_bf16 v[60:63], v[128:131], v[180:183], v[60:63]
	v_mfma_f32_16x16x32_bf16 v[60:63], v[132:135], v[192:195], v[60:63]
	v_mfma_f32_16x16x32_bf16 v[56:59], v[136:139], v[180:183], v[56:59]
	v_mfma_f32_16x16x32_bf16 v[56:59], v[140:143], v[192:195], v[56:59]
	v_mfma_f32_16x16x32_bf16 v[44:47], v[128:131], v[196:199], v[44:47]
	v_mfma_f32_16x16x32_bf16 v[44:47], v[132:135], v[200:203], v[44:47]
	v_mfma_f32_16x16x32_bf16 v[40:43], v[136:139], v[196:199], v[40:43]
	v_mfma_f32_16x16x32_bf16 v[40:43], v[140:143], v[200:203], v[40:43]
	v_mfma_f32_16x16x32_bf16 v[28:31], v[128:131], v[204:207], v[28:31]
	v_mfma_f32_16x16x32_bf16 v[28:31], v[132:135], v[208:211], v[28:31]
	v_mfma_f32_16x16x32_bf16 v[24:27], v[136:139], v[204:207], v[24:27]
	v_mfma_f32_16x16x32_bf16 v[24:27], v[140:143], v[208:211], v[24:27]
	v_mfma_f32_16x16x32_bf16 v[12:15], v[128:131], v[212:215], v[12:15]
	v_mfma_f32_16x16x32_bf16 v[12:15], v[132:135], v[216:219], v[12:15]
	v_mfma_f32_16x16x32_bf16 v[8:11], v[136:139], v[212:215], v[8:11]
	v_mfma_f32_16x16x32_bf16 v[8:11], v[140:143], v[216:219], v[8:11]
	s_setprio 0
	s_setprio 1
	v_mfma_f32_16x16x32_bf16 v[52:55], v[144:147], v[180:183], v[52:55]
	v_mfma_f32_16x16x32_bf16 v[52:55], v[148:151], v[192:195], v[52:55]
	v_mfma_f32_16x16x32_bf16 v[48:51], v[172:175], v[180:183], v[48:51]
	v_mfma_f32_16x16x32_bf16 v[48:51], v[176:179], v[192:195], v[48:51]
	v_mfma_f32_16x16x32_bf16 v[36:39], v[144:147], v[196:199], v[36:39]
	v_mfma_f32_16x16x32_bf16 v[36:39], v[148:151], v[200:203], v[36:39]
	v_mfma_f32_16x16x32_bf16 v[32:35], v[172:175], v[196:199], v[32:35]
	v_mfma_f32_16x16x32_bf16 v[32:35], v[176:179], v[200:203], v[32:35]
	v_mfma_f32_16x16x32_bf16 v[20:23], v[144:147], v[204:207], v[20:23]
	v_mfma_f32_16x16x32_bf16 v[20:23], v[148:151], v[208:211], v[20:23]
	v_mfma_f32_16x16x32_bf16 v[16:19], v[172:175], v[204:207], v[16:19]
	v_mfma_f32_16x16x32_bf16 v[16:19], v[176:179], v[208:211], v[16:19]
	v_mfma_f32_16x16x32_bf16 v[4:7], v[144:147], v[212:215], v[4:7]
	v_mfma_f32_16x16x32_bf16 v[4:7], v[148:151], v[216:219], v[4:7]
	v_mfma_f32_16x16x32_bf16 v[0:3], v[172:175], v[212:215], v[0:3]
	v_mfma_f32_16x16x32_bf16 v[0:3], v[176:179], v[216:219], v[0:3]
	s_setprio 0
	s_barrier
	s_add_i32 s74, s74, 2
	s_add_u32 s72, s72, 0x100
	s_addc_u32 s73, s73, 0
	s_cmp_gt_u32 s74, 41
	s_mov_b64 s[48:49], s[50:51]
.LBB0_1181:
	ds_read_b128 v[128:131], v188
	v_xor_b32_e32 v253, 64, v188
	ds_read_b128 v[132:135], v253
	ds_read_b128 v[136:139], v188 offset:2048
	ds_read_b128 v[140:143], v253 offset:2048
	ds_read_b128 v[144:147], v189
	v_xor_b32_e32 v253, 64, v189
	ds_read_b128 v[148:151], v253
	ds_read_b128 v[172:175], v189 offset:2048
	ds_read_b128 v[176:179], v253 offset:2048
	s_add_u32 s50, s48, 0x100
	s_addc_u32 s51, s49, 0
	s_cmp_eq_u32 s74, 40
	s_cselect_b32 s55, s11, s51
	s_cselect_b32 s54, s10, s50
	s_cselect_b32 s53, s47, s73
	s_cselect_b32 s52, s46, s72
	v_lshl_add_u64 v[220:221], s[48:49], 0, v[166:167]
	s_add_i32 m0, s59, 0xc000
	ds_read_b128 v[180:183], v190
	v_xor_b32_e32 v253, 64, v190
	ds_read_b128 v[192:195], v253
	ds_read_b128 v[196:199], v190 offset:2048
	ds_read_b128 v[200:203], v253 offset:2048
	ds_read_b128 v[204:207], v190 offset:4096
	ds_read_b128 v[208:211], v253 offset:4096
	ds_read_b128 v[212:215], v190 offset:6144
	ds_read_b128 v[216:219], v253 offset:6144
	global_load_lds_dwordx4 v[220:221], off
	v_lshl_add_u64 v[220:221], s[48:49], 0, v[164:165]
	s_add_i32 m0, s59, 0xe000
	s_nop 0
	global_load_lds_dwordx4 v[220:221], off
	s_waitcnt vmcnt(8)
	s_waitcnt lgkmcnt(0)
	s_barrier
	s_setprio 1
	s_waitcnt lgkmcnt(0)
	v_mfma_f32_16x16x32_bf16 v[124:127], v[128:131], v[180:183], v[124:127]
	v_mfma_f32_16x16x32_bf16 v[124:127], v[132:135], v[192:195], v[124:127]
	v_mfma_f32_16x16x32_bf16 v[120:123], v[136:139], v[180:183], v[120:123]
	v_mfma_f32_16x16x32_bf16 v[120:123], v[140:143], v[192:195], v[120:123]
	v_mfma_f32_16x16x32_bf16 v[108:111], v[128:131], v[196:199], v[108:111]
	v_mfma_f32_16x16x32_bf16 v[108:111], v[132:135], v[200:203], v[108:111]
	v_mfma_f32_16x16x32_bf16 v[104:107], v[136:139], v[196:199], v[104:107]
	v_mfma_f32_16x16x32_bf16 v[104:107], v[140:143], v[200:203], v[104:107]
	v_mfma_f32_16x16x32_bf16 v[92:95], v[128:131], v[204:207], v[92:95]
	v_mfma_f32_16x16x32_bf16 v[92:95], v[132:135], v[208:211], v[92:95]
	v_mfma_f32_16x16x32_bf16 v[88:91], v[136:139], v[204:207], v[88:91]
	v_mfma_f32_16x16x32_bf16 v[88:91], v[140:143], v[208:211], v[88:91]
	v_mfma_f32_16x16x32_bf16 v[76:79], v[128:131], v[212:215], v[76:79]
	v_mfma_f32_16x16x32_bf16 v[76:79], v[132:135], v[216:219], v[76:79]
	v_mfma_f32_16x16x32_bf16 v[72:75], v[136:139], v[212:215], v[72:75]
	v_mfma_f32_16x16x32_bf16 v[72:75], v[140:143], v[216:219], v[72:75]
	s_setprio 0
	s_setprio 1
	v_mfma_f32_16x16x32_bf16 v[116:119], v[144:147], v[180:183], v[116:119]
	v_mfma_f32_16x16x32_bf16 v[116:119], v[148:151], v[192:195], v[116:119]
	v_mfma_f32_16x16x32_bf16 v[112:115], v[172:175], v[180:183], v[112:115]
	v_mfma_f32_16x16x32_bf16 v[112:115], v[176:179], v[192:195], v[112:115]
	v_mfma_f32_16x16x32_bf16 v[100:103], v[144:147], v[196:199], v[100:103]
	v_mfma_f32_16x16x32_bf16 v[100:103], v[148:151], v[200:203], v[100:103]
	v_mfma_f32_16x16x32_bf16 v[96:99], v[172:175], v[196:199], v[96:99]
	v_mfma_f32_16x16x32_bf16 v[96:99], v[176:179], v[200:203], v[96:99]
	v_mfma_f32_16x16x32_bf16 v[84:87], v[144:147], v[204:207], v[84:87]
	v_mfma_f32_16x16x32_bf16 v[84:87], v[148:151], v[208:211], v[84:87]
	v_mfma_f32_16x16x32_bf16 v[80:83], v[172:175], v[204:207], v[80:83]
	v_mfma_f32_16x16x32_bf16 v[80:83], v[176:179], v[208:211], v[80:83]
	v_mfma_f32_16x16x32_bf16 v[68:71], v[144:147], v[212:215], v[68:71]
	v_mfma_f32_16x16x32_bf16 v[68:71], v[148:151], v[216:219], v[68:71]
	v_mfma_f32_16x16x32_bf16 v[64:67], v[172:175], v[212:215], v[64:67]
	v_mfma_f32_16x16x32_bf16 v[64:67], v[176:179], v[216:219], v[64:67]
	s_setprio 0
	s_barrier
	s_add_i32 s48, s68, s58
	v_lshl_add_u64 v[220:221], s[52:53], 0, v[154:155]
	s_mov_b32 m0, s48
	ds_read_b128 v[180:183], v190 offset:16384
	v_xor_b32_e32 v253, 64, v190
	ds_read_b128 v[192:195], v253 offset:16384
	ds_read_b128 v[196:199], v190 offset:18432
	ds_read_b128 v[200:203], v253 offset:18432
	ds_read_b128 v[204:207], v190 offset:20480
	ds_read_b128 v[208:211], v253 offset:20480
	ds_read_b128 v[212:215], v190 offset:22528
	ds_read_b128 v[216:219], v253 offset:22528
	global_load_lds_dwordx4 v[220:221], off
	s_add_i32 m0, s48, 0x2000
	s_add_u32 s48, s52, 0xb0000
	v_lshl_add_u64 v[222:223], s[52:53], 0, v[162:163]
	s_addc_u32 s49, s53, 0
	s_add_i32 s75, s69, s58
	global_load_lds_dwordx4 v[222:223], off
	v_lshl_add_u64 v[224:225], s[48:49], 0, v[154:155]
	s_mov_b32 m0, s75
	v_lshl_add_u64 v[226:227], s[54:55], 0, v[160:161]
	global_load_lds_dwordx4 v[224:225], off
	v_lshl_add_u64 v[224:225], s[48:49], 0, v[162:163]
	s_add_i32 m0, s75, 0x2000
	s_nop 0
	global_load_lds_dwordx4 v[224:225], off
	v_lshl_add_u64 v[224:225], s[54:55], 0, v[152:153]
	s_mov_b32 m0, s59
	s_nop 0
	global_load_lds_dwordx4 v[224:225], off
	s_mov_b32 m0, s60
	s_nop 0
	global_load_lds_dwordx4 v[226:227], off
	s_waitcnt vmcnt(8)
	s_waitcnt lgkmcnt(0)
	s_barrier
	s_setprio 1
	s_waitcnt lgkmcnt(0)
	v_mfma_f32_16x16x32_bf16 v[60:63], v[128:131], v[180:183], v[60:63]
	v_mfma_f32_16x16x32_bf16 v[60:63], v[132:135], v[192:195], v[60:63]
	v_mfma_f32_16x16x32_bf16 v[56:59], v[136:139], v[180:183], v[56:59]
	v_mfma_f32_16x16x32_bf16 v[56:59], v[140:143], v[192:195], v[56:59]
	v_mfma_f32_16x16x32_bf16 v[44:47], v[128:131], v[196:199], v[44:47]
	v_mfma_f32_16x16x32_bf16 v[44:47], v[132:135], v[200:203], v[44:47]
	v_mfma_f32_16x16x32_bf16 v[40:43], v[136:139], v[196:199], v[40:43]
	v_mfma_f32_16x16x32_bf16 v[40:43], v[140:143], v[200:203], v[40:43]
	v_mfma_f32_16x16x32_bf16 v[28:31], v[128:131], v[204:207], v[28:31]
	v_mfma_f32_16x16x32_bf16 v[28:31], v[132:135], v[208:211], v[28:31]
	v_mfma_f32_16x16x32_bf16 v[24:27], v[136:139], v[204:207], v[24:27]
	v_mfma_f32_16x16x32_bf16 v[24:27], v[140:143], v[208:211], v[24:27]
	v_mfma_f32_16x16x32_bf16 v[12:15], v[128:131], v[212:215], v[12:15]
	v_mfma_f32_16x16x32_bf16 v[12:15], v[132:135], v[216:219], v[12:15]
	v_mfma_f32_16x16x32_bf16 v[8:11], v[136:139], v[212:215], v[8:11]
	v_mfma_f32_16x16x32_bf16 v[8:11], v[140:143], v[216:219], v[8:11]
	s_setprio 0
	s_setprio 1
	v_mfma_f32_16x16x32_bf16 v[52:55], v[144:147], v[180:183], v[52:55]
	v_mfma_f32_16x16x32_bf16 v[52:55], v[148:151], v[192:195], v[52:55]
	v_mfma_f32_16x16x32_bf16 v[48:51], v[172:175], v[180:183], v[48:51]
	v_mfma_f32_16x16x32_bf16 v[48:51], v[176:179], v[192:195], v[48:51]
	v_mfma_f32_16x16x32_bf16 v[36:39], v[144:147], v[196:199], v[36:39]
	v_mfma_f32_16x16x32_bf16 v[36:39], v[148:151], v[200:203], v[36:39]
	v_mfma_f32_16x16x32_bf16 v[32:35], v[172:175], v[196:199], v[32:35]
	v_mfma_f32_16x16x32_bf16 v[32:35], v[176:179], v[200:203], v[32:35]
	v_mfma_f32_16x16x32_bf16 v[20:23], v[144:147], v[204:207], v[20:23]
	v_mfma_f32_16x16x32_bf16 v[20:23], v[148:151], v[208:211], v[20:23]
	v_mfma_f32_16x16x32_bf16 v[16:19], v[172:175], v[204:207], v[16:19]
	v_mfma_f32_16x16x32_bf16 v[16:19], v[176:179], v[208:211], v[16:19]
	v_mfma_f32_16x16x32_bf16 v[4:7], v[144:147], v[212:215], v[4:7]
	v_mfma_f32_16x16x32_bf16 v[4:7], v[148:151], v[216:219], v[4:7]
	v_mfma_f32_16x16x32_bf16 v[0:3], v[172:175], v[212:215], v[0:3]
	v_mfma_f32_16x16x32_bf16 v[0:3], v[176:179], v[216:219], v[0:3]
	s_setprio 0
	s_barrier
	s_add_i32 s75, 0, 0x18000
	s_add_i32 s76, 0, 0x1c000
	v_add_u32_e32 v140, s75, v185
	v_add_u32_e32 v176, s76, v185
	ds_read_b128 v[128:131], v140
	v_xor_b32_e32 v253, 64, v140
	ds_read_b128 v[132:135], v253
	ds_read_b128 v[136:139], v140 offset:2048
	ds_read_b128 v[140:143], v253 offset:2048
	ds_read_b128 v[144:147], v176
	v_xor_b32_e32 v253, 64, v176
	ds_read_b128 v[148:151], v253
	ds_read_b128 v[172:175], v176 offset:2048
	ds_read_b128 v[176:179], v253 offset:2048
	s_add_u32 s48, s54, 0xb0000
	s_addc_u32 s49, s55, 0
	s_mov_b32 m0, s61
	v_lshl_add_u64 v[228:229], s[48:49], 0, v[152:153]
	ds_read_b128 v[180:183], v190 offset:32768
	v_xor_b32_e32 v253, 64, v190
	ds_read_b128 v[192:195], v253 offset:32768
	ds_read_b128 v[196:199], v190 offset:34816
	ds_read_b128 v[200:203], v253 offset:34816
	ds_read_b128 v[204:207], v190 offset:36864
	ds_read_b128 v[208:211], v253 offset:36864
	ds_read_b128 v[212:215], v190 offset:38912
	ds_read_b128 v[216:219], v253 offset:38912
	global_load_lds_dwordx4 v[228:229], off
	v_lshl_add_u64 v[228:229], s[48:49], 0, v[160:161]
	s_mov_b32 m0, s62
	s_nop 0
	global_load_lds_dwordx4 v[228:229], off
	s_waitcnt vmcnt(8)
	s_waitcnt lgkmcnt(0)
	s_barrier
	s_setprio 1
	s_waitcnt lgkmcnt(0)
	v_mfma_f32_16x16x32_bf16 v[124:127], v[128:131], v[180:183], v[124:127]
	v_mfma_f32_16x16x32_bf16 v[124:127], v[132:135], v[192:195], v[124:127]
	v_mfma_f32_16x16x32_bf16 v[120:123], v[136:139], v[180:183], v[120:123]
	v_mfma_f32_16x16x32_bf16 v[120:123], v[140:143], v[192:195], v[120:123]
	v_mfma_f32_16x16x32_bf16 v[108:111], v[128:131], v[196:199], v[108:111]
	v_mfma_f32_16x16x32_bf16 v[108:111], v[132:135], v[200:203], v[108:111]
	v_mfma_f32_16x16x32_bf16 v[104:107], v[136:139], v[196:199], v[104:107]
	v_mfma_f32_16x16x32_bf16 v[104:107], v[140:143], v[200:203], v[104:107]
	v_mfma_f32_16x16x32_bf16 v[92:95], v[128:131], v[204:207], v[92:95]
	v_mfma_f32_16x16x32_bf16 v[92:95], v[132:135], v[208:211], v[92:95]
	v_mfma_f32_16x16x32_bf16 v[88:91], v[136:139], v[204:207], v[88:91]
	v_mfma_f32_16x16x32_bf16 v[88:91], v[140:143], v[208:211], v[88:91]
	v_mfma_f32_16x16x32_bf16 v[76:79], v[128:131], v[212:215], v[76:79]
	v_mfma_f32_16x16x32_bf16 v[76:79], v[132:135], v[216:219], v[76:79]
	v_mfma_f32_16x16x32_bf16 v[72:75], v[136:139], v[212:215], v[72:75]
	v_mfma_f32_16x16x32_bf16 v[72:75], v[140:143], v[216:219], v[72:75]
	s_setprio 0
	s_setprio 1
	v_mfma_f32_16x16x32_bf16 v[116:119], v[144:147], v[180:183], v[116:119]
	v_mfma_f32_16x16x32_bf16 v[116:119], v[148:151], v[192:195], v[116:119]
	v_mfma_f32_16x16x32_bf16 v[112:115], v[172:175], v[180:183], v[112:115]
	v_mfma_f32_16x16x32_bf16 v[112:115], v[176:179], v[192:195], v[112:115]
	v_mfma_f32_16x16x32_bf16 v[100:103], v[144:147], v[196:199], v[100:103]
	v_mfma_f32_16x16x32_bf16 v[100:103], v[148:151], v[200:203], v[100:103]
	v_mfma_f32_16x16x32_bf16 v[96:99], v[172:175], v[196:199], v[96:99]
	v_mfma_f32_16x16x32_bf16 v[96:99], v[176:179], v[200:203], v[96:99]
	v_mfma_f32_16x16x32_bf16 v[84:87], v[144:147], v[204:207], v[84:87]
	v_mfma_f32_16x16x32_bf16 v[84:87], v[148:151], v[208:211], v[84:87]
	v_mfma_f32_16x16x32_bf16 v[80:83], v[172:175], v[204:207], v[80:83]
	v_mfma_f32_16x16x32_bf16 v[80:83], v[176:179], v[208:211], v[80:83]
	v_mfma_f32_16x16x32_bf16 v[68:71], v[144:147], v[212:215], v[68:71]
	v_mfma_f32_16x16x32_bf16 v[68:71], v[148:151], v[216:219], v[68:71]
	v_mfma_f32_16x16x32_bf16 v[64:67], v[172:175], v[212:215], v[64:67]
	v_mfma_f32_16x16x32_bf16 v[64:67], v[176:179], v[216:219], v[64:67]
	s_setprio 0
	s_barrier
	s_add_i32 s48, s75, s58
	v_lshl_add_u64 v[220:221], v[220:221], 0, s[22:23]
	s_mov_b32 m0, s48
	ds_read_b128 v[180:183], v190 offset:49152
	v_xor_b32_e32 v253, 64, v190
	ds_read_b128 v[192:195], v253 offset:49152
	ds_read_b128 v[196:199], v190 offset:51200
	ds_read_b128 v[200:203], v253 offset:51200
	ds_read_b128 v[204:207], v190 offset:53248
	ds_read_b128 v[208:211], v253 offset:53248
	ds_read_b128 v[212:215], v190 offset:55296
	ds_read_b128 v[216:219], v253 offset:55296
	global_load_lds_dwordx4 v[220:221], off
	s_add_i32 m0, s48, 0x2000
	s_add_u32 s48, s52, 0xb0080
	v_lshl_add_u64 v[220:221], v[222:223], 0, s[22:23]
	s_addc_u32 s49, s53, 0
	s_add_i32 s52, s76, s58
	global_load_lds_dwordx4 v[220:221], off
	v_lshl_add_u64 v[220:221], s[48:49], 0, v[154:155]
	s_mov_b32 m0, s52
	s_nop 0
	global_load_lds_dwordx4 v[220:221], off
	v_lshl_add_u64 v[220:221], s[48:49], 0, v[162:163]
	s_add_i32 m0, s52, 0x2000
	s_nop 0
	global_load_lds_dwordx4 v[220:221], off
	v_lshl_add_u64 v[220:221], v[224:225], 0, s[22:23]
	s_mov_b32 m0, s3
	s_nop 0
	global_load_lds_dwordx4 v[220:221], off
	v_lshl_add_u64 v[220:221], v[226:227], 0, s[22:23]
	s_mov_b32 m0, s64
	s_nop 0
	global_load_lds_dwordx4 v[220:221], off
	s_waitcnt vmcnt(8)
	s_waitcnt lgkmcnt(0)
	s_barrier
	s_setprio 1
	s_waitcnt lgkmcnt(0)
	v_mfma_f32_16x16x32_bf16 v[60:63], v[128:131], v[180:183], v[60:63]
	v_mfma_f32_16x16x32_bf16 v[60:63], v[132:135], v[192:195], v[60:63]
	v_mfma_f32_16x16x32_bf16 v[56:59], v[136:139], v[180:183], v[56:59]
	v_mfma_f32_16x16x32_bf16 v[56:59], v[140:143], v[192:195], v[56:59]
	v_mfma_f32_16x16x32_bf16 v[44:47], v[128:131], v[196:199], v[44:47]
	v_mfma_f32_16x16x32_bf16 v[44:47], v[132:135], v[200:203], v[44:47]
	v_mfma_f32_16x16x32_bf16 v[40:43], v[136:139], v[196:199], v[40:43]
	v_mfma_f32_16x16x32_bf16 v[40:43], v[140:143], v[200:203], v[40:43]
	v_mfma_f32_16x16x32_bf16 v[28:31], v[128:131], v[204:207], v[28:31]
	v_mfma_f32_16x16x32_bf16 v[28:31], v[132:135], v[208:211], v[28:31]
	v_mfma_f32_16x16x32_bf16 v[24:27], v[136:139], v[204:207], v[24:27]
	v_mfma_f32_16x16x32_bf16 v[24:27], v[140:143], v[208:211], v[24:27]
	v_mfma_f32_16x16x32_bf16 v[12:15], v[128:131], v[212:215], v[12:15]
	v_mfma_f32_16x16x32_bf16 v[12:15], v[132:135], v[216:219], v[12:15]
	v_mfma_f32_16x16x32_bf16 v[8:11], v[136:139], v[212:215], v[8:11]
	v_mfma_f32_16x16x32_bf16 v[8:11], v[140:143], v[216:219], v[8:11]
	s_setprio 0
	s_setprio 1
	v_mfma_f32_16x16x32_bf16 v[52:55], v[144:147], v[180:183], v[52:55]
	v_mfma_f32_16x16x32_bf16 v[52:55], v[148:151], v[192:195], v[52:55]
	v_mfma_f32_16x16x32_bf16 v[48:51], v[172:175], v[180:183], v[48:51]
	v_mfma_f32_16x16x32_bf16 v[48:51], v[176:179], v[192:195], v[48:51]
	v_mfma_f32_16x16x32_bf16 v[36:39], v[144:147], v[196:199], v[36:39]
	v_mfma_f32_16x16x32_bf16 v[36:39], v[148:151], v[200:203], v[36:39]
	v_mfma_f32_16x16x32_bf16 v[32:35], v[172:175], v[196:199], v[32:35]
	v_mfma_f32_16x16x32_bf16 v[32:35], v[176:179], v[200:203], v[32:35]
	v_mfma_f32_16x16x32_bf16 v[20:23], v[144:147], v[204:207], v[20:23]
	v_mfma_f32_16x16x32_bf16 v[20:23], v[148:151], v[208:211], v[20:23]
	v_mfma_f32_16x16x32_bf16 v[16:19], v[172:175], v[204:207], v[16:19]
	v_mfma_f32_16x16x32_bf16 v[16:19], v[176:179], v[208:211], v[16:19]
	v_mfma_f32_16x16x32_bf16 v[4:7], v[144:147], v[212:215], v[4:7]
	v_mfma_f32_16x16x32_bf16 v[4:7], v[148:151], v[216:219], v[4:7]
	v_mfma_f32_16x16x32_bf16 v[0:3], v[172:175], v[212:215], v[0:3]
	v_mfma_f32_16x16x32_bf16 v[0:3], v[176:179], v[216:219], v[0:3]
	s_setprio 0
	s_barrier
	s_add_i32 s74, s74, 2
	s_add_u32 s72, s72, 0x100
	s_addc_u32 s73, s73, 0
	s_cmp_gt_u32 s74, 41
	s_mov_b64 s[48:49], s[50:51]
	s_cbranch_scc0 .LBB0_1181
	s_and_b64 vcc, exec, s[24:25]
	s_cbranch_vccz .LBB0_1184
	s_barrier
